# GEMM K-loops: pre-barrier lgkmcnt(8) scheduling waits removed (post-barrier lgkmcnt(0) kept)
# speedup vs baseline: 1.0014x; 1.0014x over previous
.LBB0_155:
	ds_read_b128 v[154:157], v150
	ds_read_b128 v[158:161], v150 offset:1024
	ds_read_b128 v[162:165], v150 offset:2048
	ds_read_b128 v[166:169], v150 offset:3072
	s_add_u32 s26, s20, 0xfffc0080
	s_addc_u32 s27, s21, -1
	s_cmp_eq_u32 s86, 12
	s_cselect_b32 s29, s15, s27
	s_cselect_b32 s28, s82, s26
	s_cselect_b32 s27, s13, s85
	s_cselect_b32 s26, s83, s84
	v_lshl_add_u64 v[202:203], s[20:21], 0, v[138:139]
	s_add_i32 m0, s11, 0xc000
	ds_read_b128 v[170:173], v151
	ds_read_b128 v[174:177], v151 offset:1024
	ds_read_b128 v[178:181], v151 offset:2048
	ds_read_b128 v[182:185], v151 offset:3072
	ds_read_b128 v[186:189], v151 offset:4096
	ds_read_b128 v[190:193], v151 offset:5120
	ds_read_b128 v[194:197], v151 offset:6144
	ds_read_b128 v[198:201], v151 offset:7168
	global_load_lds_dwordx4 v[202:203], off
	v_lshl_add_u64 v[202:203], s[20:21], 0, v[140:141]
	s_add_i32 m0, s11, 0xe000
	s_nop 0
	global_load_lds_dwordx4 v[202:203], off
	s_barrier
	s_waitcnt lgkmcnt(0)
	s_waitcnt lgkmcnt(0)
	v_mfma_f32_16x16x32_bf16 v[124:127], v[154:157], v[170:173], v[124:127]
	v_mfma_f32_16x16x32_bf16 v[120:123], v[162:165], v[170:173], v[120:123]
	v_mfma_f32_16x16x32_bf16 v[116:119], v[154:157], v[178:181], v[116:119]
	v_mfma_f32_16x16x32_bf16 v[112:115], v[162:165], v[178:181], v[112:115]
	v_mfma_f32_16x16x32_bf16 v[100:103], v[154:157], v[186:189], v[100:103]
	v_mfma_f32_16x16x32_bf16 v[96:99], v[162:165], v[186:189], v[96:99]
	v_mfma_f32_16x16x32_bf16 v[84:87], v[154:157], v[194:197], v[84:87]
	v_mfma_f32_16x16x32_bf16 v[80:83], v[162:165], v[194:197], v[80:83]
	v_mfma_f32_16x16x32_bf16 v[124:127], v[158:161], v[174:177], v[124:127]
	v_mfma_f32_16x16x32_bf16 v[120:123], v[166:169], v[174:177], v[120:123]
	v_mfma_f32_16x16x32_bf16 v[116:119], v[158:161], v[182:185], v[116:119]
	v_mfma_f32_16x16x32_bf16 v[112:115], v[166:169], v[182:185], v[112:115]
	v_mfma_f32_16x16x32_bf16 v[100:103], v[158:161], v[190:193], v[100:103]
	v_mfma_f32_16x16x32_bf16 v[96:99], v[166:169], v[190:193], v[96:99]
	v_mfma_f32_16x16x32_bf16 v[84:87], v[158:161], v[198:201], v[84:87]
	v_mfma_f32_16x16x32_bf16 v[80:83], v[166:169], v[198:201], v[80:83]
	s_barrier
	s_add_i32 s87, s72, s34
	v_lshl_add_u64 v[218:219], s[26:27], 0, v[134:135]
	s_mov_b32 m0, s87
	ds_read_b128 v[202:205], v152
	ds_read_b128 v[206:209], v152 offset:1024
	ds_read_b128 v[210:213], v152 offset:2048
	ds_read_b128 v[214:217], v152 offset:3072
	global_load_lds_dwordx4 v[218:219], off
	v_lshl_add_u64 v[220:221], s[26:27], 0, v[130:131]
	s_add_i32 m0, s87, 0x2000
	s_nop 0
	global_load_lds_dwordx4 v[220:221], off
	s_barrier
	s_waitcnt lgkmcnt(0)
	s_waitcnt lgkmcnt(0)
	v_mfma_f32_16x16x32_bf16 v[108:111], v[202:205], v[170:173], v[108:111]
	v_mfma_f32_16x16x32_bf16 v[104:107], v[210:213], v[170:173], v[104:107]
	v_mfma_f32_16x16x32_bf16 v[92:95], v[202:205], v[178:181], v[92:95]
	v_mfma_f32_16x16x32_bf16 v[88:91], v[210:213], v[178:181], v[88:91]
	v_mfma_f32_16x16x32_bf16 v[76:79], v[202:205], v[186:189], v[76:79]
	v_mfma_f32_16x16x32_bf16 v[72:75], v[210:213], v[186:189], v[72:75]
	v_mfma_f32_16x16x32_bf16 v[68:71], v[202:205], v[194:197], v[68:71]
	v_mfma_f32_16x16x32_bf16 v[64:67], v[210:213], v[194:197], v[64:67]
	v_mfma_f32_16x16x32_bf16 v[108:111], v[206:209], v[174:177], v[108:111]
	v_mfma_f32_16x16x32_bf16 v[104:107], v[214:217], v[174:177], v[104:107]
	v_mfma_f32_16x16x32_bf16 v[92:95], v[206:209], v[182:185], v[92:95]
	v_mfma_f32_16x16x32_bf16 v[88:91], v[214:217], v[182:185], v[88:91]
	v_mfma_f32_16x16x32_bf16 v[76:79], v[206:209], v[190:193], v[76:79]
	v_mfma_f32_16x16x32_bf16 v[72:75], v[214:217], v[190:193], v[72:75]
	v_mfma_f32_16x16x32_bf16 v[68:71], v[206:209], v[198:201], v[68:71]
	v_mfma_f32_16x16x32_bf16 v[64:67], v[214:217], v[198:201], v[64:67]
	s_mov_b32 m0, s11
	v_lshl_add_u64 v[222:223], s[28:29], 0, v[136:137]
	s_barrier
	ds_read_b128 v[170:173], v151 offset:16384
	ds_read_b128 v[174:177], v151 offset:17408
	ds_read_b128 v[178:181], v151 offset:18432
	ds_read_b128 v[182:185], v151 offset:19456
	ds_read_b128 v[186:189], v151 offset:20480
	ds_read_b128 v[190:193], v151 offset:21504
	ds_read_b128 v[194:197], v151 offset:22528
	ds_read_b128 v[198:201], v151 offset:23552
	global_load_lds_dwordx4 v[222:223], off
	v_lshl_add_u64 v[224:225], s[28:29], 0, v[132:133]
	s_mov_b32 m0, s35
	s_nop 0
	global_load_lds_dwordx4 v[224:225], off
	s_barrier
	s_waitcnt lgkmcnt(0)
	s_waitcnt lgkmcnt(0)
	v_mfma_f32_16x16x32_bf16 v[60:63], v[154:157], v[170:173], v[60:63]
	v_mfma_f32_16x16x32_bf16 v[56:59], v[162:165], v[170:173], v[56:59]
	v_mfma_f32_16x16x32_bf16 v[52:55], v[154:157], v[178:181], v[52:55]
	v_mfma_f32_16x16x32_bf16 v[48:51], v[162:165], v[178:181], v[48:51]
	v_mfma_f32_16x16x32_bf16 v[36:39], v[154:157], v[186:189], v[36:39]
	v_mfma_f32_16x16x32_bf16 v[32:35], v[162:165], v[186:189], v[32:35]
	v_mfma_f32_16x16x32_bf16 v[20:23], v[154:157], v[194:197], v[20:23]
	v_mfma_f32_16x16x32_bf16 v[16:19], v[162:165], v[194:197], v[16:19]
	v_mfma_f32_16x16x32_bf16 v[60:63], v[158:161], v[174:177], v[60:63]
	v_mfma_f32_16x16x32_bf16 v[56:59], v[166:169], v[174:177], v[56:59]
	v_mfma_f32_16x16x32_bf16 v[52:55], v[158:161], v[182:185], v[52:55]
	v_mfma_f32_16x16x32_bf16 v[48:51], v[166:169], v[182:185], v[48:51]
	v_mfma_f32_16x16x32_bf16 v[36:39], v[158:161], v[190:193], v[36:39]
	v_mfma_f32_16x16x32_bf16 v[32:35], v[166:169], v[190:193], v[32:35]
	v_mfma_f32_16x16x32_bf16 v[20:23], v[158:161], v[198:201], v[20:23]
	v_mfma_f32_16x16x32_bf16 v[16:19], v[166:169], v[198:201], v[16:19]
	s_barrier
	s_add_u32 s88, s26, 0x40000
	s_addc_u32 s89, s27, 0
	s_add_i32 s87, s73, s34
	v_lshl_add_u64 v[154:155], s[88:89], 0, v[134:135]
	s_mov_b32 m0, s87
	s_nop 0
	global_load_lds_dwordx4 v[154:155], off
	v_lshl_add_u64 v[154:155], s[88:89], 0, v[130:131]
	s_add_i32 m0, s87, 0x2000
	s_nop 0
	global_load_lds_dwordx4 v[154:155], off
	s_waitcnt vmcnt(6)
	s_barrier
	v_mfma_f32_16x16x32_bf16 v[44:47], v[202:205], v[170:173], v[44:47]
	v_mfma_f32_16x16x32_bf16 v[40:43], v[210:213], v[170:173], v[40:43]
	v_mfma_f32_16x16x32_bf16 v[28:31], v[202:205], v[178:181], v[28:31]
	v_mfma_f32_16x16x32_bf16 v[24:27], v[210:213], v[178:181], v[24:27]
	v_mfma_f32_16x16x32_bf16 v[12:15], v[202:205], v[186:189], v[12:15]
	v_mfma_f32_16x16x32_bf16 v[8:11], v[210:213], v[186:189], v[8:11]
	v_mfma_f32_16x16x32_bf16 v[4:7], v[202:205], v[194:197], v[4:7]
	v_mfma_f32_16x16x32_bf16 v[0:3], v[210:213], v[194:197], v[0:3]
	v_mfma_f32_16x16x32_bf16 v[44:47], v[206:209], v[174:177], v[44:47]
	v_mfma_f32_16x16x32_bf16 v[40:43], v[214:217], v[174:177], v[40:43]
	v_mfma_f32_16x16x32_bf16 v[28:31], v[206:209], v[182:185], v[28:31]
	v_mfma_f32_16x16x32_bf16 v[24:27], v[214:217], v[182:185], v[24:27]
	v_mfma_f32_16x16x32_bf16 v[12:15], v[206:209], v[190:193], v[12:15]
	v_mfma_f32_16x16x32_bf16 v[8:11], v[214:217], v[190:193], v[8:11]
	v_mfma_f32_16x16x32_bf16 v[4:7], v[206:209], v[198:201], v[4:7]
	v_mfma_f32_16x16x32_bf16 v[0:3], v[214:217], v[198:201], v[0:3]
	s_add_i32 s87, 0, 0x18000
	v_add_u32_e32 v153, s87, v148
	s_barrier
	ds_read_b128 v[154:157], v153
	ds_read_b128 v[158:161], v153 offset:1024
	ds_read_b128 v[162:165], v153 offset:2048
	ds_read_b128 v[166:169], v153 offset:3072
	s_add_u32 s28, s28, 0x40000
	s_addc_u32 s29, s29, 0
	s_mov_b32 m0, s54
	v_lshl_add_u64 v[202:203], s[28:29], 0, v[136:137]
	ds_read_b128 v[170:173], v151 offset:32768
	ds_read_b128 v[174:177], v151 offset:33792
	ds_read_b128 v[178:181], v151 offset:34816
	ds_read_b128 v[182:185], v151 offset:35840
	ds_read_b128 v[186:189], v151 offset:36864
	ds_read_b128 v[190:193], v151 offset:37888
	ds_read_b128 v[194:197], v151 offset:38912
	ds_read_b128 v[198:201], v151 offset:39936
	global_load_lds_dwordx4 v[202:203], off
	v_lshl_add_u64 v[202:203], s[28:29], 0, v[132:133]
	s_mov_b32 m0, s55
	s_nop 0
	global_load_lds_dwordx4 v[202:203], off
	s_barrier
	s_waitcnt lgkmcnt(0)
	s_waitcnt lgkmcnt(0)
	v_mfma_f32_16x16x32_bf16 v[124:127], v[154:157], v[170:173], v[124:127]
	v_mfma_f32_16x16x32_bf16 v[120:123], v[162:165], v[170:173], v[120:123]
	v_mfma_f32_16x16x32_bf16 v[116:119], v[154:157], v[178:181], v[116:119]
	v_mfma_f32_16x16x32_bf16 v[112:115], v[162:165], v[178:181], v[112:115]
	v_mfma_f32_16x16x32_bf16 v[100:103], v[154:157], v[186:189], v[100:103]
	v_mfma_f32_16x16x32_bf16 v[96:99], v[162:165], v[186:189], v[96:99]
	v_mfma_f32_16x16x32_bf16 v[84:87], v[154:157], v[194:197], v[84:87]
	v_mfma_f32_16x16x32_bf16 v[80:83], v[162:165], v[194:197], v[80:83]
	v_mfma_f32_16x16x32_bf16 v[124:127], v[158:161], v[174:177], v[124:127]
	v_mfma_f32_16x16x32_bf16 v[120:123], v[166:169], v[174:177], v[120:123]
	v_mfma_f32_16x16x32_bf16 v[116:119], v[158:161], v[182:185], v[116:119]
	v_mfma_f32_16x16x32_bf16 v[112:115], v[166:169], v[182:185], v[112:115]
	v_mfma_f32_16x16x32_bf16 v[100:103], v[158:161], v[190:193], v[100:103]
	v_mfma_f32_16x16x32_bf16 v[96:99], v[166:169], v[190:193], v[96:99]
	v_mfma_f32_16x16x32_bf16 v[84:87], v[158:161], v[198:201], v[84:87]
	v_mfma_f32_16x16x32_bf16 v[80:83], v[166:169], v[198:201], v[80:83]
	s_barrier
	s_add_i32 s28, 0, 0x1c000
	s_add_i32 s29, s87, s34
	v_add_u32_e32 v153, s28, v148
	v_lshl_add_u64 v[218:219], v[218:219], 0, s[8:9]
	s_mov_b32 m0, s29
	ds_read_b128 v[202:205], v153
	ds_read_b128 v[206:209], v153 offset:1024
	ds_read_b128 v[210:213], v153 offset:2048
	ds_read_b128 v[214:217], v153 offset:3072
	global_load_lds_dwordx4 v[218:219], off
	v_lshl_add_u64 v[218:219], v[220:221], 0, s[8:9]
	s_add_i32 m0, s29, 0x2000
	s_nop 0
	global_load_lds_dwordx4 v[218:219], off
	s_barrier
	s_waitcnt lgkmcnt(0)
	s_waitcnt lgkmcnt(0)
	v_mfma_f32_16x16x32_bf16 v[108:111], v[202:205], v[170:173], v[108:111]
	v_mfma_f32_16x16x32_bf16 v[104:107], v[210:213], v[170:173], v[104:107]
	v_mfma_f32_16x16x32_bf16 v[92:95], v[202:205], v[178:181], v[92:95]
	v_mfma_f32_16x16x32_bf16 v[88:91], v[210:213], v[178:181], v[88:91]
	v_mfma_f32_16x16x32_bf16 v[76:79], v[202:205], v[186:189], v[76:79]
	v_mfma_f32_16x16x32_bf16 v[72:75], v[210:213], v[186:189], v[72:75]
	v_mfma_f32_16x16x32_bf16 v[68:71], v[202:205], v[194:197], v[68:71]
	v_mfma_f32_16x16x32_bf16 v[64:67], v[210:213], v[194:197], v[64:67]
	v_mfma_f32_16x16x32_bf16 v[108:111], v[206:209], v[174:177], v[108:111]
	v_mfma_f32_16x16x32_bf16 v[104:107], v[214:217], v[174:177], v[104:107]
	v_mfma_f32_16x16x32_bf16 v[92:95], v[206:209], v[182:185], v[92:95]
	v_mfma_f32_16x16x32_bf16 v[88:91], v[214:217], v[182:185], v[88:91]
	v_mfma_f32_16x16x32_bf16 v[76:79], v[206:209], v[190:193], v[76:79]
	v_mfma_f32_16x16x32_bf16 v[72:75], v[214:217], v[190:193], v[72:75]
	v_mfma_f32_16x16x32_bf16 v[68:71], v[206:209], v[198:201], v[68:71]
	v_mfma_f32_16x16x32_bf16 v[64:67], v[214:217], v[198:201], v[64:67]
	s_mov_b32 m0, s57
	v_lshl_add_u64 v[218:219], v[222:223], 0, s[8:9]
	s_barrier
	ds_read_b128 v[170:173], v151 offset:49152
	ds_read_b128 v[174:177], v151 offset:50176
	ds_read_b128 v[178:181], v151 offset:51200
	ds_read_b128 v[182:185], v151 offset:52224
	ds_read_b128 v[186:189], v151 offset:53248
	ds_read_b128 v[190:193], v151 offset:54272
	ds_read_b128 v[194:197], v151 offset:55296
	ds_read_b128 v[198:201], v151 offset:56320
	global_load_lds_dwordx4 v[218:219], off
	v_lshl_add_u64 v[218:219], v[224:225], 0, s[8:9]
	s_mov_b32 m0, s70
	s_nop 0
	global_load_lds_dwordx4 v[218:219], off
	s_barrier
	s_waitcnt lgkmcnt(0)
	s_waitcnt lgkmcnt(0)
	v_mfma_f32_16x16x32_bf16 v[60:63], v[154:157], v[170:173], v[60:63]
	v_mfma_f32_16x16x32_bf16 v[56:59], v[162:165], v[170:173], v[56:59]
	v_mfma_f32_16x16x32_bf16 v[52:55], v[154:157], v[178:181], v[52:55]
	v_mfma_f32_16x16x32_bf16 v[48:51], v[162:165], v[178:181], v[48:51]
	v_mfma_f32_16x16x32_bf16 v[36:39], v[154:157], v[186:189], v[36:39]
	v_mfma_f32_16x16x32_bf16 v[32:35], v[162:165], v[186:189], v[32:35]
	v_mfma_f32_16x16x32_bf16 v[20:23], v[154:157], v[194:197], v[20:23]
	v_mfma_f32_16x16x32_bf16 v[16:19], v[162:165], v[194:197], v[16:19]
	v_mfma_f32_16x16x32_bf16 v[60:63], v[158:161], v[174:177], v[60:63]
	v_mfma_f32_16x16x32_bf16 v[56:59], v[166:169], v[174:177], v[56:59]
	v_mfma_f32_16x16x32_bf16 v[52:55], v[158:161], v[182:185], v[52:55]
	v_mfma_f32_16x16x32_bf16 v[48:51], v[166:169], v[182:185], v[48:51]
	v_mfma_f32_16x16x32_bf16 v[36:39], v[158:161], v[190:193], v[36:39]
	v_mfma_f32_16x16x32_bf16 v[32:35], v[166:169], v[190:193], v[32:35]
	v_mfma_f32_16x16x32_bf16 v[20:23], v[158:161], v[198:201], v[20:23]
	v_mfma_f32_16x16x32_bf16 v[16:19], v[166:169], v[198:201], v[16:19]
	s_barrier
	s_add_u32 s26, s26, 0x40080
	s_addc_u32 s27, s27, 0
	s_add_i32 s28, s28, s34
	v_lshl_add_u64 v[154:155], s[26:27], 0, v[134:135]
	s_mov_b32 m0, s28
	s_nop 0
	global_load_lds_dwordx4 v[154:155], off
	v_lshl_add_u64 v[154:155], s[26:27], 0, v[130:131]
	s_add_i32 m0, s28, 0x2000
	s_nop 0
	global_load_lds_dwordx4 v[154:155], off
	s_waitcnt vmcnt(6)
	s_barrier
	v_mfma_f32_16x16x32_bf16 v[44:47], v[202:205], v[170:173], v[44:47]
	v_mfma_f32_16x16x32_bf16 v[40:43], v[210:213], v[170:173], v[40:43]
	v_mfma_f32_16x16x32_bf16 v[28:31], v[202:205], v[178:181], v[28:31]
	v_mfma_f32_16x16x32_bf16 v[24:27], v[210:213], v[178:181], v[24:27]
	v_mfma_f32_16x16x32_bf16 v[12:15], v[202:205], v[186:189], v[12:15]
	v_mfma_f32_16x16x32_bf16 v[8:11], v[210:213], v[186:189], v[8:11]
	v_mfma_f32_16x16x32_bf16 v[4:7], v[202:205], v[194:197], v[4:7]
	v_mfma_f32_16x16x32_bf16 v[0:3], v[210:213], v[194:197], v[0:3]
	v_mfma_f32_16x16x32_bf16 v[44:47], v[206:209], v[174:177], v[44:47]
	v_mfma_f32_16x16x32_bf16 v[40:43], v[214:217], v[174:177], v[40:43]
	v_mfma_f32_16x16x32_bf16 v[28:31], v[206:209], v[182:185], v[28:31]
	v_mfma_f32_16x16x32_bf16 v[24:27], v[214:217], v[182:185], v[24:27]
	v_mfma_f32_16x16x32_bf16 v[12:15], v[206:209], v[190:193], v[12:15]
	v_mfma_f32_16x16x32_bf16 v[8:11], v[214:217], v[190:193], v[8:11]
	v_mfma_f32_16x16x32_bf16 v[4:7], v[206:209], v[198:201], v[4:7]
	v_mfma_f32_16x16x32_bf16 v[0:3], v[214:217], v[198:201], v[0:3]
	s_add_i32 s86, s86, 2
	s_add_u32 s20, s20, 0x100
	s_addc_u32 s21, s21, 0
	s_add_u32 s84, s84, 0x100
	s_addc_u32 s85, s85, 0
	s_cmp_gt_u32 s86, 13
	s_barrier
	s_cbranch_scc0 .LBB0_155
	v_lshl_add_u32 v153, s10, 8, v147
	v_lshl_or_b32 v154, s75, 8, v149
	v_mov_b64_e32 v[156:157], s[46:47]
	v_ashrrev_i32_e32 v155, 31, v154
	v_cvt_pk_bf16_f32 v68, v68, v69
	v_cvt_pk_bf16_f32 v69, v70, v71
	v_cvt_pk_bf16_f32 v70, v64, v65
	v_add_u32_e32 v64, 0x80, v153
	v_mad_i64_i32 v[158:159], s[20:21], v153, s74, v[156:157]
	v_cvt_pk_bf16_f32 v124, v124, v125
	v_cvt_pk_bf16_f32 v125, v126, v127
	v_cvt_pk_bf16_f32 v126, v120, v121
	v_lshlrev_b64 v[120:121], 1, v[154:155]
	v_mad_i64_i32 v[64:65], s[20:21], v64, s74, v[156:157]
	v_cvt_pk_bf16_f32 v127, v122, v123
	v_lshl_add_u64 v[122:123], v[158:159], 0, v[120:121]
	v_cvt_pk_bf16_f32 v108, v108, v109
	v_cvt_pk_bf16_f32 v109, v110, v111
	v_cvt_pk_bf16_f32 v110, v104, v105
	v_cvt_pk_bf16_f32 v111, v106, v107
	v_or_b32_e32 v104, 16, v153
	v_cvt_pk_bf16_f32 v60, v60, v61
	v_cvt_pk_bf16_f32 v61, v62, v63
	v_cvt_pk_bf16_f32 v62, v56, v57
	v_lshl_add_u64 v[56:57], v[64:65], 0, v[120:121]
	v_cvt_pk_bf16_f32 v44, v44, v45
	v_cvt_pk_bf16_f32 v45, v46, v47
	v_cvt_pk_bf16_f32 v46, v40, v41
	v_cvt_pk_bf16_f32 v47, v42, v43
	v_add_u32_e32 v40, 0x90, v153
	global_store_dwordx4 v[122:123], v[108:111], off offset:256
	global_store_dwordx4 v[56:57], v[44:47], off offset:256
	v_cvt_pk_bf16_f32 v92, v92, v93
	v_mad_i64_i32 v[108:109], s[20:21], v104, s74, v[156:157]
	v_mad_i64_i32 v[44:45], s[20:21], v40, s74, v[156:157]
	v_lshl_add_u64 v[108:109], v[108:109], 0, v[120:121]
	v_cvt_pk_bf16_f32 v93, v94, v95
	v_cvt_pk_bf16_f32 v94, v88, v89
	v_cvt_pk_bf16_f32 v95, v90, v91
	v_or_b32_e32 v88, 32, v153
	v_lshl_add_u64 v[44:45], v[44:45], 0, v[120:121]
	v_cvt_pk_bf16_f32 v28, v28, v29
	v_cvt_pk_bf16_f32 v29, v30, v31
	v_cvt_pk_bf16_f32 v30, v24, v25
	v_cvt_pk_bf16_f32 v31, v26, v27
	v_add_u32_e32 v24, 0xa0, v153
	global_store_dwordx4 v[108:109], v[92:95], off offset:256
	global_store_dwordx4 v[44:45], v[28:31], off offset:256
	v_cvt_pk_bf16_f32 v76, v76, v77
	v_mad_i64_i32 v[92:93], s[20:21], v88, s74, v[156:157]
	v_mad_i64_i32 v[28:29], s[20:21], v24, s74, v[156:157]
	v_lshl_add_u64 v[92:93], v[92:93], 0, v[120:121]
	v_cvt_pk_bf16_f32 v77, v78, v79
	v_cvt_pk_bf16_f32 v78, v72, v73
	v_cvt_pk_bf16_f32 v79, v74, v75
	v_or_b32_e32 v72, 48, v153
	v_lshl_add_u64 v[28:29], v[28:29], 0, v[120:121]
	v_cvt_pk_bf16_f32 v12, v12, v13
	v_cvt_pk_bf16_f32 v13, v14, v15
	v_cvt_pk_bf16_f32 v14, v8, v9
	v_cvt_pk_bf16_f32 v15, v10, v11
	v_add_u32_e32 v8, 0xb0, v153
	global_store_dwordx4 v[92:93], v[76:79], off offset:256
	global_store_dwordx4 v[28:29], v[12:15], off offset:256
	v_cvt_pk_bf16_f32 v104, v116, v117
	v_mad_i64_i32 v[76:77], s[20:21], v72, s74, v[156:157]
	v_mad_i64_i32 v[12:13], s[20:21], v8, s74, v[156:157]
	v_cvt_pk_bf16_f32 v105, v118, v119
	v_cvt_pk_bf16_f32 v106, v112, v113
	v_cvt_pk_bf16_f32 v107, v114, v115
	v_cvt_pk_bf16_f32 v88, v100, v101
	v_cvt_pk_bf16_f32 v89, v102, v103
	v_cvt_pk_bf16_f32 v90, v96, v97
	v_cvt_pk_bf16_f32 v91, v98, v99
	v_cvt_pk_bf16_f32 v72, v84, v85
	v_cvt_pk_bf16_f32 v73, v86, v87
	v_cvt_pk_bf16_f32 v74, v80, v81
	v_cvt_pk_bf16_f32 v75, v82, v83
	v_lshl_add_u64 v[76:77], v[76:77], 0, v[120:121]
	v_cvt_pk_bf16_f32 v71, v66, v67
	v_cvt_pk_bf16_f32 v63, v58, v59
	v_cvt_pk_bf16_f32 v40, v52, v53
	v_cvt_pk_bf16_f32 v41, v54, v55
	v_cvt_pk_bf16_f32 v42, v48, v49
	v_cvt_pk_bf16_f32 v43, v50, v51
	v_cvt_pk_bf16_f32 v24, v36, v37
	v_cvt_pk_bf16_f32 v25, v38, v39
	v_cvt_pk_bf16_f32 v26, v32, v33
	v_cvt_pk_bf16_f32 v27, v34, v35
	v_cvt_pk_bf16_f32 v8, v20, v21
	v_cvt_pk_bf16_f32 v9, v22, v23
	v_cvt_pk_bf16_f32 v10, v16, v17
	v_cvt_pk_bf16_f32 v11, v18, v19
	v_lshl_add_u64 v[12:13], v[12:13], 0, v[120:121]
	v_cvt_pk_bf16_f32 v4, v4, v5
	v_cvt_pk_bf16_f32 v5, v6, v7
	v_cvt_pk_bf16_f32 v6, v0, v1
	v_cvt_pk_bf16_f32 v7, v2, v3
	s_and_b64 vcc, exec, s[4:5]
	s_mov_b32 s75, s12
	s_mov_b32 s10, s14
	s_mov_b64 s[26:27], s[18:19]
	s_mov_b64 s[20:21], s[16:17]
	global_store_dwordx4 v[122:123], v[124:127], off
	global_store_dwordx4 v[108:109], v[104:107], off
	global_store_dwordx4 v[92:93], v[88:91], off
	global_store_dwordx4 v[76:77], v[72:75], off
	global_store_dwordx4 v[76:77], v[68:71], off offset:256
	global_store_dwordx4 v[56:57], v[60:63], off
	global_store_dwordx4 v[44:45], v[40:43], off
	global_store_dwordx4 v[28:29], v[24:27], off
	global_store_dwordx4 v[12:13], v[8:11], off
	global_store_dwordx4 v[12:13], v[4:7], off offset:256
	s_cbranch_vccz .LBB0_152
	s_waitcnt vmcnt(0)
	s_cmpk_gt_u32 s30, 0xff
	s_cbranch_scc1 .LBB0_159
	s_barrier

.LBB0_486:
	ds_read_b128 v[154:157], v151
	ds_read_b128 v[158:161], v151 offset:1024
	ds_read_b128 v[162:165], v151 offset:2048
	ds_read_b128 v[166:169], v151 offset:3072
	s_add_u32 s30, s28, 0xfffc0080
	s_addc_u32 s31, s29, -1
	s_cmp_eq_u32 s84, 12
	s_cselect_b32 s35, s19, s31
	s_cselect_b32 s34, s80, s30
	s_cselect_b32 s31, s17, s83
	s_cselect_b32 s30, s81, s82
	v_lshl_add_u64 v[202:203], s[28:29], 0, v[138:139]
	s_add_i32 m0, s15, 0xc000
	ds_read_b128 v[170:173], v152
	ds_read_b128 v[174:177], v152 offset:1024
	ds_read_b128 v[178:181], v152 offset:2048
	ds_read_b128 v[182:185], v152 offset:3072
	ds_read_b128 v[186:189], v152 offset:4096
	ds_read_b128 v[190:193], v152 offset:5120
	ds_read_b128 v[194:197], v152 offset:6144
	ds_read_b128 v[198:201], v152 offset:7168
	global_load_lds_dwordx4 v[202:203], off
	v_lshl_add_u64 v[202:203], s[28:29], 0, v[140:141]
	s_add_i32 m0, s15, 0xe000
	s_nop 0
	global_load_lds_dwordx4 v[202:203], off
	s_barrier
	s_waitcnt lgkmcnt(0)
	s_waitcnt lgkmcnt(0)
	v_mfma_f32_16x16x32_bf16 v[124:127], v[154:157], v[170:173], v[124:127]
	v_mfma_f32_16x16x32_bf16 v[120:123], v[162:165], v[170:173], v[120:123]
	v_mfma_f32_16x16x32_bf16 v[116:119], v[154:157], v[178:181], v[116:119]
	v_mfma_f32_16x16x32_bf16 v[112:115], v[162:165], v[178:181], v[112:115]
	v_mfma_f32_16x16x32_bf16 v[100:103], v[154:157], v[186:189], v[100:103]
	v_mfma_f32_16x16x32_bf16 v[96:99], v[162:165], v[186:189], v[96:99]
	v_mfma_f32_16x16x32_bf16 v[84:87], v[154:157], v[194:197], v[84:87]
	v_mfma_f32_16x16x32_bf16 v[80:83], v[162:165], v[194:197], v[80:83]
	v_mfma_f32_16x16x32_bf16 v[124:127], v[158:161], v[174:177], v[124:127]
	v_mfma_f32_16x16x32_bf16 v[120:123], v[166:169], v[174:177], v[120:123]
	v_mfma_f32_16x16x32_bf16 v[116:119], v[158:161], v[182:185], v[116:119]
	v_mfma_f32_16x16x32_bf16 v[112:115], v[166:169], v[182:185], v[112:115]
	v_mfma_f32_16x16x32_bf16 v[100:103], v[158:161], v[190:193], v[100:103]
	v_mfma_f32_16x16x32_bf16 v[96:99], v[166:169], v[190:193], v[96:99]
	v_mfma_f32_16x16x32_bf16 v[84:87], v[158:161], v[198:201], v[84:87]
	v_mfma_f32_16x16x32_bf16 v[80:83], v[166:169], v[198:201], v[80:83]
	s_barrier
	s_add_i32 s85, s74, s55
	v_lshl_add_u64 v[218:219], s[30:31], 0, v[134:135]
	s_mov_b32 m0, s85
	ds_read_b128 v[202:205], v153
	ds_read_b128 v[206:209], v153 offset:1024
	ds_read_b128 v[210:213], v153 offset:2048
	ds_read_b128 v[214:217], v153 offset:3072
	global_load_lds_dwordx4 v[218:219], off
	v_lshl_add_u64 v[220:221], s[30:31], 0, v[130:131]
	s_add_i32 m0, s85, 0x2000
	s_nop 0
	global_load_lds_dwordx4 v[220:221], off
	s_barrier
	s_waitcnt lgkmcnt(0)
	s_waitcnt lgkmcnt(0)
	v_mfma_f32_16x16x32_bf16 v[108:111], v[202:205], v[170:173], v[108:111]
	v_mfma_f32_16x16x32_bf16 v[104:107], v[210:213], v[170:173], v[104:107]
	v_mfma_f32_16x16x32_bf16 v[92:95], v[202:205], v[178:181], v[92:95]
	v_mfma_f32_16x16x32_bf16 v[88:91], v[210:213], v[178:181], v[88:91]
	v_mfma_f32_16x16x32_bf16 v[76:79], v[202:205], v[186:189], v[76:79]
	v_mfma_f32_16x16x32_bf16 v[72:75], v[210:213], v[186:189], v[72:75]
	v_mfma_f32_16x16x32_bf16 v[68:71], v[202:205], v[194:197], v[68:71]
	v_mfma_f32_16x16x32_bf16 v[64:67], v[210:213], v[194:197], v[64:67]
	v_mfma_f32_16x16x32_bf16 v[108:111], v[206:209], v[174:177], v[108:111]
	v_mfma_f32_16x16x32_bf16 v[104:107], v[214:217], v[174:177], v[104:107]
	v_mfma_f32_16x16x32_bf16 v[92:95], v[206:209], v[182:185], v[92:95]
	v_mfma_f32_16x16x32_bf16 v[88:91], v[214:217], v[182:185], v[88:91]
	v_mfma_f32_16x16x32_bf16 v[76:79], v[206:209], v[190:193], v[76:79]
	v_mfma_f32_16x16x32_bf16 v[72:75], v[214:217], v[190:193], v[72:75]
	v_mfma_f32_16x16x32_bf16 v[68:71], v[206:209], v[198:201], v[68:71]
	v_mfma_f32_16x16x32_bf16 v[64:67], v[214:217], v[198:201], v[64:67]
	s_mov_b32 m0, s15
	v_lshl_add_u64 v[222:223], s[34:35], 0, v[136:137]
	s_barrier
	ds_read_b128 v[170:173], v152 offset:16384
	ds_read_b128 v[174:177], v152 offset:17408
	ds_read_b128 v[178:181], v152 offset:18432
	ds_read_b128 v[182:185], v152 offset:19456
	ds_read_b128 v[186:189], v152 offset:20480
	ds_read_b128 v[190:193], v152 offset:21504
	ds_read_b128 v[194:197], v152 offset:22528
	ds_read_b128 v[198:201], v152 offset:23552
	global_load_lds_dwordx4 v[222:223], off
	v_lshl_add_u64 v[224:225], s[34:35], 0, v[132:133]
	s_mov_b32 m0, s57
	s_nop 0
	global_load_lds_dwordx4 v[224:225], off
	s_barrier
	s_waitcnt lgkmcnt(0)
	s_waitcnt lgkmcnt(0)
	v_mfma_f32_16x16x32_bf16 v[60:63], v[154:157], v[170:173], v[60:63]
	v_mfma_f32_16x16x32_bf16 v[56:59], v[162:165], v[170:173], v[56:59]
	v_mfma_f32_16x16x32_bf16 v[52:55], v[154:157], v[178:181], v[52:55]
	v_mfma_f32_16x16x32_bf16 v[48:51], v[162:165], v[178:181], v[48:51]
	v_mfma_f32_16x16x32_bf16 v[36:39], v[154:157], v[186:189], v[36:39]
	v_mfma_f32_16x16x32_bf16 v[32:35], v[162:165], v[186:189], v[32:35]
	v_mfma_f32_16x16x32_bf16 v[20:23], v[154:157], v[194:197], v[20:23]
	v_mfma_f32_16x16x32_bf16 v[16:19], v[162:165], v[194:197], v[16:19]
	v_mfma_f32_16x16x32_bf16 v[60:63], v[158:161], v[174:177], v[60:63]
	v_mfma_f32_16x16x32_bf16 v[56:59], v[166:169], v[174:177], v[56:59]
	v_mfma_f32_16x16x32_bf16 v[52:55], v[158:161], v[182:185], v[52:55]
	v_mfma_f32_16x16x32_bf16 v[48:51], v[166:169], v[182:185], v[48:51]
	v_mfma_f32_16x16x32_bf16 v[36:39], v[158:161], v[190:193], v[36:39]
	v_mfma_f32_16x16x32_bf16 v[32:35], v[166:169], v[190:193], v[32:35]
	v_mfma_f32_16x16x32_bf16 v[20:23], v[158:161], v[198:201], v[20:23]
	v_mfma_f32_16x16x32_bf16 v[16:19], v[166:169], v[198:201], v[16:19]
	s_barrier
	s_add_u32 s86, s30, 0x40000
	s_addc_u32 s87, s31, 0
	s_add_i32 s85, s75, s55
	v_lshl_add_u64 v[154:155], s[86:87], 0, v[134:135]
	s_mov_b32 m0, s85
	s_nop 0
	global_load_lds_dwordx4 v[154:155], off
	v_lshl_add_u64 v[154:155], s[86:87], 0, v[130:131]
	s_add_i32 m0, s85, 0x2000
	s_nop 0
	global_load_lds_dwordx4 v[154:155], off
	s_waitcnt vmcnt(6)
	s_barrier
	v_mfma_f32_16x16x32_bf16 v[44:47], v[202:205], v[170:173], v[44:47]
	v_mfma_f32_16x16x32_bf16 v[40:43], v[210:213], v[170:173], v[40:43]
	v_mfma_f32_16x16x32_bf16 v[28:31], v[202:205], v[178:181], v[28:31]
	v_mfma_f32_16x16x32_bf16 v[24:27], v[210:213], v[178:181], v[24:27]
	v_mfma_f32_16x16x32_bf16 v[12:15], v[202:205], v[186:189], v[12:15]
	v_mfma_f32_16x16x32_bf16 v[8:11], v[210:213], v[186:189], v[8:11]
	v_mfma_f32_16x16x32_bf16 v[4:7], v[202:205], v[194:197], v[4:7]
	v_mfma_f32_16x16x32_bf16 v[0:3], v[210:213], v[194:197], v[0:3]
	v_mfma_f32_16x16x32_bf16 v[44:47], v[206:209], v[174:177], v[44:47]
	v_mfma_f32_16x16x32_bf16 v[40:43], v[214:217], v[174:177], v[40:43]
	v_mfma_f32_16x16x32_bf16 v[28:31], v[206:209], v[182:185], v[28:31]
	v_mfma_f32_16x16x32_bf16 v[24:27], v[214:217], v[182:185], v[24:27]
	v_mfma_f32_16x16x32_bf16 v[12:15], v[206:209], v[190:193], v[12:15]
	v_mfma_f32_16x16x32_bf16 v[8:11], v[214:217], v[190:193], v[8:11]
	v_mfma_f32_16x16x32_bf16 v[4:7], v[206:209], v[198:201], v[4:7]
	v_mfma_f32_16x16x32_bf16 v[0:3], v[214:217], v[198:201], v[0:3]
	s_add_i32 s85, 0, 0x18000
	v_add_u32_e32 v166, s85, v149
	s_barrier
	ds_read_b128 v[154:157], v166
	ds_read_b128 v[158:161], v166 offset:1024
	ds_read_b128 v[162:165], v166 offset:2048
	ds_read_b128 v[166:169], v166 offset:3072
	s_add_u32 s34, s34, 0x40000
	s_addc_u32 s35, s35, 0
	s_mov_b32 m0, s60
	v_lshl_add_u64 v[202:203], s[34:35], 0, v[136:137]
	ds_read_b128 v[170:173], v152 offset:32768
	ds_read_b128 v[174:177], v152 offset:33792
	ds_read_b128 v[178:181], v152 offset:34816
	ds_read_b128 v[182:185], v152 offset:35840
	ds_read_b128 v[186:189], v152 offset:36864
	ds_read_b128 v[190:193], v152 offset:37888
	ds_read_b128 v[194:197], v152 offset:38912
	ds_read_b128 v[198:201], v152 offset:39936
	global_load_lds_dwordx4 v[202:203], off
	v_lshl_add_u64 v[202:203], s[34:35], 0, v[132:133]
	s_mov_b32 m0, s61
	s_nop 0
	global_load_lds_dwordx4 v[202:203], off
	s_barrier
	s_waitcnt lgkmcnt(0)
	s_waitcnt lgkmcnt(0)
	v_mfma_f32_16x16x32_bf16 v[124:127], v[154:157], v[170:173], v[124:127]
	v_mfma_f32_16x16x32_bf16 v[120:123], v[162:165], v[170:173], v[120:123]
	v_mfma_f32_16x16x32_bf16 v[116:119], v[154:157], v[178:181], v[116:119]
	v_mfma_f32_16x16x32_bf16 v[112:115], v[162:165], v[178:181], v[112:115]
	v_mfma_f32_16x16x32_bf16 v[100:103], v[154:157], v[186:189], v[100:103]
	v_mfma_f32_16x16x32_bf16 v[96:99], v[162:165], v[186:189], v[96:99]
	v_mfma_f32_16x16x32_bf16 v[84:87], v[154:157], v[194:197], v[84:87]
	v_mfma_f32_16x16x32_bf16 v[80:83], v[162:165], v[194:197], v[80:83]
	v_mfma_f32_16x16x32_bf16 v[124:127], v[158:161], v[174:177], v[124:127]
	v_mfma_f32_16x16x32_bf16 v[120:123], v[166:169], v[174:177], v[120:123]
	v_mfma_f32_16x16x32_bf16 v[116:119], v[158:161], v[182:185], v[116:119]
	v_mfma_f32_16x16x32_bf16 v[112:115], v[166:169], v[182:185], v[112:115]
	v_mfma_f32_16x16x32_bf16 v[100:103], v[158:161], v[190:193], v[100:103]
	v_mfma_f32_16x16x32_bf16 v[96:99], v[166:169], v[190:193], v[96:99]
	v_mfma_f32_16x16x32_bf16 v[84:87], v[158:161], v[198:201], v[84:87]
	v_mfma_f32_16x16x32_bf16 v[80:83], v[166:169], v[198:201], v[80:83]
	s_barrier
	s_add_i32 s34, 0, 0x1c000
	s_add_i32 s35, s85, s55
	v_add_u32_e32 v214, s34, v149
	v_lshl_add_u64 v[218:219], v[218:219], 0, s[8:9]
	s_mov_b32 m0, s35
	ds_read_b128 v[202:205], v214
	ds_read_b128 v[206:209], v214 offset:1024
	ds_read_b128 v[210:213], v214 offset:2048
	ds_read_b128 v[214:217], v214 offset:3072
	global_load_lds_dwordx4 v[218:219], off
	v_lshl_add_u64 v[218:219], v[220:221], 0, s[8:9]
	s_add_i32 m0, s35, 0x2000
	s_nop 0
	global_load_lds_dwordx4 v[218:219], off
	s_barrier
	s_waitcnt lgkmcnt(0)
	s_waitcnt lgkmcnt(0)
	v_mfma_f32_16x16x32_bf16 v[108:111], v[202:205], v[170:173], v[108:111]
	v_mfma_f32_16x16x32_bf16 v[104:107], v[210:213], v[170:173], v[104:107]
	v_mfma_f32_16x16x32_bf16 v[92:95], v[202:205], v[178:181], v[92:95]
	v_mfma_f32_16x16x32_bf16 v[88:91], v[210:213], v[178:181], v[88:91]
	v_mfma_f32_16x16x32_bf16 v[76:79], v[202:205], v[186:189], v[76:79]
	v_mfma_f32_16x16x32_bf16 v[72:75], v[210:213], v[186:189], v[72:75]
	v_mfma_f32_16x16x32_bf16 v[68:71], v[202:205], v[194:197], v[68:71]
	v_mfma_f32_16x16x32_bf16 v[64:67], v[210:213], v[194:197], v[64:67]
	v_mfma_f32_16x16x32_bf16 v[108:111], v[206:209], v[174:177], v[108:111]
	v_mfma_f32_16x16x32_bf16 v[104:107], v[214:217], v[174:177], v[104:107]
	v_mfma_f32_16x16x32_bf16 v[92:95], v[206:209], v[182:185], v[92:95]
	v_mfma_f32_16x16x32_bf16 v[88:91], v[214:217], v[182:185], v[88:91]
	v_mfma_f32_16x16x32_bf16 v[76:79], v[206:209], v[190:193], v[76:79]
	v_mfma_f32_16x16x32_bf16 v[72:75], v[214:217], v[190:193], v[72:75]
	v_mfma_f32_16x16x32_bf16 v[68:71], v[206:209], v[198:201], v[68:71]
	v_mfma_f32_16x16x32_bf16 v[64:67], v[214:217], v[198:201], v[64:67]
	s_mov_b32 m0, s71
	v_lshl_add_u64 v[218:219], v[222:223], 0, s[8:9]
	s_barrier
	ds_read_b128 v[170:173], v152 offset:49152
	ds_read_b128 v[174:177], v152 offset:50176
	ds_read_b128 v[178:181], v152 offset:51200
	ds_read_b128 v[182:185], v152 offset:52224
	ds_read_b128 v[186:189], v152 offset:53248
	ds_read_b128 v[190:193], v152 offset:54272
	ds_read_b128 v[194:197], v152 offset:55296
	ds_read_b128 v[198:201], v152 offset:56320
	global_load_lds_dwordx4 v[218:219], off
	v_lshl_add_u64 v[218:219], v[224:225], 0, s[8:9]
	s_mov_b32 m0, s72
	s_nop 0
	global_load_lds_dwordx4 v[218:219], off
	s_barrier
	s_waitcnt lgkmcnt(0)
	s_waitcnt lgkmcnt(0)
	v_mfma_f32_16x16x32_bf16 v[60:63], v[154:157], v[170:173], v[60:63]
	v_mfma_f32_16x16x32_bf16 v[56:59], v[162:165], v[170:173], v[56:59]
	v_mfma_f32_16x16x32_bf16 v[52:55], v[154:157], v[178:181], v[52:55]
	v_mfma_f32_16x16x32_bf16 v[48:51], v[162:165], v[178:181], v[48:51]
	v_mfma_f32_16x16x32_bf16 v[36:39], v[154:157], v[186:189], v[36:39]
	v_mfma_f32_16x16x32_bf16 v[32:35], v[162:165], v[186:189], v[32:35]
	v_mfma_f32_16x16x32_bf16 v[20:23], v[154:157], v[194:197], v[20:23]
	v_mfma_f32_16x16x32_bf16 v[16:19], v[162:165], v[194:197], v[16:19]
	v_mfma_f32_16x16x32_bf16 v[60:63], v[158:161], v[174:177], v[60:63]
	v_mfma_f32_16x16x32_bf16 v[56:59], v[166:169], v[174:177], v[56:59]
	v_mfma_f32_16x16x32_bf16 v[52:55], v[158:161], v[182:185], v[52:55]
	v_mfma_f32_16x16x32_bf16 v[48:51], v[166:169], v[182:185], v[48:51]
	v_mfma_f32_16x16x32_bf16 v[36:39], v[158:161], v[190:193], v[36:39]
	v_mfma_f32_16x16x32_bf16 v[32:35], v[166:169], v[190:193], v[32:35]
	v_mfma_f32_16x16x32_bf16 v[20:23], v[158:161], v[198:201], v[20:23]
	v_mfma_f32_16x16x32_bf16 v[16:19], v[166:169], v[198:201], v[16:19]
	s_barrier
	s_add_u32 s30, s30, 0x40080
	s_addc_u32 s31, s31, 0
	s_add_i32 s34, s34, s55
	v_lshl_add_u64 v[154:155], s[30:31], 0, v[134:135]
	s_mov_b32 m0, s34
	s_nop 0
	global_load_lds_dwordx4 v[154:155], off
	v_lshl_add_u64 v[154:155], s[30:31], 0, v[130:131]
	s_add_i32 m0, s34, 0x2000
	s_nop 0
	global_load_lds_dwordx4 v[154:155], off
	s_waitcnt vmcnt(6)
	s_barrier
	v_mfma_f32_16x16x32_bf16 v[44:47], v[202:205], v[170:173], v[44:47]
	v_mfma_f32_16x16x32_bf16 v[40:43], v[210:213], v[170:173], v[40:43]
	v_mfma_f32_16x16x32_bf16 v[28:31], v[202:205], v[178:181], v[28:31]
	v_mfma_f32_16x16x32_bf16 v[24:27], v[210:213], v[178:181], v[24:27]
	v_mfma_f32_16x16x32_bf16 v[12:15], v[202:205], v[186:189], v[12:15]
	v_mfma_f32_16x16x32_bf16 v[8:11], v[210:213], v[186:189], v[8:11]
	v_mfma_f32_16x16x32_bf16 v[4:7], v[202:205], v[194:197], v[4:7]
	v_mfma_f32_16x16x32_bf16 v[0:3], v[210:213], v[194:197], v[0:3]
	v_mfma_f32_16x16x32_bf16 v[44:47], v[206:209], v[174:177], v[44:47]
	v_mfma_f32_16x16x32_bf16 v[40:43], v[214:217], v[174:177], v[40:43]
	v_mfma_f32_16x16x32_bf16 v[28:31], v[206:209], v[182:185], v[28:31]
	v_mfma_f32_16x16x32_bf16 v[24:27], v[214:217], v[182:185], v[24:27]
	v_mfma_f32_16x16x32_bf16 v[12:15], v[206:209], v[190:193], v[12:15]
	v_mfma_f32_16x16x32_bf16 v[8:11], v[214:217], v[190:193], v[8:11]
	v_mfma_f32_16x16x32_bf16 v[4:7], v[206:209], v[198:201], v[4:7]
	v_mfma_f32_16x16x32_bf16 v[0:3], v[214:217], v[198:201], v[0:3]
	s_add_i32 s84, s84, 2
	s_add_u32 s28, s28, 0x100
	s_addc_u32 s29, s29, 0
	s_add_u32 s82, s82, 0x100
	s_addc_u32 s83, s83, 0
	s_cmp_gt_u32 s84, 13
	s_barrier
	s_cbranch_scc0 .LBB0_486
	v_lshl_add_u32 v154, s14, 8, v148
	v_lshl_or_b32 v156, s79, 8, v150
	v_ashrrev_i32_e32 v155, 31, v154
	v_lshlrev_b64 v[158:159], 11, v[154:155]
	v_ashrrev_i32_e32 v157, 31, v156
	v_lshl_add_u64 v[158:159], s[46:47], 0, v[158:159]
	v_cvt_pk_bf16_f32 v124, v124, v125
	v_cvt_pk_bf16_f32 v125, v126, v127
	v_cvt_pk_bf16_f32 v126, v120, v121
	v_lshlrev_b64 v[120:121], 1, v[156:157]
	v_cvt_pk_bf16_f32 v127, v122, v123
	v_lshl_add_u64 v[122:123], v[158:159], 0, v[120:121]
	s_mov_b32 s14, 0x40000
	v_cvt_pk_bf16_f32 v108, v108, v109
	v_cvt_pk_bf16_f32 v109, v110, v111
	v_cvt_pk_bf16_f32 v110, v104, v105
	v_or_b32_e32 v104, 16, v154
	v_cvt_pk_bf16_f32 v60, v60, v61
	v_cvt_pk_bf16_f32 v61, v62, v63
	v_cvt_pk_bf16_f32 v63, v58, v59
	s_mov_b64 s[28:29], 0x40000
	v_add_co_u32_e32 v58, vcc, s14, v122
	v_ashrrev_i32_e32 v105, 31, v104
	v_cvt_pk_bf16_f32 v62, v56, v57
	v_lshl_add_u64 v[56:57], v[122:123], 0, s[28:29]
	v_addc_co_u32_e32 v59, vcc, 0, v123, vcc
	v_cvt_pk_bf16_f32 v44, v44, v45
	v_cvt_pk_bf16_f32 v45, v46, v47
	v_cvt_pk_bf16_f32 v46, v40, v41
	v_cvt_pk_bf16_f32 v47, v42, v43
	v_cvt_pk_bf16_f32 v111, v106, v107
	v_lshlrev_b64 v[104:105], 11, v[104:105]
	v_cvt_pk_bf16_f32 v92, v92, v93
	v_cvt_pk_bf16_f32 v93, v94, v95
	v_cvt_pk_bf16_f32 v94, v88, v89
	v_or_b32_e32 v88, 32, v154
	global_store_dwordx4 v[56:57], v[44:47], off offset:256
	s_mov_b64 s[28:29], 0x48000
	global_store_dwordx4 v[122:123], v[108:111], off offset:256
	v_add_co_u32_e32 v46, vcc, s76, v122
	s_nop 0
	v_lshl_add_u64 v[108:109], s[46:47], 0, v[104:105]
	v_ashrrev_i32_e32 v89, 31, v88
	v_lshl_add_u64 v[44:45], v[122:123], 0, s[28:29]
	v_addc_co_u32_e32 v47, vcc, 0, v123, vcc
	v_cvt_pk_bf16_f32 v28, v28, v29
	v_cvt_pk_bf16_f32 v29, v30, v31
	v_cvt_pk_bf16_f32 v30, v24, v25
	v_cvt_pk_bf16_f32 v31, v26, v27
	v_lshl_add_u64 v[108:109], v[108:109], 0, v[120:121]
	v_cvt_pk_bf16_f32 v95, v90, v91
	v_lshlrev_b64 v[88:89], 11, v[88:89]
	v_cvt_pk_bf16_f32 v76, v76, v77
	v_cvt_pk_bf16_f32 v77, v78, v79
	v_cvt_pk_bf16_f32 v78, v72, v73
	v_or_b32_e32 v72, 48, v154
	global_store_dwordx4 v[44:45], v[28:31], off offset:256
	global_store_dwordx4 v[108:109], v[92:95], off offset:256
	v_ashrrev_i32_e32 v73, 31, v72
	v_add_co_u32_e32 v30, vcc, s77, v122
	v_lshl_add_u64 v[92:93], s[46:47], 0, v[88:89]
	v_lshl_add_u64 v[28:29], v[122:123], 0, s[10:11]
	v_addc_co_u32_e32 v31, vcc, 0, v123, vcc
	v_cvt_pk_bf16_f32 v12, v12, v13
	v_cvt_pk_bf16_f32 v13, v14, v15
	v_cvt_pk_bf16_f32 v14, v8, v9
	v_cvt_pk_bf16_f32 v15, v10, v11
	v_lshl_add_u64 v[92:93], v[92:93], 0, v[120:121]
	v_cvt_pk_bf16_f32 v79, v74, v75
	v_lshlrev_b64 v[72:73], 11, v[72:73]
	global_store_dwordx4 v[28:29], v[12:15], off offset:256
	global_store_dwordx4 v[92:93], v[76:79], off offset:256
	v_cvt_pk_bf16_f32 v104, v116, v117
	v_add_co_u32_e32 v14, vcc, s78, v122
	v_lshl_add_u64 v[76:77], s[46:47], 0, v[72:73]
	s_nop 0
	v_addc_co_u32_e32 v15, vcc, 0, v123, vcc
	v_cvt_pk_bf16_f32 v105, v118, v119
	v_cvt_pk_bf16_f32 v106, v112, v113
	v_cvt_pk_bf16_f32 v107, v114, v115
	v_cvt_pk_bf16_f32 v88, v100, v101
	v_cvt_pk_bf16_f32 v89, v102, v103
	v_cvt_pk_bf16_f32 v90, v96, v97
	v_cvt_pk_bf16_f32 v91, v98, v99
	v_cvt_pk_bf16_f32 v72, v84, v85
	v_cvt_pk_bf16_f32 v73, v86, v87
	v_cvt_pk_bf16_f32 v74, v80, v81
	v_cvt_pk_bf16_f32 v75, v82, v83
	v_lshl_add_u64 v[76:77], v[76:77], 0, v[120:121]
	v_cvt_pk_bf16_f32 v68, v68, v69
	v_cvt_pk_bf16_f32 v69, v70, v71
	v_cvt_pk_bf16_f32 v70, v64, v65
	v_cvt_pk_bf16_f32 v71, v66, v67
	v_cvt_pk_bf16_f32 v40, v52, v53
	v_cvt_pk_bf16_f32 v41, v54, v55
	v_cvt_pk_bf16_f32 v42, v48, v49
	v_cvt_pk_bf16_f32 v43, v50, v51
	v_cvt_pk_bf16_f32 v24, v36, v37
	v_cvt_pk_bf16_f32 v25, v38, v39
	v_cvt_pk_bf16_f32 v26, v32, v33
	v_cvt_pk_bf16_f32 v27, v34, v35
	v_cvt_pk_bf16_f32 v8, v20, v21
	v_cvt_pk_bf16_f32 v9, v22, v23
	v_cvt_pk_bf16_f32 v10, v16, v17
	v_cvt_pk_bf16_f32 v11, v18, v19
	v_lshl_add_u64 v[12:13], v[122:123], 0, s[12:13]
	v_cvt_pk_bf16_f32 v4, v4, v5
	v_cvt_pk_bf16_f32 v5, v6, v7
	v_cvt_pk_bf16_f32 v6, v0, v1
	v_cvt_pk_bf16_f32 v7, v2, v3
	s_and_b64 vcc, exec, s[4:5]
	s_mov_b32 s79, s16
	s_mov_b32 s14, s18
	s_mov_b64 s[30:31], s[26:27]
	s_mov_b64 s[28:29], s[20:21]
	global_store_dwordx4 v[122:123], v[124:127], off
	global_store_dwordx4 v[108:109], v[104:107], off
	global_store_dwordx4 v[92:93], v[88:91], off
	global_store_dwordx4 v[76:77], v[72:75], off
	global_store_dwordx4 v[76:77], v[68:71], off offset:256
	global_store_dwordx4 v[58:59], v[60:63], off
	global_store_dwordx4 v[46:47], v[40:43], off
	global_store_dwordx4 v[30:31], v[24:27], off
	global_store_dwordx4 v[14:15], v[8:11], off
	global_store_dwordx4 v[12:13], v[4:7], off offset:256
	s_cbranch_vccz .LBB0_483
	s_waitcnt vmcnt(0)
	s_cmpk_gt_u32 s54, 0xff
	s_cbranch_scc1 .LBB0_490
	s_barrier

.LBB0_683:
	ds_read_b128 v[154:157], v151
	ds_read_b128 v[158:161], v151 offset:1024
	ds_read_b128 v[162:165], v151 offset:2048
	ds_read_b128 v[166:169], v151 offset:3072
	s_add_u32 s34, s30, 0xfffc0080
	s_addc_u32 s35, s31, -1
	s_cmp_eq_u32 s85, 12
	s_cselect_b32 s55, s19, s35
	s_cselect_b32 s54, s81, s34
	s_cselect_b32 s35, s17, s84
	s_cselect_b32 s34, s82, s83
	v_lshl_add_u64 v[202:203], s[30:31], 0, v[138:139]
	s_add_i32 m0, s29, 0xc000
	ds_read_b128 v[170:173], v152
	ds_read_b128 v[174:177], v152 offset:1024
	ds_read_b128 v[178:181], v152 offset:2048
	ds_read_b128 v[182:185], v152 offset:3072
	ds_read_b128 v[186:189], v152 offset:4096
	ds_read_b128 v[190:193], v152 offset:5120
	ds_read_b128 v[194:197], v152 offset:6144
	ds_read_b128 v[198:201], v152 offset:7168
	global_load_lds_dwordx4 v[202:203], off
	v_lshl_add_u64 v[202:203], s[30:31], 0, v[140:141]
	s_add_i32 m0, s29, 0xe000
	s_nop 0
	global_load_lds_dwordx4 v[202:203], off
	s_barrier
	s_waitcnt lgkmcnt(0)
	s_waitcnt lgkmcnt(0)
	v_mfma_f32_16x16x32_bf16 v[124:127], v[154:157], v[170:173], v[124:127]
	v_mfma_f32_16x16x32_bf16 v[120:123], v[162:165], v[170:173], v[120:123]
	v_mfma_f32_16x16x32_bf16 v[108:111], v[154:157], v[178:181], v[108:111]
	v_mfma_f32_16x16x32_bf16 v[104:107], v[162:165], v[178:181], v[104:107]
	v_mfma_f32_16x16x32_bf16 v[92:95], v[154:157], v[186:189], v[92:95]
	v_mfma_f32_16x16x32_bf16 v[88:91], v[162:165], v[186:189], v[88:91]
	v_mfma_f32_16x16x32_bf16 v[76:79], v[154:157], v[194:197], v[76:79]
	v_mfma_f32_16x16x32_bf16 v[72:75], v[162:165], v[194:197], v[72:75]
	v_mfma_f32_16x16x32_bf16 v[124:127], v[158:161], v[174:177], v[124:127]
	v_mfma_f32_16x16x32_bf16 v[120:123], v[166:169], v[174:177], v[120:123]
	v_mfma_f32_16x16x32_bf16 v[108:111], v[158:161], v[182:185], v[108:111]
	v_mfma_f32_16x16x32_bf16 v[104:107], v[166:169], v[182:185], v[104:107]
	v_mfma_f32_16x16x32_bf16 v[92:95], v[158:161], v[190:193], v[92:95]
	v_mfma_f32_16x16x32_bf16 v[88:91], v[166:169], v[190:193], v[88:91]
	v_mfma_f32_16x16x32_bf16 v[76:79], v[158:161], v[198:201], v[76:79]
	v_mfma_f32_16x16x32_bf16 v[72:75], v[166:169], v[198:201], v[72:75]
	s_barrier
	s_add_i32 s86, s74, s60
	v_lshl_add_u64 v[218:219], s[34:35], 0, v[132:133]
	s_mov_b32 m0, s86
	ds_read_b128 v[202:205], v153
	ds_read_b128 v[206:209], v153 offset:1024
	ds_read_b128 v[210:213], v153 offset:2048
	ds_read_b128 v[214:217], v153 offset:3072
	global_load_lds_dwordx4 v[218:219], off
	v_lshl_add_u64 v[220:221], s[34:35], 0, v[136:137]
	s_add_i32 m0, s86, 0x2000
	s_nop 0
	global_load_lds_dwordx4 v[220:221], off
	s_barrier
	s_waitcnt lgkmcnt(0)
	s_waitcnt lgkmcnt(0)
	v_mfma_f32_16x16x32_bf16 v[116:119], v[202:205], v[170:173], v[116:119]
	v_mfma_f32_16x16x32_bf16 v[112:115], v[210:213], v[170:173], v[112:115]
	v_mfma_f32_16x16x32_bf16 v[100:103], v[202:205], v[178:181], v[100:103]
	v_mfma_f32_16x16x32_bf16 v[96:99], v[210:213], v[178:181], v[96:99]
	v_mfma_f32_16x16x32_bf16 v[84:87], v[202:205], v[186:189], v[84:87]
	v_mfma_f32_16x16x32_bf16 v[80:83], v[210:213], v[186:189], v[80:83]
	v_mfma_f32_16x16x32_bf16 v[68:71], v[202:205], v[194:197], v[68:71]
	v_mfma_f32_16x16x32_bf16 v[64:67], v[210:213], v[194:197], v[64:67]
	v_mfma_f32_16x16x32_bf16 v[116:119], v[206:209], v[174:177], v[116:119]
	v_mfma_f32_16x16x32_bf16 v[112:115], v[214:217], v[174:177], v[112:115]
	v_mfma_f32_16x16x32_bf16 v[100:103], v[206:209], v[182:185], v[100:103]
	v_mfma_f32_16x16x32_bf16 v[96:99], v[214:217], v[182:185], v[96:99]
	v_mfma_f32_16x16x32_bf16 v[84:87], v[206:209], v[190:193], v[84:87]
	v_mfma_f32_16x16x32_bf16 v[80:83], v[214:217], v[190:193], v[80:83]
	v_mfma_f32_16x16x32_bf16 v[68:71], v[206:209], v[198:201], v[68:71]
	v_mfma_f32_16x16x32_bf16 v[64:67], v[214:217], v[198:201], v[64:67]
	s_mov_b32 m0, s29
	v_lshl_add_u64 v[222:223], s[54:55], 0, v[130:131]
	s_barrier
	ds_read_b128 v[170:173], v152 offset:16384
	ds_read_b128 v[174:177], v152 offset:17408
	ds_read_b128 v[178:181], v152 offset:18432
	ds_read_b128 v[182:185], v152 offset:19456
	ds_read_b128 v[186:189], v152 offset:20480
	ds_read_b128 v[190:193], v152 offset:21504
	ds_read_b128 v[194:197], v152 offset:22528
	ds_read_b128 v[198:201], v152 offset:23552
	global_load_lds_dwordx4 v[222:223], off
	v_lshl_add_u64 v[224:225], s[54:55], 0, v[134:135]
	s_mov_b32 m0, s61
	s_nop 0
	global_load_lds_dwordx4 v[224:225], off
	s_barrier
	s_waitcnt lgkmcnt(0)
	s_waitcnt lgkmcnt(0)
	v_mfma_f32_16x16x32_bf16 v[60:63], v[154:157], v[170:173], v[60:63]
	v_mfma_f32_16x16x32_bf16 v[56:59], v[162:165], v[170:173], v[56:59]
	v_mfma_f32_16x16x32_bf16 v[44:47], v[154:157], v[178:181], v[44:47]
	v_mfma_f32_16x16x32_bf16 v[40:43], v[162:165], v[178:181], v[40:43]
	v_mfma_f32_16x16x32_bf16 v[28:31], v[154:157], v[186:189], v[28:31]
	v_mfma_f32_16x16x32_bf16 v[24:27], v[162:165], v[186:189], v[24:27]
	v_mfma_f32_16x16x32_bf16 v[12:15], v[154:157], v[194:197], v[12:15]
	v_mfma_f32_16x16x32_bf16 v[8:11], v[162:165], v[194:197], v[8:11]
	v_mfma_f32_16x16x32_bf16 v[60:63], v[158:161], v[174:177], v[60:63]
	v_mfma_f32_16x16x32_bf16 v[56:59], v[166:169], v[174:177], v[56:59]
	v_mfma_f32_16x16x32_bf16 v[44:47], v[158:161], v[182:185], v[44:47]
	v_mfma_f32_16x16x32_bf16 v[40:43], v[166:169], v[182:185], v[40:43]
	v_mfma_f32_16x16x32_bf16 v[28:31], v[158:161], v[190:193], v[28:31]
	v_mfma_f32_16x16x32_bf16 v[24:27], v[166:169], v[190:193], v[24:27]
	v_mfma_f32_16x16x32_bf16 v[12:15], v[158:161], v[198:201], v[12:15]
	v_mfma_f32_16x16x32_bf16 v[8:11], v[166:169], v[198:201], v[8:11]
	s_barrier
	s_add_u32 s86, s34, 0x40000
	s_addc_u32 s87, s35, 0
	s_add_i32 s88, s75, s60
	v_lshl_add_u64 v[154:155], s[86:87], 0, v[132:133]
	s_mov_b32 m0, s88
	s_nop 0
	global_load_lds_dwordx4 v[154:155], off
	v_lshl_add_u64 v[154:155], s[86:87], 0, v[136:137]
	s_add_i32 m0, s88, 0x2000
	s_nop 0
	global_load_lds_dwordx4 v[154:155], off
	s_waitcnt vmcnt(6)
	s_barrier
	v_mfma_f32_16x16x32_bf16 v[52:55], v[202:205], v[170:173], v[52:55]
	v_mfma_f32_16x16x32_bf16 v[48:51], v[210:213], v[170:173], v[48:51]
	v_mfma_f32_16x16x32_bf16 v[36:39], v[202:205], v[178:181], v[36:39]
	v_mfma_f32_16x16x32_bf16 v[32:35], v[210:213], v[178:181], v[32:35]
	v_mfma_f32_16x16x32_bf16 v[20:23], v[202:205], v[186:189], v[20:23]
	v_mfma_f32_16x16x32_bf16 v[16:19], v[210:213], v[186:189], v[16:19]
	v_mfma_f32_16x16x32_bf16 v[4:7], v[202:205], v[194:197], v[4:7]
	v_mfma_f32_16x16x32_bf16 v[0:3], v[210:213], v[194:197], v[0:3]
	v_mfma_f32_16x16x32_bf16 v[52:55], v[206:209], v[174:177], v[52:55]
	v_mfma_f32_16x16x32_bf16 v[48:51], v[214:217], v[174:177], v[48:51]
	v_mfma_f32_16x16x32_bf16 v[36:39], v[206:209], v[182:185], v[36:39]
	v_mfma_f32_16x16x32_bf16 v[32:35], v[214:217], v[182:185], v[32:35]
	v_mfma_f32_16x16x32_bf16 v[20:23], v[206:209], v[190:193], v[20:23]
	v_mfma_f32_16x16x32_bf16 v[16:19], v[214:217], v[190:193], v[16:19]
	v_mfma_f32_16x16x32_bf16 v[4:7], v[206:209], v[198:201], v[4:7]
	v_mfma_f32_16x16x32_bf16 v[0:3], v[214:217], v[198:201], v[0:3]
	s_add_i32 s86, 0, 0x18000
	v_add_u32_e32 v166, s86, v149
	s_barrier
	ds_read_b128 v[154:157], v166
	ds_read_b128 v[158:161], v166 offset:1024
	ds_read_b128 v[162:165], v166 offset:2048
	ds_read_b128 v[166:169], v166 offset:3072
	s_add_u32 s54, s54, 0x40000
	s_addc_u32 s55, s55, 0
	s_mov_b32 m0, s62
	v_lshl_add_u64 v[202:203], s[54:55], 0, v[130:131]
	ds_read_b128 v[170:173], v152 offset:32768
	ds_read_b128 v[174:177], v152 offset:33792
	ds_read_b128 v[178:181], v152 offset:34816
	ds_read_b128 v[182:185], v152 offset:35840
	ds_read_b128 v[186:189], v152 offset:36864
	ds_read_b128 v[190:193], v152 offset:37888
	ds_read_b128 v[194:197], v152 offset:38912
	ds_read_b128 v[198:201], v152 offset:39936
	global_load_lds_dwordx4 v[202:203], off
	v_lshl_add_u64 v[202:203], s[54:55], 0, v[134:135]
	s_mov_b32 m0, s63
	s_nop 0
	global_load_lds_dwordx4 v[202:203], off
	s_barrier
	s_waitcnt lgkmcnt(0)
	s_waitcnt lgkmcnt(0)
	v_mfma_f32_16x16x32_bf16 v[124:127], v[154:157], v[170:173], v[124:127]
	v_mfma_f32_16x16x32_bf16 v[120:123], v[162:165], v[170:173], v[120:123]
	v_mfma_f32_16x16x32_bf16 v[108:111], v[154:157], v[178:181], v[108:111]
	v_mfma_f32_16x16x32_bf16 v[104:107], v[162:165], v[178:181], v[104:107]
	v_mfma_f32_16x16x32_bf16 v[92:95], v[154:157], v[186:189], v[92:95]
	v_mfma_f32_16x16x32_bf16 v[88:91], v[162:165], v[186:189], v[88:91]
	v_mfma_f32_16x16x32_bf16 v[76:79], v[154:157], v[194:197], v[76:79]
	v_mfma_f32_16x16x32_bf16 v[72:75], v[162:165], v[194:197], v[72:75]
	v_mfma_f32_16x16x32_bf16 v[124:127], v[158:161], v[174:177], v[124:127]
	v_mfma_f32_16x16x32_bf16 v[120:123], v[166:169], v[174:177], v[120:123]
	v_mfma_f32_16x16x32_bf16 v[108:111], v[158:161], v[182:185], v[108:111]
	v_mfma_f32_16x16x32_bf16 v[104:107], v[166:169], v[182:185], v[104:107]
	v_mfma_f32_16x16x32_bf16 v[92:95], v[158:161], v[190:193], v[92:95]
	v_mfma_f32_16x16x32_bf16 v[88:91], v[166:169], v[190:193], v[88:91]
	v_mfma_f32_16x16x32_bf16 v[76:79], v[158:161], v[198:201], v[76:79]
	v_mfma_f32_16x16x32_bf16 v[72:75], v[166:169], v[198:201], v[72:75]
	s_barrier
	s_add_i32 s54, 0, 0x1c000
	s_add_i32 s55, s86, s60
	v_add_u32_e32 v214, s54, v149
	v_lshl_add_u64 v[218:219], v[218:219], 0, s[8:9]
	s_mov_b32 m0, s55
	ds_read_b128 v[202:205], v214
	ds_read_b128 v[206:209], v214 offset:1024
	ds_read_b128 v[210:213], v214 offset:2048
	ds_read_b128 v[214:217], v214 offset:3072
	global_load_lds_dwordx4 v[218:219], off
	v_lshl_add_u64 v[218:219], v[220:221], 0, s[8:9]
	s_add_i32 m0, s55, 0x2000
	s_nop 0
	global_load_lds_dwordx4 v[218:219], off
	s_barrier
	s_waitcnt lgkmcnt(0)
	s_waitcnt lgkmcnt(0)
	v_mfma_f32_16x16x32_bf16 v[116:119], v[202:205], v[170:173], v[116:119]
	v_mfma_f32_16x16x32_bf16 v[112:115], v[210:213], v[170:173], v[112:115]
	v_mfma_f32_16x16x32_bf16 v[100:103], v[202:205], v[178:181], v[100:103]
	v_mfma_f32_16x16x32_bf16 v[96:99], v[210:213], v[178:181], v[96:99]
	v_mfma_f32_16x16x32_bf16 v[84:87], v[202:205], v[186:189], v[84:87]
	v_mfma_f32_16x16x32_bf16 v[80:83], v[210:213], v[186:189], v[80:83]
	v_mfma_f32_16x16x32_bf16 v[68:71], v[202:205], v[194:197], v[68:71]
	v_mfma_f32_16x16x32_bf16 v[64:67], v[210:213], v[194:197], v[64:67]
	v_mfma_f32_16x16x32_bf16 v[116:119], v[206:209], v[174:177], v[116:119]
	v_mfma_f32_16x16x32_bf16 v[112:115], v[214:217], v[174:177], v[112:115]
	v_mfma_f32_16x16x32_bf16 v[100:103], v[206:209], v[182:185], v[100:103]
	v_mfma_f32_16x16x32_bf16 v[96:99], v[214:217], v[182:185], v[96:99]
	v_mfma_f32_16x16x32_bf16 v[84:87], v[206:209], v[190:193], v[84:87]
	v_mfma_f32_16x16x32_bf16 v[80:83], v[214:217], v[190:193], v[80:83]
	v_mfma_f32_16x16x32_bf16 v[68:71], v[206:209], v[198:201], v[68:71]
	v_mfma_f32_16x16x32_bf16 v[64:67], v[214:217], v[198:201], v[64:67]
	s_mov_b32 m0, s71
	v_lshl_add_u64 v[218:219], v[222:223], 0, s[8:9]
	s_barrier
	ds_read_b128 v[170:173], v152 offset:49152
	ds_read_b128 v[174:177], v152 offset:50176
	ds_read_b128 v[178:181], v152 offset:51200
	ds_read_b128 v[182:185], v152 offset:52224
	ds_read_b128 v[186:189], v152 offset:53248
	ds_read_b128 v[190:193], v152 offset:54272
	ds_read_b128 v[194:197], v152 offset:55296
	ds_read_b128 v[198:201], v152 offset:56320
	global_load_lds_dwordx4 v[218:219], off
	v_lshl_add_u64 v[218:219], v[224:225], 0, s[8:9]
	s_mov_b32 m0, s72
	s_nop 0
	global_load_lds_dwordx4 v[218:219], off
	s_barrier
	s_waitcnt lgkmcnt(0)
	s_waitcnt lgkmcnt(0)
	v_mfma_f32_16x16x32_bf16 v[60:63], v[154:157], v[170:173], v[60:63]
	v_mfma_f32_16x16x32_bf16 v[56:59], v[162:165], v[170:173], v[56:59]
	v_mfma_f32_16x16x32_bf16 v[44:47], v[154:157], v[178:181], v[44:47]
	v_mfma_f32_16x16x32_bf16 v[40:43], v[162:165], v[178:181], v[40:43]
	v_mfma_f32_16x16x32_bf16 v[28:31], v[154:157], v[186:189], v[28:31]
	v_mfma_f32_16x16x32_bf16 v[24:27], v[162:165], v[186:189], v[24:27]
	v_mfma_f32_16x16x32_bf16 v[12:15], v[154:157], v[194:197], v[12:15]
	v_mfma_f32_16x16x32_bf16 v[8:11], v[162:165], v[194:197], v[8:11]
	v_mfma_f32_16x16x32_bf16 v[60:63], v[158:161], v[174:177], v[60:63]
	v_mfma_f32_16x16x32_bf16 v[56:59], v[166:169], v[174:177], v[56:59]
	v_mfma_f32_16x16x32_bf16 v[44:47], v[158:161], v[182:185], v[44:47]
	v_mfma_f32_16x16x32_bf16 v[40:43], v[166:169], v[182:185], v[40:43]
	v_mfma_f32_16x16x32_bf16 v[28:31], v[158:161], v[190:193], v[28:31]
	v_mfma_f32_16x16x32_bf16 v[24:27], v[166:169], v[190:193], v[24:27]
	v_mfma_f32_16x16x32_bf16 v[12:15], v[158:161], v[198:201], v[12:15]
	v_mfma_f32_16x16x32_bf16 v[8:11], v[166:169], v[198:201], v[8:11]
	s_barrier
	s_add_u32 s34, s34, 0x40080
	s_addc_u32 s35, s35, 0
	s_add_i32 s54, s54, s60
	v_lshl_add_u64 v[154:155], s[34:35], 0, v[132:133]
	s_mov_b32 m0, s54
	s_nop 0
	global_load_lds_dwordx4 v[154:155], off
	v_lshl_add_u64 v[154:155], s[34:35], 0, v[136:137]
	s_add_i32 m0, s54, 0x2000
	s_nop 0
	global_load_lds_dwordx4 v[154:155], off
	s_waitcnt vmcnt(6)
	s_barrier
	v_mfma_f32_16x16x32_bf16 v[52:55], v[202:205], v[170:173], v[52:55]
	v_mfma_f32_16x16x32_bf16 v[48:51], v[210:213], v[170:173], v[48:51]
	v_mfma_f32_16x16x32_bf16 v[36:39], v[202:205], v[178:181], v[36:39]
	v_mfma_f32_16x16x32_bf16 v[32:35], v[210:213], v[178:181], v[32:35]
	v_mfma_f32_16x16x32_bf16 v[20:23], v[202:205], v[186:189], v[20:23]
	v_mfma_f32_16x16x32_bf16 v[16:19], v[210:213], v[186:189], v[16:19]
	v_mfma_f32_16x16x32_bf16 v[4:7], v[202:205], v[194:197], v[4:7]
	v_mfma_f32_16x16x32_bf16 v[0:3], v[210:213], v[194:197], v[0:3]
	v_mfma_f32_16x16x32_bf16 v[52:55], v[206:209], v[174:177], v[52:55]
	v_mfma_f32_16x16x32_bf16 v[48:51], v[214:217], v[174:177], v[48:51]
	v_mfma_f32_16x16x32_bf16 v[36:39], v[206:209], v[182:185], v[36:39]
	v_mfma_f32_16x16x32_bf16 v[32:35], v[214:217], v[182:185], v[32:35]
	v_mfma_f32_16x16x32_bf16 v[20:23], v[206:209], v[190:193], v[20:23]
	v_mfma_f32_16x16x32_bf16 v[16:19], v[214:217], v[190:193], v[16:19]
	v_mfma_f32_16x16x32_bf16 v[4:7], v[206:209], v[198:201], v[4:7]
	v_mfma_f32_16x16x32_bf16 v[0:3], v[214:217], v[198:201], v[0:3]
	s_add_i32 s85, s85, 2
	s_add_u32 s30, s30, 0x100
	s_addc_u32 s31, s31, 0
	s_add_u32 s83, s83, 0x100
	s_addc_u32 s84, s84, 0
	s_cmp_gt_u32 s85, 13
	s_barrier
	s_cbranch_scc0 .LBB0_683
	v_lshl_add_u32 v154, s28, 8, v148
	v_max_f32_e32 v126, v126, v126
	v_max_f32_e32 v127, v127, v127
	v_lshl_or_b32 v156, s80, 8, v150
	v_ashrrev_i32_e32 v155, 31, v154
	v_max_f32_e32 v124, v124, v124
	v_max_f32_e32 v120, v120, v120
	v_max_f32_e32 v125, v125, v125
	v_max_f32_e32 v121, v121, v121
	v_max_f32_e32 v126, 0, v126
	v_max_f32_e32 v122, v122, v122
	v_max_f32_e32 v127, 0, v127
	v_max_f32_e32 v123, v123, v123
	v_lshlrev_b64 v[158:159], 13, v[154:155]
	v_max_f32_e32 v124, 0, v124
	v_max_f32_e32 v120, 0, v120
	v_max_f32_e32 v125, 0, v125
	v_max_f32_e32 v121, 0, v121
	v_max_f32_e32 v122, 0, v122
	v_max_f32_e32 v123, 0, v123
	v_pk_mul_f32 v[126:127], v[126:127], v[126:127]
	v_ashrrev_i32_e32 v157, 31, v156
	v_lshl_add_u64 v[158:159], s[46:47], 0, v[158:159]
	v_pk_mul_f32 v[124:125], v[124:125], v[124:125]
	v_pk_mul_f32 v[120:121], v[120:121], v[120:121]
	v_pk_mul_f32 v[160:161], v[122:123], v[122:123]
	v_cvt_pk_bf16_f32 v123, v126, v127
	v_lshlrev_b64 v[126:127], 1, v[156:157]
	v_max_f32_e32 v112, v112, v112
	v_max_f32_e32 v113, v113, v113
	v_cvt_pk_bf16_f32 v122, v124, v125
	v_cvt_pk_bf16_f32 v124, v120, v121
	v_cvt_pk_bf16_f32 v125, v160, v161
	v_lshl_add_u64 v[120:121], v[158:159], 0, v[126:127]
	v_max_f32_e32 v112, 0, v112
	v_max_f32_e32 v113, 0, v113
	global_store_dwordx4 v[120:121], v[122:125], off
	v_max_f32_e32 v116, v116, v116
	v_max_f32_e32 v117, v117, v117
	v_pk_mul_f32 v[122:123], v[112:113], v[112:113]
	v_max_f32_e32 v113, v114, v114
	v_max_f32_e32 v112, v118, v118
	v_max_f32_e32 v114, 0, v113
	v_max_f32_e32 v113, v119, v119
	v_max_f32_e32 v115, v115, v115
	v_max_f32_e32 v116, 0, v116
	v_max_f32_e32 v117, 0, v117
	v_max_f32_e32 v112, 0, v112
	v_max_f32_e32 v113, 0, v113
	v_max_f32_e32 v115, 0, v115
	v_pk_mul_f32 v[116:117], v[116:117], v[116:117]
	v_pk_mul_f32 v[118:119], v[112:113], v[112:113]
	v_pk_mul_f32 v[124:125], v[114:115], v[114:115]
	v_max_f32_e32 v104, v104, v104
	v_max_f32_e32 v105, v105, v105
	v_cvt_pk_bf16_f32 v112, v116, v117
	v_cvt_pk_bf16_f32 v113, v118, v119
	v_cvt_pk_bf16_f32 v114, v122, v123
	v_cvt_pk_bf16_f32 v115, v124, v125
	v_max_f32_e32 v104, 0, v104
	v_max_f32_e32 v105, 0, v105
	global_store_dwordx4 v[120:121], v[112:115], off offset:256
	v_max_f32_e32 v108, v108, v108
	v_max_f32_e32 v109, v109, v109
	v_or_b32_e32 v112, 16, v154
	v_pk_mul_f32 v[114:115], v[104:105], v[104:105]
	v_max_f32_e32 v105, v106, v106
	v_ashrrev_i32_e32 v113, 31, v112
	v_max_f32_e32 v104, v110, v110
	v_max_f32_e32 v106, 0, v105
	v_max_f32_e32 v105, v111, v111
	v_max_f32_e32 v107, v107, v107
	v_lshlrev_b64 v[112:113], 13, v[112:113]
	v_max_f32_e32 v108, 0, v108
	v_max_f32_e32 v109, 0, v109
	v_max_f32_e32 v104, 0, v104
	v_max_f32_e32 v105, 0, v105
	v_max_f32_e32 v107, 0, v107
	v_lshl_add_u64 v[112:113], s[46:47], 0, v[112:113]
	v_pk_mul_f32 v[108:109], v[108:109], v[108:109]
	v_pk_mul_f32 v[110:111], v[104:105], v[104:105]
	v_pk_mul_f32 v[116:117], v[106:107], v[106:107]
	v_max_f32_e32 v96, v96, v96
	v_max_f32_e32 v97, v97, v97
	v_cvt_pk_bf16_f32 v104, v108, v109
	v_cvt_pk_bf16_f32 v105, v110, v111
	v_cvt_pk_bf16_f32 v106, v114, v115
	v_cvt_pk_bf16_f32 v107, v116, v117
	v_lshl_add_u64 v[108:109], v[112:113], 0, v[126:127]
	v_max_f32_e32 v96, 0, v96
	v_max_f32_e32 v97, 0, v97
	global_store_dwordx4 v[108:109], v[104:107], off
	v_max_f32_e32 v100, v100, v100
	v_max_f32_e32 v101, v101, v101
	v_pk_mul_f32 v[104:105], v[96:97], v[96:97]
	v_max_f32_e32 v97, v98, v98
	v_max_f32_e32 v96, v102, v102
	v_max_f32_e32 v98, 0, v97
	v_max_f32_e32 v97, v103, v103
	v_max_f32_e32 v99, v99, v99
	v_max_f32_e32 v100, 0, v100
	v_max_f32_e32 v101, 0, v101
	v_max_f32_e32 v96, 0, v96
	v_max_f32_e32 v97, 0, v97
	v_max_f32_e32 v99, 0, v99
	v_pk_mul_f32 v[100:101], v[100:101], v[100:101]
	v_pk_mul_f32 v[102:103], v[96:97], v[96:97]
	v_pk_mul_f32 v[106:107], v[98:99], v[98:99]
	v_max_f32_e32 v88, v88, v88
	v_max_f32_e32 v89, v89, v89
	v_cvt_pk_bf16_f32 v96, v100, v101
	v_cvt_pk_bf16_f32 v97, v102, v103
	v_cvt_pk_bf16_f32 v98, v104, v105
	v_cvt_pk_bf16_f32 v99, v106, v107
	v_max_f32_e32 v88, 0, v88
	v_max_f32_e32 v89, 0, v89
	global_store_dwordx4 v[108:109], v[96:99], off offset:256
	v_max_f32_e32 v92, v92, v92
	v_max_f32_e32 v93, v93, v93
	v_or_b32_e32 v96, 32, v154
	v_pk_mul_f32 v[98:99], v[88:89], v[88:89]
	v_max_f32_e32 v89, v90, v90
	v_ashrrev_i32_e32 v97, 31, v96
	v_max_f32_e32 v88, v94, v94
	v_max_f32_e32 v90, 0, v89
	v_max_f32_e32 v89, v95, v95
	v_max_f32_e32 v91, v91, v91
	v_lshlrev_b64 v[96:97], 13, v[96:97]
	v_max_f32_e32 v92, 0, v92
	v_max_f32_e32 v93, 0, v93
	v_max_f32_e32 v88, 0, v88
	v_max_f32_e32 v89, 0, v89
	v_max_f32_e32 v91, 0, v91
	v_lshl_add_u64 v[96:97], s[46:47], 0, v[96:97]
	v_pk_mul_f32 v[92:93], v[92:93], v[92:93]
	v_pk_mul_f32 v[94:95], v[88:89], v[88:89]
	v_pk_mul_f32 v[100:101], v[90:91], v[90:91]
	v_max_f32_e32 v80, v80, v80
	v_max_f32_e32 v81, v81, v81
	v_cvt_pk_bf16_f32 v88, v92, v93
	v_cvt_pk_bf16_f32 v89, v94, v95
	v_cvt_pk_bf16_f32 v90, v98, v99
	v_cvt_pk_bf16_f32 v91, v100, v101
	v_lshl_add_u64 v[92:93], v[96:97], 0, v[126:127]
	v_max_f32_e32 v80, 0, v80
	v_max_f32_e32 v81, 0, v81
	global_store_dwordx4 v[92:93], v[88:91], off
	v_max_f32_e32 v84, v84, v84
	v_max_f32_e32 v85, v85, v85
	v_pk_mul_f32 v[88:89], v[80:81], v[80:81]
	v_max_f32_e32 v81, v82, v82
	v_max_f32_e32 v80, v86, v86
	v_max_f32_e32 v82, 0, v81
	v_max_f32_e32 v81, v87, v87
	v_max_f32_e32 v83, v83, v83
	v_max_f32_e32 v84, 0, v84
	v_max_f32_e32 v85, 0, v85
	v_max_f32_e32 v80, 0, v80
	v_max_f32_e32 v81, 0, v81
	v_max_f32_e32 v83, 0, v83
	v_pk_mul_f32 v[84:85], v[84:85], v[84:85]
	v_pk_mul_f32 v[86:87], v[80:81], v[80:81]
	v_pk_mul_f32 v[90:91], v[82:83], v[82:83]
	v_max_f32_e32 v72, v72, v72
	v_max_f32_e32 v73, v73, v73
	v_cvt_pk_bf16_f32 v80, v84, v85
	v_cvt_pk_bf16_f32 v81, v86, v87
	v_cvt_pk_bf16_f32 v82, v88, v89
	v_cvt_pk_bf16_f32 v83, v90, v91
	v_max_f32_e32 v72, 0, v72
	v_max_f32_e32 v73, 0, v73
	global_store_dwordx4 v[92:93], v[80:83], off offset:256
	v_max_f32_e32 v76, v76, v76
	v_max_f32_e32 v77, v77, v77
	v_or_b32_e32 v80, 48, v154
	v_pk_mul_f32 v[82:83], v[72:73], v[72:73]
	v_max_f32_e32 v73, v74, v74
	v_ashrrev_i32_e32 v81, 31, v80
	v_max_f32_e32 v72, v78, v78
	v_max_f32_e32 v74, 0, v73
	v_max_f32_e32 v73, v79, v79
	v_max_f32_e32 v75, v75, v75
	v_lshlrev_b64 v[80:81], 13, v[80:81]
	v_max_f32_e32 v76, 0, v76
	v_max_f32_e32 v77, 0, v77
	v_max_f32_e32 v72, 0, v72
	v_max_f32_e32 v73, 0, v73
	v_max_f32_e32 v75, 0, v75
	v_lshl_add_u64 v[80:81], s[46:47], 0, v[80:81]
	v_pk_mul_f32 v[76:77], v[76:77], v[76:77]
	v_pk_mul_f32 v[78:79], v[72:73], v[72:73]
	v_pk_mul_f32 v[84:85], v[74:75], v[74:75]
	v_max_f32_e32 v64, v64, v64
	v_max_f32_e32 v65, v65, v65
	v_cvt_pk_bf16_f32 v72, v76, v77
	v_cvt_pk_bf16_f32 v73, v78, v79
	v_cvt_pk_bf16_f32 v74, v82, v83
	v_cvt_pk_bf16_f32 v75, v84, v85
	v_lshl_add_u64 v[76:77], v[80:81], 0, v[126:127]
	v_max_f32_e32 v64, 0, v64
	v_max_f32_e32 v65, 0, v65
	global_store_dwordx4 v[76:77], v[72:75], off
	v_max_f32_e32 v68, v68, v68
	v_max_f32_e32 v69, v69, v69
	v_pk_mul_f32 v[72:73], v[64:65], v[64:65]
	v_max_f32_e32 v65, v66, v66
	v_max_f32_e32 v64, v70, v70
	v_max_f32_e32 v66, 0, v65
	v_max_f32_e32 v65, v71, v71
	v_max_f32_e32 v67, v67, v67
	v_max_f32_e32 v68, 0, v68
	v_max_f32_e32 v69, 0, v69
	v_max_f32_e32 v64, 0, v64
	v_max_f32_e32 v65, 0, v65
	v_max_f32_e32 v67, 0, v67
	v_pk_mul_f32 v[68:69], v[68:69], v[68:69]
	v_pk_mul_f32 v[70:71], v[64:65], v[64:65]
	v_pk_mul_f32 v[74:75], v[66:67], v[66:67]
	v_max_f32_e32 v56, v56, v56
	v_max_f32_e32 v57, v57, v57
	v_cvt_pk_bf16_f32 v64, v68, v69
	v_cvt_pk_bf16_f32 v65, v70, v71
	v_cvt_pk_bf16_f32 v66, v72, v73
	v_cvt_pk_bf16_f32 v67, v74, v75
	v_max_f32_e32 v56, 0, v56
	v_max_f32_e32 v57, 0, v57
	global_store_dwordx4 v[76:77], v[64:67], off offset:256
	v_max_f32_e32 v60, v60, v60
	v_max_f32_e32 v61, v61, v61
	v_pk_mul_f32 v[64:65], v[56:57], v[56:57]
	v_max_f32_e32 v57, v58, v58
	v_max_f32_e32 v56, v62, v62
	v_max_f32_e32 v58, 0, v57
	v_max_f32_e32 v57, v63, v63
	v_max_f32_e32 v56, 0, v56
	v_max_f32_e32 v57, 0, v57
	v_max_f32_e32 v59, v59, v59
	v_max_f32_e32 v60, 0, v60
	v_max_f32_e32 v61, 0, v61
	v_max_f32_e32 v59, 0, v59
	v_pk_mul_f32 v[62:63], v[56:57], v[56:57]
	v_pk_mul_f32 v[60:61], v[60:61], v[60:61]
	v_pk_mul_f32 v[66:67], v[58:59], v[58:59]
	v_cvt_pk_bf16_f32 v57, v62, v63
	v_add_co_u32_e32 v62, vcc, s76, v120
	v_max_f32_e32 v48, v48, v48
	v_max_f32_e32 v49, v49, v49
	v_cvt_pk_bf16_f32 v56, v60, v61
	v_cvt_pk_bf16_f32 v58, v64, v65
	v_cvt_pk_bf16_f32 v59, v66, v67
	v_addc_co_u32_e32 v63, vcc, 0, v121, vcc
	v_max_f32_e32 v48, 0, v48
	v_max_f32_e32 v49, 0, v49
	global_store_dwordx4 v[62:63], v[56:59], off
	v_max_f32_e32 v52, v52, v52
	v_max_f32_e32 v53, v53, v53
	v_pk_mul_f32 v[56:57], v[48:49], v[48:49]
	v_max_f32_e32 v49, v50, v50
	v_max_f32_e32 v48, v54, v54
	v_max_f32_e32 v50, 0, v49
	v_max_f32_e32 v49, v55, v55
	v_max_f32_e32 v51, v51, v51
	v_max_f32_e32 v52, 0, v52
	v_max_f32_e32 v53, 0, v53
	v_max_f32_e32 v48, 0, v48
	v_max_f32_e32 v49, 0, v49
	v_max_f32_e32 v51, 0, v51
	s_mov_b64 s[30:31], 0x100000
	v_pk_mul_f32 v[52:53], v[52:53], v[52:53]
	v_pk_mul_f32 v[54:55], v[48:49], v[48:49]
	v_pk_mul_f32 v[58:59], v[50:51], v[50:51]
	v_max_f32_e32 v40, v40, v40
	v_max_f32_e32 v41, v41, v41
	v_lshl_add_u64 v[60:61], v[120:121], 0, s[30:31]
	v_cvt_pk_bf16_f32 v48, v52, v53
	v_cvt_pk_bf16_f32 v49, v54, v55
	v_cvt_pk_bf16_f32 v50, v56, v57
	v_cvt_pk_bf16_f32 v51, v58, v59
	v_max_f32_e32 v40, 0, v40
	v_max_f32_e32 v41, 0, v41
	global_store_dwordx4 v[60:61], v[48:51], off offset:256
	v_max_f32_e32 v44, v44, v44
	v_max_f32_e32 v45, v45, v45
	v_pk_mul_f32 v[48:49], v[40:41], v[40:41]
	v_max_f32_e32 v41, v42, v42
	v_max_f32_e32 v40, v46, v46
	v_max_f32_e32 v42, 0, v41
	v_max_f32_e32 v41, v47, v47
	v_max_f32_e32 v40, 0, v40
	v_max_f32_e32 v41, 0, v41
	v_max_f32_e32 v43, v43, v43
	v_max_f32_e32 v44, 0, v44
	v_max_f32_e32 v45, 0, v45
	v_max_f32_e32 v43, 0, v43
	v_pk_mul_f32 v[46:47], v[40:41], v[40:41]
	v_pk_mul_f32 v[44:45], v[44:45], v[44:45]
	v_pk_mul_f32 v[50:51], v[42:43], v[42:43]
	v_cvt_pk_bf16_f32 v41, v46, v47
	v_add_co_u32_e32 v46, vcc, s77, v120
	v_max_f32_e32 v32, v32, v32
	v_max_f32_e32 v33, v33, v33
	v_cvt_pk_bf16_f32 v40, v44, v45
	v_cvt_pk_bf16_f32 v42, v48, v49
	v_cvt_pk_bf16_f32 v43, v50, v51
	v_addc_co_u32_e32 v47, vcc, 0, v121, vcc
	v_max_f32_e32 v32, 0, v32
	v_max_f32_e32 v33, 0, v33
	global_store_dwordx4 v[46:47], v[40:43], off
	v_max_f32_e32 v36, v36, v36
	v_max_f32_e32 v37, v37, v37
	v_pk_mul_f32 v[40:41], v[32:33], v[32:33]
	v_max_f32_e32 v33, v34, v34
	v_max_f32_e32 v32, v38, v38
	v_max_f32_e32 v34, 0, v33
	v_max_f32_e32 v33, v39, v39
	v_max_f32_e32 v35, v35, v35
	v_max_f32_e32 v36, 0, v36
	v_max_f32_e32 v37, 0, v37
	v_max_f32_e32 v32, 0, v32
	v_max_f32_e32 v33, 0, v33
	v_max_f32_e32 v35, 0, v35
	v_pk_mul_f32 v[36:37], v[36:37], v[36:37]
	v_pk_mul_f32 v[38:39], v[32:33], v[32:33]
	v_pk_mul_f32 v[42:43], v[34:35], v[34:35]
	v_max_f32_e32 v24, v24, v24
	v_max_f32_e32 v25, v25, v25
	v_lshl_add_u64 v[44:45], v[120:121], 0, s[10:11]
	v_cvt_pk_bf16_f32 v32, v36, v37
	v_cvt_pk_bf16_f32 v33, v38, v39
	v_cvt_pk_bf16_f32 v34, v40, v41
	v_cvt_pk_bf16_f32 v35, v42, v43
	v_max_f32_e32 v24, 0, v24
	v_max_f32_e32 v25, 0, v25
	global_store_dwordx4 v[44:45], v[32:35], off offset:256
	v_max_f32_e32 v28, v28, v28
	v_max_f32_e32 v29, v29, v29
	v_pk_mul_f32 v[32:33], v[24:25], v[24:25]
	v_max_f32_e32 v25, v26, v26
	v_max_f32_e32 v24, v30, v30
	v_max_f32_e32 v26, 0, v25
	v_max_f32_e32 v25, v31, v31
	v_max_f32_e32 v24, 0, v24
	v_max_f32_e32 v25, 0, v25
	v_max_f32_e32 v27, v27, v27
	v_max_f32_e32 v28, 0, v28
	v_max_f32_e32 v29, 0, v29
	v_max_f32_e32 v27, 0, v27
	v_pk_mul_f32 v[30:31], v[24:25], v[24:25]
	v_pk_mul_f32 v[28:29], v[28:29], v[28:29]
	v_pk_mul_f32 v[34:35], v[26:27], v[26:27]
	v_cvt_pk_bf16_f32 v25, v30, v31
	v_add_co_u32_e32 v30, vcc, s78, v120
	v_max_f32_e32 v16, v16, v16
	v_max_f32_e32 v17, v17, v17
	v_cvt_pk_bf16_f32 v24, v28, v29
	v_cvt_pk_bf16_f32 v26, v32, v33
	v_cvt_pk_bf16_f32 v27, v34, v35
	v_addc_co_u32_e32 v31, vcc, 0, v121, vcc
	v_max_f32_e32 v16, 0, v16
	v_max_f32_e32 v17, 0, v17
	global_store_dwordx4 v[30:31], v[24:27], off
	v_max_f32_e32 v20, v20, v20
	v_max_f32_e32 v21, v21, v21
	v_pk_mul_f32 v[24:25], v[16:17], v[16:17]
	v_max_f32_e32 v17, v18, v18
	v_max_f32_e32 v16, v22, v22
	v_max_f32_e32 v18, 0, v17
	v_max_f32_e32 v17, v23, v23
	v_max_f32_e32 v19, v19, v19
	v_max_f32_e32 v20, 0, v20
	v_max_f32_e32 v21, 0, v21
	v_max_f32_e32 v16, 0, v16
	v_max_f32_e32 v17, 0, v17
	v_max_f32_e32 v19, 0, v19
	v_pk_mul_f32 v[20:21], v[20:21], v[20:21]
	v_pk_mul_f32 v[22:23], v[16:17], v[16:17]
	v_pk_mul_f32 v[26:27], v[18:19], v[18:19]
	v_max_f32_e32 v8, v8, v8
	v_max_f32_e32 v9, v9, v9
	v_lshl_add_u64 v[28:29], v[120:121], 0, s[12:13]
	v_cvt_pk_bf16_f32 v16, v20, v21
	v_cvt_pk_bf16_f32 v17, v22, v23
	v_cvt_pk_bf16_f32 v18, v24, v25
	v_cvt_pk_bf16_f32 v19, v26, v27
	v_max_f32_e32 v8, 0, v8
	v_max_f32_e32 v9, 0, v9
	global_store_dwordx4 v[28:29], v[16:19], off offset:256
	v_max_f32_e32 v12, v12, v12
	v_max_f32_e32 v13, v13, v13
	v_pk_mul_f32 v[16:17], v[8:9], v[8:9]
	v_max_f32_e32 v9, v10, v10
	v_max_f32_e32 v8, v14, v14
	v_max_f32_e32 v10, 0, v9
	v_max_f32_e32 v9, v15, v15
	v_max_f32_e32 v8, 0, v8
	v_max_f32_e32 v9, 0, v9
	v_max_f32_e32 v11, v11, v11
	v_max_f32_e32 v12, 0, v12
	v_max_f32_e32 v13, 0, v13
	v_max_f32_e32 v11, 0, v11
	v_pk_mul_f32 v[14:15], v[8:9], v[8:9]
	v_pk_mul_f32 v[12:13], v[12:13], v[12:13]
	v_pk_mul_f32 v[18:19], v[10:11], v[10:11]
	v_cvt_pk_bf16_f32 v9, v14, v15
	v_add_co_u32_e32 v14, vcc, s79, v120
	v_max_f32_e32 v0, v0, v0
	v_max_f32_e32 v1, v1, v1
	v_cvt_pk_bf16_f32 v8, v12, v13
	v_cvt_pk_bf16_f32 v10, v16, v17
	v_cvt_pk_bf16_f32 v11, v18, v19
	v_addc_co_u32_e32 v15, vcc, 0, v121, vcc
	v_max_f32_e32 v0, 0, v0
	v_max_f32_e32 v1, 0, v1
	global_store_dwordx4 v[14:15], v[8:11], off
	v_max_f32_e32 v4, v4, v4
	v_max_f32_e32 v5, v5, v5
	v_pk_mul_f32 v[8:9], v[0:1], v[0:1]
	v_max_f32_e32 v1, v2, v2
	v_max_f32_e32 v0, v6, v6
	v_max_f32_e32 v2, 0, v1
	v_max_f32_e32 v1, v7, v7
	v_max_f32_e32 v3, v3, v3
	v_max_f32_e32 v4, 0, v4
	v_max_f32_e32 v5, 0, v5
	v_max_f32_e32 v0, 0, v0
	v_max_f32_e32 v1, 0, v1
	v_max_f32_e32 v3, 0, v3
	v_pk_mul_f32 v[4:5], v[4:5], v[4:5]
	v_pk_mul_f32 v[6:7], v[0:1], v[0:1]
	v_pk_mul_f32 v[10:11], v[2:3], v[2:3]
	v_lshl_add_u64 v[12:13], v[120:121], 0, s[14:15]
	v_cvt_pk_bf16_f32 v0, v4, v5
	v_cvt_pk_bf16_f32 v1, v6, v7
	v_cvt_pk_bf16_f32 v2, v8, v9
	v_cvt_pk_bf16_f32 v3, v10, v11
	s_and_b64 vcc, exec, s[4:5]
	s_mov_b32 s80, s16
	s_mov_b32 s28, s18
	s_mov_b64 s[34:35], s[26:27]
	s_mov_b64 s[30:31], s[20:21]
	global_store_dwordx4 v[12:13], v[0:3], off offset:256
	s_cbranch_vccz .LBB0_676
	s_waitcnt vmcnt(0)
	s_cmpk_gt_u32 s56, 0xff
	s_cbranch_scc1 .LBB0_687
	s_barrier

.LBB0_776:
	ds_read_b128 v[156:159], v152
	ds_read_b128 v[160:163], v152 offset:1024
	ds_read_b128 v[164:167], v152 offset:2048
	ds_read_b128 v[168:171], v152 offset:3072
	s_add_u32 s34, s30, 0xfff00080
	s_addc_u32 s35, s31, -1
	s_cmp_eq_u32 s85, 60
	s_cselect_b32 s55, s21, s35
	s_cselect_b32 s54, s81, s34
	s_cselect_b32 s35, s19, s84
	s_cselect_b32 s34, s82, s83
	v_lshl_add_u64 v[204:205], s[30:31], 0, v[138:139]
	s_add_i32 m0, s17, 0xc000
	ds_read_b128 v[172:175], v153
	ds_read_b128 v[176:179], v153 offset:1024
	ds_read_b128 v[180:183], v153 offset:2048
	ds_read_b128 v[184:187], v153 offset:3072
	ds_read_b128 v[188:191], v153 offset:4096
	ds_read_b128 v[192:195], v153 offset:5120
	ds_read_b128 v[196:199], v153 offset:6144
	ds_read_b128 v[200:203], v153 offset:7168
	global_load_lds_dwordx4 v[204:205], off
	v_lshl_add_u64 v[204:205], s[30:31], 0, v[140:141]
	s_add_i32 m0, s17, 0xe000
	s_nop 0
	global_load_lds_dwordx4 v[204:205], off
	s_barrier
	s_waitcnt lgkmcnt(0)
	s_waitcnt lgkmcnt(0)
	v_mfma_f32_16x16x32_bf16 v[124:127], v[156:159], v[172:175], v[124:127]
	v_mfma_f32_16x16x32_bf16 v[120:123], v[164:167], v[172:175], v[120:123]
	v_mfma_f32_16x16x32_bf16 v[116:119], v[156:159], v[180:183], v[116:119]
	v_mfma_f32_16x16x32_bf16 v[112:115], v[164:167], v[180:183], v[112:115]
	v_mfma_f32_16x16x32_bf16 v[100:103], v[156:159], v[188:191], v[100:103]
	v_mfma_f32_16x16x32_bf16 v[96:99], v[164:167], v[188:191], v[96:99]
	v_mfma_f32_16x16x32_bf16 v[84:87], v[156:159], v[196:199], v[84:87]
	v_mfma_f32_16x16x32_bf16 v[80:83], v[164:167], v[196:199], v[80:83]
	v_mfma_f32_16x16x32_bf16 v[124:127], v[160:163], v[176:179], v[124:127]
	v_mfma_f32_16x16x32_bf16 v[120:123], v[168:171], v[176:179], v[120:123]
	v_mfma_f32_16x16x32_bf16 v[116:119], v[160:163], v[184:187], v[116:119]
	v_mfma_f32_16x16x32_bf16 v[112:115], v[168:171], v[184:187], v[112:115]
	v_mfma_f32_16x16x32_bf16 v[100:103], v[160:163], v[192:195], v[100:103]
	v_mfma_f32_16x16x32_bf16 v[96:99], v[168:171], v[192:195], v[96:99]
	v_mfma_f32_16x16x32_bf16 v[84:87], v[160:163], v[200:203], v[84:87]
	v_mfma_f32_16x16x32_bf16 v[80:83], v[168:171], v[200:203], v[80:83]
	s_barrier
	s_add_i32 s86, s74, s57
	v_lshl_add_u64 v[220:221], s[34:35], 0, v[134:135]
	s_mov_b32 m0, s86
	ds_read_b128 v[204:207], v154
	ds_read_b128 v[208:211], v154 offset:1024
	ds_read_b128 v[212:215], v154 offset:2048
	ds_read_b128 v[216:219], v154 offset:3072
	global_load_lds_dwordx4 v[220:221], off
	v_lshl_add_u64 v[222:223], s[34:35], 0, v[130:131]
	s_add_i32 m0, s86, 0x2000
	s_nop 0
	global_load_lds_dwordx4 v[222:223], off
	s_barrier
	s_waitcnt lgkmcnt(0)
	s_waitcnt lgkmcnt(0)
	v_mfma_f32_16x16x32_bf16 v[108:111], v[204:207], v[172:175], v[108:111]
	v_mfma_f32_16x16x32_bf16 v[104:107], v[212:215], v[172:175], v[104:107]
	v_mfma_f32_16x16x32_bf16 v[92:95], v[204:207], v[180:183], v[92:95]
	v_mfma_f32_16x16x32_bf16 v[88:91], v[212:215], v[180:183], v[88:91]
	v_mfma_f32_16x16x32_bf16 v[76:79], v[204:207], v[188:191], v[76:79]
	v_mfma_f32_16x16x32_bf16 v[72:75], v[212:215], v[188:191], v[72:75]
	v_mfma_f32_16x16x32_bf16 v[68:71], v[204:207], v[196:199], v[68:71]
	v_mfma_f32_16x16x32_bf16 v[64:67], v[212:215], v[196:199], v[64:67]
	v_mfma_f32_16x16x32_bf16 v[108:111], v[208:211], v[176:179], v[108:111]
	v_mfma_f32_16x16x32_bf16 v[104:107], v[216:219], v[176:179], v[104:107]
	v_mfma_f32_16x16x32_bf16 v[92:95], v[208:211], v[184:187], v[92:95]
	v_mfma_f32_16x16x32_bf16 v[88:91], v[216:219], v[184:187], v[88:91]
	v_mfma_f32_16x16x32_bf16 v[76:79], v[208:211], v[192:195], v[76:79]
	v_mfma_f32_16x16x32_bf16 v[72:75], v[216:219], v[192:195], v[72:75]
	v_mfma_f32_16x16x32_bf16 v[68:71], v[208:211], v[200:203], v[68:71]
	v_mfma_f32_16x16x32_bf16 v[64:67], v[216:219], v[200:203], v[64:67]
	s_mov_b32 m0, s17
	v_lshl_add_u64 v[224:225], s[54:55], 0, v[136:137]
	s_barrier
	ds_read_b128 v[172:175], v153 offset:16384
	ds_read_b128 v[176:179], v153 offset:17408
	ds_read_b128 v[180:183], v153 offset:18432
	ds_read_b128 v[184:187], v153 offset:19456
	ds_read_b128 v[188:191], v153 offset:20480
	ds_read_b128 v[192:195], v153 offset:21504
	ds_read_b128 v[196:199], v153 offset:22528
	ds_read_b128 v[200:203], v153 offset:23552
	global_load_lds_dwordx4 v[224:225], off
	v_lshl_add_u64 v[226:227], s[54:55], 0, v[132:133]
	s_mov_b32 m0, s61
	s_nop 0
	global_load_lds_dwordx4 v[226:227], off
	s_barrier
	s_waitcnt lgkmcnt(0)
	s_waitcnt lgkmcnt(0)
	v_mfma_f32_16x16x32_bf16 v[60:63], v[156:159], v[172:175], v[60:63]
	v_mfma_f32_16x16x32_bf16 v[56:59], v[164:167], v[172:175], v[56:59]
	v_mfma_f32_16x16x32_bf16 v[52:55], v[156:159], v[180:183], v[52:55]
	v_mfma_f32_16x16x32_bf16 v[48:51], v[164:167], v[180:183], v[48:51]
	v_mfma_f32_16x16x32_bf16 v[36:39], v[156:159], v[188:191], v[36:39]
	v_mfma_f32_16x16x32_bf16 v[32:35], v[164:167], v[188:191], v[32:35]
	v_mfma_f32_16x16x32_bf16 v[20:23], v[156:159], v[196:199], v[20:23]
	v_mfma_f32_16x16x32_bf16 v[16:19], v[164:167], v[196:199], v[16:19]
	v_mfma_f32_16x16x32_bf16 v[60:63], v[160:163], v[176:179], v[60:63]
	v_mfma_f32_16x16x32_bf16 v[56:59], v[168:171], v[176:179], v[56:59]
	v_mfma_f32_16x16x32_bf16 v[52:55], v[160:163], v[184:187], v[52:55]
	v_mfma_f32_16x16x32_bf16 v[48:51], v[168:171], v[184:187], v[48:51]
	v_mfma_f32_16x16x32_bf16 v[36:39], v[160:163], v[192:195], v[36:39]
	v_mfma_f32_16x16x32_bf16 v[32:35], v[168:171], v[192:195], v[32:35]
	v_mfma_f32_16x16x32_bf16 v[20:23], v[160:163], v[200:203], v[20:23]
	v_mfma_f32_16x16x32_bf16 v[16:19], v[168:171], v[200:203], v[16:19]
	s_barrier
	s_add_u32 s86, s34, 0x100000
	s_addc_u32 s87, s35, 0
	s_add_i32 s88, s75, s57
	v_lshl_add_u64 v[156:157], s[86:87], 0, v[134:135]
	s_mov_b32 m0, s88
	s_nop 0
	global_load_lds_dwordx4 v[156:157], off
	v_lshl_add_u64 v[156:157], s[86:87], 0, v[130:131]
	s_add_i32 m0, s88, 0x2000
	s_nop 0
	global_load_lds_dwordx4 v[156:157], off
	s_waitcnt vmcnt(6)
	s_barrier
	v_mfma_f32_16x16x32_bf16 v[44:47], v[204:207], v[172:175], v[44:47]
	v_mfma_f32_16x16x32_bf16 v[40:43], v[212:215], v[172:175], v[40:43]
	v_mfma_f32_16x16x32_bf16 v[28:31], v[204:207], v[180:183], v[28:31]
	v_mfma_f32_16x16x32_bf16 v[24:27], v[212:215], v[180:183], v[24:27]
	v_mfma_f32_16x16x32_bf16 v[12:15], v[204:207], v[188:191], v[12:15]
	v_mfma_f32_16x16x32_bf16 v[8:11], v[212:215], v[188:191], v[8:11]
	v_mfma_f32_16x16x32_bf16 v[4:7], v[204:207], v[196:199], v[4:7]
	v_mfma_f32_16x16x32_bf16 v[0:3], v[212:215], v[196:199], v[0:3]
	v_mfma_f32_16x16x32_bf16 v[44:47], v[208:211], v[176:179], v[44:47]
	v_mfma_f32_16x16x32_bf16 v[40:43], v[216:219], v[176:179], v[40:43]
	v_mfma_f32_16x16x32_bf16 v[28:31], v[208:211], v[184:187], v[28:31]
	v_mfma_f32_16x16x32_bf16 v[24:27], v[216:219], v[184:187], v[24:27]
	v_mfma_f32_16x16x32_bf16 v[12:15], v[208:211], v[192:195], v[12:15]
	v_mfma_f32_16x16x32_bf16 v[8:11], v[216:219], v[192:195], v[8:11]
	v_mfma_f32_16x16x32_bf16 v[4:7], v[208:211], v[200:203], v[4:7]
	v_mfma_f32_16x16x32_bf16 v[0:3], v[216:219], v[200:203], v[0:3]
	s_add_i32 s86, 0, 0x18000
	v_add_u32_e32 v155, s86, v150
	s_barrier
	ds_read_b128 v[156:159], v155
	ds_read_b128 v[160:163], v155 offset:1024
	ds_read_b128 v[164:167], v155 offset:2048
	ds_read_b128 v[168:171], v155 offset:3072
	s_add_u32 s54, s54, 0x100000
	s_addc_u32 s55, s55, 0
	s_mov_b32 m0, s62
	v_lshl_add_u64 v[204:205], s[54:55], 0, v[136:137]
	ds_read_b128 v[172:175], v153 offset:32768
	ds_read_b128 v[176:179], v153 offset:33792
	ds_read_b128 v[180:183], v153 offset:34816
	ds_read_b128 v[184:187], v153 offset:35840
	ds_read_b128 v[188:191], v153 offset:36864
	ds_read_b128 v[192:195], v153 offset:37888
	ds_read_b128 v[196:199], v153 offset:38912
	ds_read_b128 v[200:203], v153 offset:39936
	global_load_lds_dwordx4 v[204:205], off
	v_lshl_add_u64 v[204:205], s[54:55], 0, v[132:133]
	s_mov_b32 m0, s63
	s_nop 0
	global_load_lds_dwordx4 v[204:205], off
	s_barrier
	s_waitcnt lgkmcnt(0)
	s_waitcnt lgkmcnt(0)
	v_mfma_f32_16x16x32_bf16 v[124:127], v[156:159], v[172:175], v[124:127]
	v_mfma_f32_16x16x32_bf16 v[120:123], v[164:167], v[172:175], v[120:123]
	v_mfma_f32_16x16x32_bf16 v[116:119], v[156:159], v[180:183], v[116:119]
	v_mfma_f32_16x16x32_bf16 v[112:115], v[164:167], v[180:183], v[112:115]
	v_mfma_f32_16x16x32_bf16 v[100:103], v[156:159], v[188:191], v[100:103]
	v_mfma_f32_16x16x32_bf16 v[96:99], v[164:167], v[188:191], v[96:99]
	v_mfma_f32_16x16x32_bf16 v[84:87], v[156:159], v[196:199], v[84:87]
	v_mfma_f32_16x16x32_bf16 v[80:83], v[164:167], v[196:199], v[80:83]
	v_mfma_f32_16x16x32_bf16 v[124:127], v[160:163], v[176:179], v[124:127]
	v_mfma_f32_16x16x32_bf16 v[120:123], v[168:171], v[176:179], v[120:123]
	v_mfma_f32_16x16x32_bf16 v[116:119], v[160:163], v[184:187], v[116:119]
	v_mfma_f32_16x16x32_bf16 v[112:115], v[168:171], v[184:187], v[112:115]
	v_mfma_f32_16x16x32_bf16 v[100:103], v[160:163], v[192:195], v[100:103]
	v_mfma_f32_16x16x32_bf16 v[96:99], v[168:171], v[192:195], v[96:99]
	v_mfma_f32_16x16x32_bf16 v[84:87], v[160:163], v[200:203], v[84:87]
	v_mfma_f32_16x16x32_bf16 v[80:83], v[168:171], v[200:203], v[80:83]
	s_barrier
	s_add_i32 s54, 0, 0x1c000
	s_add_i32 s55, s86, s57
	v_add_u32_e32 v155, s54, v150
	v_lshl_add_u64 v[220:221], v[220:221], 0, s[8:9]
	s_mov_b32 m0, s55
	ds_read_b128 v[204:207], v155
	ds_read_b128 v[208:211], v155 offset:1024
	ds_read_b128 v[212:215], v155 offset:2048
	ds_read_b128 v[216:219], v155 offset:3072
	global_load_lds_dwordx4 v[220:221], off
	v_lshl_add_u64 v[220:221], v[222:223], 0, s[8:9]
	s_add_i32 m0, s55, 0x2000
	s_nop 0
	global_load_lds_dwordx4 v[220:221], off
	s_barrier
	s_waitcnt lgkmcnt(0)
	s_waitcnt lgkmcnt(0)
	v_mfma_f32_16x16x32_bf16 v[108:111], v[204:207], v[172:175], v[108:111]
	v_mfma_f32_16x16x32_bf16 v[104:107], v[212:215], v[172:175], v[104:107]
	v_mfma_f32_16x16x32_bf16 v[92:95], v[204:207], v[180:183], v[92:95]
	v_mfma_f32_16x16x32_bf16 v[88:91], v[212:215], v[180:183], v[88:91]
	v_mfma_f32_16x16x32_bf16 v[76:79], v[204:207], v[188:191], v[76:79]
	v_mfma_f32_16x16x32_bf16 v[72:75], v[212:215], v[188:191], v[72:75]
	v_mfma_f32_16x16x32_bf16 v[68:71], v[204:207], v[196:199], v[68:71]
	v_mfma_f32_16x16x32_bf16 v[64:67], v[212:215], v[196:199], v[64:67]
	v_mfma_f32_16x16x32_bf16 v[108:111], v[208:211], v[176:179], v[108:111]
	v_mfma_f32_16x16x32_bf16 v[104:107], v[216:219], v[176:179], v[104:107]
	v_mfma_f32_16x16x32_bf16 v[92:95], v[208:211], v[184:187], v[92:95]
	v_mfma_f32_16x16x32_bf16 v[88:91], v[216:219], v[184:187], v[88:91]
	v_mfma_f32_16x16x32_bf16 v[76:79], v[208:211], v[192:195], v[76:79]
	v_mfma_f32_16x16x32_bf16 v[72:75], v[216:219], v[192:195], v[72:75]
	v_mfma_f32_16x16x32_bf16 v[68:71], v[208:211], v[200:203], v[68:71]
	v_mfma_f32_16x16x32_bf16 v[64:67], v[216:219], v[200:203], v[64:67]
	s_mov_b32 m0, s71
	v_lshl_add_u64 v[220:221], v[224:225], 0, s[8:9]
	s_barrier
	ds_read_b128 v[172:175], v153 offset:49152
	ds_read_b128 v[176:179], v153 offset:50176
	ds_read_b128 v[180:183], v153 offset:51200
	ds_read_b128 v[184:187], v153 offset:52224
	ds_read_b128 v[188:191], v153 offset:53248
	ds_read_b128 v[192:195], v153 offset:54272
	ds_read_b128 v[196:199], v153 offset:55296
	ds_read_b128 v[200:203], v153 offset:56320
	global_load_lds_dwordx4 v[220:221], off
	v_lshl_add_u64 v[220:221], v[226:227], 0, s[8:9]
	s_mov_b32 m0, s72
	s_nop 0
	global_load_lds_dwordx4 v[220:221], off
	s_barrier
	s_waitcnt lgkmcnt(0)
	s_waitcnt lgkmcnt(0)
	v_mfma_f32_16x16x32_bf16 v[60:63], v[156:159], v[172:175], v[60:63]
	v_mfma_f32_16x16x32_bf16 v[56:59], v[164:167], v[172:175], v[56:59]
	v_mfma_f32_16x16x32_bf16 v[52:55], v[156:159], v[180:183], v[52:55]
	v_mfma_f32_16x16x32_bf16 v[48:51], v[164:167], v[180:183], v[48:51]
	v_mfma_f32_16x16x32_bf16 v[36:39], v[156:159], v[188:191], v[36:39]
	v_mfma_f32_16x16x32_bf16 v[32:35], v[164:167], v[188:191], v[32:35]
	v_mfma_f32_16x16x32_bf16 v[20:23], v[156:159], v[196:199], v[20:23]
	v_mfma_f32_16x16x32_bf16 v[16:19], v[164:167], v[196:199], v[16:19]
	v_mfma_f32_16x16x32_bf16 v[60:63], v[160:163], v[176:179], v[60:63]
	v_mfma_f32_16x16x32_bf16 v[56:59], v[168:171], v[176:179], v[56:59]
	v_mfma_f32_16x16x32_bf16 v[52:55], v[160:163], v[184:187], v[52:55]
	v_mfma_f32_16x16x32_bf16 v[48:51], v[168:171], v[184:187], v[48:51]
	v_mfma_f32_16x16x32_bf16 v[36:39], v[160:163], v[192:195], v[36:39]
	v_mfma_f32_16x16x32_bf16 v[32:35], v[168:171], v[192:195], v[32:35]
	v_mfma_f32_16x16x32_bf16 v[20:23], v[160:163], v[200:203], v[20:23]
	v_mfma_f32_16x16x32_bf16 v[16:19], v[168:171], v[200:203], v[16:19]
	s_barrier
	s_add_u32 s34, s34, 0x100080
	s_addc_u32 s35, s35, 0
	s_add_i32 s54, s54, s57
	v_lshl_add_u64 v[156:157], s[34:35], 0, v[134:135]
	s_mov_b32 m0, s54
	s_nop 0
	global_load_lds_dwordx4 v[156:157], off
	v_lshl_add_u64 v[156:157], s[34:35], 0, v[130:131]
	s_add_i32 m0, s54, 0x2000
	s_nop 0
	global_load_lds_dwordx4 v[156:157], off
	s_waitcnt vmcnt(6)
	s_barrier
	v_mfma_f32_16x16x32_bf16 v[44:47], v[204:207], v[172:175], v[44:47]
	v_mfma_f32_16x16x32_bf16 v[40:43], v[212:215], v[172:175], v[40:43]
	v_mfma_f32_16x16x32_bf16 v[28:31], v[204:207], v[180:183], v[28:31]
	v_mfma_f32_16x16x32_bf16 v[24:27], v[212:215], v[180:183], v[24:27]
	v_mfma_f32_16x16x32_bf16 v[12:15], v[204:207], v[188:191], v[12:15]
	v_mfma_f32_16x16x32_bf16 v[8:11], v[212:215], v[188:191], v[8:11]
	v_mfma_f32_16x16x32_bf16 v[4:7], v[204:207], v[196:199], v[4:7]
	v_mfma_f32_16x16x32_bf16 v[0:3], v[212:215], v[196:199], v[0:3]
	v_mfma_f32_16x16x32_bf16 v[44:47], v[208:211], v[176:179], v[44:47]
	v_mfma_f32_16x16x32_bf16 v[40:43], v[216:219], v[176:179], v[40:43]
	v_mfma_f32_16x16x32_bf16 v[28:31], v[208:211], v[184:187], v[28:31]
	v_mfma_f32_16x16x32_bf16 v[24:27], v[216:219], v[184:187], v[24:27]
	v_mfma_f32_16x16x32_bf16 v[12:15], v[208:211], v[192:195], v[12:15]
	v_mfma_f32_16x16x32_bf16 v[8:11], v[216:219], v[192:195], v[8:11]
	v_mfma_f32_16x16x32_bf16 v[4:7], v[208:211], v[200:203], v[4:7]
	v_mfma_f32_16x16x32_bf16 v[0:3], v[216:219], v[200:203], v[0:3]
	s_add_i32 s85, s85, 2
	s_add_u32 s30, s30, 0x100
	s_addc_u32 s31, s31, 0
	s_add_u32 s83, s83, 0x100
	s_addc_u32 s84, s84, 0
	s_cmp_gt_u32 s85, 61
	s_barrier
	s_cbranch_scc0 .LBB0_776
	v_lshl_add_u32 v156, s16, 8, v149
	v_lshl_or_b32 v158, s80, 8, v151
	v_ashrrev_i32_e32 v157, 31, v156
	v_lshlrev_b64 v[160:161], 11, v[156:157]
	v_ashrrev_i32_e32 v159, 31, v158
	v_lshl_add_u64 v[160:161], s[44:45], 0, v[160:161]
	v_cvt_pk_bf16_f32 v124, v124, v125
	v_cvt_pk_bf16_f32 v125, v126, v127
	v_cvt_pk_bf16_f32 v126, v120, v121
	v_lshlrev_b64 v[120:121], 1, v[158:159]
	v_cvt_pk_bf16_f32 v127, v122, v123
	v_lshl_add_u64 v[122:123], v[160:161], 0, v[120:121]
	v_cvt_pk_bf16_f32 v108, v108, v109
	v_cvt_pk_bf16_f32 v109, v110, v111
	v_cvt_pk_bf16_f32 v110, v104, v105
	v_or_b32_e32 v104, 16, v156
	v_cvt_pk_bf16_f32 v60, v60, v61
	v_cvt_pk_bf16_f32 v61, v62, v63
	v_cvt_pk_bf16_f32 v63, v58, v59
	s_mov_b64 s[30:31], 0x40000
	v_add_co_u32_e32 v58, vcc, s76, v122
	v_ashrrev_i32_e32 v105, 31, v104
	v_cvt_pk_bf16_f32 v62, v56, v57
	v_lshl_add_u64 v[56:57], v[122:123], 0, s[30:31]
	v_addc_co_u32_e32 v59, vcc, 0, v123, vcc
	v_cvt_pk_bf16_f32 v44, v44, v45
	v_cvt_pk_bf16_f32 v45, v46, v47
	v_cvt_pk_bf16_f32 v46, v40, v41
	v_cvt_pk_bf16_f32 v47, v42, v43
	v_cvt_pk_bf16_f32 v111, v106, v107
	v_lshlrev_b64 v[104:105], 11, v[104:105]
	v_cvt_pk_bf16_f32 v92, v92, v93
	v_cvt_pk_bf16_f32 v93, v94, v95
	v_cvt_pk_bf16_f32 v94, v88, v89
	v_or_b32_e32 v88, 32, v156
	global_store_dwordx4 v[56:57], v[44:47], off offset:256
	global_store_dwordx4 v[122:123], v[108:111], off offset:256
	v_ashrrev_i32_e32 v89, 31, v88
	v_add_co_u32_e32 v46, vcc, s77, v122
	v_lshl_add_u64 v[108:109], s[44:45], 0, v[104:105]
	v_lshl_add_u64 v[44:45], v[122:123], 0, s[10:11]
	v_addc_co_u32_e32 v47, vcc, 0, v123, vcc
	v_cvt_pk_bf16_f32 v28, v28, v29
	v_cvt_pk_bf16_f32 v29, v30, v31
	v_cvt_pk_bf16_f32 v30, v24, v25
	v_cvt_pk_bf16_f32 v31, v26, v27
	v_lshl_add_u64 v[108:109], v[108:109], 0, v[120:121]
	v_cvt_pk_bf16_f32 v95, v90, v91
	v_lshlrev_b64 v[88:89], 11, v[88:89]
	v_cvt_pk_bf16_f32 v76, v76, v77
	v_cvt_pk_bf16_f32 v77, v78, v79
	v_cvt_pk_bf16_f32 v78, v72, v73
	v_or_b32_e32 v72, 48, v156
	global_store_dwordx4 v[44:45], v[28:31], off offset:256
	global_store_dwordx4 v[108:109], v[92:95], off offset:256
	v_ashrrev_i32_e32 v73, 31, v72
	v_add_co_u32_e32 v30, vcc, s78, v122
	v_lshl_add_u64 v[92:93], s[44:45], 0, v[88:89]
	v_lshl_add_u64 v[28:29], v[122:123], 0, s[12:13]
	v_addc_co_u32_e32 v31, vcc, 0, v123, vcc
	v_cvt_pk_bf16_f32 v12, v12, v13
	v_cvt_pk_bf16_f32 v13, v14, v15
	v_cvt_pk_bf16_f32 v14, v8, v9
	v_cvt_pk_bf16_f32 v15, v10, v11
	v_lshl_add_u64 v[92:93], v[92:93], 0, v[120:121]
	v_cvt_pk_bf16_f32 v79, v74, v75
	v_lshlrev_b64 v[72:73], 11, v[72:73]
	global_store_dwordx4 v[28:29], v[12:15], off offset:256
	global_store_dwordx4 v[92:93], v[76:79], off offset:256
	v_cvt_pk_bf16_f32 v104, v116, v117
	v_add_co_u32_e32 v14, vcc, s79, v122
	v_lshl_add_u64 v[76:77], s[44:45], 0, v[72:73]
	s_nop 0
	v_addc_co_u32_e32 v15, vcc, 0, v123, vcc
	v_cvt_pk_bf16_f32 v105, v118, v119
	v_cvt_pk_bf16_f32 v106, v112, v113
	v_cvt_pk_bf16_f32 v107, v114, v115
	v_cvt_pk_bf16_f32 v88, v100, v101
	v_cvt_pk_bf16_f32 v89, v102, v103
	v_cvt_pk_bf16_f32 v90, v96, v97
	v_cvt_pk_bf16_f32 v91, v98, v99
	v_cvt_pk_bf16_f32 v72, v84, v85
	v_cvt_pk_bf16_f32 v73, v86, v87
	v_cvt_pk_bf16_f32 v74, v80, v81
	v_cvt_pk_bf16_f32 v75, v82, v83
	v_lshl_add_u64 v[76:77], v[76:77], 0, v[120:121]
	v_cvt_pk_bf16_f32 v68, v68, v69
	v_cvt_pk_bf16_f32 v69, v70, v71
	v_cvt_pk_bf16_f32 v70, v64, v65
	v_cvt_pk_bf16_f32 v71, v66, v67
	v_cvt_pk_bf16_f32 v40, v52, v53
	v_cvt_pk_bf16_f32 v41, v54, v55
	v_cvt_pk_bf16_f32 v42, v48, v49
	v_cvt_pk_bf16_f32 v43, v50, v51
	v_cvt_pk_bf16_f32 v24, v36, v37
	v_cvt_pk_bf16_f32 v25, v38, v39
	v_cvt_pk_bf16_f32 v26, v32, v33
	v_cvt_pk_bf16_f32 v27, v34, v35
	v_cvt_pk_bf16_f32 v8, v20, v21
	v_cvt_pk_bf16_f32 v9, v22, v23
	v_cvt_pk_bf16_f32 v10, v16, v17
	v_cvt_pk_bf16_f32 v11, v18, v19
	v_lshl_add_u64 v[12:13], v[122:123], 0, s[14:15]
	v_cvt_pk_bf16_f32 v4, v4, v5
	v_cvt_pk_bf16_f32 v5, v6, v7
	v_cvt_pk_bf16_f32 v6, v0, v1
	v_cvt_pk_bf16_f32 v7, v2, v3
	s_and_b64 vcc, exec, s[4:5]
	s_mov_b32 s80, s18
	s_mov_b32 s16, s20
	s_mov_b64 s[34:35], s[28:29]
	s_mov_b64 s[30:31], s[26:27]
	global_store_dwordx4 v[122:123], v[124:127], off
	global_store_dwordx4 v[108:109], v[104:107], off
	global_store_dwordx4 v[92:93], v[88:91], off
	global_store_dwordx4 v[76:77], v[72:75], off
	global_store_dwordx4 v[76:77], v[68:71], off offset:256
	global_store_dwordx4 v[58:59], v[60:63], off
	global_store_dwordx4 v[46:47], v[40:43], off
	global_store_dwordx4 v[30:31], v[24:27], off
	global_store_dwordx4 v[14:15], v[8:11], off
	global_store_dwordx4 v[12:13], v[4:7], off offset:256
	s_cbranch_vccz .LBB0_773
	s_waitcnt vmcnt(0)
	s_cmpk_gt_u32 s56, 0xff
	s_cbranch_scc1 .LBB0_780
	s_barrier

.LBB0_912:
	ds_read_b128 v[156:159], v152
	ds_read_b128 v[160:163], v152 offset:1024
	ds_read_b128 v[164:167], v152 offset:2048
	ds_read_b128 v[168:171], v152 offset:3072
	s_add_u32 s54, s34, 0xfffc0080
	s_addc_u32 s55, s35, -1
	s_cmp_eq_u32 s87, 12
	s_cselect_b32 s57, s27, s55
	s_cselect_b32 s56, s83, s54
	s_cselect_b32 s55, s21, s86
	s_cselect_b32 s54, s84, s85
	v_lshl_add_u64 v[204:205], s[34:35], 0, v[138:139]
	s_add_i32 m0, s19, 0xc000
	ds_read_b128 v[172:175], v153
	ds_read_b128 v[176:179], v153 offset:1024
	ds_read_b128 v[180:183], v153 offset:2048
	ds_read_b128 v[184:187], v153 offset:3072
	ds_read_b128 v[188:191], v153 offset:4096
	ds_read_b128 v[192:195], v153 offset:5120
	ds_read_b128 v[196:199], v153 offset:6144
	ds_read_b128 v[200:203], v153 offset:7168
	global_load_lds_dwordx4 v[204:205], off
	v_lshl_add_u64 v[204:205], s[34:35], 0, v[140:141]
	s_add_i32 m0, s19, 0xe000
	s_nop 0
	global_load_lds_dwordx4 v[204:205], off
	s_barrier
	s_waitcnt lgkmcnt(0)
	s_waitcnt lgkmcnt(0)
	v_mfma_f32_16x16x32_bf16 v[124:127], v[156:159], v[172:175], v[124:127]
	v_mfma_f32_16x16x32_bf16 v[120:123], v[164:167], v[172:175], v[120:123]
	v_mfma_f32_16x16x32_bf16 v[116:119], v[156:159], v[180:183], v[116:119]
	v_mfma_f32_16x16x32_bf16 v[112:115], v[164:167], v[180:183], v[112:115]
	v_mfma_f32_16x16x32_bf16 v[100:103], v[156:159], v[188:191], v[100:103]
	v_mfma_f32_16x16x32_bf16 v[96:99], v[164:167], v[188:191], v[96:99]
	v_mfma_f32_16x16x32_bf16 v[84:87], v[156:159], v[196:199], v[84:87]
	v_mfma_f32_16x16x32_bf16 v[80:83], v[164:167], v[196:199], v[80:83]
	v_mfma_f32_16x16x32_bf16 v[124:127], v[160:163], v[176:179], v[124:127]
	v_mfma_f32_16x16x32_bf16 v[120:123], v[168:171], v[176:179], v[120:123]
	v_mfma_f32_16x16x32_bf16 v[116:119], v[160:163], v[184:187], v[116:119]
	v_mfma_f32_16x16x32_bf16 v[112:115], v[168:171], v[184:187], v[112:115]
	v_mfma_f32_16x16x32_bf16 v[100:103], v[160:163], v[192:195], v[100:103]
	v_mfma_f32_16x16x32_bf16 v[96:99], v[168:171], v[192:195], v[96:99]
	v_mfma_f32_16x16x32_bf16 v[84:87], v[160:163], v[200:203], v[84:87]
	v_mfma_f32_16x16x32_bf16 v[80:83], v[168:171], v[200:203], v[80:83]
	s_barrier
	s_add_i32 s88, s76, s61
	v_lshl_add_u64 v[220:221], s[54:55], 0, v[134:135]
	s_mov_b32 m0, s88
	ds_read_b128 v[204:207], v154
	ds_read_b128 v[208:211], v154 offset:1024
	ds_read_b128 v[212:215], v154 offset:2048
	ds_read_b128 v[216:219], v154 offset:3072
	global_load_lds_dwordx4 v[220:221], off
	v_lshl_add_u64 v[222:223], s[54:55], 0, v[130:131]
	s_add_i32 m0, s88, 0x2000
	s_nop 0
	global_load_lds_dwordx4 v[222:223], off
	s_barrier
	s_waitcnt lgkmcnt(0)
	s_waitcnt lgkmcnt(0)
	v_mfma_f32_16x16x32_bf16 v[108:111], v[204:207], v[172:175], v[108:111]
	v_mfma_f32_16x16x32_bf16 v[104:107], v[212:215], v[172:175], v[104:107]
	v_mfma_f32_16x16x32_bf16 v[92:95], v[204:207], v[180:183], v[92:95]
	v_mfma_f32_16x16x32_bf16 v[88:91], v[212:215], v[180:183], v[88:91]
	v_mfma_f32_16x16x32_bf16 v[76:79], v[204:207], v[188:191], v[76:79]
	v_mfma_f32_16x16x32_bf16 v[72:75], v[212:215], v[188:191], v[72:75]
	v_mfma_f32_16x16x32_bf16 v[68:71], v[204:207], v[196:199], v[68:71]
	v_mfma_f32_16x16x32_bf16 v[64:67], v[212:215], v[196:199], v[64:67]
	v_mfma_f32_16x16x32_bf16 v[108:111], v[208:211], v[176:179], v[108:111]
	v_mfma_f32_16x16x32_bf16 v[104:107], v[216:219], v[176:179], v[104:107]
	v_mfma_f32_16x16x32_bf16 v[92:95], v[208:211], v[184:187], v[92:95]
	v_mfma_f32_16x16x32_bf16 v[88:91], v[216:219], v[184:187], v[88:91]
	v_mfma_f32_16x16x32_bf16 v[76:79], v[208:211], v[192:195], v[76:79]
	v_mfma_f32_16x16x32_bf16 v[72:75], v[216:219], v[192:195], v[72:75]
	v_mfma_f32_16x16x32_bf16 v[68:71], v[208:211], v[200:203], v[68:71]
	v_mfma_f32_16x16x32_bf16 v[64:67], v[216:219], v[200:203], v[64:67]
	s_mov_b32 m0, s19
	v_lshl_add_u64 v[224:225], s[56:57], 0, v[136:137]
	s_barrier
	ds_read_b128 v[172:175], v153 offset:16384
	ds_read_b128 v[176:179], v153 offset:17408
	ds_read_b128 v[180:183], v153 offset:18432
	ds_read_b128 v[184:187], v153 offset:19456
	ds_read_b128 v[188:191], v153 offset:20480
	ds_read_b128 v[192:195], v153 offset:21504
	ds_read_b128 v[196:199], v153 offset:22528
	ds_read_b128 v[200:203], v153 offset:23552
	global_load_lds_dwordx4 v[224:225], off
	v_lshl_add_u64 v[226:227], s[56:57], 0, v[132:133]
	s_mov_b32 m0, s63
	s_nop 0
	global_load_lds_dwordx4 v[226:227], off
	s_barrier
	s_waitcnt lgkmcnt(0)
	s_waitcnt lgkmcnt(0)
	v_mfma_f32_16x16x32_bf16 v[60:63], v[156:159], v[172:175], v[60:63]
	v_mfma_f32_16x16x32_bf16 v[56:59], v[164:167], v[172:175], v[56:59]
	v_mfma_f32_16x16x32_bf16 v[52:55], v[156:159], v[180:183], v[52:55]
	v_mfma_f32_16x16x32_bf16 v[48:51], v[164:167], v[180:183], v[48:51]
	v_mfma_f32_16x16x32_bf16 v[36:39], v[156:159], v[188:191], v[36:39]
	v_mfma_f32_16x16x32_bf16 v[32:35], v[164:167], v[188:191], v[32:35]
	v_mfma_f32_16x16x32_bf16 v[20:23], v[156:159], v[196:199], v[20:23]
	v_mfma_f32_16x16x32_bf16 v[16:19], v[164:167], v[196:199], v[16:19]
	v_mfma_f32_16x16x32_bf16 v[60:63], v[160:163], v[176:179], v[60:63]
	v_mfma_f32_16x16x32_bf16 v[56:59], v[168:171], v[176:179], v[56:59]
	v_mfma_f32_16x16x32_bf16 v[52:55], v[160:163], v[184:187], v[52:55]
	v_mfma_f32_16x16x32_bf16 v[48:51], v[168:171], v[184:187], v[48:51]
	v_mfma_f32_16x16x32_bf16 v[36:39], v[160:163], v[192:195], v[36:39]
	v_mfma_f32_16x16x32_bf16 v[32:35], v[168:171], v[192:195], v[32:35]
	v_mfma_f32_16x16x32_bf16 v[20:23], v[160:163], v[200:203], v[20:23]
	v_mfma_f32_16x16x32_bf16 v[16:19], v[168:171], v[200:203], v[16:19]
	s_barrier
	s_add_u32 s88, s54, 0x40000
	s_addc_u32 s89, s55, 0
	s_add_i32 s90, s77, s61
	v_lshl_add_u64 v[156:157], s[88:89], 0, v[134:135]
	s_mov_b32 m0, s90
	s_nop 0
	global_load_lds_dwordx4 v[156:157], off
	v_lshl_add_u64 v[156:157], s[88:89], 0, v[130:131]
	s_add_i32 m0, s90, 0x2000
	s_nop 0
	global_load_lds_dwordx4 v[156:157], off
	s_waitcnt vmcnt(6)
	s_barrier
	v_mfma_f32_16x16x32_bf16 v[44:47], v[204:207], v[172:175], v[44:47]
	v_mfma_f32_16x16x32_bf16 v[40:43], v[212:215], v[172:175], v[40:43]
	v_mfma_f32_16x16x32_bf16 v[28:31], v[204:207], v[180:183], v[28:31]
	v_mfma_f32_16x16x32_bf16 v[24:27], v[212:215], v[180:183], v[24:27]
	v_mfma_f32_16x16x32_bf16 v[12:15], v[204:207], v[188:191], v[12:15]
	v_mfma_f32_16x16x32_bf16 v[8:11], v[212:215], v[188:191], v[8:11]
	v_mfma_f32_16x16x32_bf16 v[4:7], v[204:207], v[196:199], v[4:7]
	v_mfma_f32_16x16x32_bf16 v[0:3], v[212:215], v[196:199], v[0:3]
	v_mfma_f32_16x16x32_bf16 v[44:47], v[208:211], v[176:179], v[44:47]
	v_mfma_f32_16x16x32_bf16 v[40:43], v[216:219], v[176:179], v[40:43]
	v_mfma_f32_16x16x32_bf16 v[28:31], v[208:211], v[184:187], v[28:31]
	v_mfma_f32_16x16x32_bf16 v[24:27], v[216:219], v[184:187], v[24:27]
	v_mfma_f32_16x16x32_bf16 v[12:15], v[208:211], v[192:195], v[12:15]
	v_mfma_f32_16x16x32_bf16 v[8:11], v[216:219], v[192:195], v[8:11]
	v_mfma_f32_16x16x32_bf16 v[4:7], v[208:211], v[200:203], v[4:7]
	v_mfma_f32_16x16x32_bf16 v[0:3], v[216:219], v[200:203], v[0:3]
	s_add_i32 s88, 0, 0x18000
	v_add_u32_e32 v155, s88, v150
	s_barrier
	ds_read_b128 v[156:159], v155
	ds_read_b128 v[160:163], v155 offset:1024
	ds_read_b128 v[164:167], v155 offset:2048
	ds_read_b128 v[168:171], v155 offset:3072
	s_add_u32 s56, s56, 0x40000
	s_addc_u32 s57, s57, 0
	s_mov_b32 m0, s70
	v_lshl_add_u64 v[204:205], s[56:57], 0, v[136:137]
	ds_read_b128 v[172:175], v153 offset:32768
	ds_read_b128 v[176:179], v153 offset:33792
	ds_read_b128 v[180:183], v153 offset:34816
	ds_read_b128 v[184:187], v153 offset:35840
	ds_read_b128 v[188:191], v153 offset:36864
	ds_read_b128 v[192:195], v153 offset:37888
	ds_read_b128 v[196:199], v153 offset:38912
	ds_read_b128 v[200:203], v153 offset:39936
	global_load_lds_dwordx4 v[204:205], off
	v_lshl_add_u64 v[204:205], s[56:57], 0, v[132:133]
	s_mov_b32 m0, s71
	s_nop 0
	global_load_lds_dwordx4 v[204:205], off
	s_barrier
	s_waitcnt lgkmcnt(0)
	s_waitcnt lgkmcnt(0)
	v_mfma_f32_16x16x32_bf16 v[124:127], v[156:159], v[172:175], v[124:127]
	v_mfma_f32_16x16x32_bf16 v[120:123], v[164:167], v[172:175], v[120:123]
	v_mfma_f32_16x16x32_bf16 v[116:119], v[156:159], v[180:183], v[116:119]
	v_mfma_f32_16x16x32_bf16 v[112:115], v[164:167], v[180:183], v[112:115]
	v_mfma_f32_16x16x32_bf16 v[100:103], v[156:159], v[188:191], v[100:103]
	v_mfma_f32_16x16x32_bf16 v[96:99], v[164:167], v[188:191], v[96:99]
	v_mfma_f32_16x16x32_bf16 v[84:87], v[156:159], v[196:199], v[84:87]
	v_mfma_f32_16x16x32_bf16 v[80:83], v[164:167], v[196:199], v[80:83]
	v_mfma_f32_16x16x32_bf16 v[124:127], v[160:163], v[176:179], v[124:127]
	v_mfma_f32_16x16x32_bf16 v[120:123], v[168:171], v[176:179], v[120:123]
	v_mfma_f32_16x16x32_bf16 v[116:119], v[160:163], v[184:187], v[116:119]
	v_mfma_f32_16x16x32_bf16 v[112:115], v[168:171], v[184:187], v[112:115]
	v_mfma_f32_16x16x32_bf16 v[100:103], v[160:163], v[192:195], v[100:103]
	v_mfma_f32_16x16x32_bf16 v[96:99], v[168:171], v[192:195], v[96:99]
	v_mfma_f32_16x16x32_bf16 v[84:87], v[160:163], v[200:203], v[84:87]
	v_mfma_f32_16x16x32_bf16 v[80:83], v[168:171], v[200:203], v[80:83]
	s_barrier
	s_add_i32 s56, 0, 0x1c000
	s_add_i32 s57, s88, s61
	v_add_u32_e32 v155, s56, v150
	v_lshl_add_u64 v[220:221], v[220:221], 0, s[10:11]
	s_mov_b32 m0, s57
	ds_read_b128 v[204:207], v155
	ds_read_b128 v[208:211], v155 offset:1024
	ds_read_b128 v[212:215], v155 offset:2048
	ds_read_b128 v[216:219], v155 offset:3072
	global_load_lds_dwordx4 v[220:221], off
	v_lshl_add_u64 v[220:221], v[222:223], 0, s[10:11]
	s_add_i32 m0, s57, 0x2000
	s_nop 0
	global_load_lds_dwordx4 v[220:221], off
	s_barrier
	s_waitcnt lgkmcnt(0)
	s_waitcnt lgkmcnt(0)
	v_mfma_f32_16x16x32_bf16 v[108:111], v[204:207], v[172:175], v[108:111]
	v_mfma_f32_16x16x32_bf16 v[104:107], v[212:215], v[172:175], v[104:107]
	v_mfma_f32_16x16x32_bf16 v[92:95], v[204:207], v[180:183], v[92:95]
	v_mfma_f32_16x16x32_bf16 v[88:91], v[212:215], v[180:183], v[88:91]
	v_mfma_f32_16x16x32_bf16 v[76:79], v[204:207], v[188:191], v[76:79]
	v_mfma_f32_16x16x32_bf16 v[72:75], v[212:215], v[188:191], v[72:75]
	v_mfma_f32_16x16x32_bf16 v[68:71], v[204:207], v[196:199], v[68:71]
	v_mfma_f32_16x16x32_bf16 v[64:67], v[212:215], v[196:199], v[64:67]
	v_mfma_f32_16x16x32_bf16 v[108:111], v[208:211], v[176:179], v[108:111]
	v_mfma_f32_16x16x32_bf16 v[104:107], v[216:219], v[176:179], v[104:107]
	v_mfma_f32_16x16x32_bf16 v[92:95], v[208:211], v[184:187], v[92:95]
	v_mfma_f32_16x16x32_bf16 v[88:91], v[216:219], v[184:187], v[88:91]
	v_mfma_f32_16x16x32_bf16 v[76:79], v[208:211], v[192:195], v[76:79]
	v_mfma_f32_16x16x32_bf16 v[72:75], v[216:219], v[192:195], v[72:75]
	v_mfma_f32_16x16x32_bf16 v[68:71], v[208:211], v[200:203], v[68:71]
	v_mfma_f32_16x16x32_bf16 v[64:67], v[216:219], v[200:203], v[64:67]
	s_mov_b32 m0, s73
	v_lshl_add_u64 v[220:221], v[224:225], 0, s[10:11]
	s_barrier
	ds_read_b128 v[172:175], v153 offset:49152
	ds_read_b128 v[176:179], v153 offset:50176
	ds_read_b128 v[180:183], v153 offset:51200
	ds_read_b128 v[184:187], v153 offset:52224
	ds_read_b128 v[188:191], v153 offset:53248
	ds_read_b128 v[192:195], v153 offset:54272
	ds_read_b128 v[196:199], v153 offset:55296
	ds_read_b128 v[200:203], v153 offset:56320
	global_load_lds_dwordx4 v[220:221], off
	v_lshl_add_u64 v[220:221], v[226:227], 0, s[10:11]
	s_mov_b32 m0, s74
	s_nop 0
	global_load_lds_dwordx4 v[220:221], off
	s_barrier
	s_waitcnt lgkmcnt(0)
	s_waitcnt lgkmcnt(0)
	v_mfma_f32_16x16x32_bf16 v[60:63], v[156:159], v[172:175], v[60:63]
	v_mfma_f32_16x16x32_bf16 v[56:59], v[164:167], v[172:175], v[56:59]
	v_mfma_f32_16x16x32_bf16 v[52:55], v[156:159], v[180:183], v[52:55]
	v_mfma_f32_16x16x32_bf16 v[48:51], v[164:167], v[180:183], v[48:51]
	v_mfma_f32_16x16x32_bf16 v[36:39], v[156:159], v[188:191], v[36:39]
	v_mfma_f32_16x16x32_bf16 v[32:35], v[164:167], v[188:191], v[32:35]
	v_mfma_f32_16x16x32_bf16 v[20:23], v[156:159], v[196:199], v[20:23]
	v_mfma_f32_16x16x32_bf16 v[16:19], v[164:167], v[196:199], v[16:19]
	v_mfma_f32_16x16x32_bf16 v[60:63], v[160:163], v[176:179], v[60:63]
	v_mfma_f32_16x16x32_bf16 v[56:59], v[168:171], v[176:179], v[56:59]
	v_mfma_f32_16x16x32_bf16 v[52:55], v[160:163], v[184:187], v[52:55]
	v_mfma_f32_16x16x32_bf16 v[48:51], v[168:171], v[184:187], v[48:51]
	v_mfma_f32_16x16x32_bf16 v[36:39], v[160:163], v[192:195], v[36:39]
	v_mfma_f32_16x16x32_bf16 v[32:35], v[168:171], v[192:195], v[32:35]
	v_mfma_f32_16x16x32_bf16 v[20:23], v[160:163], v[200:203], v[20:23]
	v_mfma_f32_16x16x32_bf16 v[16:19], v[168:171], v[200:203], v[16:19]
	s_barrier
	s_add_u32 s54, s54, 0x40080
	s_addc_u32 s55, s55, 0
	s_add_i32 s56, s56, s61
	v_lshl_add_u64 v[156:157], s[54:55], 0, v[134:135]
	s_mov_b32 m0, s56
	s_nop 0
	global_load_lds_dwordx4 v[156:157], off
	v_lshl_add_u64 v[156:157], s[54:55], 0, v[130:131]
	s_add_i32 m0, s56, 0x2000
	s_nop 0
	global_load_lds_dwordx4 v[156:157], off
	s_waitcnt vmcnt(6)
	s_barrier
	v_mfma_f32_16x16x32_bf16 v[44:47], v[204:207], v[172:175], v[44:47]
	v_mfma_f32_16x16x32_bf16 v[40:43], v[212:215], v[172:175], v[40:43]
	v_mfma_f32_16x16x32_bf16 v[28:31], v[204:207], v[180:183], v[28:31]
	v_mfma_f32_16x16x32_bf16 v[24:27], v[212:215], v[180:183], v[24:27]
	v_mfma_f32_16x16x32_bf16 v[12:15], v[204:207], v[188:191], v[12:15]
	v_mfma_f32_16x16x32_bf16 v[8:11], v[212:215], v[188:191], v[8:11]
	v_mfma_f32_16x16x32_bf16 v[4:7], v[204:207], v[196:199], v[4:7]
	v_mfma_f32_16x16x32_bf16 v[0:3], v[212:215], v[196:199], v[0:3]
	v_mfma_f32_16x16x32_bf16 v[44:47], v[208:211], v[176:179], v[44:47]
	v_mfma_f32_16x16x32_bf16 v[40:43], v[216:219], v[176:179], v[40:43]
	v_mfma_f32_16x16x32_bf16 v[28:31], v[208:211], v[184:187], v[28:31]
	v_mfma_f32_16x16x32_bf16 v[24:27], v[216:219], v[184:187], v[24:27]
	v_mfma_f32_16x16x32_bf16 v[12:15], v[208:211], v[192:195], v[12:15]
	v_mfma_f32_16x16x32_bf16 v[8:11], v[216:219], v[192:195], v[8:11]
	v_mfma_f32_16x16x32_bf16 v[4:7], v[208:211], v[200:203], v[4:7]
	v_mfma_f32_16x16x32_bf16 v[0:3], v[216:219], v[200:203], v[0:3]
	s_add_i32 s87, s87, 2
	s_add_u32 s34, s34, 0x100
	s_addc_u32 s35, s35, 0
	s_add_u32 s85, s85, 0x100
	s_addc_u32 s86, s86, 0
	s_cmp_gt_u32 s87, 13
	s_barrier
	s_cbranch_scc0 .LBB0_912
	v_lshl_add_u32 v156, s18, 8, v149
	v_lshl_or_b32 v158, s82, 8, v151
	v_ashrrev_i32_e32 v157, 31, v156
	v_lshlrev_b64 v[160:161], 11, v[156:157]
	v_ashrrev_i32_e32 v159, 31, v158
	v_lshl_add_u64 v[160:161], s[46:47], 0, v[160:161]
	v_cvt_pk_bf16_f32 v124, v124, v125
	v_cvt_pk_bf16_f32 v125, v126, v127
	v_cvt_pk_bf16_f32 v126, v120, v121
	v_lshlrev_b64 v[120:121], 1, v[158:159]
	v_cvt_pk_bf16_f32 v127, v122, v123
	v_lshl_add_u64 v[122:123], v[160:161], 0, v[120:121]
	v_cvt_pk_bf16_f32 v108, v108, v109
	v_cvt_pk_bf16_f32 v109, v110, v111
	v_cvt_pk_bf16_f32 v110, v104, v105
	v_or_b32_e32 v104, 16, v156
	v_cvt_pk_bf16_f32 v60, v60, v61
	v_cvt_pk_bf16_f32 v61, v62, v63
	v_cvt_pk_bf16_f32 v63, v58, v59
	v_add_co_u32_e32 v58, vcc, s78, v122
	v_ashrrev_i32_e32 v105, 31, v104
	v_cvt_pk_bf16_f32 v62, v56, v57
	v_lshl_add_u64 v[56:57], v[122:123], 0, s[8:9]
	v_addc_co_u32_e32 v59, vcc, 0, v123, vcc
	v_cvt_pk_bf16_f32 v44, v44, v45
	v_cvt_pk_bf16_f32 v45, v46, v47
	v_cvt_pk_bf16_f32 v46, v40, v41
	v_cvt_pk_bf16_f32 v47, v42, v43
	v_cvt_pk_bf16_f32 v111, v106, v107
	v_lshlrev_b64 v[104:105], 11, v[104:105]
	v_cvt_pk_bf16_f32 v92, v92, v93
	v_cvt_pk_bf16_f32 v93, v94, v95
	v_cvt_pk_bf16_f32 v94, v88, v89
	v_or_b32_e32 v88, 32, v156
	global_store_dwordx4 v[56:57], v[44:47], off offset:256
	global_store_dwordx4 v[122:123], v[108:111], off offset:256
	v_ashrrev_i32_e32 v89, 31, v88
	v_add_co_u32_e32 v46, vcc, s79, v122
	v_lshl_add_u64 v[108:109], s[46:47], 0, v[104:105]
	v_lshl_add_u64 v[44:45], v[122:123], 0, s[12:13]
	v_addc_co_u32_e32 v47, vcc, 0, v123, vcc
	v_cvt_pk_bf16_f32 v28, v28, v29
	v_cvt_pk_bf16_f32 v29, v30, v31
	v_cvt_pk_bf16_f32 v30, v24, v25
	v_cvt_pk_bf16_f32 v31, v26, v27
	v_lshl_add_u64 v[108:109], v[108:109], 0, v[120:121]
	v_cvt_pk_bf16_f32 v95, v90, v91
	v_lshlrev_b64 v[88:89], 11, v[88:89]
	v_cvt_pk_bf16_f32 v76, v76, v77
	v_cvt_pk_bf16_f32 v77, v78, v79
	v_cvt_pk_bf16_f32 v78, v72, v73
	v_or_b32_e32 v72, 48, v156
	global_store_dwordx4 v[44:45], v[28:31], off offset:256
	global_store_dwordx4 v[108:109], v[92:95], off offset:256
	v_ashrrev_i32_e32 v73, 31, v72
	v_add_co_u32_e32 v30, vcc, s80, v122
	v_lshl_add_u64 v[92:93], s[46:47], 0, v[88:89]
	v_lshl_add_u64 v[28:29], v[122:123], 0, s[14:15]
	v_addc_co_u32_e32 v31, vcc, 0, v123, vcc
	v_cvt_pk_bf16_f32 v12, v12, v13
	v_cvt_pk_bf16_f32 v13, v14, v15
	v_cvt_pk_bf16_f32 v14, v8, v9
	v_cvt_pk_bf16_f32 v15, v10, v11
	v_lshl_add_u64 v[92:93], v[92:93], 0, v[120:121]
	v_cvt_pk_bf16_f32 v79, v74, v75
	v_lshlrev_b64 v[72:73], 11, v[72:73]
	global_store_dwordx4 v[28:29], v[12:15], off offset:256
	global_store_dwordx4 v[92:93], v[76:79], off offset:256
	v_cvt_pk_bf16_f32 v104, v116, v117
	v_add_co_u32_e32 v14, vcc, s81, v122
	v_lshl_add_u64 v[76:77], s[46:47], 0, v[72:73]
	s_nop 0
	v_addc_co_u32_e32 v15, vcc, 0, v123, vcc
	v_cvt_pk_bf16_f32 v105, v118, v119
	v_cvt_pk_bf16_f32 v106, v112, v113
	v_cvt_pk_bf16_f32 v107, v114, v115
	v_cvt_pk_bf16_f32 v88, v100, v101
	v_cvt_pk_bf16_f32 v89, v102, v103
	v_cvt_pk_bf16_f32 v90, v96, v97
	v_cvt_pk_bf16_f32 v91, v98, v99
	v_cvt_pk_bf16_f32 v72, v84, v85
	v_cvt_pk_bf16_f32 v73, v86, v87
	v_cvt_pk_bf16_f32 v74, v80, v81
	v_cvt_pk_bf16_f32 v75, v82, v83
	v_lshl_add_u64 v[76:77], v[76:77], 0, v[120:121]
	v_cvt_pk_bf16_f32 v68, v68, v69
	v_cvt_pk_bf16_f32 v69, v70, v71
	v_cvt_pk_bf16_f32 v70, v64, v65
	v_cvt_pk_bf16_f32 v71, v66, v67
	v_cvt_pk_bf16_f32 v40, v52, v53
	v_cvt_pk_bf16_f32 v41, v54, v55
	v_cvt_pk_bf16_f32 v42, v48, v49
	v_cvt_pk_bf16_f32 v43, v50, v51
	v_cvt_pk_bf16_f32 v24, v36, v37
	v_cvt_pk_bf16_f32 v25, v38, v39
	v_cvt_pk_bf16_f32 v26, v32, v33
	v_cvt_pk_bf16_f32 v27, v34, v35
	v_cvt_pk_bf16_f32 v8, v20, v21
	v_cvt_pk_bf16_f32 v9, v22, v23
	v_cvt_pk_bf16_f32 v10, v16, v17
	v_cvt_pk_bf16_f32 v11, v18, v19
	v_lshl_add_u64 v[12:13], v[122:123], 0, s[16:17]
	v_cvt_pk_bf16_f32 v4, v4, v5
	v_cvt_pk_bf16_f32 v5, v6, v7
	v_cvt_pk_bf16_f32 v6, v0, v1
	v_cvt_pk_bf16_f32 v7, v2, v3
	s_and_b64 vcc, exec, s[4:5]
	s_mov_b32 s82, s20
	s_mov_b32 s18, s26
	s_mov_b64 s[54:55], s[30:31]
	s_mov_b64 s[34:35], s[28:29]
	global_store_dwordx4 v[122:123], v[124:127], off
	global_store_dwordx4 v[108:109], v[104:107], off
	global_store_dwordx4 v[92:93], v[88:91], off
	global_store_dwordx4 v[76:77], v[72:75], off
	global_store_dwordx4 v[76:77], v[68:71], off offset:256
	global_store_dwordx4 v[58:59], v[60:63], off
	global_store_dwordx4 v[46:47], v[40:43], off
	global_store_dwordx4 v[30:31], v[24:27], off
	global_store_dwordx4 v[14:15], v[8:11], off
	global_store_dwordx4 v[12:13], v[4:7], off offset:256
	s_cbranch_vccz .LBB0_909
	s_waitcnt vmcnt(0)
	s_cmpk_gt_u32 s60, 0xff
	s_cbranch_scc1 .LBB0_916
	s_barrier

.LBB0_1116:
	ds_read_b128 v[154:157], v150
	ds_read_b128 v[158:161], v150 offset:1024
	ds_read_b128 v[162:165], v150 offset:2048
	ds_read_b128 v[166:169], v150 offset:3072
	s_add_u32 s34, s30, 0xfffc0080
	s_addc_u32 s35, s31, -1
	s_cmp_eq_u32 s77, 12
	s_cselect_b32 s37, s19, s35
	s_cselect_b32 s36, s73, s34
	s_cselect_b32 s35, s17, s76
	s_cselect_b32 s34, s74, s75
	v_lshl_add_u64 v[202:203], s[30:31], 0, v[134:135]
	s_add_i32 m0, s29, 0xc000
	ds_read_b128 v[170:173], v151
	ds_read_b128 v[174:177], v151 offset:1024
	ds_read_b128 v[178:181], v151 offset:2048
	ds_read_b128 v[182:185], v151 offset:3072
	ds_read_b128 v[186:189], v151 offset:4096
	ds_read_b128 v[190:193], v151 offset:5120
	ds_read_b128 v[194:197], v151 offset:6144
	ds_read_b128 v[198:201], v151 offset:7168
	global_load_lds_dwordx4 v[202:203], off
	v_lshl_add_u64 v[202:203], s[30:31], 0, v[136:137]
	s_add_i32 m0, s29, 0xe000
	s_nop 0
	global_load_lds_dwordx4 v[202:203], off
	s_barrier
	s_waitcnt lgkmcnt(0)
	s_waitcnt lgkmcnt(0)
	v_mfma_f32_16x16x32_bf16 v[120:123], v[154:157], v[170:173], v[120:123]
	v_mfma_f32_16x16x32_bf16 v[124:127], v[162:165], v[170:173], v[124:127]
	v_mfma_f32_16x16x32_bf16 v[104:107], v[154:157], v[178:181], v[104:107]
	v_mfma_f32_16x16x32_bf16 v[108:111], v[162:165], v[178:181], v[108:111]
	v_mfma_f32_16x16x32_bf16 v[88:91], v[154:157], v[186:189], v[88:91]
	v_mfma_f32_16x16x32_bf16 v[92:95], v[162:165], v[186:189], v[92:95]
	v_mfma_f32_16x16x32_bf16 v[72:75], v[154:157], v[194:197], v[72:75]
	v_mfma_f32_16x16x32_bf16 v[76:79], v[162:165], v[194:197], v[76:79]
	v_mfma_f32_16x16x32_bf16 v[120:123], v[158:161], v[174:177], v[120:123]
	v_mfma_f32_16x16x32_bf16 v[124:127], v[166:169], v[174:177], v[124:127]
	v_mfma_f32_16x16x32_bf16 v[104:107], v[158:161], v[182:185], v[104:107]
	v_mfma_f32_16x16x32_bf16 v[108:111], v[166:169], v[182:185], v[108:111]
	v_mfma_f32_16x16x32_bf16 v[88:91], v[158:161], v[190:193], v[88:91]
	v_mfma_f32_16x16x32_bf16 v[92:95], v[166:169], v[190:193], v[92:95]
	v_mfma_f32_16x16x32_bf16 v[72:75], v[158:161], v[198:201], v[72:75]
	v_mfma_f32_16x16x32_bf16 v[76:79], v[166:169], v[198:201], v[76:79]
	s_barrier
	s_add_i32 s78, s60, s42
	v_lshl_add_u64 v[218:219], s[34:35], 0, v[130:131]
	s_mov_b32 m0, s78
	ds_read_b128 v[202:205], v152
	ds_read_b128 v[206:209], v152 offset:1024
	ds_read_b128 v[210:213], v152 offset:2048
	ds_read_b128 v[214:217], v152 offset:3072
	global_load_lds_dwordx4 v[218:219], off
	v_lshl_add_u64 v[220:221], s[34:35], 0, v[132:133]
	s_add_i32 m0, s78, 0x2000
	s_nop 0
	global_load_lds_dwordx4 v[220:221], off
	s_barrier
	s_waitcnt lgkmcnt(0)
	s_waitcnt lgkmcnt(0)
	v_mfma_f32_16x16x32_bf16 v[112:115], v[202:205], v[170:173], v[112:115]
	v_mfma_f32_16x16x32_bf16 v[116:119], v[210:213], v[170:173], v[116:119]
	v_mfma_f32_16x16x32_bf16 v[96:99], v[202:205], v[178:181], v[96:99]
	v_mfma_f32_16x16x32_bf16 v[100:103], v[210:213], v[178:181], v[100:103]
	v_mfma_f32_16x16x32_bf16 v[80:83], v[202:205], v[186:189], v[80:83]
	v_mfma_f32_16x16x32_bf16 v[84:87], v[210:213], v[186:189], v[84:87]
	v_mfma_f32_16x16x32_bf16 v[64:67], v[202:205], v[194:197], v[64:67]
	v_mfma_f32_16x16x32_bf16 v[68:71], v[210:213], v[194:197], v[68:71]
	v_mfma_f32_16x16x32_bf16 v[112:115], v[206:209], v[174:177], v[112:115]
	v_mfma_f32_16x16x32_bf16 v[116:119], v[214:217], v[174:177], v[116:119]
	v_mfma_f32_16x16x32_bf16 v[96:99], v[206:209], v[182:185], v[96:99]
	v_mfma_f32_16x16x32_bf16 v[100:103], v[214:217], v[182:185], v[100:103]
	v_mfma_f32_16x16x32_bf16 v[80:83], v[206:209], v[190:193], v[80:83]
	v_mfma_f32_16x16x32_bf16 v[84:87], v[214:217], v[190:193], v[84:87]
	v_mfma_f32_16x16x32_bf16 v[64:67], v[206:209], v[198:201], v[64:67]
	v_mfma_f32_16x16x32_bf16 v[68:71], v[214:217], v[198:201], v[68:71]
	s_mov_b32 m0, s29
	v_lshl_add_u64 v[222:223], s[36:37], 0, v[130:131]
	s_barrier
	ds_read_b128 v[170:173], v151 offset:16384
	ds_read_b128 v[174:177], v151 offset:17408
	ds_read_b128 v[178:181], v151 offset:18432
	ds_read_b128 v[182:185], v151 offset:19456
	ds_read_b128 v[186:189], v151 offset:20480
	ds_read_b128 v[190:193], v151 offset:21504
	ds_read_b128 v[194:197], v151 offset:22528
	ds_read_b128 v[198:201], v151 offset:23552
	global_load_lds_dwordx4 v[222:223], off
	v_lshl_add_u64 v[224:225], s[36:37], 0, v[132:133]
	s_mov_b32 m0, s43
	s_nop 0
	global_load_lds_dwordx4 v[224:225], off
	s_barrier
	s_waitcnt lgkmcnt(0)
	s_waitcnt lgkmcnt(0)
	v_mfma_f32_16x16x32_bf16 v[56:59], v[154:157], v[170:173], v[56:59]
	v_mfma_f32_16x16x32_bf16 v[60:63], v[162:165], v[170:173], v[60:63]
	v_mfma_f32_16x16x32_bf16 v[40:43], v[154:157], v[178:181], v[40:43]
	v_mfma_f32_16x16x32_bf16 v[44:47], v[162:165], v[178:181], v[44:47]
	v_mfma_f32_16x16x32_bf16 v[24:27], v[154:157], v[186:189], v[24:27]
	v_mfma_f32_16x16x32_bf16 v[28:31], v[162:165], v[186:189], v[28:31]
	v_mfma_f32_16x16x32_bf16 v[8:11], v[154:157], v[194:197], v[8:11]
	v_mfma_f32_16x16x32_bf16 v[12:15], v[162:165], v[194:197], v[12:15]
	v_mfma_f32_16x16x32_bf16 v[56:59], v[158:161], v[174:177], v[56:59]
	v_mfma_f32_16x16x32_bf16 v[60:63], v[166:169], v[174:177], v[60:63]
	v_mfma_f32_16x16x32_bf16 v[40:43], v[158:161], v[182:185], v[40:43]
	v_mfma_f32_16x16x32_bf16 v[44:47], v[166:169], v[182:185], v[44:47]
	v_mfma_f32_16x16x32_bf16 v[24:27], v[158:161], v[190:193], v[24:27]
	v_mfma_f32_16x16x32_bf16 v[28:31], v[166:169], v[190:193], v[28:31]
	v_mfma_f32_16x16x32_bf16 v[8:11], v[158:161], v[198:201], v[8:11]
	v_mfma_f32_16x16x32_bf16 v[12:15], v[166:169], v[198:201], v[12:15]
	s_barrier
	s_add_u32 s78, s34, 0x40000
	s_addc_u32 s79, s35, 0
	s_add_i32 s80, s61, s42
	v_lshl_add_u64 v[154:155], s[78:79], 0, v[130:131]
	s_mov_b32 m0, s80
	s_nop 0
	global_load_lds_dwordx4 v[154:155], off
	v_lshl_add_u64 v[154:155], s[78:79], 0, v[132:133]
	s_add_i32 m0, s80, 0x2000
	s_nop 0
	global_load_lds_dwordx4 v[154:155], off
	s_waitcnt vmcnt(6)
	s_barrier
	v_mfma_f32_16x16x32_bf16 v[48:51], v[202:205], v[170:173], v[48:51]
	v_mfma_f32_16x16x32_bf16 v[52:55], v[210:213], v[170:173], v[52:55]
	v_mfma_f32_16x16x32_bf16 v[32:35], v[202:205], v[178:181], v[32:35]
	v_mfma_f32_16x16x32_bf16 v[36:39], v[210:213], v[178:181], v[36:39]
	v_mfma_f32_16x16x32_bf16 v[16:19], v[202:205], v[186:189], v[16:19]
	v_mfma_f32_16x16x32_bf16 v[20:23], v[210:213], v[186:189], v[20:23]
	v_mfma_f32_16x16x32_bf16 v[0:3], v[202:205], v[194:197], v[0:3]
	v_mfma_f32_16x16x32_bf16 v[4:7], v[210:213], v[194:197], v[4:7]
	v_mfma_f32_16x16x32_bf16 v[48:51], v[206:209], v[174:177], v[48:51]
	v_mfma_f32_16x16x32_bf16 v[52:55], v[214:217], v[174:177], v[52:55]
	v_mfma_f32_16x16x32_bf16 v[32:35], v[206:209], v[182:185], v[32:35]
	v_mfma_f32_16x16x32_bf16 v[36:39], v[214:217], v[182:185], v[36:39]
	v_mfma_f32_16x16x32_bf16 v[16:19], v[206:209], v[190:193], v[16:19]
	v_mfma_f32_16x16x32_bf16 v[20:23], v[214:217], v[190:193], v[20:23]
	v_mfma_f32_16x16x32_bf16 v[0:3], v[206:209], v[198:201], v[0:3]
	v_mfma_f32_16x16x32_bf16 v[4:7], v[214:217], v[198:201], v[4:7]
	s_add_i32 s78, 0, 0x18000
	v_add_u32_e32 v153, s78, v148
	s_barrier
	ds_read_b128 v[154:157], v153
	ds_read_b128 v[158:161], v153 offset:1024
	ds_read_b128 v[162:165], v153 offset:2048
	ds_read_b128 v[166:169], v153 offset:3072
	s_add_u32 s36, s36, 0x40000
	s_addc_u32 s37, s37, 0
	s_mov_b32 m0, s52
	v_lshl_add_u64 v[202:203], s[36:37], 0, v[130:131]
	ds_read_b128 v[170:173], v151 offset:32768
	ds_read_b128 v[174:177], v151 offset:33792
	ds_read_b128 v[178:181], v151 offset:34816
	ds_read_b128 v[182:185], v151 offset:35840
	ds_read_b128 v[186:189], v151 offset:36864
	ds_read_b128 v[190:193], v151 offset:37888
	ds_read_b128 v[194:197], v151 offset:38912
	ds_read_b128 v[198:201], v151 offset:39936
	global_load_lds_dwordx4 v[202:203], off
	v_lshl_add_u64 v[202:203], s[36:37], 0, v[132:133]
	s_mov_b32 m0, s53
	s_nop 0
	global_load_lds_dwordx4 v[202:203], off
	s_barrier
	s_waitcnt lgkmcnt(0)
	s_waitcnt lgkmcnt(0)
	v_mfma_f32_16x16x32_bf16 v[120:123], v[154:157], v[170:173], v[120:123]
	v_mfma_f32_16x16x32_bf16 v[124:127], v[162:165], v[170:173], v[124:127]
	v_mfma_f32_16x16x32_bf16 v[104:107], v[154:157], v[178:181], v[104:107]
	v_mfma_f32_16x16x32_bf16 v[108:111], v[162:165], v[178:181], v[108:111]
	v_mfma_f32_16x16x32_bf16 v[88:91], v[154:157], v[186:189], v[88:91]
	v_mfma_f32_16x16x32_bf16 v[92:95], v[162:165], v[186:189], v[92:95]
	v_mfma_f32_16x16x32_bf16 v[72:75], v[154:157], v[194:197], v[72:75]
	v_mfma_f32_16x16x32_bf16 v[76:79], v[162:165], v[194:197], v[76:79]
	v_mfma_f32_16x16x32_bf16 v[120:123], v[158:161], v[174:177], v[120:123]
	v_mfma_f32_16x16x32_bf16 v[124:127], v[166:169], v[174:177], v[124:127]
	v_mfma_f32_16x16x32_bf16 v[104:107], v[158:161], v[182:185], v[104:107]
	v_mfma_f32_16x16x32_bf16 v[108:111], v[166:169], v[182:185], v[108:111]
	v_mfma_f32_16x16x32_bf16 v[88:91], v[158:161], v[190:193], v[88:91]
	v_mfma_f32_16x16x32_bf16 v[92:95], v[166:169], v[190:193], v[92:95]
	v_mfma_f32_16x16x32_bf16 v[72:75], v[158:161], v[198:201], v[72:75]
	v_mfma_f32_16x16x32_bf16 v[76:79], v[166:169], v[198:201], v[76:79]
	s_barrier
	s_add_i32 s36, 0, 0x1c000
	s_add_i32 s37, s78, s42
	v_add_u32_e32 v153, s36, v148
	v_lshl_add_u64 v[218:219], v[218:219], 0, s[8:9]
	s_mov_b32 m0, s37
	ds_read_b128 v[202:205], v153
	ds_read_b128 v[206:209], v153 offset:1024
	ds_read_b128 v[210:213], v153 offset:2048
	ds_read_b128 v[214:217], v153 offset:3072
	global_load_lds_dwordx4 v[218:219], off
	v_lshl_add_u64 v[218:219], v[220:221], 0, s[8:9]
	s_add_i32 m0, s37, 0x2000
	s_nop 0
	global_load_lds_dwordx4 v[218:219], off
	s_barrier
	s_waitcnt lgkmcnt(0)
	s_waitcnt lgkmcnt(0)
	v_mfma_f32_16x16x32_bf16 v[112:115], v[202:205], v[170:173], v[112:115]
	v_mfma_f32_16x16x32_bf16 v[116:119], v[210:213], v[170:173], v[116:119]
	v_mfma_f32_16x16x32_bf16 v[96:99], v[202:205], v[178:181], v[96:99]
	v_mfma_f32_16x16x32_bf16 v[100:103], v[210:213], v[178:181], v[100:103]
	v_mfma_f32_16x16x32_bf16 v[80:83], v[202:205], v[186:189], v[80:83]
	v_mfma_f32_16x16x32_bf16 v[84:87], v[210:213], v[186:189], v[84:87]
	v_mfma_f32_16x16x32_bf16 v[64:67], v[202:205], v[194:197], v[64:67]
	v_mfma_f32_16x16x32_bf16 v[68:71], v[210:213], v[194:197], v[68:71]
	v_mfma_f32_16x16x32_bf16 v[112:115], v[206:209], v[174:177], v[112:115]
	v_mfma_f32_16x16x32_bf16 v[116:119], v[214:217], v[174:177], v[116:119]
	v_mfma_f32_16x16x32_bf16 v[96:99], v[206:209], v[182:185], v[96:99]
	v_mfma_f32_16x16x32_bf16 v[100:103], v[214:217], v[182:185], v[100:103]
	v_mfma_f32_16x16x32_bf16 v[80:83], v[206:209], v[190:193], v[80:83]
	v_mfma_f32_16x16x32_bf16 v[84:87], v[214:217], v[190:193], v[84:87]
	v_mfma_f32_16x16x32_bf16 v[64:67], v[206:209], v[198:201], v[64:67]
	v_mfma_f32_16x16x32_bf16 v[68:71], v[214:217], v[198:201], v[68:71]
	s_mov_b32 m0, s55
	v_lshl_add_u64 v[218:219], v[222:223], 0, s[8:9]
	s_barrier
	ds_read_b128 v[170:173], v151 offset:49152
	ds_read_b128 v[174:177], v151 offset:50176
	ds_read_b128 v[178:181], v151 offset:51200
	ds_read_b128 v[182:185], v151 offset:52224
	ds_read_b128 v[186:189], v151 offset:53248
	ds_read_b128 v[190:193], v151 offset:54272
	ds_read_b128 v[194:197], v151 offset:55296
	ds_read_b128 v[198:201], v151 offset:56320
	global_load_lds_dwordx4 v[218:219], off
	v_lshl_add_u64 v[218:219], v[224:225], 0, s[8:9]
	s_mov_b32 m0, s56
	s_nop 0
	global_load_lds_dwordx4 v[218:219], off
	s_barrier
	s_waitcnt lgkmcnt(0)
	s_waitcnt lgkmcnt(0)
	v_mfma_f32_16x16x32_bf16 v[56:59], v[154:157], v[170:173], v[56:59]
	v_mfma_f32_16x16x32_bf16 v[60:63], v[162:165], v[170:173], v[60:63]
	v_mfma_f32_16x16x32_bf16 v[40:43], v[154:157], v[178:181], v[40:43]
	v_mfma_f32_16x16x32_bf16 v[44:47], v[162:165], v[178:181], v[44:47]
	v_mfma_f32_16x16x32_bf16 v[24:27], v[154:157], v[186:189], v[24:27]
	v_mfma_f32_16x16x32_bf16 v[28:31], v[162:165], v[186:189], v[28:31]
	v_mfma_f32_16x16x32_bf16 v[8:11], v[154:157], v[194:197], v[8:11]
	v_mfma_f32_16x16x32_bf16 v[12:15], v[162:165], v[194:197], v[12:15]
	v_mfma_f32_16x16x32_bf16 v[56:59], v[158:161], v[174:177], v[56:59]
	v_mfma_f32_16x16x32_bf16 v[60:63], v[166:169], v[174:177], v[60:63]
	v_mfma_f32_16x16x32_bf16 v[40:43], v[158:161], v[182:185], v[40:43]
	v_mfma_f32_16x16x32_bf16 v[44:47], v[166:169], v[182:185], v[44:47]
	v_mfma_f32_16x16x32_bf16 v[24:27], v[158:161], v[190:193], v[24:27]
	v_mfma_f32_16x16x32_bf16 v[28:31], v[166:169], v[190:193], v[28:31]
	v_mfma_f32_16x16x32_bf16 v[8:11], v[158:161], v[198:201], v[8:11]
	v_mfma_f32_16x16x32_bf16 v[12:15], v[166:169], v[198:201], v[12:15]
	s_barrier
	s_add_u32 s34, s34, 0x40080
	s_addc_u32 s35, s35, 0
	s_add_i32 s36, s36, s42
	v_lshl_add_u64 v[154:155], s[34:35], 0, v[130:131]
	s_mov_b32 m0, s36
	s_nop 0
	global_load_lds_dwordx4 v[154:155], off
	v_lshl_add_u64 v[154:155], s[34:35], 0, v[132:133]
	s_add_i32 m0, s36, 0x2000
	s_nop 0
	global_load_lds_dwordx4 v[154:155], off
	s_waitcnt vmcnt(6)
	s_barrier
	v_mfma_f32_16x16x32_bf16 v[48:51], v[202:205], v[170:173], v[48:51]
	v_mfma_f32_16x16x32_bf16 v[52:55], v[210:213], v[170:173], v[52:55]
	v_mfma_f32_16x16x32_bf16 v[32:35], v[202:205], v[178:181], v[32:35]
	v_mfma_f32_16x16x32_bf16 v[36:39], v[210:213], v[178:181], v[36:39]
	v_mfma_f32_16x16x32_bf16 v[16:19], v[202:205], v[186:189], v[16:19]
	v_mfma_f32_16x16x32_bf16 v[20:23], v[210:213], v[186:189], v[20:23]
	v_mfma_f32_16x16x32_bf16 v[0:3], v[202:205], v[194:197], v[0:3]
	v_mfma_f32_16x16x32_bf16 v[4:7], v[210:213], v[194:197], v[4:7]
	v_mfma_f32_16x16x32_bf16 v[48:51], v[206:209], v[174:177], v[48:51]
	v_mfma_f32_16x16x32_bf16 v[52:55], v[214:217], v[174:177], v[52:55]
	v_mfma_f32_16x16x32_bf16 v[32:35], v[206:209], v[182:185], v[32:35]
	v_mfma_f32_16x16x32_bf16 v[36:39], v[214:217], v[182:185], v[36:39]
	v_mfma_f32_16x16x32_bf16 v[16:19], v[206:209], v[190:193], v[16:19]
	v_mfma_f32_16x16x32_bf16 v[20:23], v[214:217], v[190:193], v[20:23]
	v_mfma_f32_16x16x32_bf16 v[0:3], v[206:209], v[198:201], v[0:3]
	v_mfma_f32_16x16x32_bf16 v[4:7], v[214:217], v[198:201], v[4:7]
	s_add_i32 s77, s77, 2
	s_add_u32 s30, s30, 0x100
	s_addc_u32 s31, s31, 0
	s_add_u32 s75, s75, 0x100
	s_addc_u32 s76, s76, 0
	s_cmp_gt_u32 s77, 13
	s_barrier
	s_cbranch_scc0 .LBB0_1116
	v_mul_f32_e32 v124, 0xbfb8aa3b, v124
	v_exp_f32_e32 v154, v124
	v_mul_f32_e32 v124, 0xbfb8aa3b, v125
	v_exp_f32_e32 v155, v124
	v_lshl_add_u32 v124, s28, 8, v145
	v_ashrrev_i32_e32 v125, 31, v124
	v_lshlrev_b64 v[158:159], 11, v[124:125]
	v_pk_add_f32 v[154:155], v[154:155], 1.0 op_sel_hi:[1,0]
	v_mul_f32_e32 v126, 0xbfb8aa3b, v126
	v_div_scale_f32 v153, s[30:31], v155, v155, v121
	v_rcp_f32_e32 v157, v153
	v_mul_f32_e32 v127, 0xbfb8aa3b, v127
	v_exp_f32_e32 v126, v126
	v_exp_f32_e32 v127, v127
	v_fma_f32 v125, -v153, v157, 1.0
	v_fmac_f32_e32 v157, v125, v157
	v_div_scale_f32 v125, vcc, v121, v155, v121
	v_mul_f32_e32 v160, v125, v157
	v_fma_f32 v161, -v153, v160, v125
	v_fmac_f32_e32 v160, v161, v157
	v_fma_f32 v125, -v153, v160, v125
	v_div_scale_f32 v153, s[30:31], v154, v154, v120
	v_rcp_f32_e32 v161, v153
	v_div_fmas_f32 v125, v125, v157, v160
	v_div_fixup_f32 v121, v125, v155, v121
	v_pk_add_f32 v[126:127], v[126:127], 1.0 op_sel_hi:[1,0]
	v_fma_f32 v125, -v153, v161, 1.0
	v_fmac_f32_e32 v161, v125, v161
	v_div_scale_f32 v125, vcc, v120, v154, v120
	v_mul_f32_e32 v155, v125, v161
	v_fma_f32 v157, -v153, v155, v125
	v_fmac_f32_e32 v155, v157, v161
	v_fma_f32 v125, -v153, v155, v125
	v_div_scale_f32 v153, s[30:31], v127, v127, v123
	v_rcp_f32_e32 v157, v153
	v_div_fmas_f32 v125, v125, v161, v155
	v_div_fixup_f32 v120, v125, v154, v120
	v_mul_f32_e32 v116, 0xbfb8aa3b, v116
	v_fma_f32 v125, -v153, v157, 1.0
	v_fmac_f32_e32 v157, v125, v157
	v_div_scale_f32 v125, vcc, v123, v127, v123
	v_mul_f32_e32 v154, v125, v157
	v_fma_f32 v155, -v153, v154, v125
	v_fmac_f32_e32 v154, v155, v157
	v_fma_f32 v125, -v153, v154, v125
	v_div_scale_f32 v153, s[30:31], v126, v126, v122
	v_rcp_f32_e32 v155, v153
	v_div_fmas_f32 v125, v125, v157, v154
	v_div_fixup_f32 v123, v125, v127, v123
	v_mul_f32_e32 v117, 0xbfb8aa3b, v117
	v_fma_f32 v125, -v153, v155, 1.0
	v_fmac_f32_e32 v155, v125, v155
	v_div_scale_f32 v125, vcc, v122, v126, v122
	v_mul_f32_e32 v127, v125, v155
	v_fma_f32 v154, -v153, v127, v125
	v_exp_f32_e32 v116, v116
	v_exp_f32_e32 v117, v117
	v_fmac_f32_e32 v127, v154, v155
	v_fma_f32 v125, -v153, v127, v125
	v_div_fmas_f32 v125, v125, v155, v127
	v_div_fixup_f32 v125, v125, v126, v122
	v_pk_add_f32 v[126:127], v[116:117], 1.0 op_sel_hi:[1,0]
	v_cvt_pk_bf16_f32 v123, v125, v123
	v_div_scale_f32 v125, s[30:31], v127, v127, v113
	v_lshl_or_b32 v156, s72, 7, v149
	v_rcp_f32_e32 v153, v125
	v_ashrrev_i32_e32 v157, 31, v156
	v_lshl_add_u64 v[158:159], s[46:47], 0, v[158:159]
	v_cvt_pk_bf16_f32 v122, v120, v121
	v_lshlrev_b64 v[120:121], 1, v[156:157]
	v_lshl_add_u64 v[116:117], v[158:159], 0, v[120:121]
	global_store_dwordx2 v[116:117], v[122:123], off
	v_fma_f32 v122, -v125, v153, 1.0
	v_fmac_f32_e32 v153, v122, v153
	v_div_scale_f32 v122, vcc, v113, v127, v113
	v_mul_f32_e32 v123, v122, v153
	v_fma_f32 v154, -v125, v123, v122
	v_fmac_f32_e32 v123, v154, v153
	v_fma_f32 v122, -v125, v123, v122
	v_div_scale_f32 v125, s[30:31], v126, v126, v112
	v_rcp_f32_e32 v154, v125
	v_div_fmas_f32 v122, v122, v153, v123
	v_mul_f32_e32 v118, 0xbfb8aa3b, v118
	v_mul_f32_e32 v119, 0xbfb8aa3b, v119
	v_div_fixup_f32 v113, v122, v127, v113
	v_fma_f32 v122, -v125, v154, 1.0
	v_exp_f32_e32 v118, v118
	v_exp_f32_e32 v119, v119
	v_fmac_f32_e32 v154, v122, v154
	v_div_scale_f32 v122, vcc, v112, v126, v112
	v_mul_f32_e32 v123, v122, v154
	v_fma_f32 v127, -v125, v123, v122
	v_fmac_f32_e32 v123, v127, v154
	v_pk_add_f32 v[118:119], v[118:119], 1.0 op_sel_hi:[1,0]
	v_fma_f32 v122, -v125, v123, v122
	v_div_scale_f32 v125, s[30:31], v119, v119, v115
	v_rcp_f32_e32 v127, v125
	v_div_fmas_f32 v122, v122, v154, v123
	v_div_fixup_f32 v112, v122, v126, v112
	v_mul_f32_e32 v108, 0xbfb8aa3b, v108
	v_fma_f32 v122, -v125, v127, 1.0
	v_fmac_f32_e32 v127, v122, v127
	v_div_scale_f32 v122, vcc, v115, v119, v115
	v_mul_f32_e32 v123, v122, v127
	v_fma_f32 v126, -v125, v123, v122
	v_fmac_f32_e32 v123, v126, v127
	v_fma_f32 v122, -v125, v123, v122
	v_div_scale_f32 v125, s[30:31], v118, v118, v114
	v_rcp_f32_e32 v126, v125
	v_div_fmas_f32 v122, v122, v127, v123
	v_div_fixup_f32 v115, v122, v119, v115
	v_mul_f32_e32 v109, 0xbfb8aa3b, v109
	v_fma_f32 v119, -v125, v126, 1.0
	v_fmac_f32_e32 v126, v119, v126
	v_div_scale_f32 v119, vcc, v114, v118, v114
	v_mul_f32_e32 v122, v119, v126
	v_fma_f32 v123, -v125, v122, v119
	v_exp_f32_e32 v108, v108
	v_exp_f32_e32 v109, v109
	v_fmac_f32_e32 v122, v123, v126
	v_fma_f32 v119, -v125, v122, v119
	v_div_fmas_f32 v119, v119, v126, v122
	v_div_fixup_f32 v114, v119, v118, v114
	v_pk_add_f32 v[108:109], v[108:109], 1.0 op_sel_hi:[1,0]
	v_cvt_pk_bf16_f32 v112, v112, v113
	v_cvt_pk_bf16_f32 v113, v114, v115
	v_div_scale_f32 v114, s[30:31], v109, v109, v105
	v_rcp_f32_e32 v115, v114
	v_mul_f32_e32 v110, 0xbfb8aa3b, v110
	v_mul_f32_e32 v111, 0xbfb8aa3b, v111
	v_exp_f32_e32 v110, v110
	v_fma_f32 v118, -v114, v115, 1.0
	v_fmac_f32_e32 v115, v118, v115
	v_div_scale_f32 v118, vcc, v105, v109, v105
	v_mul_f32_e32 v119, v118, v115
	v_fma_f32 v122, -v114, v119, v118
	v_fmac_f32_e32 v119, v122, v115
	v_fma_f32 v114, -v114, v119, v118
	v_div_scale_f32 v118, s[30:31], v108, v108, v104
	v_rcp_f32_e32 v122, v118
	v_div_fmas_f32 v114, v114, v115, v119
	v_exp_f32_e32 v111, v111
	v_div_fixup_f32 v105, v114, v109, v105
	v_fma_f32 v109, -v118, v122, 1.0
	v_fmac_f32_e32 v122, v109, v122
	v_div_scale_f32 v109, vcc, v104, v108, v104
	v_mul_f32_e32 v114, v109, v122
	v_fma_f32 v115, -v118, v114, v109
	v_pk_add_f32 v[110:111], v[110:111], 1.0 op_sel_hi:[1,0]
	v_fmac_f32_e32 v114, v115, v122
	v_div_scale_f32 v115, s[30:31], v111, v111, v107
	v_fma_f32 v109, -v118, v114, v109
	v_rcp_f32_e32 v118, v115
	v_div_fmas_f32 v109, v109, v122, v114
	v_div_fixup_f32 v104, v109, v108, v104
	v_mul_f32_e32 v100, 0xbfb8aa3b, v100
	v_fma_f32 v108, -v115, v118, 1.0
	v_fmac_f32_e32 v118, v108, v118
	v_div_scale_f32 v108, vcc, v107, v111, v107
	v_mul_f32_e32 v109, v108, v118
	v_fma_f32 v114, -v115, v109, v108
	v_fmac_f32_e32 v109, v114, v118
	v_div_scale_f32 v114, s[30:31], v110, v110, v106
	v_fma_f32 v108, -v115, v109, v108
	v_rcp_f32_e32 v115, v114
	v_div_fmas_f32 v108, v108, v118, v109
	v_div_fixup_f32 v107, v108, v111, v107
	v_mul_f32_e32 v101, 0xbfb8aa3b, v101
	v_fma_f32 v108, -v114, v115, 1.0
	v_fmac_f32_e32 v115, v108, v115
	v_div_scale_f32 v108, vcc, v106, v110, v106
	v_mul_f32_e32 v109, v108, v115
	v_exp_f32_e32 v100, v100
	v_exp_f32_e32 v101, v101
	v_fma_f32 v111, -v114, v109, v108
	v_fmac_f32_e32 v109, v111, v115
	v_fma_f32 v108, -v114, v109, v108
	v_div_fmas_f32 v108, v108, v115, v109
	v_pk_add_f32 v[100:101], v[100:101], 1.0 op_sel_hi:[1,0]
	global_store_dwordx2 v[116:117], v[112:113], off offset:128
	v_or_b32_e32 v112, 16, v124
	v_div_fixup_f32 v106, v108, v110, v106
	v_div_scale_f32 v108, s[30:31], v101, v101, v97
	v_ashrrev_i32_e32 v113, 31, v112
	v_rcp_f32_e32 v109, v108
	v_lshlrev_b64 v[112:113], 11, v[112:113]
	v_lshl_add_u64 v[112:113], s[46:47], 0, v[112:113]
	v_cvt_pk_bf16_f32 v104, v104, v105
	v_cvt_pk_bf16_f32 v105, v106, v107
	v_lshl_add_u64 v[106:107], v[112:113], 0, v[120:121]
	global_store_dwordx2 v[106:107], v[104:105], off
	v_fma_f32 v104, -v108, v109, 1.0
	v_fmac_f32_e32 v109, v104, v109
	v_div_scale_f32 v104, vcc, v97, v101, v97
	v_mul_f32_e32 v105, v104, v109
	v_fma_f32 v110, -v108, v105, v104
	v_fmac_f32_e32 v105, v110, v109
	v_fma_f32 v104, -v108, v105, v104
	v_div_scale_f32 v108, s[30:31], v100, v100, v96
	v_rcp_f32_e32 v110, v108
	v_mul_f32_e32 v102, 0xbfb8aa3b, v102
	v_mul_f32_e32 v103, 0xbfb8aa3b, v103
	v_div_fmas_f32 v104, v104, v109, v105
	v_exp_f32_e32 v102, v102
	v_exp_f32_e32 v103, v103
	v_div_fixup_f32 v97, v104, v101, v97
	v_fma_f32 v101, -v108, v110, 1.0
	v_fmac_f32_e32 v110, v101, v110
	v_div_scale_f32 v101, vcc, v96, v100, v96
	v_mul_f32_e32 v104, v101, v110
	v_fma_f32 v105, -v108, v104, v101
	v_pk_add_f32 v[102:103], v[102:103], 1.0 op_sel_hi:[1,0]
	v_fmac_f32_e32 v104, v105, v110
	v_div_scale_f32 v105, s[30:31], v103, v103, v99
	v_fma_f32 v101, -v108, v104, v101
	v_rcp_f32_e32 v108, v105
	v_div_fmas_f32 v101, v101, v110, v104
	v_div_fixup_f32 v96, v101, v100, v96
	v_mul_f32_e32 v92, 0xbfb8aa3b, v92
	v_fma_f32 v100, -v105, v108, 1.0
	v_fmac_f32_e32 v108, v100, v108
	v_div_scale_f32 v100, vcc, v99, v103, v99
	v_mul_f32_e32 v101, v100, v108
	v_fma_f32 v104, -v105, v101, v100
	v_fmac_f32_e32 v101, v104, v108
	v_div_scale_f32 v104, s[30:31], v102, v102, v98
	v_fma_f32 v100, -v105, v101, v100
	v_rcp_f32_e32 v105, v104
	v_div_fmas_f32 v100, v100, v108, v101
	v_div_fixup_f32 v99, v100, v103, v99
	v_mul_f32_e32 v93, 0xbfb8aa3b, v93
	v_fma_f32 v100, -v104, v105, 1.0
	v_fmac_f32_e32 v105, v100, v105
	v_div_scale_f32 v100, vcc, v98, v102, v98
	v_mul_f32_e32 v101, v100, v105
	v_fma_f32 v103, -v104, v101, v100
	v_exp_f32_e32 v92, v92
	v_exp_f32_e32 v93, v93
	v_fmac_f32_e32 v101, v103, v105
	v_fma_f32 v100, -v104, v101, v100
	v_div_fmas_f32 v100, v100, v105, v101
	v_div_fixup_f32 v98, v100, v102, v98
	v_pk_add_f32 v[92:93], v[92:93], 1.0 op_sel_hi:[1,0]
	v_cvt_pk_bf16_f32 v96, v96, v97
	v_cvt_pk_bf16_f32 v97, v98, v99
	v_div_scale_f32 v98, s[30:31], v93, v93, v89
	v_rcp_f32_e32 v99, v98
	v_mul_f32_e32 v94, 0xbfb8aa3b, v94
	v_mul_f32_e32 v95, 0xbfb8aa3b, v95
	v_exp_f32_e32 v94, v94
	v_fma_f32 v100, -v98, v99, 1.0
	v_fmac_f32_e32 v99, v100, v99
	v_div_scale_f32 v100, vcc, v89, v93, v89
	v_mul_f32_e32 v101, v100, v99
	v_fma_f32 v102, -v98, v101, v100
	v_fmac_f32_e32 v101, v102, v99
	v_fma_f32 v98, -v98, v101, v100
	v_div_scale_f32 v100, s[30:31], v92, v92, v88
	v_rcp_f32_e32 v102, v100
	v_div_fmas_f32 v98, v98, v99, v101
	v_exp_f32_e32 v95, v95
	v_div_fixup_f32 v89, v98, v93, v89
	v_fma_f32 v93, -v100, v102, 1.0
	v_fmac_f32_e32 v102, v93, v102
	v_div_scale_f32 v93, vcc, v88, v92, v88
	v_mul_f32_e32 v98, v93, v102
	v_fma_f32 v99, -v100, v98, v93
	v_pk_add_f32 v[94:95], v[94:95], 1.0 op_sel_hi:[1,0]
	v_fmac_f32_e32 v98, v99, v102
	v_div_scale_f32 v99, s[30:31], v95, v95, v91
	v_fma_f32 v93, -v100, v98, v93
	v_rcp_f32_e32 v100, v99
	v_div_fmas_f32 v93, v93, v102, v98
	v_div_fixup_f32 v88, v93, v92, v88
	v_mul_f32_e32 v84, 0xbfb8aa3b, v84
	v_fma_f32 v92, -v99, v100, 1.0
	v_fmac_f32_e32 v100, v92, v100
	v_div_scale_f32 v92, vcc, v91, v95, v91
	v_mul_f32_e32 v93, v92, v100
	v_fma_f32 v98, -v99, v93, v92
	v_fmac_f32_e32 v93, v98, v100
	v_div_scale_f32 v98, s[30:31], v94, v94, v90
	v_fma_f32 v92, -v99, v93, v92
	v_rcp_f32_e32 v99, v98
	v_div_fmas_f32 v92, v92, v100, v93
	v_div_fixup_f32 v91, v92, v95, v91
	v_mul_f32_e32 v85, 0xbfb8aa3b, v85
	v_fma_f32 v92, -v98, v99, 1.0
	v_fmac_f32_e32 v99, v92, v99
	v_div_scale_f32 v92, vcc, v90, v94, v90
	v_mul_f32_e32 v93, v92, v99
	v_exp_f32_e32 v84, v84
	v_exp_f32_e32 v85, v85
	v_fma_f32 v95, -v98, v93, v92
	v_fmac_f32_e32 v93, v95, v99
	v_fma_f32 v92, -v98, v93, v92
	v_div_fmas_f32 v92, v92, v99, v93
	v_pk_add_f32 v[84:85], v[84:85], 1.0 op_sel_hi:[1,0]
	global_store_dwordx2 v[106:107], v[96:97], off offset:128
	v_or_b32_e32 v96, 32, v124
	v_div_fixup_f32 v90, v92, v94, v90
	v_div_scale_f32 v92, s[30:31], v85, v85, v81
	v_ashrrev_i32_e32 v97, 31, v96
	v_rcp_f32_e32 v93, v92
	v_lshlrev_b64 v[96:97], 11, v[96:97]
	v_lshl_add_u64 v[96:97], s[46:47], 0, v[96:97]
	v_cvt_pk_bf16_f32 v88, v88, v89
	v_cvt_pk_bf16_f32 v89, v90, v91
	v_lshl_add_u64 v[90:91], v[96:97], 0, v[120:121]
	global_store_dwordx2 v[90:91], v[88:89], off
	v_fma_f32 v88, -v92, v93, 1.0
	v_fmac_f32_e32 v93, v88, v93
	v_div_scale_f32 v88, vcc, v81, v85, v81
	v_mul_f32_e32 v89, v88, v93
	v_fma_f32 v94, -v92, v89, v88
	v_fmac_f32_e32 v89, v94, v93
	v_fma_f32 v88, -v92, v89, v88
	v_div_scale_f32 v92, s[30:31], v84, v84, v80
	v_rcp_f32_e32 v94, v92
	v_mul_f32_e32 v86, 0xbfb8aa3b, v86
	v_mul_f32_e32 v87, 0xbfb8aa3b, v87
	v_div_fmas_f32 v88, v88, v93, v89
	v_exp_f32_e32 v86, v86
	v_exp_f32_e32 v87, v87
	v_div_fixup_f32 v81, v88, v85, v81
	v_fma_f32 v85, -v92, v94, 1.0
	v_fmac_f32_e32 v94, v85, v94
	v_div_scale_f32 v85, vcc, v80, v84, v80
	v_mul_f32_e32 v88, v85, v94
	v_fma_f32 v89, -v92, v88, v85
	v_pk_add_f32 v[86:87], v[86:87], 1.0 op_sel_hi:[1,0]
	v_fmac_f32_e32 v88, v89, v94
	v_div_scale_f32 v89, s[30:31], v87, v87, v83
	v_fma_f32 v85, -v92, v88, v85
	v_rcp_f32_e32 v92, v89
	v_div_fmas_f32 v85, v85, v94, v88
	v_div_fixup_f32 v80, v85, v84, v80
	v_mul_f32_e32 v76, 0xbfb8aa3b, v76
	v_fma_f32 v84, -v89, v92, 1.0
	v_fmac_f32_e32 v92, v84, v92
	v_div_scale_f32 v84, vcc, v83, v87, v83
	v_mul_f32_e32 v85, v84, v92
	v_fma_f32 v88, -v89, v85, v84
	v_fmac_f32_e32 v85, v88, v92
	v_div_scale_f32 v88, s[30:31], v86, v86, v82
	v_fma_f32 v84, -v89, v85, v84
	v_rcp_f32_e32 v89, v88
	v_div_fmas_f32 v84, v84, v92, v85
	v_div_fixup_f32 v83, v84, v87, v83
	v_mul_f32_e32 v77, 0xbfb8aa3b, v77
	v_fma_f32 v84, -v88, v89, 1.0
	v_fmac_f32_e32 v89, v84, v89
	v_div_scale_f32 v84, vcc, v82, v86, v82
	v_mul_f32_e32 v85, v84, v89
	v_fma_f32 v87, -v88, v85, v84
	v_exp_f32_e32 v76, v76
	v_exp_f32_e32 v77, v77
	v_fmac_f32_e32 v85, v87, v89
	v_fma_f32 v84, -v88, v85, v84
	v_div_fmas_f32 v84, v84, v89, v85
	v_div_fixup_f32 v82, v84, v86, v82
	v_pk_add_f32 v[76:77], v[76:77], 1.0 op_sel_hi:[1,0]
	v_cvt_pk_bf16_f32 v80, v80, v81
	v_cvt_pk_bf16_f32 v81, v82, v83
	v_div_scale_f32 v82, s[30:31], v77, v77, v73
	v_rcp_f32_e32 v83, v82
	v_mul_f32_e32 v78, 0xbfb8aa3b, v78
	v_mul_f32_e32 v79, 0xbfb8aa3b, v79
	v_exp_f32_e32 v78, v78
	v_fma_f32 v84, -v82, v83, 1.0
	v_fmac_f32_e32 v83, v84, v83
	v_div_scale_f32 v84, vcc, v73, v77, v73
	v_mul_f32_e32 v85, v84, v83
	v_fma_f32 v86, -v82, v85, v84
	v_fmac_f32_e32 v85, v86, v83
	v_fma_f32 v82, -v82, v85, v84
	v_div_scale_f32 v84, s[30:31], v76, v76, v72
	v_rcp_f32_e32 v86, v84
	v_div_fmas_f32 v82, v82, v83, v85
	v_exp_f32_e32 v79, v79
	v_div_fixup_f32 v73, v82, v77, v73
	v_fma_f32 v77, -v84, v86, 1.0
	v_fmac_f32_e32 v86, v77, v86
	v_div_scale_f32 v77, vcc, v72, v76, v72
	v_mul_f32_e32 v82, v77, v86
	v_fma_f32 v83, -v84, v82, v77
	v_pk_add_f32 v[78:79], v[78:79], 1.0 op_sel_hi:[1,0]
	v_fmac_f32_e32 v82, v83, v86
	v_div_scale_f32 v83, s[30:31], v79, v79, v75
	v_fma_f32 v77, -v84, v82, v77
	v_rcp_f32_e32 v84, v83
	v_div_fmas_f32 v77, v77, v86, v82
	v_div_fixup_f32 v72, v77, v76, v72
	v_mul_f32_e32 v68, 0xbfb8aa3b, v68
	v_fma_f32 v76, -v83, v84, 1.0
	v_fmac_f32_e32 v84, v76, v84
	v_div_scale_f32 v76, vcc, v75, v79, v75
	v_mul_f32_e32 v77, v76, v84
	v_fma_f32 v82, -v83, v77, v76
	v_fmac_f32_e32 v77, v82, v84
	v_div_scale_f32 v82, s[30:31], v78, v78, v74
	v_fma_f32 v76, -v83, v77, v76
	v_rcp_f32_e32 v83, v82
	v_div_fmas_f32 v76, v76, v84, v77
	v_div_fixup_f32 v75, v76, v79, v75
	v_mul_f32_e32 v69, 0xbfb8aa3b, v69
	v_fma_f32 v76, -v82, v83, 1.0
	v_fmac_f32_e32 v83, v76, v83
	v_div_scale_f32 v76, vcc, v74, v78, v74
	v_mul_f32_e32 v77, v76, v83
	v_exp_f32_e32 v68, v68
	v_exp_f32_e32 v69, v69
	v_fma_f32 v79, -v82, v77, v76
	v_fmac_f32_e32 v77, v79, v83
	v_fma_f32 v76, -v82, v77, v76
	v_div_fmas_f32 v76, v76, v83, v77
	v_pk_add_f32 v[68:69], v[68:69], 1.0 op_sel_hi:[1,0]
	global_store_dwordx2 v[90:91], v[80:81], off offset:128
	v_or_b32_e32 v80, 48, v124
	v_div_fixup_f32 v74, v76, v78, v74
	v_div_scale_f32 v76, s[30:31], v69, v69, v65
	v_ashrrev_i32_e32 v81, 31, v80
	v_rcp_f32_e32 v77, v76
	v_lshlrev_b64 v[80:81], 11, v[80:81]
	v_lshl_add_u64 v[80:81], s[46:47], 0, v[80:81]
	v_cvt_pk_bf16_f32 v72, v72, v73
	v_cvt_pk_bf16_f32 v73, v74, v75
	v_lshl_add_u64 v[74:75], v[80:81], 0, v[120:121]
	global_store_dwordx2 v[74:75], v[72:73], off
	v_fma_f32 v72, -v76, v77, 1.0
	v_fmac_f32_e32 v77, v72, v77
	v_div_scale_f32 v72, vcc, v65, v69, v65
	v_mul_f32_e32 v73, v72, v77
	v_fma_f32 v78, -v76, v73, v72
	v_fmac_f32_e32 v73, v78, v77
	v_fma_f32 v72, -v76, v73, v72
	v_div_scale_f32 v76, s[30:31], v68, v68, v64
	v_rcp_f32_e32 v78, v76
	v_mul_f32_e32 v70, 0xbfb8aa3b, v70
	v_mul_f32_e32 v71, 0xbfb8aa3b, v71
	v_div_fmas_f32 v72, v72, v77, v73
	v_exp_f32_e32 v70, v70
	v_exp_f32_e32 v71, v71
	v_div_fixup_f32 v65, v72, v69, v65
	v_fma_f32 v69, -v76, v78, 1.0
	v_fmac_f32_e32 v78, v69, v78
	v_div_scale_f32 v69, vcc, v64, v68, v64
	v_mul_f32_e32 v72, v69, v78
	v_fma_f32 v73, -v76, v72, v69
	v_pk_add_f32 v[70:71], v[70:71], 1.0 op_sel_hi:[1,0]
	v_fmac_f32_e32 v72, v73, v78
	v_div_scale_f32 v73, s[30:31], v71, v71, v67
	v_fma_f32 v69, -v76, v72, v69
	v_rcp_f32_e32 v76, v73
	v_div_fmas_f32 v69, v69, v78, v72
	v_div_fixup_f32 v64, v69, v68, v64
	v_mul_f32_e32 v60, 0xbfb8aa3b, v60
	v_fma_f32 v68, -v73, v76, 1.0
	v_fmac_f32_e32 v76, v68, v76
	v_div_scale_f32 v68, vcc, v67, v71, v67
	v_mul_f32_e32 v69, v68, v76
	v_fma_f32 v72, -v73, v69, v68
	v_fmac_f32_e32 v69, v72, v76
	v_div_scale_f32 v72, s[30:31], v70, v70, v66
	v_fma_f32 v68, -v73, v69, v68
	v_rcp_f32_e32 v73, v72
	v_div_fmas_f32 v68, v68, v76, v69
	v_div_fixup_f32 v67, v68, v71, v67
	v_mul_f32_e32 v61, 0xbfb8aa3b, v61
	v_fma_f32 v68, -v72, v73, 1.0
	v_fmac_f32_e32 v73, v68, v73
	v_div_scale_f32 v68, vcc, v66, v70, v66
	v_mul_f32_e32 v69, v68, v73
	v_exp_f32_e32 v60, v60
	v_exp_f32_e32 v61, v61
	v_fma_f32 v71, -v72, v69, v68
	v_fmac_f32_e32 v69, v71, v73
	v_fma_f32 v68, -v72, v69, v68
	v_div_fmas_f32 v68, v68, v73, v69
	v_pk_add_f32 v[60:61], v[60:61], 1.0 op_sel_hi:[1,0]
	v_div_fixup_f32 v66, v68, v70, v66
	v_div_scale_f32 v68, s[30:31], v61, v61, v57
	v_rcp_f32_e32 v69, v68
	v_cvt_pk_bf16_f32 v64, v64, v65
	v_cvt_pk_bf16_f32 v65, v66, v67
	global_store_dwordx2 v[74:75], v[64:65], off offset:128
	v_fma_f32 v64, -v68, v69, 1.0
	v_fmac_f32_e32 v69, v64, v69
	v_div_scale_f32 v64, vcc, v57, v61, v57
	v_mul_f32_e32 v65, v64, v69
	v_fma_f32 v66, -v68, v65, v64
	v_fmac_f32_e32 v65, v66, v69
	v_div_scale_f32 v66, s[30:31], v60, v60, v56
	v_rcp_f32_e32 v67, v66
	v_fma_f32 v64, -v68, v65, v64
	v_mul_f32_e32 v62, 0xbfb8aa3b, v62
	v_mul_f32_e32 v63, 0xbfb8aa3b, v63
	v_div_fmas_f32 v64, v64, v69, v65
	v_exp_f32_e32 v62, v62
	v_exp_f32_e32 v63, v63
	v_div_fixup_f32 v57, v64, v61, v57
	v_fma_f32 v61, -v66, v67, 1.0
	v_fmac_f32_e32 v67, v61, v67
	v_div_scale_f32 v61, vcc, v56, v60, v56
	v_mul_f32_e32 v64, v61, v67
	v_fma_f32 v65, -v66, v64, v61
	v_pk_add_f32 v[62:63], v[62:63], 1.0 op_sel_hi:[1,0]
	v_fmac_f32_e32 v64, v65, v67
	v_div_scale_f32 v65, s[30:31], v63, v63, v59
	v_fma_f32 v61, -v66, v64, v61
	v_rcp_f32_e32 v66, v65
	v_div_fmas_f32 v61, v61, v67, v64
	v_div_fixup_f32 v56, v61, v60, v56
	v_mul_f32_e32 v52, 0xbfb8aa3b, v52
	v_fma_f32 v60, -v65, v66, 1.0
	v_fmac_f32_e32 v66, v60, v66
	v_div_scale_f32 v60, vcc, v59, v63, v59
	v_mul_f32_e32 v61, v60, v66
	v_fma_f32 v64, -v65, v61, v60
	v_fmac_f32_e32 v61, v64, v66
	v_div_scale_f32 v64, s[30:31], v62, v62, v58
	v_fma_f32 v60, -v65, v61, v60
	v_rcp_f32_e32 v65, v64
	v_div_fmas_f32 v60, v60, v66, v61
	v_div_fixup_f32 v59, v60, v63, v59
	v_mul_f32_e32 v53, 0xbfb8aa3b, v53
	v_fma_f32 v60, -v64, v65, 1.0
	v_fmac_f32_e32 v65, v60, v65
	v_div_scale_f32 v60, vcc, v58, v62, v58
	v_mul_f32_e32 v61, v60, v65
	v_exp_f32_e32 v52, v52
	v_exp_f32_e32 v53, v53
	v_fma_f32 v63, -v64, v61, v60
	v_fmac_f32_e32 v61, v63, v65
	v_fma_f32 v60, -v64, v61, v60
	v_div_fmas_f32 v60, v60, v65, v61
	v_pk_add_f32 v[52:53], v[52:53], 1.0 op_sel_hi:[1,0]
	v_div_fixup_f32 v58, v60, v62, v58
	v_div_scale_f32 v62, s[30:31], v53, v53, v49
	v_rcp_f32_e32 v63, v62
	v_add_co_u32_e32 v60, vcc, s62, v116
	v_cvt_pk_bf16_f32 v56, v56, v57
	v_cvt_pk_bf16_f32 v57, v58, v59
	v_addc_co_u32_e32 v61, vcc, 0, v117, vcc
	global_store_dwordx2 v[60:61], v[56:57], off
	v_fma_f32 v56, -v62, v63, 1.0
	v_fmac_f32_e32 v63, v56, v63
	v_div_scale_f32 v56, vcc, v49, v53, v49
	v_mul_f32_e32 v57, v56, v63
	v_fma_f32 v60, -v62, v57, v56
	v_fmac_f32_e32 v57, v60, v63
	v_div_scale_f32 v60, s[30:31], v52, v52, v48
	v_rcp_f32_e32 v61, v60
	v_fma_f32 v56, -v62, v57, v56
	v_mul_f32_e32 v54, 0xbfb8aa3b, v54
	v_mul_f32_e32 v55, 0xbfb8aa3b, v55
	v_div_fmas_f32 v56, v56, v63, v57
	v_exp_f32_e32 v54, v54
	v_exp_f32_e32 v55, v55
	v_div_fixup_f32 v49, v56, v53, v49
	v_fma_f32 v53, -v60, v61, 1.0
	v_fmac_f32_e32 v61, v53, v61
	v_div_scale_f32 v53, vcc, v48, v52, v48
	v_mul_f32_e32 v56, v53, v61
	v_fma_f32 v57, -v60, v56, v53
	v_pk_add_f32 v[54:55], v[54:55], 1.0 op_sel_hi:[1,0]
	v_fmac_f32_e32 v56, v57, v61
	v_div_scale_f32 v57, s[30:31], v55, v55, v51
	v_fma_f32 v53, -v60, v56, v53
	v_rcp_f32_e32 v60, v57
	v_div_fmas_f32 v53, v53, v61, v56
	v_div_fixup_f32 v48, v53, v52, v48
	v_mul_f32_e32 v44, 0xbfb8aa3b, v44
	v_fma_f32 v52, -v57, v60, 1.0
	v_fmac_f32_e32 v60, v52, v60
	v_div_scale_f32 v52, vcc, v51, v55, v51
	v_mul_f32_e32 v53, v52, v60
	v_fma_f32 v56, -v57, v53, v52
	v_fmac_f32_e32 v53, v56, v60
	v_div_scale_f32 v56, s[30:31], v54, v54, v50
	v_fma_f32 v52, -v57, v53, v52
	v_rcp_f32_e32 v57, v56
	v_div_fmas_f32 v52, v52, v60, v53
	v_div_fixup_f32 v51, v52, v55, v51
	v_mul_f32_e32 v45, 0xbfb8aa3b, v45
	v_fma_f32 v52, -v56, v57, 1.0
	v_fmac_f32_e32 v57, v52, v57
	v_div_scale_f32 v52, vcc, v50, v54, v50
	v_mul_f32_e32 v53, v52, v57
	v_exp_f32_e32 v44, v44
	v_exp_f32_e32 v45, v45
	v_fma_f32 v55, -v56, v53, v52
	v_fmac_f32_e32 v53, v55, v57
	v_fma_f32 v52, -v56, v53, v52
	v_div_fmas_f32 v52, v52, v57, v53
	v_pk_add_f32 v[44:45], v[44:45], 1.0 op_sel_hi:[1,0]
	v_div_fixup_f32 v50, v52, v54, v50
	v_div_scale_f32 v52, s[30:31], v45, v45, v41
	v_rcp_f32_e32 v53, v52
	v_lshl_add_u64 v[58:59], v[116:117], 0, s[6:7]
	v_cvt_pk_bf16_f32 v48, v48, v49
	v_cvt_pk_bf16_f32 v49, v50, v51
	global_store_dwordx2 v[58:59], v[48:49], off offset:128
	v_fma_f32 v48, -v52, v53, 1.0
	v_fmac_f32_e32 v53, v48, v53
	v_div_scale_f32 v48, vcc, v41, v45, v41
	v_mul_f32_e32 v49, v48, v53
	v_fma_f32 v50, -v52, v49, v48
	v_fmac_f32_e32 v49, v50, v53
	v_div_scale_f32 v50, s[30:31], v44, v44, v40
	v_rcp_f32_e32 v51, v50
	v_fma_f32 v48, -v52, v49, v48
	v_mul_f32_e32 v46, 0xbfb8aa3b, v46
	v_mul_f32_e32 v47, 0xbfb8aa3b, v47
	v_div_fmas_f32 v48, v48, v53, v49
	v_exp_f32_e32 v46, v46
	v_exp_f32_e32 v47, v47
	v_div_fixup_f32 v41, v48, v45, v41
	v_fma_f32 v45, -v50, v51, 1.0
	v_fmac_f32_e32 v51, v45, v51
	v_div_scale_f32 v45, vcc, v40, v44, v40
	v_mul_f32_e32 v48, v45, v51
	v_fma_f32 v49, -v50, v48, v45
	v_pk_add_f32 v[46:47], v[46:47], 1.0 op_sel_hi:[1,0]
	v_fmac_f32_e32 v48, v49, v51
	v_div_scale_f32 v49, s[30:31], v47, v47, v43
	v_fma_f32 v45, -v50, v48, v45
	v_rcp_f32_e32 v50, v49
	v_div_fmas_f32 v45, v45, v51, v48
	v_div_fixup_f32 v40, v45, v44, v40
	v_mul_f32_e32 v36, 0xbfb8aa3b, v36
	v_fma_f32 v44, -v49, v50, 1.0
	v_fmac_f32_e32 v50, v44, v50
	v_div_scale_f32 v44, vcc, v43, v47, v43
	v_mul_f32_e32 v45, v44, v50
	v_fma_f32 v48, -v49, v45, v44
	v_fmac_f32_e32 v45, v48, v50
	v_div_scale_f32 v48, s[30:31], v46, v46, v42
	v_fma_f32 v44, -v49, v45, v44
	v_rcp_f32_e32 v49, v48
	v_div_fmas_f32 v44, v44, v50, v45
	v_div_fixup_f32 v43, v44, v47, v43
	v_mul_f32_e32 v37, 0xbfb8aa3b, v37
	v_fma_f32 v44, -v48, v49, 1.0
	v_fmac_f32_e32 v49, v44, v49
	v_div_scale_f32 v44, vcc, v42, v46, v42
	v_mul_f32_e32 v45, v44, v49
	v_exp_f32_e32 v36, v36
	v_exp_f32_e32 v37, v37
	v_fma_f32 v47, -v48, v45, v44
	v_fmac_f32_e32 v45, v47, v49
	v_fma_f32 v44, -v48, v45, v44
	v_div_fmas_f32 v44, v44, v49, v45
	v_pk_add_f32 v[36:37], v[36:37], 1.0 op_sel_hi:[1,0]
	v_div_fixup_f32 v42, v44, v46, v42
	v_div_scale_f32 v46, s[30:31], v37, v37, v33
	v_rcp_f32_e32 v47, v46
	v_add_co_u32_e32 v44, vcc, s63, v116
	v_cvt_pk_bf16_f32 v40, v40, v41
	v_cvt_pk_bf16_f32 v41, v42, v43
	v_addc_co_u32_e32 v45, vcc, 0, v117, vcc
	global_store_dwordx2 v[44:45], v[40:41], off
	v_fma_f32 v40, -v46, v47, 1.0
	v_fmac_f32_e32 v47, v40, v47
	v_div_scale_f32 v40, vcc, v33, v37, v33
	v_mul_f32_e32 v41, v40, v47
	v_fma_f32 v44, -v46, v41, v40
	v_fmac_f32_e32 v41, v44, v47
	v_div_scale_f32 v44, s[30:31], v36, v36, v32
	v_rcp_f32_e32 v45, v44
	v_fma_f32 v40, -v46, v41, v40
	v_mul_f32_e32 v38, 0xbfb8aa3b, v38
	v_mul_f32_e32 v39, 0xbfb8aa3b, v39
	v_div_fmas_f32 v40, v40, v47, v41
	v_exp_f32_e32 v38, v38
	v_exp_f32_e32 v39, v39
	v_div_fixup_f32 v33, v40, v37, v33
	v_fma_f32 v37, -v44, v45, 1.0
	v_fmac_f32_e32 v45, v37, v45
	v_div_scale_f32 v37, vcc, v32, v36, v32
	v_mul_f32_e32 v40, v37, v45
	v_fma_f32 v41, -v44, v40, v37
	v_pk_add_f32 v[38:39], v[38:39], 1.0 op_sel_hi:[1,0]
	v_fmac_f32_e32 v40, v41, v45
	v_div_scale_f32 v41, s[30:31], v39, v39, v35
	v_fma_f32 v37, -v44, v40, v37
	v_rcp_f32_e32 v44, v41
	v_div_fmas_f32 v37, v37, v45, v40
	v_div_fixup_f32 v32, v37, v36, v32
	v_mul_f32_e32 v28, 0xbfb8aa3b, v28
	v_fma_f32 v36, -v41, v44, 1.0
	v_fmac_f32_e32 v44, v36, v44
	v_div_scale_f32 v36, vcc, v35, v39, v35
	v_mul_f32_e32 v37, v36, v44
	v_fma_f32 v40, -v41, v37, v36
	v_fmac_f32_e32 v37, v40, v44
	v_div_scale_f32 v40, s[30:31], v38, v38, v34
	v_fma_f32 v36, -v41, v37, v36
	v_rcp_f32_e32 v41, v40
	v_div_fmas_f32 v36, v36, v44, v37
	v_div_fixup_f32 v35, v36, v39, v35
	v_mul_f32_e32 v29, 0xbfb8aa3b, v29
	v_fma_f32 v36, -v40, v41, 1.0
	v_fmac_f32_e32 v41, v36, v41
	v_div_scale_f32 v36, vcc, v34, v38, v34
	v_mul_f32_e32 v37, v36, v41
	v_exp_f32_e32 v28, v28
	v_exp_f32_e32 v29, v29
	v_fma_f32 v39, -v40, v37, v36
	v_fmac_f32_e32 v37, v39, v41
	v_fma_f32 v36, -v40, v37, v36
	v_div_fmas_f32 v36, v36, v41, v37
	v_pk_add_f32 v[28:29], v[28:29], 1.0 op_sel_hi:[1,0]
	v_div_fixup_f32 v34, v36, v38, v34
	v_div_scale_f32 v36, s[30:31], v29, v29, v25
	v_rcp_f32_e32 v37, v36
	v_lshl_add_u64 v[42:43], v[116:117], 0, s[10:11]
	v_cvt_pk_bf16_f32 v32, v32, v33
	v_cvt_pk_bf16_f32 v33, v34, v35
	global_store_dwordx2 v[42:43], v[32:33], off offset:128
	v_fma_f32 v32, -v36, v37, 1.0
	v_fmac_f32_e32 v37, v32, v37
	v_div_scale_f32 v32, vcc, v25, v29, v25
	v_mul_f32_e32 v33, v32, v37
	v_fma_f32 v34, -v36, v33, v32
	v_fmac_f32_e32 v33, v34, v37
	v_div_scale_f32 v34, s[30:31], v28, v28, v24
	v_rcp_f32_e32 v35, v34
	v_fma_f32 v32, -v36, v33, v32
	v_mul_f32_e32 v30, 0xbfb8aa3b, v30
	v_mul_f32_e32 v31, 0xbfb8aa3b, v31
	v_div_fmas_f32 v32, v32, v37, v33
	v_exp_f32_e32 v30, v30
	v_exp_f32_e32 v31, v31
	v_div_fixup_f32 v25, v32, v29, v25
	v_fma_f32 v29, -v34, v35, 1.0
	v_fmac_f32_e32 v35, v29, v35
	v_div_scale_f32 v29, vcc, v24, v28, v24
	v_mul_f32_e32 v32, v29, v35
	v_fma_f32 v33, -v34, v32, v29
	v_pk_add_f32 v[30:31], v[30:31], 1.0 op_sel_hi:[1,0]
	v_fmac_f32_e32 v32, v33, v35
	v_div_scale_f32 v33, s[30:31], v31, v31, v27
	v_fma_f32 v29, -v34, v32, v29
	v_rcp_f32_e32 v34, v33
	v_div_fmas_f32 v29, v29, v35, v32
	v_div_fixup_f32 v24, v29, v28, v24
	v_mul_f32_e32 v20, 0xbfb8aa3b, v20
	v_fma_f32 v28, -v33, v34, 1.0
	v_fmac_f32_e32 v34, v28, v34
	v_div_scale_f32 v28, vcc, v27, v31, v27
	v_mul_f32_e32 v29, v28, v34
	v_fma_f32 v32, -v33, v29, v28
	v_fmac_f32_e32 v29, v32, v34
	v_div_scale_f32 v32, s[30:31], v30, v30, v26
	v_fma_f32 v28, -v33, v29, v28
	v_rcp_f32_e32 v33, v32
	v_div_fmas_f32 v28, v28, v34, v29
	v_div_fixup_f32 v27, v28, v31, v27
	v_mul_f32_e32 v21, 0xbfb8aa3b, v21
	v_fma_f32 v28, -v32, v33, 1.0
	v_fmac_f32_e32 v33, v28, v33
	v_div_scale_f32 v28, vcc, v26, v30, v26
	v_mul_f32_e32 v29, v28, v33
	v_exp_f32_e32 v20, v20
	v_exp_f32_e32 v21, v21
	v_fma_f32 v31, -v32, v29, v28
	v_fmac_f32_e32 v29, v31, v33
	v_fma_f32 v28, -v32, v29, v28
	v_div_fmas_f32 v28, v28, v33, v29
	v_pk_add_f32 v[20:21], v[20:21], 1.0 op_sel_hi:[1,0]
	v_div_fixup_f32 v26, v28, v30, v26
	v_div_scale_f32 v30, s[30:31], v21, v21, v17
	v_rcp_f32_e32 v31, v30
	v_add_co_u32_e32 v28, vcc, s70, v116
	v_cvt_pk_bf16_f32 v24, v24, v25
	v_cvt_pk_bf16_f32 v25, v26, v27
	v_addc_co_u32_e32 v29, vcc, 0, v117, vcc
	global_store_dwordx2 v[28:29], v[24:25], off
	v_fma_f32 v24, -v30, v31, 1.0
	v_fmac_f32_e32 v31, v24, v31
	v_div_scale_f32 v24, vcc, v17, v21, v17
	v_mul_f32_e32 v25, v24, v31
	v_fma_f32 v28, -v30, v25, v24
	v_fmac_f32_e32 v25, v28, v31
	v_div_scale_f32 v28, s[30:31], v20, v20, v16
	v_rcp_f32_e32 v29, v28
	v_fma_f32 v24, -v30, v25, v24
	v_mul_f32_e32 v22, 0xbfb8aa3b, v22
	v_mul_f32_e32 v23, 0xbfb8aa3b, v23
	v_div_fmas_f32 v24, v24, v31, v25
	v_exp_f32_e32 v22, v22
	v_exp_f32_e32 v23, v23
	v_div_fixup_f32 v17, v24, v21, v17
	v_fma_f32 v21, -v28, v29, 1.0
	v_fmac_f32_e32 v29, v21, v29
	v_div_scale_f32 v21, vcc, v16, v20, v16
	v_mul_f32_e32 v24, v21, v29
	v_fma_f32 v25, -v28, v24, v21
	v_pk_add_f32 v[22:23], v[22:23], 1.0 op_sel_hi:[1,0]
	v_fmac_f32_e32 v24, v25, v29
	v_div_scale_f32 v25, s[30:31], v23, v23, v19
	v_fma_f32 v21, -v28, v24, v21
	v_rcp_f32_e32 v28, v25
	v_div_fmas_f32 v21, v21, v29, v24
	v_div_fixup_f32 v16, v21, v20, v16
	v_mul_f32_e32 v12, 0xbfb8aa3b, v12
	v_fma_f32 v20, -v25, v28, 1.0
	v_fmac_f32_e32 v28, v20, v28
	v_div_scale_f32 v20, vcc, v19, v23, v19
	v_mul_f32_e32 v21, v20, v28
	v_fma_f32 v24, -v25, v21, v20
	v_fmac_f32_e32 v21, v24, v28
	v_div_scale_f32 v24, s[30:31], v22, v22, v18
	v_fma_f32 v20, -v25, v21, v20
	v_rcp_f32_e32 v25, v24
	v_div_fmas_f32 v20, v20, v28, v21
	v_div_fixup_f32 v19, v20, v23, v19
	v_mul_f32_e32 v13, 0xbfb8aa3b, v13
	v_fma_f32 v20, -v24, v25, 1.0
	v_fmac_f32_e32 v25, v20, v25
	v_div_scale_f32 v20, vcc, v18, v22, v18
	v_mul_f32_e32 v21, v20, v25
	v_exp_f32_e32 v12, v12
	v_exp_f32_e32 v13, v13
	v_fma_f32 v23, -v24, v21, v20
	v_fmac_f32_e32 v21, v23, v25
	v_fma_f32 v20, -v24, v21, v20
	v_div_fmas_f32 v20, v20, v25, v21
	v_pk_add_f32 v[12:13], v[12:13], 1.0 op_sel_hi:[1,0]
	v_div_fixup_f32 v18, v20, v22, v18
	v_div_scale_f32 v20, s[30:31], v13, v13, v9
	v_rcp_f32_e32 v21, v20
	v_lshl_add_u64 v[26:27], v[116:117], 0, s[12:13]
	v_cvt_pk_bf16_f32 v16, v16, v17
	v_cvt_pk_bf16_f32 v17, v18, v19
	global_store_dwordx2 v[26:27], v[16:17], off offset:128
	v_fma_f32 v16, -v20, v21, 1.0
	v_fmac_f32_e32 v21, v16, v21
	v_div_scale_f32 v16, vcc, v9, v13, v9
	v_mul_f32_e32 v17, v16, v21
	v_fma_f32 v18, -v20, v17, v16
	v_fmac_f32_e32 v17, v18, v21
	v_div_scale_f32 v18, s[30:31], v12, v12, v8
	v_rcp_f32_e32 v19, v18
	v_fma_f32 v16, -v20, v17, v16
	v_mul_f32_e32 v14, 0xbfb8aa3b, v14
	v_mul_f32_e32 v15, 0xbfb8aa3b, v15
	v_div_fmas_f32 v16, v16, v21, v17
	v_exp_f32_e32 v14, v14
	v_exp_f32_e32 v15, v15
	v_div_fixup_f32 v9, v16, v13, v9
	v_fma_f32 v13, -v18, v19, 1.0
	v_fmac_f32_e32 v19, v13, v19
	v_div_scale_f32 v13, vcc, v8, v12, v8
	v_mul_f32_e32 v16, v13, v19
	v_fma_f32 v17, -v18, v16, v13
	v_pk_add_f32 v[14:15], v[14:15], 1.0 op_sel_hi:[1,0]
	v_fmac_f32_e32 v16, v17, v19
	v_div_scale_f32 v17, s[30:31], v15, v15, v11
	v_fma_f32 v13, -v18, v16, v13
	v_rcp_f32_e32 v18, v17
	v_div_fmas_f32 v13, v13, v19, v16
	v_div_fixup_f32 v8, v13, v12, v8
	v_mul_f32_e32 v4, 0xbfb8aa3b, v4
	v_fma_f32 v12, -v17, v18, 1.0
	v_fmac_f32_e32 v18, v12, v18
	v_div_scale_f32 v12, vcc, v11, v15, v11
	v_mul_f32_e32 v13, v12, v18
	v_fma_f32 v16, -v17, v13, v12
	v_fmac_f32_e32 v13, v16, v18
	v_div_scale_f32 v16, s[30:31], v14, v14, v10
	v_fma_f32 v12, -v17, v13, v12
	v_rcp_f32_e32 v17, v16
	v_div_fmas_f32 v12, v12, v18, v13
	v_div_fixup_f32 v11, v12, v15, v11
	v_mul_f32_e32 v5, 0xbfb8aa3b, v5
	v_fma_f32 v12, -v16, v17, 1.0
	v_fmac_f32_e32 v17, v12, v17
	v_div_scale_f32 v12, vcc, v10, v14, v10
	v_mul_f32_e32 v13, v12, v17
	v_exp_f32_e32 v4, v4
	v_exp_f32_e32 v5, v5
	v_fma_f32 v15, -v16, v13, v12
	v_fmac_f32_e32 v13, v15, v17
	v_fma_f32 v12, -v16, v13, v12
	v_div_fmas_f32 v12, v12, v17, v13
	v_pk_add_f32 v[4:5], v[4:5], 1.0 op_sel_hi:[1,0]
	v_div_fixup_f32 v10, v12, v14, v10
	v_div_scale_f32 v14, s[30:31], v5, v5, v1
	v_rcp_f32_e32 v15, v14
	v_add_co_u32_e32 v12, vcc, s71, v116
	v_cvt_pk_bf16_f32 v8, v8, v9
	v_cvt_pk_bf16_f32 v9, v10, v11
	v_addc_co_u32_e32 v13, vcc, 0, v117, vcc
	global_store_dwordx2 v[12:13], v[8:9], off
	v_fma_f32 v8, -v14, v15, 1.0
	v_fmac_f32_e32 v15, v8, v15
	v_div_scale_f32 v8, vcc, v1, v5, v1
	v_mul_f32_e32 v9, v8, v15
	v_fma_f32 v12, -v14, v9, v8
	v_fmac_f32_e32 v9, v12, v15
	v_div_scale_f32 v12, s[30:31], v4, v4, v0
	v_rcp_f32_e32 v13, v12
	v_fma_f32 v8, -v14, v9, v8
	v_mul_f32_e32 v6, 0xbfb8aa3b, v6
	v_mul_f32_e32 v7, 0xbfb8aa3b, v7
	v_div_fmas_f32 v8, v8, v15, v9
	v_exp_f32_e32 v6, v6
	v_exp_f32_e32 v7, v7
	v_div_fixup_f32 v1, v8, v5, v1
	v_fma_f32 v5, -v12, v13, 1.0
	v_fmac_f32_e32 v13, v5, v13
	v_div_scale_f32 v5, vcc, v0, v4, v0
	v_mul_f32_e32 v8, v5, v13
	v_fma_f32 v9, -v12, v8, v5
	v_pk_add_f32 v[6:7], v[6:7], 1.0 op_sel_hi:[1,0]
	v_fmac_f32_e32 v8, v9, v13
	v_div_scale_f32 v9, s[30:31], v7, v7, v3
	v_fma_f32 v5, -v12, v8, v5
	v_rcp_f32_e32 v12, v9
	v_div_fmas_f32 v5, v5, v13, v8
	v_div_fixup_f32 v0, v5, v4, v0
	v_lshl_add_u64 v[10:11], v[116:117], 0, s[14:15]
	v_fma_f32 v4, -v9, v12, 1.0
	v_fmac_f32_e32 v12, v4, v12
	v_div_scale_f32 v4, vcc, v3, v7, v3
	v_mul_f32_e32 v5, v4, v12
	v_fma_f32 v8, -v9, v5, v4
	v_fmac_f32_e32 v5, v8, v12
	v_div_scale_f32 v8, s[30:31], v6, v6, v2
	v_fma_f32 v4, -v9, v5, v4
	v_rcp_f32_e32 v9, v8
	v_div_fmas_f32 v4, v4, v12, v5
	v_div_fixup_f32 v3, v4, v7, v3
	v_cvt_pk_bf16_f32 v0, v0, v1
	v_fma_f32 v4, -v8, v9, 1.0
	v_fmac_f32_e32 v9, v4, v9
	v_div_scale_f32 v4, vcc, v2, v6, v2
	v_mul_f32_e32 v5, v4, v9
	v_fma_f32 v7, -v8, v5, v4
	v_fmac_f32_e32 v5, v7, v9
	v_fma_f32 v4, -v8, v5, v4
	v_div_fmas_f32 v4, v4, v9, v5
	v_div_fixup_f32 v2, v4, v6, v2
	v_cvt_pk_bf16_f32 v1, v2, v3
	s_and_b64 vcc, exec, s[4:5]
	s_mov_b32 s72, s16
	s_mov_b32 s28, s18
	s_mov_b64 s[34:35], s[26:27]
	s_mov_b64 s[30:31], s[20:21]
	global_store_dwordx2 v[10:11], v[0:1], off offset:128
	s_cbranch_vccz .LBB0_1109
	s_waitcnt vmcnt(0)
	s_cmpk_gt_u32 s40, 0xff
	s_cbranch_scc1 .LBB0_1120
	s_barrier

.LBB0_1141:
	ds_read_b128 v[150:153], v145
	ds_read_b128 v[154:157], v145 offset:1024
	ds_read_b128 v[158:161], v145 offset:2048
	ds_read_b128 v[162:165], v145 offset:3072
	s_add_u32 s34, s30, 0xfffc0080
	s_addc_u32 s35, s31, -1
	s_cmp_eq_u32 s77, 12
	s_cselect_b32 s37, s19, s35
	s_cselect_b32 s36, s73, s34
	s_cselect_b32 s35, s17, s76
	s_cselect_b32 s34, s74, s75
	v_lshl_add_u64 v[198:199], s[30:31], 0, v[134:135]
	s_add_i32 m0, s29, 0xc000
	ds_read_b128 v[166:169], v148
	ds_read_b128 v[170:173], v148 offset:1024
	ds_read_b128 v[174:177], v148 offset:2048
	ds_read_b128 v[178:181], v148 offset:3072
	ds_read_b128 v[182:185], v148 offset:4096
	ds_read_b128 v[186:189], v148 offset:5120
	ds_read_b128 v[190:193], v148 offset:6144
	ds_read_b128 v[194:197], v148 offset:7168
	global_load_lds_dwordx4 v[198:199], off
	v_lshl_add_u64 v[198:199], s[30:31], 0, v[136:137]
	s_add_i32 m0, s29, 0xe000
	s_nop 0
	global_load_lds_dwordx4 v[198:199], off
	s_barrier
	s_waitcnt lgkmcnt(0)
	s_waitcnt lgkmcnt(0)
	v_mfma_f32_16x16x32_bf16 v[120:123], v[150:153], v[166:169], v[120:123]
	v_mfma_f32_16x16x32_bf16 v[124:127], v[158:161], v[166:169], v[124:127]
	v_mfma_f32_16x16x32_bf16 v[104:107], v[150:153], v[174:177], v[104:107]
	v_mfma_f32_16x16x32_bf16 v[108:111], v[158:161], v[174:177], v[108:111]
	v_mfma_f32_16x16x32_bf16 v[88:91], v[150:153], v[182:185], v[88:91]
	v_mfma_f32_16x16x32_bf16 v[92:95], v[158:161], v[182:185], v[92:95]
	v_mfma_f32_16x16x32_bf16 v[72:75], v[150:153], v[190:193], v[72:75]
	v_mfma_f32_16x16x32_bf16 v[76:79], v[158:161], v[190:193], v[76:79]
	v_mfma_f32_16x16x32_bf16 v[120:123], v[154:157], v[170:173], v[120:123]
	v_mfma_f32_16x16x32_bf16 v[124:127], v[162:165], v[170:173], v[124:127]
	v_mfma_f32_16x16x32_bf16 v[104:107], v[154:157], v[178:181], v[104:107]
	v_mfma_f32_16x16x32_bf16 v[108:111], v[162:165], v[178:181], v[108:111]
	v_mfma_f32_16x16x32_bf16 v[88:91], v[154:157], v[186:189], v[88:91]
	v_mfma_f32_16x16x32_bf16 v[92:95], v[162:165], v[186:189], v[92:95]
	v_mfma_f32_16x16x32_bf16 v[72:75], v[154:157], v[194:197], v[72:75]
	v_mfma_f32_16x16x32_bf16 v[76:79], v[162:165], v[194:197], v[76:79]
	s_barrier
	s_add_i32 s78, s60, s42
	v_lshl_add_u64 v[214:215], s[34:35], 0, v[130:131]
	s_mov_b32 m0, s78
	ds_read_b128 v[198:201], v149
	ds_read_b128 v[202:205], v149 offset:1024
	ds_read_b128 v[206:209], v149 offset:2048
	ds_read_b128 v[210:213], v149 offset:3072
	global_load_lds_dwordx4 v[214:215], off
	v_lshl_add_u64 v[216:217], s[34:35], 0, v[132:133]
	s_add_i32 m0, s78, 0x2000
	s_nop 0
	global_load_lds_dwordx4 v[216:217], off
	s_barrier
	s_waitcnt lgkmcnt(0)
	s_waitcnt lgkmcnt(0)
	v_mfma_f32_16x16x32_bf16 v[112:115], v[198:201], v[166:169], v[112:115]
	v_mfma_f32_16x16x32_bf16 v[116:119], v[206:209], v[166:169], v[116:119]
	v_mfma_f32_16x16x32_bf16 v[96:99], v[198:201], v[174:177], v[96:99]
	v_mfma_f32_16x16x32_bf16 v[100:103], v[206:209], v[174:177], v[100:103]
	v_mfma_f32_16x16x32_bf16 v[80:83], v[198:201], v[182:185], v[80:83]
	v_mfma_f32_16x16x32_bf16 v[84:87], v[206:209], v[182:185], v[84:87]
	v_mfma_f32_16x16x32_bf16 v[64:67], v[198:201], v[190:193], v[64:67]
	v_mfma_f32_16x16x32_bf16 v[68:71], v[206:209], v[190:193], v[68:71]
	v_mfma_f32_16x16x32_bf16 v[112:115], v[202:205], v[170:173], v[112:115]
	v_mfma_f32_16x16x32_bf16 v[116:119], v[210:213], v[170:173], v[116:119]
	v_mfma_f32_16x16x32_bf16 v[96:99], v[202:205], v[178:181], v[96:99]
	v_mfma_f32_16x16x32_bf16 v[100:103], v[210:213], v[178:181], v[100:103]
	v_mfma_f32_16x16x32_bf16 v[80:83], v[202:205], v[186:189], v[80:83]
	v_mfma_f32_16x16x32_bf16 v[84:87], v[210:213], v[186:189], v[84:87]
	v_mfma_f32_16x16x32_bf16 v[64:67], v[202:205], v[194:197], v[64:67]
	v_mfma_f32_16x16x32_bf16 v[68:71], v[210:213], v[194:197], v[68:71]
	s_mov_b32 m0, s29
	v_lshl_add_u64 v[218:219], s[36:37], 0, v[130:131]
	s_barrier
	ds_read_b128 v[166:169], v148 offset:16384
	ds_read_b128 v[170:173], v148 offset:17408
	ds_read_b128 v[174:177], v148 offset:18432
	ds_read_b128 v[178:181], v148 offset:19456
	ds_read_b128 v[182:185], v148 offset:20480
	ds_read_b128 v[186:189], v148 offset:21504
	ds_read_b128 v[190:193], v148 offset:22528
	ds_read_b128 v[194:197], v148 offset:23552
	global_load_lds_dwordx4 v[218:219], off
	v_lshl_add_u64 v[220:221], s[36:37], 0, v[132:133]
	s_mov_b32 m0, s43
	s_nop 0
	global_load_lds_dwordx4 v[220:221], off
	s_barrier
	s_waitcnt lgkmcnt(0)
	s_waitcnt lgkmcnt(0)
	v_mfma_f32_16x16x32_bf16 v[56:59], v[150:153], v[166:169], v[56:59]
	v_mfma_f32_16x16x32_bf16 v[60:63], v[158:161], v[166:169], v[60:63]
	v_mfma_f32_16x16x32_bf16 v[40:43], v[150:153], v[174:177], v[40:43]
	v_mfma_f32_16x16x32_bf16 v[44:47], v[158:161], v[174:177], v[44:47]
	v_mfma_f32_16x16x32_bf16 v[24:27], v[150:153], v[182:185], v[24:27]
	v_mfma_f32_16x16x32_bf16 v[28:31], v[158:161], v[182:185], v[28:31]
	v_mfma_f32_16x16x32_bf16 v[8:11], v[150:153], v[190:193], v[8:11]
	v_mfma_f32_16x16x32_bf16 v[12:15], v[158:161], v[190:193], v[12:15]
	v_mfma_f32_16x16x32_bf16 v[56:59], v[154:157], v[170:173], v[56:59]
	v_mfma_f32_16x16x32_bf16 v[60:63], v[162:165], v[170:173], v[60:63]
	v_mfma_f32_16x16x32_bf16 v[40:43], v[154:157], v[178:181], v[40:43]
	v_mfma_f32_16x16x32_bf16 v[44:47], v[162:165], v[178:181], v[44:47]
	v_mfma_f32_16x16x32_bf16 v[24:27], v[154:157], v[186:189], v[24:27]
	v_mfma_f32_16x16x32_bf16 v[28:31], v[162:165], v[186:189], v[28:31]
	v_mfma_f32_16x16x32_bf16 v[8:11], v[154:157], v[194:197], v[8:11]
	v_mfma_f32_16x16x32_bf16 v[12:15], v[162:165], v[194:197], v[12:15]
	s_barrier
	s_add_u32 s78, s34, 0x40000
	s_addc_u32 s79, s35, 0
	s_add_i32 s80, s61, s42
	v_lshl_add_u64 v[150:151], s[78:79], 0, v[130:131]
	s_mov_b32 m0, s80
	s_nop 0
	global_load_lds_dwordx4 v[150:151], off
	v_lshl_add_u64 v[150:151], s[78:79], 0, v[132:133]
	s_add_i32 m0, s80, 0x2000
	s_nop 0
	global_load_lds_dwordx4 v[150:151], off
	s_waitcnt vmcnt(6)
	s_barrier
	v_mfma_f32_16x16x32_bf16 v[48:51], v[198:201], v[166:169], v[48:51]
	v_mfma_f32_16x16x32_bf16 v[52:55], v[206:209], v[166:169], v[52:55]
	v_mfma_f32_16x16x32_bf16 v[32:35], v[198:201], v[174:177], v[32:35]
	v_mfma_f32_16x16x32_bf16 v[36:39], v[206:209], v[174:177], v[36:39]
	v_mfma_f32_16x16x32_bf16 v[16:19], v[198:201], v[182:185], v[16:19]
	v_mfma_f32_16x16x32_bf16 v[20:23], v[206:209], v[182:185], v[20:23]
	v_mfma_f32_16x16x32_bf16 v[0:3], v[198:201], v[190:193], v[0:3]
	v_mfma_f32_16x16x32_bf16 v[4:7], v[206:209], v[190:193], v[4:7]
	v_mfma_f32_16x16x32_bf16 v[48:51], v[202:205], v[170:173], v[48:51]
	v_mfma_f32_16x16x32_bf16 v[52:55], v[210:213], v[170:173], v[52:55]
	v_mfma_f32_16x16x32_bf16 v[32:35], v[202:205], v[178:181], v[32:35]
	v_mfma_f32_16x16x32_bf16 v[36:39], v[210:213], v[178:181], v[36:39]
	v_mfma_f32_16x16x32_bf16 v[16:19], v[202:205], v[186:189], v[16:19]
	v_mfma_f32_16x16x32_bf16 v[20:23], v[210:213], v[186:189], v[20:23]
	v_mfma_f32_16x16x32_bf16 v[0:3], v[202:205], v[194:197], v[0:3]
	v_mfma_f32_16x16x32_bf16 v[4:7], v[210:213], v[194:197], v[4:7]
	s_add_i32 s78, 0, 0x18000
	v_add_u32_e32 v162, s78, v143
	s_barrier
	ds_read_b128 v[150:153], v162
	ds_read_b128 v[154:157], v162 offset:1024
	ds_read_b128 v[158:161], v162 offset:2048
	ds_read_b128 v[162:165], v162 offset:3072
	s_add_u32 s36, s36, 0x40000
	s_addc_u32 s37, s37, 0
	s_mov_b32 m0, s52
	v_lshl_add_u64 v[198:199], s[36:37], 0, v[130:131]
	ds_read_b128 v[166:169], v148 offset:32768
	ds_read_b128 v[170:173], v148 offset:33792
	ds_read_b128 v[174:177], v148 offset:34816
	ds_read_b128 v[178:181], v148 offset:35840
	ds_read_b128 v[182:185], v148 offset:36864
	ds_read_b128 v[186:189], v148 offset:37888
	ds_read_b128 v[190:193], v148 offset:38912
	ds_read_b128 v[194:197], v148 offset:39936
	global_load_lds_dwordx4 v[198:199], off
	v_lshl_add_u64 v[198:199], s[36:37], 0, v[132:133]
	s_mov_b32 m0, s53
	s_nop 0
	global_load_lds_dwordx4 v[198:199], off
	s_barrier
	s_waitcnt lgkmcnt(0)
	s_waitcnt lgkmcnt(0)
	v_mfma_f32_16x16x32_bf16 v[120:123], v[150:153], v[166:169], v[120:123]
	v_mfma_f32_16x16x32_bf16 v[124:127], v[158:161], v[166:169], v[124:127]
	v_mfma_f32_16x16x32_bf16 v[104:107], v[150:153], v[174:177], v[104:107]
	v_mfma_f32_16x16x32_bf16 v[108:111], v[158:161], v[174:177], v[108:111]
	v_mfma_f32_16x16x32_bf16 v[88:91], v[150:153], v[182:185], v[88:91]
	v_mfma_f32_16x16x32_bf16 v[92:95], v[158:161], v[182:185], v[92:95]
	v_mfma_f32_16x16x32_bf16 v[72:75], v[150:153], v[190:193], v[72:75]
	v_mfma_f32_16x16x32_bf16 v[76:79], v[158:161], v[190:193], v[76:79]
	v_mfma_f32_16x16x32_bf16 v[120:123], v[154:157], v[170:173], v[120:123]
	v_mfma_f32_16x16x32_bf16 v[124:127], v[162:165], v[170:173], v[124:127]
	v_mfma_f32_16x16x32_bf16 v[104:107], v[154:157], v[178:181], v[104:107]
	v_mfma_f32_16x16x32_bf16 v[108:111], v[162:165], v[178:181], v[108:111]
	v_mfma_f32_16x16x32_bf16 v[88:91], v[154:157], v[186:189], v[88:91]
	v_mfma_f32_16x16x32_bf16 v[92:95], v[162:165], v[186:189], v[92:95]
	v_mfma_f32_16x16x32_bf16 v[72:75], v[154:157], v[194:197], v[72:75]
	v_mfma_f32_16x16x32_bf16 v[76:79], v[162:165], v[194:197], v[76:79]
	s_barrier
	s_add_i32 s36, 0, 0x1c000
	s_add_i32 s37, s78, s42
	v_add_u32_e32 v210, s36, v143
	v_lshl_add_u64 v[214:215], v[214:215], 0, s[8:9]
	s_mov_b32 m0, s37
	ds_read_b128 v[198:201], v210
	ds_read_b128 v[202:205], v210 offset:1024
	ds_read_b128 v[206:209], v210 offset:2048
	ds_read_b128 v[210:213], v210 offset:3072
	global_load_lds_dwordx4 v[214:215], off
	v_lshl_add_u64 v[214:215], v[216:217], 0, s[8:9]
	s_add_i32 m0, s37, 0x2000
	s_nop 0
	global_load_lds_dwordx4 v[214:215], off
	s_barrier
	s_waitcnt lgkmcnt(0)
	s_waitcnt lgkmcnt(0)
	v_mfma_f32_16x16x32_bf16 v[112:115], v[198:201], v[166:169], v[112:115]
	v_mfma_f32_16x16x32_bf16 v[116:119], v[206:209], v[166:169], v[116:119]
	v_mfma_f32_16x16x32_bf16 v[96:99], v[198:201], v[174:177], v[96:99]
	v_mfma_f32_16x16x32_bf16 v[100:103], v[206:209], v[174:177], v[100:103]
	v_mfma_f32_16x16x32_bf16 v[80:83], v[198:201], v[182:185], v[80:83]
	v_mfma_f32_16x16x32_bf16 v[84:87], v[206:209], v[182:185], v[84:87]
	v_mfma_f32_16x16x32_bf16 v[64:67], v[198:201], v[190:193], v[64:67]
	v_mfma_f32_16x16x32_bf16 v[68:71], v[206:209], v[190:193], v[68:71]
	v_mfma_f32_16x16x32_bf16 v[112:115], v[202:205], v[170:173], v[112:115]
	v_mfma_f32_16x16x32_bf16 v[116:119], v[210:213], v[170:173], v[116:119]
	v_mfma_f32_16x16x32_bf16 v[96:99], v[202:205], v[178:181], v[96:99]
	v_mfma_f32_16x16x32_bf16 v[100:103], v[210:213], v[178:181], v[100:103]
	v_mfma_f32_16x16x32_bf16 v[80:83], v[202:205], v[186:189], v[80:83]
	v_mfma_f32_16x16x32_bf16 v[84:87], v[210:213], v[186:189], v[84:87]
	v_mfma_f32_16x16x32_bf16 v[64:67], v[202:205], v[194:197], v[64:67]
	v_mfma_f32_16x16x32_bf16 v[68:71], v[210:213], v[194:197], v[68:71]
	s_mov_b32 m0, s55
	v_lshl_add_u64 v[214:215], v[218:219], 0, s[8:9]
	s_barrier
	ds_read_b128 v[166:169], v148 offset:49152
	ds_read_b128 v[170:173], v148 offset:50176
	ds_read_b128 v[174:177], v148 offset:51200
	ds_read_b128 v[178:181], v148 offset:52224
	ds_read_b128 v[182:185], v148 offset:53248
	ds_read_b128 v[186:189], v148 offset:54272
	ds_read_b128 v[190:193], v148 offset:55296
	ds_read_b128 v[194:197], v148 offset:56320
	global_load_lds_dwordx4 v[214:215], off
	v_lshl_add_u64 v[214:215], v[220:221], 0, s[8:9]
	s_mov_b32 m0, s56
	s_nop 0
	global_load_lds_dwordx4 v[214:215], off
	s_barrier
	s_waitcnt lgkmcnt(0)
	s_waitcnt lgkmcnt(0)
	v_mfma_f32_16x16x32_bf16 v[56:59], v[150:153], v[166:169], v[56:59]
	v_mfma_f32_16x16x32_bf16 v[60:63], v[158:161], v[166:169], v[60:63]
	v_mfma_f32_16x16x32_bf16 v[40:43], v[150:153], v[174:177], v[40:43]
	v_mfma_f32_16x16x32_bf16 v[44:47], v[158:161], v[174:177], v[44:47]
	v_mfma_f32_16x16x32_bf16 v[24:27], v[150:153], v[182:185], v[24:27]
	v_mfma_f32_16x16x32_bf16 v[28:31], v[158:161], v[182:185], v[28:31]
	v_mfma_f32_16x16x32_bf16 v[8:11], v[150:153], v[190:193], v[8:11]
	v_mfma_f32_16x16x32_bf16 v[12:15], v[158:161], v[190:193], v[12:15]
	v_mfma_f32_16x16x32_bf16 v[56:59], v[154:157], v[170:173], v[56:59]
	v_mfma_f32_16x16x32_bf16 v[60:63], v[162:165], v[170:173], v[60:63]
	v_mfma_f32_16x16x32_bf16 v[40:43], v[154:157], v[178:181], v[40:43]
	v_mfma_f32_16x16x32_bf16 v[44:47], v[162:165], v[178:181], v[44:47]
	v_mfma_f32_16x16x32_bf16 v[24:27], v[154:157], v[186:189], v[24:27]
	v_mfma_f32_16x16x32_bf16 v[28:31], v[162:165], v[186:189], v[28:31]
	v_mfma_f32_16x16x32_bf16 v[8:11], v[154:157], v[194:197], v[8:11]
	v_mfma_f32_16x16x32_bf16 v[12:15], v[162:165], v[194:197], v[12:15]
	s_barrier
	s_add_u32 s34, s34, 0x40080
	s_addc_u32 s35, s35, 0
	s_add_i32 s36, s36, s42
	v_lshl_add_u64 v[150:151], s[34:35], 0, v[130:131]
	s_mov_b32 m0, s36
	s_nop 0
	global_load_lds_dwordx4 v[150:151], off
	v_lshl_add_u64 v[150:151], s[34:35], 0, v[132:133]
	s_add_i32 m0, s36, 0x2000
	s_nop 0
	global_load_lds_dwordx4 v[150:151], off
	s_waitcnt vmcnt(6)
	s_barrier
	v_mfma_f32_16x16x32_bf16 v[48:51], v[198:201], v[166:169], v[48:51]
	v_mfma_f32_16x16x32_bf16 v[52:55], v[206:209], v[166:169], v[52:55]
	v_mfma_f32_16x16x32_bf16 v[32:35], v[198:201], v[174:177], v[32:35]
	v_mfma_f32_16x16x32_bf16 v[36:39], v[206:209], v[174:177], v[36:39]
	v_mfma_f32_16x16x32_bf16 v[16:19], v[198:201], v[182:185], v[16:19]
	v_mfma_f32_16x16x32_bf16 v[20:23], v[206:209], v[182:185], v[20:23]
	v_mfma_f32_16x16x32_bf16 v[0:3], v[198:201], v[190:193], v[0:3]
	v_mfma_f32_16x16x32_bf16 v[4:7], v[206:209], v[190:193], v[4:7]
	v_mfma_f32_16x16x32_bf16 v[48:51], v[202:205], v[170:173], v[48:51]
	v_mfma_f32_16x16x32_bf16 v[52:55], v[210:213], v[170:173], v[52:55]
	v_mfma_f32_16x16x32_bf16 v[32:35], v[202:205], v[178:181], v[32:35]
	v_mfma_f32_16x16x32_bf16 v[36:39], v[210:213], v[178:181], v[36:39]
	v_mfma_f32_16x16x32_bf16 v[16:19], v[202:205], v[186:189], v[16:19]
	v_mfma_f32_16x16x32_bf16 v[20:23], v[210:213], v[186:189], v[20:23]
	v_mfma_f32_16x16x32_bf16 v[0:3], v[202:205], v[194:197], v[0:3]
	v_mfma_f32_16x16x32_bf16 v[4:7], v[210:213], v[194:197], v[4:7]
	s_add_i32 s77, s77, 2
	s_add_u32 s30, s30, 0x100
	s_addc_u32 s31, s31, 0
	s_add_u32 s75, s75, 0x100
	s_addc_u32 s76, s76, 0
	s_cmp_gt_u32 s77, 13
	s_barrier
	s_cbranch_scc0 .LBB0_1141
	v_mul_f32_e32 v124, 0xbfb8aa3b, v124
	v_exp_f32_e32 v150, v124
	v_mul_f32_e32 v124, 0xbfb8aa3b, v125
	v_exp_f32_e32 v151, v124
	v_lshl_add_u32 v124, s28, 8, v142
	v_ashrrev_i32_e32 v125, 31, v124
	v_lshlrev_b64 v[154:155], 11, v[124:125]
	v_pk_add_f32 v[150:151], v[150:151], 1.0 op_sel_hi:[1,0]
	v_mul_f32_e32 v126, 0xbfb8aa3b, v126
	v_div_scale_f32 v153, s[30:31], v151, v151, v121
	v_rcp_f32_e32 v156, v153
	v_mul_f32_e32 v127, 0xbfb8aa3b, v127
	v_exp_f32_e32 v126, v126
	v_exp_f32_e32 v127, v127
	v_fma_f32 v125, -v153, v156, 1.0
	v_fmac_f32_e32 v156, v125, v156
	v_div_scale_f32 v125, vcc, v121, v151, v121
	v_mul_f32_e32 v157, v125, v156
	v_fma_f32 v158, -v153, v157, v125
	v_fmac_f32_e32 v157, v158, v156
	v_fma_f32 v125, -v153, v157, v125
	v_div_scale_f32 v153, s[30:31], v150, v150, v120
	v_rcp_f32_e32 v158, v153
	v_div_fmas_f32 v125, v125, v156, v157
	v_div_fixup_f32 v121, v125, v151, v121
	v_pk_add_f32 v[126:127], v[126:127], 1.0 op_sel_hi:[1,0]
	v_fma_f32 v125, -v153, v158, 1.0
	v_fmac_f32_e32 v158, v125, v158
	v_div_scale_f32 v125, vcc, v120, v150, v120
	v_mul_f32_e32 v151, v125, v158
	v_fma_f32 v156, -v153, v151, v125
	v_fmac_f32_e32 v151, v156, v158
	v_fma_f32 v125, -v153, v151, v125
	v_div_scale_f32 v153, s[30:31], v127, v127, v123
	v_rcp_f32_e32 v156, v153
	v_div_fmas_f32 v125, v125, v158, v151
	v_div_fixup_f32 v120, v125, v150, v120
	v_mul_f32_e32 v116, 0xbfb8aa3b, v116
	v_fma_f32 v125, -v153, v156, 1.0
	v_fmac_f32_e32 v156, v125, v156
	v_div_scale_f32 v125, vcc, v123, v127, v123
	v_mul_f32_e32 v150, v125, v156
	v_fma_f32 v151, -v153, v150, v125
	v_fmac_f32_e32 v150, v151, v156
	v_div_scale_f32 v151, s[30:31], v126, v126, v122
	v_fma_f32 v125, -v153, v150, v125
	v_rcp_f32_e32 v153, v151
	v_div_fmas_f32 v125, v125, v156, v150
	v_div_fixup_f32 v123, v125, v127, v123
	v_mul_f32_e32 v117, 0xbfb8aa3b, v117
	v_fma_f32 v125, -v151, v153, 1.0
	v_fmac_f32_e32 v153, v125, v153
	v_div_scale_f32 v125, vcc, v122, v126, v122
	v_mul_f32_e32 v127, v125, v153
	v_fma_f32 v150, -v151, v127, v125
	v_exp_f32_e32 v116, v116
	v_exp_f32_e32 v117, v117
	v_fmac_f32_e32 v127, v150, v153
	v_fma_f32 v125, -v151, v127, v125
	v_div_fmas_f32 v125, v125, v153, v127
	v_div_fixup_f32 v125, v125, v126, v122
	v_pk_add_f32 v[126:127], v[116:117], 1.0 op_sel_hi:[1,0]
	v_cvt_pk_bf16_f32 v123, v125, v123
	v_div_scale_f32 v125, s[30:31], v127, v127, v113
	v_lshl_or_b32 v152, s72, 7, v144
	v_rcp_f32_e32 v150, v125
	v_ashrrev_i32_e32 v153, 31, v152
	v_lshl_add_u64 v[154:155], s[46:47], 0, v[154:155]
	v_cvt_pk_bf16_f32 v122, v120, v121
	v_lshlrev_b64 v[120:121], 1, v[152:153]
	v_lshl_add_u64 v[116:117], v[154:155], 0, v[120:121]
	global_store_dwordx2 v[116:117], v[122:123], off
	v_fma_f32 v122, -v125, v150, 1.0
	v_fmac_f32_e32 v150, v122, v150
	v_div_scale_f32 v122, vcc, v113, v127, v113
	v_mul_f32_e32 v123, v122, v150
	v_fma_f32 v151, -v125, v123, v122
	v_fmac_f32_e32 v123, v151, v150
	v_fma_f32 v122, -v125, v123, v122
	v_div_scale_f32 v125, s[30:31], v126, v126, v112
	v_rcp_f32_e32 v151, v125
	v_div_fmas_f32 v122, v122, v150, v123
	v_mul_f32_e32 v118, 0xbfb8aa3b, v118
	v_mul_f32_e32 v119, 0xbfb8aa3b, v119
	v_div_fixup_f32 v113, v122, v127, v113
	v_fma_f32 v122, -v125, v151, 1.0
	v_exp_f32_e32 v118, v118
	v_exp_f32_e32 v119, v119
	v_fmac_f32_e32 v151, v122, v151
	v_div_scale_f32 v122, vcc, v112, v126, v112
	v_mul_f32_e32 v123, v122, v151
	v_fma_f32 v127, -v125, v123, v122
	v_fmac_f32_e32 v123, v127, v151
	v_pk_add_f32 v[118:119], v[118:119], 1.0 op_sel_hi:[1,0]
	v_fma_f32 v122, -v125, v123, v122
	v_div_scale_f32 v125, s[30:31], v119, v119, v115
	v_rcp_f32_e32 v127, v125
	v_div_fmas_f32 v122, v122, v151, v123
	v_div_fixup_f32 v112, v122, v126, v112
	v_mul_f32_e32 v108, 0xbfb8aa3b, v108
	v_fma_f32 v122, -v125, v127, 1.0
	v_fmac_f32_e32 v127, v122, v127
	v_div_scale_f32 v122, vcc, v115, v119, v115
	v_mul_f32_e32 v123, v122, v127
	v_fma_f32 v126, -v125, v123, v122
	v_fmac_f32_e32 v123, v126, v127
	v_fma_f32 v122, -v125, v123, v122
	v_div_scale_f32 v125, s[30:31], v118, v118, v114
	v_rcp_f32_e32 v126, v125
	v_div_fmas_f32 v122, v122, v127, v123
	v_div_fixup_f32 v115, v122, v119, v115
	v_mul_f32_e32 v109, 0xbfb8aa3b, v109
	v_fma_f32 v119, -v125, v126, 1.0
	v_fmac_f32_e32 v126, v119, v126
	v_div_scale_f32 v119, vcc, v114, v118, v114
	v_mul_f32_e32 v122, v119, v126
	v_fma_f32 v123, -v125, v122, v119
	v_exp_f32_e32 v108, v108
	v_exp_f32_e32 v109, v109
	v_fmac_f32_e32 v122, v123, v126
	v_fma_f32 v119, -v125, v122, v119
	v_div_fmas_f32 v119, v119, v126, v122
	v_div_fixup_f32 v114, v119, v118, v114
	v_pk_add_f32 v[108:109], v[108:109], 1.0 op_sel_hi:[1,0]
	v_cvt_pk_bf16_f32 v112, v112, v113
	v_cvt_pk_bf16_f32 v113, v114, v115
	v_div_scale_f32 v114, s[30:31], v109, v109, v105
	v_rcp_f32_e32 v115, v114
	v_mul_f32_e32 v110, 0xbfb8aa3b, v110
	v_mul_f32_e32 v111, 0xbfb8aa3b, v111
	v_exp_f32_e32 v110, v110
	v_fma_f32 v118, -v114, v115, 1.0
	v_fmac_f32_e32 v115, v118, v115
	v_div_scale_f32 v118, vcc, v105, v109, v105
	v_mul_f32_e32 v119, v118, v115
	v_fma_f32 v122, -v114, v119, v118
	v_fmac_f32_e32 v119, v122, v115
	v_fma_f32 v114, -v114, v119, v118
	v_div_scale_f32 v118, s[30:31], v108, v108, v104
	v_rcp_f32_e32 v122, v118
	v_div_fmas_f32 v114, v114, v115, v119
	v_exp_f32_e32 v111, v111
	v_div_fixup_f32 v105, v114, v109, v105
	v_fma_f32 v109, -v118, v122, 1.0
	v_fmac_f32_e32 v122, v109, v122
	v_div_scale_f32 v109, vcc, v104, v108, v104
	v_mul_f32_e32 v114, v109, v122
	v_fma_f32 v115, -v118, v114, v109
	v_pk_add_f32 v[110:111], v[110:111], 1.0 op_sel_hi:[1,0]
	v_fmac_f32_e32 v114, v115, v122
	v_div_scale_f32 v115, s[30:31], v111, v111, v107
	v_fma_f32 v109, -v118, v114, v109
	v_rcp_f32_e32 v118, v115
	v_div_fmas_f32 v109, v109, v122, v114
	v_div_fixup_f32 v104, v109, v108, v104
	v_mul_f32_e32 v100, 0xbfb8aa3b, v100
	v_fma_f32 v108, -v115, v118, 1.0
	v_fmac_f32_e32 v118, v108, v118
	v_div_scale_f32 v108, vcc, v107, v111, v107
	v_mul_f32_e32 v109, v108, v118
	v_fma_f32 v114, -v115, v109, v108
	v_fmac_f32_e32 v109, v114, v118
	v_div_scale_f32 v114, s[30:31], v110, v110, v106
	v_fma_f32 v108, -v115, v109, v108
	v_rcp_f32_e32 v115, v114
	v_div_fmas_f32 v108, v108, v118, v109
	v_div_fixup_f32 v107, v108, v111, v107
	v_mul_f32_e32 v101, 0xbfb8aa3b, v101
	v_fma_f32 v108, -v114, v115, 1.0
	v_fmac_f32_e32 v115, v108, v115
	v_div_scale_f32 v108, vcc, v106, v110, v106
	v_mul_f32_e32 v109, v108, v115
	v_exp_f32_e32 v100, v100
	v_exp_f32_e32 v101, v101
	v_fma_f32 v111, -v114, v109, v108
	v_fmac_f32_e32 v109, v111, v115
	v_fma_f32 v108, -v114, v109, v108
	v_div_fmas_f32 v108, v108, v115, v109
	v_pk_add_f32 v[100:101], v[100:101], 1.0 op_sel_hi:[1,0]
	global_store_dwordx2 v[116:117], v[112:113], off offset:128
	v_or_b32_e32 v112, 16, v124
	v_div_fixup_f32 v106, v108, v110, v106
	v_div_scale_f32 v108, s[30:31], v101, v101, v97
	v_ashrrev_i32_e32 v113, 31, v112
	v_rcp_f32_e32 v109, v108
	v_lshlrev_b64 v[112:113], 11, v[112:113]
	v_lshl_add_u64 v[112:113], s[46:47], 0, v[112:113]
	v_cvt_pk_bf16_f32 v104, v104, v105
	v_cvt_pk_bf16_f32 v105, v106, v107
	v_lshl_add_u64 v[106:107], v[112:113], 0, v[120:121]
	global_store_dwordx2 v[106:107], v[104:105], off
	v_fma_f32 v104, -v108, v109, 1.0
	v_fmac_f32_e32 v109, v104, v109
	v_div_scale_f32 v104, vcc, v97, v101, v97
	v_mul_f32_e32 v105, v104, v109
	v_fma_f32 v110, -v108, v105, v104
	v_fmac_f32_e32 v105, v110, v109
	v_fma_f32 v104, -v108, v105, v104
	v_div_scale_f32 v108, s[30:31], v100, v100, v96
	v_rcp_f32_e32 v110, v108
	v_mul_f32_e32 v102, 0xbfb8aa3b, v102
	v_mul_f32_e32 v103, 0xbfb8aa3b, v103
	v_div_fmas_f32 v104, v104, v109, v105
	v_exp_f32_e32 v102, v102
	v_exp_f32_e32 v103, v103
	v_div_fixup_f32 v97, v104, v101, v97
	v_fma_f32 v101, -v108, v110, 1.0
	v_fmac_f32_e32 v110, v101, v110
	v_div_scale_f32 v101, vcc, v96, v100, v96
	v_mul_f32_e32 v104, v101, v110
	v_fma_f32 v105, -v108, v104, v101
	v_pk_add_f32 v[102:103], v[102:103], 1.0 op_sel_hi:[1,0]
	v_fmac_f32_e32 v104, v105, v110
	v_div_scale_f32 v105, s[30:31], v103, v103, v99
	v_fma_f32 v101, -v108, v104, v101
	v_rcp_f32_e32 v108, v105
	v_div_fmas_f32 v101, v101, v110, v104
	v_div_fixup_f32 v96, v101, v100, v96
	v_mul_f32_e32 v92, 0xbfb8aa3b, v92
	v_fma_f32 v100, -v105, v108, 1.0
	v_fmac_f32_e32 v108, v100, v108
	v_div_scale_f32 v100, vcc, v99, v103, v99
	v_mul_f32_e32 v101, v100, v108
	v_fma_f32 v104, -v105, v101, v100
	v_fmac_f32_e32 v101, v104, v108
	v_div_scale_f32 v104, s[30:31], v102, v102, v98
	v_fma_f32 v100, -v105, v101, v100
	v_rcp_f32_e32 v105, v104
	v_div_fmas_f32 v100, v100, v108, v101
	v_div_fixup_f32 v99, v100, v103, v99
	v_mul_f32_e32 v93, 0xbfb8aa3b, v93
	v_fma_f32 v100, -v104, v105, 1.0
	v_fmac_f32_e32 v105, v100, v105
	v_div_scale_f32 v100, vcc, v98, v102, v98
	v_mul_f32_e32 v101, v100, v105
	v_fma_f32 v103, -v104, v101, v100
	v_exp_f32_e32 v92, v92
	v_exp_f32_e32 v93, v93
	v_fmac_f32_e32 v101, v103, v105
	v_fma_f32 v100, -v104, v101, v100
	v_div_fmas_f32 v100, v100, v105, v101
	v_div_fixup_f32 v98, v100, v102, v98
	v_pk_add_f32 v[92:93], v[92:93], 1.0 op_sel_hi:[1,0]
	v_cvt_pk_bf16_f32 v96, v96, v97
	v_cvt_pk_bf16_f32 v97, v98, v99
	v_div_scale_f32 v98, s[30:31], v93, v93, v89
	v_rcp_f32_e32 v99, v98
	v_mul_f32_e32 v94, 0xbfb8aa3b, v94
	v_mul_f32_e32 v95, 0xbfb8aa3b, v95
	v_exp_f32_e32 v94, v94
	v_fma_f32 v100, -v98, v99, 1.0
	v_fmac_f32_e32 v99, v100, v99
	v_div_scale_f32 v100, vcc, v89, v93, v89
	v_mul_f32_e32 v101, v100, v99
	v_fma_f32 v102, -v98, v101, v100
	v_fmac_f32_e32 v101, v102, v99
	v_fma_f32 v98, -v98, v101, v100
	v_div_scale_f32 v100, s[30:31], v92, v92, v88
	v_rcp_f32_e32 v102, v100
	v_div_fmas_f32 v98, v98, v99, v101
	v_exp_f32_e32 v95, v95
	v_div_fixup_f32 v89, v98, v93, v89
	v_fma_f32 v93, -v100, v102, 1.0
	v_fmac_f32_e32 v102, v93, v102
	v_div_scale_f32 v93, vcc, v88, v92, v88
	v_mul_f32_e32 v98, v93, v102
	v_fma_f32 v99, -v100, v98, v93
	v_pk_add_f32 v[94:95], v[94:95], 1.0 op_sel_hi:[1,0]
	v_fmac_f32_e32 v98, v99, v102
	v_div_scale_f32 v99, s[30:31], v95, v95, v91
	v_fma_f32 v93, -v100, v98, v93
	v_rcp_f32_e32 v100, v99
	v_div_fmas_f32 v93, v93, v102, v98
	v_div_fixup_f32 v88, v93, v92, v88
	v_mul_f32_e32 v84, 0xbfb8aa3b, v84
	v_fma_f32 v92, -v99, v100, 1.0
	v_fmac_f32_e32 v100, v92, v100
	v_div_scale_f32 v92, vcc, v91, v95, v91
	v_mul_f32_e32 v93, v92, v100
	v_fma_f32 v98, -v99, v93, v92
	v_fmac_f32_e32 v93, v98, v100
	v_div_scale_f32 v98, s[30:31], v94, v94, v90
	v_fma_f32 v92, -v99, v93, v92
	v_rcp_f32_e32 v99, v98
	v_div_fmas_f32 v92, v92, v100, v93
	v_div_fixup_f32 v91, v92, v95, v91
	v_mul_f32_e32 v85, 0xbfb8aa3b, v85
	v_fma_f32 v92, -v98, v99, 1.0
	v_fmac_f32_e32 v99, v92, v99
	v_div_scale_f32 v92, vcc, v90, v94, v90
	v_mul_f32_e32 v93, v92, v99
	v_exp_f32_e32 v84, v84
	v_exp_f32_e32 v85, v85
	v_fma_f32 v95, -v98, v93, v92
	v_fmac_f32_e32 v93, v95, v99
	v_fma_f32 v92, -v98, v93, v92
	v_div_fmas_f32 v92, v92, v99, v93
	v_pk_add_f32 v[84:85], v[84:85], 1.0 op_sel_hi:[1,0]
	global_store_dwordx2 v[106:107], v[96:97], off offset:128
	v_or_b32_e32 v96, 32, v124
	v_div_fixup_f32 v90, v92, v94, v90
	v_div_scale_f32 v92, s[30:31], v85, v85, v81
	v_ashrrev_i32_e32 v97, 31, v96
	v_rcp_f32_e32 v93, v92
	v_lshlrev_b64 v[96:97], 11, v[96:97]
	v_lshl_add_u64 v[96:97], s[46:47], 0, v[96:97]
	v_cvt_pk_bf16_f32 v88, v88, v89
	v_cvt_pk_bf16_f32 v89, v90, v91
	v_lshl_add_u64 v[90:91], v[96:97], 0, v[120:121]
	global_store_dwordx2 v[90:91], v[88:89], off
	v_fma_f32 v88, -v92, v93, 1.0
	v_fmac_f32_e32 v93, v88, v93
	v_div_scale_f32 v88, vcc, v81, v85, v81
	v_mul_f32_e32 v89, v88, v93
	v_fma_f32 v94, -v92, v89, v88
	v_fmac_f32_e32 v89, v94, v93
	v_fma_f32 v88, -v92, v89, v88
	v_div_scale_f32 v92, s[30:31], v84, v84, v80
	v_rcp_f32_e32 v94, v92
	v_mul_f32_e32 v86, 0xbfb8aa3b, v86
	v_mul_f32_e32 v87, 0xbfb8aa3b, v87
	v_div_fmas_f32 v88, v88, v93, v89
	v_exp_f32_e32 v86, v86
	v_exp_f32_e32 v87, v87
	v_div_fixup_f32 v81, v88, v85, v81
	v_fma_f32 v85, -v92, v94, 1.0
	v_fmac_f32_e32 v94, v85, v94
	v_div_scale_f32 v85, vcc, v80, v84, v80
	v_mul_f32_e32 v88, v85, v94
	v_fma_f32 v89, -v92, v88, v85
	v_pk_add_f32 v[86:87], v[86:87], 1.0 op_sel_hi:[1,0]
	v_fmac_f32_e32 v88, v89, v94
	v_div_scale_f32 v89, s[30:31], v87, v87, v83
	v_fma_f32 v85, -v92, v88, v85
	v_rcp_f32_e32 v92, v89
	v_div_fmas_f32 v85, v85, v94, v88
	v_div_fixup_f32 v80, v85, v84, v80
	v_mul_f32_e32 v76, 0xbfb8aa3b, v76
	v_fma_f32 v84, -v89, v92, 1.0
	v_fmac_f32_e32 v92, v84, v92
	v_div_scale_f32 v84, vcc, v83, v87, v83
	v_mul_f32_e32 v85, v84, v92
	v_fma_f32 v88, -v89, v85, v84
	v_fmac_f32_e32 v85, v88, v92
	v_div_scale_f32 v88, s[30:31], v86, v86, v82
	v_fma_f32 v84, -v89, v85, v84
	v_rcp_f32_e32 v89, v88
	v_div_fmas_f32 v84, v84, v92, v85
	v_div_fixup_f32 v83, v84, v87, v83
	v_mul_f32_e32 v77, 0xbfb8aa3b, v77
	v_fma_f32 v84, -v88, v89, 1.0
	v_fmac_f32_e32 v89, v84, v89
	v_div_scale_f32 v84, vcc, v82, v86, v82
	v_mul_f32_e32 v85, v84, v89
	v_fma_f32 v87, -v88, v85, v84
	v_exp_f32_e32 v76, v76
	v_exp_f32_e32 v77, v77
	v_fmac_f32_e32 v85, v87, v89
	v_fma_f32 v84, -v88, v85, v84
	v_div_fmas_f32 v84, v84, v89, v85
	v_div_fixup_f32 v82, v84, v86, v82
	v_pk_add_f32 v[76:77], v[76:77], 1.0 op_sel_hi:[1,0]
	v_cvt_pk_bf16_f32 v80, v80, v81
	v_cvt_pk_bf16_f32 v81, v82, v83
	v_div_scale_f32 v82, s[30:31], v77, v77, v73
	v_rcp_f32_e32 v83, v82
	v_mul_f32_e32 v78, 0xbfb8aa3b, v78
	v_mul_f32_e32 v79, 0xbfb8aa3b, v79
	v_exp_f32_e32 v78, v78
	v_fma_f32 v84, -v82, v83, 1.0
	v_fmac_f32_e32 v83, v84, v83
	v_div_scale_f32 v84, vcc, v73, v77, v73
	v_mul_f32_e32 v85, v84, v83
	v_fma_f32 v86, -v82, v85, v84
	v_fmac_f32_e32 v85, v86, v83
	v_fma_f32 v82, -v82, v85, v84
	v_div_scale_f32 v84, s[30:31], v76, v76, v72
	v_rcp_f32_e32 v86, v84
	v_div_fmas_f32 v82, v82, v83, v85
	v_exp_f32_e32 v79, v79
	v_div_fixup_f32 v73, v82, v77, v73
	v_fma_f32 v77, -v84, v86, 1.0
	v_fmac_f32_e32 v86, v77, v86
	v_div_scale_f32 v77, vcc, v72, v76, v72
	v_mul_f32_e32 v82, v77, v86
	v_fma_f32 v83, -v84, v82, v77
	v_pk_add_f32 v[78:79], v[78:79], 1.0 op_sel_hi:[1,0]
	v_fmac_f32_e32 v82, v83, v86
	v_div_scale_f32 v83, s[30:31], v79, v79, v75
	v_fma_f32 v77, -v84, v82, v77
	v_rcp_f32_e32 v84, v83
	v_div_fmas_f32 v77, v77, v86, v82
	v_div_fixup_f32 v72, v77, v76, v72
	v_mul_f32_e32 v68, 0xbfb8aa3b, v68
	v_fma_f32 v76, -v83, v84, 1.0
	v_fmac_f32_e32 v84, v76, v84
	v_div_scale_f32 v76, vcc, v75, v79, v75
	v_mul_f32_e32 v77, v76, v84
	v_fma_f32 v82, -v83, v77, v76
	v_fmac_f32_e32 v77, v82, v84
	v_div_scale_f32 v82, s[30:31], v78, v78, v74
	v_fma_f32 v76, -v83, v77, v76
	v_rcp_f32_e32 v83, v82
	v_div_fmas_f32 v76, v76, v84, v77
	v_div_fixup_f32 v75, v76, v79, v75
	v_mul_f32_e32 v69, 0xbfb8aa3b, v69
	v_fma_f32 v76, -v82, v83, 1.0
	v_fmac_f32_e32 v83, v76, v83
	v_div_scale_f32 v76, vcc, v74, v78, v74
	v_mul_f32_e32 v77, v76, v83
	v_exp_f32_e32 v68, v68
	v_exp_f32_e32 v69, v69
	v_fma_f32 v79, -v82, v77, v76
	v_fmac_f32_e32 v77, v79, v83
	v_fma_f32 v76, -v82, v77, v76
	v_div_fmas_f32 v76, v76, v83, v77
	v_pk_add_f32 v[68:69], v[68:69], 1.0 op_sel_hi:[1,0]
	global_store_dwordx2 v[90:91], v[80:81], off offset:128
	v_or_b32_e32 v80, 48, v124
	v_div_fixup_f32 v74, v76, v78, v74
	v_div_scale_f32 v76, s[30:31], v69, v69, v65
	v_ashrrev_i32_e32 v81, 31, v80
	v_rcp_f32_e32 v77, v76
	v_lshlrev_b64 v[80:81], 11, v[80:81]
	v_lshl_add_u64 v[80:81], s[46:47], 0, v[80:81]
	v_cvt_pk_bf16_f32 v72, v72, v73
	v_cvt_pk_bf16_f32 v73, v74, v75
	v_lshl_add_u64 v[74:75], v[80:81], 0, v[120:121]
	global_store_dwordx2 v[74:75], v[72:73], off
	v_fma_f32 v72, -v76, v77, 1.0
	v_fmac_f32_e32 v77, v72, v77
	v_div_scale_f32 v72, vcc, v65, v69, v65
	v_mul_f32_e32 v73, v72, v77
	v_fma_f32 v78, -v76, v73, v72
	v_fmac_f32_e32 v73, v78, v77
	v_fma_f32 v72, -v76, v73, v72
	v_div_scale_f32 v76, s[30:31], v68, v68, v64
	v_rcp_f32_e32 v78, v76
	v_mul_f32_e32 v70, 0xbfb8aa3b, v70
	v_mul_f32_e32 v71, 0xbfb8aa3b, v71
	v_div_fmas_f32 v72, v72, v77, v73
	v_exp_f32_e32 v70, v70
	v_exp_f32_e32 v71, v71
	v_div_fixup_f32 v65, v72, v69, v65
	v_fma_f32 v69, -v76, v78, 1.0
	v_fmac_f32_e32 v78, v69, v78
	v_div_scale_f32 v69, vcc, v64, v68, v64
	v_mul_f32_e32 v72, v69, v78
	v_fma_f32 v73, -v76, v72, v69
	v_pk_add_f32 v[70:71], v[70:71], 1.0 op_sel_hi:[1,0]
	v_fmac_f32_e32 v72, v73, v78
	v_div_scale_f32 v73, s[30:31], v71, v71, v67
	v_fma_f32 v69, -v76, v72, v69
	v_rcp_f32_e32 v76, v73
	v_div_fmas_f32 v69, v69, v78, v72
	v_div_fixup_f32 v64, v69, v68, v64
	v_mul_f32_e32 v60, 0xbfb8aa3b, v60
	v_fma_f32 v68, -v73, v76, 1.0
	v_fmac_f32_e32 v76, v68, v76
	v_div_scale_f32 v68, vcc, v67, v71, v67
	v_mul_f32_e32 v69, v68, v76
	v_fma_f32 v72, -v73, v69, v68
	v_fmac_f32_e32 v69, v72, v76
	v_div_scale_f32 v72, s[30:31], v70, v70, v66
	v_fma_f32 v68, -v73, v69, v68
	v_rcp_f32_e32 v73, v72
	v_div_fmas_f32 v68, v68, v76, v69
	v_div_fixup_f32 v67, v68, v71, v67
	v_mul_f32_e32 v61, 0xbfb8aa3b, v61
	v_fma_f32 v68, -v72, v73, 1.0
	v_fmac_f32_e32 v73, v68, v73
	v_div_scale_f32 v68, vcc, v66, v70, v66
	v_mul_f32_e32 v69, v68, v73
	v_exp_f32_e32 v60, v60
	v_exp_f32_e32 v61, v61
	v_fma_f32 v71, -v72, v69, v68
	v_fmac_f32_e32 v69, v71, v73
	v_fma_f32 v68, -v72, v69, v68
	v_div_fmas_f32 v68, v68, v73, v69
	v_pk_add_f32 v[60:61], v[60:61], 1.0 op_sel_hi:[1,0]
	v_div_fixup_f32 v66, v68, v70, v66
	v_div_scale_f32 v68, s[30:31], v61, v61, v57
	v_rcp_f32_e32 v69, v68
	v_cvt_pk_bf16_f32 v64, v64, v65
	v_cvt_pk_bf16_f32 v65, v66, v67
	global_store_dwordx2 v[74:75], v[64:65], off offset:128
	v_fma_f32 v64, -v68, v69, 1.0
	v_fmac_f32_e32 v69, v64, v69
	v_div_scale_f32 v64, vcc, v57, v61, v57
	v_mul_f32_e32 v65, v64, v69
	v_fma_f32 v66, -v68, v65, v64
	v_fmac_f32_e32 v65, v66, v69
	v_div_scale_f32 v66, s[30:31], v60, v60, v56
	v_rcp_f32_e32 v67, v66
	v_fma_f32 v64, -v68, v65, v64
	v_mul_f32_e32 v62, 0xbfb8aa3b, v62
	v_mul_f32_e32 v63, 0xbfb8aa3b, v63
	v_div_fmas_f32 v64, v64, v69, v65
	v_exp_f32_e32 v62, v62
	v_exp_f32_e32 v63, v63
	v_div_fixup_f32 v57, v64, v61, v57
	v_fma_f32 v61, -v66, v67, 1.0
	v_fmac_f32_e32 v67, v61, v67
	v_div_scale_f32 v61, vcc, v56, v60, v56
	v_mul_f32_e32 v64, v61, v67
	v_fma_f32 v65, -v66, v64, v61
	v_pk_add_f32 v[62:63], v[62:63], 1.0 op_sel_hi:[1,0]
	v_fmac_f32_e32 v64, v65, v67
	v_div_scale_f32 v65, s[30:31], v63, v63, v59
	v_fma_f32 v61, -v66, v64, v61
	v_rcp_f32_e32 v66, v65
	v_div_fmas_f32 v61, v61, v67, v64
	v_div_fixup_f32 v56, v61, v60, v56
	v_mul_f32_e32 v52, 0xbfb8aa3b, v52
	v_fma_f32 v60, -v65, v66, 1.0
	v_fmac_f32_e32 v66, v60, v66
	v_div_scale_f32 v60, vcc, v59, v63, v59
	v_mul_f32_e32 v61, v60, v66
	v_fma_f32 v64, -v65, v61, v60
	v_fmac_f32_e32 v61, v64, v66
	v_div_scale_f32 v64, s[30:31], v62, v62, v58
	v_fma_f32 v60, -v65, v61, v60
	v_rcp_f32_e32 v65, v64
	v_div_fmas_f32 v60, v60, v66, v61
	v_div_fixup_f32 v59, v60, v63, v59
	v_mul_f32_e32 v53, 0xbfb8aa3b, v53
	v_fma_f32 v60, -v64, v65, 1.0
	v_fmac_f32_e32 v65, v60, v65
	v_div_scale_f32 v60, vcc, v58, v62, v58
	v_mul_f32_e32 v61, v60, v65
	v_exp_f32_e32 v52, v52
	v_exp_f32_e32 v53, v53
	v_fma_f32 v63, -v64, v61, v60
	v_fmac_f32_e32 v61, v63, v65
	v_fma_f32 v60, -v64, v61, v60
	v_div_fmas_f32 v60, v60, v65, v61
	v_pk_add_f32 v[52:53], v[52:53], 1.0 op_sel_hi:[1,0]
	v_div_fixup_f32 v58, v60, v62, v58
	v_div_scale_f32 v62, s[30:31], v53, v53, v49
	v_rcp_f32_e32 v63, v62
	v_add_co_u32_e32 v60, vcc, s62, v116
	v_cvt_pk_bf16_f32 v56, v56, v57
	v_cvt_pk_bf16_f32 v57, v58, v59
	v_addc_co_u32_e32 v61, vcc, 0, v117, vcc
	global_store_dwordx2 v[60:61], v[56:57], off
	v_fma_f32 v56, -v62, v63, 1.0
	v_fmac_f32_e32 v63, v56, v63
	v_div_scale_f32 v56, vcc, v49, v53, v49
	v_mul_f32_e32 v57, v56, v63
	v_fma_f32 v60, -v62, v57, v56
	v_fmac_f32_e32 v57, v60, v63
	v_div_scale_f32 v60, s[30:31], v52, v52, v48
	v_rcp_f32_e32 v61, v60
	v_fma_f32 v56, -v62, v57, v56
	v_mul_f32_e32 v54, 0xbfb8aa3b, v54
	v_mul_f32_e32 v55, 0xbfb8aa3b, v55
	v_div_fmas_f32 v56, v56, v63, v57
	v_exp_f32_e32 v54, v54
	v_exp_f32_e32 v55, v55
	v_div_fixup_f32 v49, v56, v53, v49
	v_fma_f32 v53, -v60, v61, 1.0
	v_fmac_f32_e32 v61, v53, v61
	v_div_scale_f32 v53, vcc, v48, v52, v48
	v_mul_f32_e32 v56, v53, v61
	v_fma_f32 v57, -v60, v56, v53
	v_pk_add_f32 v[54:55], v[54:55], 1.0 op_sel_hi:[1,0]
	v_fmac_f32_e32 v56, v57, v61
	v_div_scale_f32 v57, s[30:31], v55, v55, v51
	v_fma_f32 v53, -v60, v56, v53
	v_rcp_f32_e32 v60, v57
	v_div_fmas_f32 v53, v53, v61, v56
	v_div_fixup_f32 v48, v53, v52, v48
	v_mul_f32_e32 v44, 0xbfb8aa3b, v44
	v_fma_f32 v52, -v57, v60, 1.0
	v_fmac_f32_e32 v60, v52, v60
	v_div_scale_f32 v52, vcc, v51, v55, v51
	v_mul_f32_e32 v53, v52, v60
	v_fma_f32 v56, -v57, v53, v52
	v_fmac_f32_e32 v53, v56, v60
	v_div_scale_f32 v56, s[30:31], v54, v54, v50
	v_fma_f32 v52, -v57, v53, v52
	v_rcp_f32_e32 v57, v56
	v_div_fmas_f32 v52, v52, v60, v53
	v_div_fixup_f32 v51, v52, v55, v51
	v_mul_f32_e32 v45, 0xbfb8aa3b, v45
	v_fma_f32 v52, -v56, v57, 1.0
	v_fmac_f32_e32 v57, v52, v57
	v_div_scale_f32 v52, vcc, v50, v54, v50
	v_mul_f32_e32 v53, v52, v57
	v_exp_f32_e32 v44, v44
	v_exp_f32_e32 v45, v45
	v_fma_f32 v55, -v56, v53, v52
	v_fmac_f32_e32 v53, v55, v57
	v_fma_f32 v52, -v56, v53, v52
	v_div_fmas_f32 v52, v52, v57, v53
	v_pk_add_f32 v[44:45], v[44:45], 1.0 op_sel_hi:[1,0]
	v_div_fixup_f32 v50, v52, v54, v50
	v_div_scale_f32 v52, s[30:31], v45, v45, v41
	v_rcp_f32_e32 v53, v52
	v_lshl_add_u64 v[58:59], v[116:117], 0, s[6:7]
	v_cvt_pk_bf16_f32 v48, v48, v49
	v_cvt_pk_bf16_f32 v49, v50, v51
	global_store_dwordx2 v[58:59], v[48:49], off offset:128
	v_fma_f32 v48, -v52, v53, 1.0
	v_fmac_f32_e32 v53, v48, v53
	v_div_scale_f32 v48, vcc, v41, v45, v41
	v_mul_f32_e32 v49, v48, v53
	v_fma_f32 v50, -v52, v49, v48
	v_fmac_f32_e32 v49, v50, v53
	v_div_scale_f32 v50, s[30:31], v44, v44, v40
	v_rcp_f32_e32 v51, v50
	v_fma_f32 v48, -v52, v49, v48
	v_mul_f32_e32 v46, 0xbfb8aa3b, v46
	v_mul_f32_e32 v47, 0xbfb8aa3b, v47
	v_div_fmas_f32 v48, v48, v53, v49
	v_exp_f32_e32 v46, v46
	v_exp_f32_e32 v47, v47
	v_div_fixup_f32 v41, v48, v45, v41
	v_fma_f32 v45, -v50, v51, 1.0
	v_fmac_f32_e32 v51, v45, v51
	v_div_scale_f32 v45, vcc, v40, v44, v40
	v_mul_f32_e32 v48, v45, v51
	v_fma_f32 v49, -v50, v48, v45
	v_pk_add_f32 v[46:47], v[46:47], 1.0 op_sel_hi:[1,0]
	v_fmac_f32_e32 v48, v49, v51
	v_div_scale_f32 v49, s[30:31], v47, v47, v43
	v_fma_f32 v45, -v50, v48, v45
	v_rcp_f32_e32 v50, v49
	v_div_fmas_f32 v45, v45, v51, v48
	v_div_fixup_f32 v40, v45, v44, v40
	v_mul_f32_e32 v36, 0xbfb8aa3b, v36
	v_fma_f32 v44, -v49, v50, 1.0
	v_fmac_f32_e32 v50, v44, v50
	v_div_scale_f32 v44, vcc, v43, v47, v43
	v_mul_f32_e32 v45, v44, v50
	v_fma_f32 v48, -v49, v45, v44
	v_fmac_f32_e32 v45, v48, v50
	v_div_scale_f32 v48, s[30:31], v46, v46, v42
	v_fma_f32 v44, -v49, v45, v44
	v_rcp_f32_e32 v49, v48
	v_div_fmas_f32 v44, v44, v50, v45
	v_div_fixup_f32 v43, v44, v47, v43
	v_mul_f32_e32 v37, 0xbfb8aa3b, v37
	v_fma_f32 v44, -v48, v49, 1.0
	v_fmac_f32_e32 v49, v44, v49
	v_div_scale_f32 v44, vcc, v42, v46, v42
	v_mul_f32_e32 v45, v44, v49
	v_exp_f32_e32 v36, v36
	v_exp_f32_e32 v37, v37
	v_fma_f32 v47, -v48, v45, v44
	v_fmac_f32_e32 v45, v47, v49
	v_fma_f32 v44, -v48, v45, v44
	v_div_fmas_f32 v44, v44, v49, v45
	v_pk_add_f32 v[36:37], v[36:37], 1.0 op_sel_hi:[1,0]
	v_div_fixup_f32 v42, v44, v46, v42
	v_div_scale_f32 v46, s[30:31], v37, v37, v33
	v_rcp_f32_e32 v47, v46
	v_add_co_u32_e32 v44, vcc, s63, v116
	v_cvt_pk_bf16_f32 v40, v40, v41
	v_cvt_pk_bf16_f32 v41, v42, v43
	v_addc_co_u32_e32 v45, vcc, 0, v117, vcc
	global_store_dwordx2 v[44:45], v[40:41], off
	v_fma_f32 v40, -v46, v47, 1.0
	v_fmac_f32_e32 v47, v40, v47
	v_div_scale_f32 v40, vcc, v33, v37, v33
	v_mul_f32_e32 v41, v40, v47
	v_fma_f32 v44, -v46, v41, v40
	v_fmac_f32_e32 v41, v44, v47
	v_div_scale_f32 v44, s[30:31], v36, v36, v32
	v_rcp_f32_e32 v45, v44
	v_fma_f32 v40, -v46, v41, v40
	v_mul_f32_e32 v38, 0xbfb8aa3b, v38
	v_mul_f32_e32 v39, 0xbfb8aa3b, v39
	v_div_fmas_f32 v40, v40, v47, v41
	v_exp_f32_e32 v38, v38
	v_exp_f32_e32 v39, v39
	v_div_fixup_f32 v33, v40, v37, v33
	v_fma_f32 v37, -v44, v45, 1.0
	v_fmac_f32_e32 v45, v37, v45
	v_div_scale_f32 v37, vcc, v32, v36, v32
	v_mul_f32_e32 v40, v37, v45
	v_fma_f32 v41, -v44, v40, v37
	v_pk_add_f32 v[38:39], v[38:39], 1.0 op_sel_hi:[1,0]
	v_fmac_f32_e32 v40, v41, v45
	v_div_scale_f32 v41, s[30:31], v39, v39, v35
	v_fma_f32 v37, -v44, v40, v37
	v_rcp_f32_e32 v44, v41
	v_div_fmas_f32 v37, v37, v45, v40
	v_div_fixup_f32 v32, v37, v36, v32
	v_mul_f32_e32 v28, 0xbfb8aa3b, v28
	v_fma_f32 v36, -v41, v44, 1.0
	v_fmac_f32_e32 v44, v36, v44
	v_div_scale_f32 v36, vcc, v35, v39, v35
	v_mul_f32_e32 v37, v36, v44
	v_fma_f32 v40, -v41, v37, v36
	v_fmac_f32_e32 v37, v40, v44
	v_div_scale_f32 v40, s[30:31], v38, v38, v34
	v_fma_f32 v36, -v41, v37, v36
	v_rcp_f32_e32 v41, v40
	v_div_fmas_f32 v36, v36, v44, v37
	v_div_fixup_f32 v35, v36, v39, v35
	v_mul_f32_e32 v29, 0xbfb8aa3b, v29
	v_fma_f32 v36, -v40, v41, 1.0
	v_fmac_f32_e32 v41, v36, v41
	v_div_scale_f32 v36, vcc, v34, v38, v34
	v_mul_f32_e32 v37, v36, v41
	v_exp_f32_e32 v28, v28
	v_exp_f32_e32 v29, v29
	v_fma_f32 v39, -v40, v37, v36
	v_fmac_f32_e32 v37, v39, v41
	v_fma_f32 v36, -v40, v37, v36
	v_div_fmas_f32 v36, v36, v41, v37
	v_pk_add_f32 v[28:29], v[28:29], 1.0 op_sel_hi:[1,0]
	v_div_fixup_f32 v34, v36, v38, v34
	v_div_scale_f32 v36, s[30:31], v29, v29, v25
	v_rcp_f32_e32 v37, v36
	v_lshl_add_u64 v[42:43], v[116:117], 0, s[10:11]
	v_cvt_pk_bf16_f32 v32, v32, v33
	v_cvt_pk_bf16_f32 v33, v34, v35
	global_store_dwordx2 v[42:43], v[32:33], off offset:128
	v_fma_f32 v32, -v36, v37, 1.0
	v_fmac_f32_e32 v37, v32, v37
	v_div_scale_f32 v32, vcc, v25, v29, v25
	v_mul_f32_e32 v33, v32, v37
	v_fma_f32 v34, -v36, v33, v32
	v_fmac_f32_e32 v33, v34, v37
	v_div_scale_f32 v34, s[30:31], v28, v28, v24
	v_rcp_f32_e32 v35, v34
	v_fma_f32 v32, -v36, v33, v32
	v_mul_f32_e32 v30, 0xbfb8aa3b, v30
	v_mul_f32_e32 v31, 0xbfb8aa3b, v31
	v_div_fmas_f32 v32, v32, v37, v33
	v_exp_f32_e32 v30, v30
	v_exp_f32_e32 v31, v31
	v_div_fixup_f32 v25, v32, v29, v25
	v_fma_f32 v29, -v34, v35, 1.0
	v_fmac_f32_e32 v35, v29, v35
	v_div_scale_f32 v29, vcc, v24, v28, v24
	v_mul_f32_e32 v32, v29, v35
	v_fma_f32 v33, -v34, v32, v29
	v_pk_add_f32 v[30:31], v[30:31], 1.0 op_sel_hi:[1,0]
	v_fmac_f32_e32 v32, v33, v35
	v_div_scale_f32 v33, s[30:31], v31, v31, v27
	v_fma_f32 v29, -v34, v32, v29
	v_rcp_f32_e32 v34, v33
	v_div_fmas_f32 v29, v29, v35, v32
	v_div_fixup_f32 v24, v29, v28, v24
	v_mul_f32_e32 v20, 0xbfb8aa3b, v20
	v_fma_f32 v28, -v33, v34, 1.0
	v_fmac_f32_e32 v34, v28, v34
	v_div_scale_f32 v28, vcc, v27, v31, v27
	v_mul_f32_e32 v29, v28, v34
	v_fma_f32 v32, -v33, v29, v28
	v_fmac_f32_e32 v29, v32, v34
	v_div_scale_f32 v32, s[30:31], v30, v30, v26
	v_fma_f32 v28, -v33, v29, v28
	v_rcp_f32_e32 v33, v32
	v_div_fmas_f32 v28, v28, v34, v29
	v_div_fixup_f32 v27, v28, v31, v27
	v_mul_f32_e32 v21, 0xbfb8aa3b, v21
	v_fma_f32 v28, -v32, v33, 1.0
	v_fmac_f32_e32 v33, v28, v33
	v_div_scale_f32 v28, vcc, v26, v30, v26
	v_mul_f32_e32 v29, v28, v33
	v_exp_f32_e32 v20, v20
	v_exp_f32_e32 v21, v21
	v_fma_f32 v31, -v32, v29, v28
	v_fmac_f32_e32 v29, v31, v33
	v_fma_f32 v28, -v32, v29, v28
	v_div_fmas_f32 v28, v28, v33, v29
	v_pk_add_f32 v[20:21], v[20:21], 1.0 op_sel_hi:[1,0]
	v_div_fixup_f32 v26, v28, v30, v26
	v_div_scale_f32 v30, s[30:31], v21, v21, v17
	v_rcp_f32_e32 v31, v30
	v_add_co_u32_e32 v28, vcc, s70, v116
	v_cvt_pk_bf16_f32 v24, v24, v25
	v_cvt_pk_bf16_f32 v25, v26, v27
	v_addc_co_u32_e32 v29, vcc, 0, v117, vcc
	global_store_dwordx2 v[28:29], v[24:25], off
	v_fma_f32 v24, -v30, v31, 1.0
	v_fmac_f32_e32 v31, v24, v31
	v_div_scale_f32 v24, vcc, v17, v21, v17
	v_mul_f32_e32 v25, v24, v31
	v_fma_f32 v28, -v30, v25, v24
	v_fmac_f32_e32 v25, v28, v31
	v_div_scale_f32 v28, s[30:31], v20, v20, v16
	v_rcp_f32_e32 v29, v28
	v_fma_f32 v24, -v30, v25, v24
	v_mul_f32_e32 v22, 0xbfb8aa3b, v22
	v_mul_f32_e32 v23, 0xbfb8aa3b, v23
	v_div_fmas_f32 v24, v24, v31, v25
	v_exp_f32_e32 v22, v22
	v_exp_f32_e32 v23, v23
	v_div_fixup_f32 v17, v24, v21, v17
	v_fma_f32 v21, -v28, v29, 1.0
	v_fmac_f32_e32 v29, v21, v29
	v_div_scale_f32 v21, vcc, v16, v20, v16
	v_mul_f32_e32 v24, v21, v29
	v_fma_f32 v25, -v28, v24, v21
	v_pk_add_f32 v[22:23], v[22:23], 1.0 op_sel_hi:[1,0]
	v_fmac_f32_e32 v24, v25, v29
	v_div_scale_f32 v25, s[30:31], v23, v23, v19
	v_fma_f32 v21, -v28, v24, v21
	v_rcp_f32_e32 v28, v25
	v_div_fmas_f32 v21, v21, v29, v24
	v_div_fixup_f32 v16, v21, v20, v16
	v_mul_f32_e32 v12, 0xbfb8aa3b, v12
	v_fma_f32 v20, -v25, v28, 1.0
	v_fmac_f32_e32 v28, v20, v28
	v_div_scale_f32 v20, vcc, v19, v23, v19
	v_mul_f32_e32 v21, v20, v28
	v_fma_f32 v24, -v25, v21, v20
	v_fmac_f32_e32 v21, v24, v28
	v_div_scale_f32 v24, s[30:31], v22, v22, v18
	v_fma_f32 v20, -v25, v21, v20
	v_rcp_f32_e32 v25, v24
	v_div_fmas_f32 v20, v20, v28, v21
	v_div_fixup_f32 v19, v20, v23, v19
	v_mul_f32_e32 v13, 0xbfb8aa3b, v13
	v_fma_f32 v20, -v24, v25, 1.0
	v_fmac_f32_e32 v25, v20, v25
	v_div_scale_f32 v20, vcc, v18, v22, v18
	v_mul_f32_e32 v21, v20, v25
	v_exp_f32_e32 v12, v12
	v_exp_f32_e32 v13, v13
	v_fma_f32 v23, -v24, v21, v20
	v_fmac_f32_e32 v21, v23, v25
	v_fma_f32 v20, -v24, v21, v20
	v_div_fmas_f32 v20, v20, v25, v21
	v_pk_add_f32 v[12:13], v[12:13], 1.0 op_sel_hi:[1,0]
	v_div_fixup_f32 v18, v20, v22, v18
	v_div_scale_f32 v20, s[30:31], v13, v13, v9
	v_rcp_f32_e32 v21, v20
	v_lshl_add_u64 v[26:27], v[116:117], 0, s[12:13]
	v_cvt_pk_bf16_f32 v16, v16, v17
	v_cvt_pk_bf16_f32 v17, v18, v19
	global_store_dwordx2 v[26:27], v[16:17], off offset:128
	v_fma_f32 v16, -v20, v21, 1.0
	v_fmac_f32_e32 v21, v16, v21
	v_div_scale_f32 v16, vcc, v9, v13, v9
	v_mul_f32_e32 v17, v16, v21
	v_fma_f32 v18, -v20, v17, v16
	v_fmac_f32_e32 v17, v18, v21
	v_div_scale_f32 v18, s[30:31], v12, v12, v8
	v_rcp_f32_e32 v19, v18
	v_fma_f32 v16, -v20, v17, v16
	v_mul_f32_e32 v14, 0xbfb8aa3b, v14
	v_mul_f32_e32 v15, 0xbfb8aa3b, v15
	v_div_fmas_f32 v16, v16, v21, v17
	v_exp_f32_e32 v14, v14
	v_exp_f32_e32 v15, v15
	v_div_fixup_f32 v9, v16, v13, v9
	v_fma_f32 v13, -v18, v19, 1.0
	v_fmac_f32_e32 v19, v13, v19
	v_div_scale_f32 v13, vcc, v8, v12, v8
	v_mul_f32_e32 v16, v13, v19
	v_fma_f32 v17, -v18, v16, v13
	v_pk_add_f32 v[14:15], v[14:15], 1.0 op_sel_hi:[1,0]
	v_fmac_f32_e32 v16, v17, v19
	v_div_scale_f32 v17, s[30:31], v15, v15, v11
	v_fma_f32 v13, -v18, v16, v13
	v_rcp_f32_e32 v18, v17
	v_div_fmas_f32 v13, v13, v19, v16
	v_div_fixup_f32 v8, v13, v12, v8
	v_mul_f32_e32 v4, 0xbfb8aa3b, v4
	v_fma_f32 v12, -v17, v18, 1.0
	v_fmac_f32_e32 v18, v12, v18
	v_div_scale_f32 v12, vcc, v11, v15, v11
	v_mul_f32_e32 v13, v12, v18
	v_fma_f32 v16, -v17, v13, v12
	v_fmac_f32_e32 v13, v16, v18
	v_div_scale_f32 v16, s[30:31], v14, v14, v10
	v_fma_f32 v12, -v17, v13, v12
	v_rcp_f32_e32 v17, v16
	v_div_fmas_f32 v12, v12, v18, v13
	v_div_fixup_f32 v11, v12, v15, v11
	v_mul_f32_e32 v5, 0xbfb8aa3b, v5
	v_fma_f32 v12, -v16, v17, 1.0
	v_fmac_f32_e32 v17, v12, v17
	v_div_scale_f32 v12, vcc, v10, v14, v10
	v_mul_f32_e32 v13, v12, v17
	v_exp_f32_e32 v4, v4
	v_exp_f32_e32 v5, v5
	v_fma_f32 v15, -v16, v13, v12
	v_fmac_f32_e32 v13, v15, v17
	v_fma_f32 v12, -v16, v13, v12
	v_div_fmas_f32 v12, v12, v17, v13
	v_pk_add_f32 v[4:5], v[4:5], 1.0 op_sel_hi:[1,0]
	v_div_fixup_f32 v10, v12, v14, v10
	v_div_scale_f32 v14, s[30:31], v5, v5, v1
	v_rcp_f32_e32 v15, v14
	v_add_co_u32_e32 v12, vcc, s71, v116
	v_cvt_pk_bf16_f32 v8, v8, v9
	v_cvt_pk_bf16_f32 v9, v10, v11
	v_addc_co_u32_e32 v13, vcc, 0, v117, vcc
	global_store_dwordx2 v[12:13], v[8:9], off
	v_fma_f32 v8, -v14, v15, 1.0
	v_fmac_f32_e32 v15, v8, v15
	v_div_scale_f32 v8, vcc, v1, v5, v1
	v_mul_f32_e32 v9, v8, v15
	v_fma_f32 v12, -v14, v9, v8
	v_fmac_f32_e32 v9, v12, v15
	v_div_scale_f32 v12, s[30:31], v4, v4, v0
	v_rcp_f32_e32 v13, v12
	v_fma_f32 v8, -v14, v9, v8
	v_mul_f32_e32 v6, 0xbfb8aa3b, v6
	v_mul_f32_e32 v7, 0xbfb8aa3b, v7
	v_div_fmas_f32 v8, v8, v15, v9
	v_exp_f32_e32 v6, v6
	v_exp_f32_e32 v7, v7
	v_div_fixup_f32 v1, v8, v5, v1
	v_fma_f32 v5, -v12, v13, 1.0
	v_fmac_f32_e32 v13, v5, v13
	v_div_scale_f32 v5, vcc, v0, v4, v0
	v_mul_f32_e32 v8, v5, v13
	v_fma_f32 v9, -v12, v8, v5
	v_pk_add_f32 v[6:7], v[6:7], 1.0 op_sel_hi:[1,0]
	v_fmac_f32_e32 v8, v9, v13
	v_div_scale_f32 v9, s[30:31], v7, v7, v3
	v_fma_f32 v5, -v12, v8, v5
	v_rcp_f32_e32 v12, v9
	v_div_fmas_f32 v5, v5, v13, v8
	v_div_fixup_f32 v0, v5, v4, v0
	v_lshl_add_u64 v[10:11], v[116:117], 0, s[14:15]
	v_fma_f32 v4, -v9, v12, 1.0
	v_fmac_f32_e32 v12, v4, v12
	v_div_scale_f32 v4, vcc, v3, v7, v3
	v_mul_f32_e32 v5, v4, v12
	v_fma_f32 v8, -v9, v5, v4
	v_fmac_f32_e32 v5, v8, v12
	v_div_scale_f32 v8, s[30:31], v6, v6, v2
	v_fma_f32 v4, -v9, v5, v4
	v_rcp_f32_e32 v9, v8
	v_div_fmas_f32 v4, v4, v12, v5
	v_div_fixup_f32 v3, v4, v7, v3
	v_cvt_pk_bf16_f32 v0, v0, v1
	v_fma_f32 v4, -v8, v9, 1.0
	v_fmac_f32_e32 v9, v4, v9
	v_div_scale_f32 v4, vcc, v2, v6, v2
	v_mul_f32_e32 v5, v4, v9
	v_fma_f32 v7, -v8, v5, v4
	v_fmac_f32_e32 v5, v7, v9
	v_fma_f32 v4, -v8, v5, v4
	v_div_fmas_f32 v4, v4, v9, v5
	v_div_fixup_f32 v2, v4, v6, v2
	v_cvt_pk_bf16_f32 v1, v2, v3
	s_and_b64 vcc, exec, s[4:5]
	s_mov_b32 s72, s16
	s_mov_b32 s28, s18
	s_mov_b64 s[34:35], s[26:27]
	s_mov_b64 s[30:31], s[20:21]
	global_store_dwordx2 v[10:11], v[0:1], off offset:128
	s_cbranch_vccz .LBB0_1134
	s_waitcnt vmcnt(0)
	s_cmpk_gt_u32 s40, 0xff
	s_cbranch_scc1 .LBB0_1145
	s_barrier

.LBB0_1291:
	ds_read_b128 v[154:157], v151
	ds_read_b128 v[158:161], v151 offset:1024
	ds_read_b128 v[162:165], v151 offset:2048
	ds_read_b128 v[166:169], v151 offset:3072
	s_add_u32 s36, s34, 0xfffc0080
	s_addc_u32 s37, s35, -1
	s_cmp_eq_u32 s79, 12
	s_cselect_b32 s39, s21, s37
	s_cselect_b32 s38, s75, s36
	s_cselect_b32 s37, s19, s78
	s_cselect_b32 s36, s76, s77
	v_lshl_add_u64 v[202:203], s[34:35], 0, v[138:139]
	s_add_i32 m0, s31, 0xc000
	ds_read_b128 v[170:173], v152
	ds_read_b128 v[174:177], v152 offset:1024
	ds_read_b128 v[178:181], v152 offset:2048
	ds_read_b128 v[182:185], v152 offset:3072
	ds_read_b128 v[186:189], v152 offset:4096
	ds_read_b128 v[190:193], v152 offset:5120
	ds_read_b128 v[194:197], v152 offset:6144
	ds_read_b128 v[198:201], v152 offset:7168
	global_load_lds_dwordx4 v[202:203], off
	v_lshl_add_u64 v[202:203], s[34:35], 0, v[140:141]
	s_add_i32 m0, s31, 0xe000
	s_nop 0
	global_load_lds_dwordx4 v[202:203], off
	s_barrier
	s_waitcnt lgkmcnt(0)
	s_waitcnt lgkmcnt(0)
	v_mfma_f32_16x16x32_bf16 v[124:127], v[154:157], v[170:173], v[124:127]
	v_mfma_f32_16x16x32_bf16 v[120:123], v[162:165], v[170:173], v[120:123]
	v_mfma_f32_16x16x32_bf16 v[108:111], v[154:157], v[178:181], v[108:111]
	v_mfma_f32_16x16x32_bf16 v[104:107], v[162:165], v[178:181], v[104:107]
	v_mfma_f32_16x16x32_bf16 v[92:95], v[154:157], v[186:189], v[92:95]
	v_mfma_f32_16x16x32_bf16 v[88:91], v[162:165], v[186:189], v[88:91]
	v_mfma_f32_16x16x32_bf16 v[76:79], v[154:157], v[194:197], v[76:79]
	v_mfma_f32_16x16x32_bf16 v[72:75], v[162:165], v[194:197], v[72:75]
	v_mfma_f32_16x16x32_bf16 v[124:127], v[158:161], v[174:177], v[124:127]
	v_mfma_f32_16x16x32_bf16 v[120:123], v[166:169], v[174:177], v[120:123]
	v_mfma_f32_16x16x32_bf16 v[108:111], v[158:161], v[182:185], v[108:111]
	v_mfma_f32_16x16x32_bf16 v[104:107], v[166:169], v[182:185], v[104:107]
	v_mfma_f32_16x16x32_bf16 v[92:95], v[158:161], v[190:193], v[92:95]
	v_mfma_f32_16x16x32_bf16 v[88:91], v[166:169], v[190:193], v[88:91]
	v_mfma_f32_16x16x32_bf16 v[76:79], v[158:161], v[198:201], v[76:79]
	v_mfma_f32_16x16x32_bf16 v[72:75], v[166:169], v[198:201], v[72:75]
	s_barrier
	s_add_i32 s80, s62, s52
	v_lshl_add_u64 v[218:219], s[36:37], 0, v[132:133]
	s_mov_b32 m0, s80
	ds_read_b128 v[202:205], v153
	ds_read_b128 v[206:209], v153 offset:1024
	ds_read_b128 v[210:213], v153 offset:2048
	ds_read_b128 v[214:217], v153 offset:3072
	global_load_lds_dwordx4 v[218:219], off
	v_lshl_add_u64 v[220:221], s[36:37], 0, v[136:137]
	s_add_i32 m0, s80, 0x2000
	s_nop 0
	global_load_lds_dwordx4 v[220:221], off
	s_barrier
	s_waitcnt lgkmcnt(0)
	s_waitcnt lgkmcnt(0)
	v_mfma_f32_16x16x32_bf16 v[116:119], v[202:205], v[170:173], v[116:119]
	v_mfma_f32_16x16x32_bf16 v[112:115], v[210:213], v[170:173], v[112:115]
	v_mfma_f32_16x16x32_bf16 v[100:103], v[202:205], v[178:181], v[100:103]
	v_mfma_f32_16x16x32_bf16 v[96:99], v[210:213], v[178:181], v[96:99]
	v_mfma_f32_16x16x32_bf16 v[84:87], v[202:205], v[186:189], v[84:87]
	v_mfma_f32_16x16x32_bf16 v[80:83], v[210:213], v[186:189], v[80:83]
	v_mfma_f32_16x16x32_bf16 v[68:71], v[202:205], v[194:197], v[68:71]
	v_mfma_f32_16x16x32_bf16 v[64:67], v[210:213], v[194:197], v[64:67]
	v_mfma_f32_16x16x32_bf16 v[116:119], v[206:209], v[174:177], v[116:119]
	v_mfma_f32_16x16x32_bf16 v[112:115], v[214:217], v[174:177], v[112:115]
	v_mfma_f32_16x16x32_bf16 v[100:103], v[206:209], v[182:185], v[100:103]
	v_mfma_f32_16x16x32_bf16 v[96:99], v[214:217], v[182:185], v[96:99]
	v_mfma_f32_16x16x32_bf16 v[84:87], v[206:209], v[190:193], v[84:87]
	v_mfma_f32_16x16x32_bf16 v[80:83], v[214:217], v[190:193], v[80:83]
	v_mfma_f32_16x16x32_bf16 v[68:71], v[206:209], v[198:201], v[68:71]
	v_mfma_f32_16x16x32_bf16 v[64:67], v[214:217], v[198:201], v[64:67]
	s_mov_b32 m0, s31
	v_lshl_add_u64 v[222:223], s[38:39], 0, v[130:131]
	s_barrier
	ds_read_b128 v[170:173], v152 offset:16384
	ds_read_b128 v[174:177], v152 offset:17408
	ds_read_b128 v[178:181], v152 offset:18432
	ds_read_b128 v[182:185], v152 offset:19456
	ds_read_b128 v[186:189], v152 offset:20480
	ds_read_b128 v[190:193], v152 offset:21504
	ds_read_b128 v[194:197], v152 offset:22528
	ds_read_b128 v[198:201], v152 offset:23552
	global_load_lds_dwordx4 v[222:223], off
	v_lshl_add_u64 v[224:225], s[38:39], 0, v[134:135]
	s_mov_b32 m0, s53
	s_nop 0
	global_load_lds_dwordx4 v[224:225], off
	s_barrier
	s_waitcnt lgkmcnt(0)
	s_waitcnt lgkmcnt(0)
	v_mfma_f32_16x16x32_bf16 v[60:63], v[154:157], v[170:173], v[60:63]
	v_mfma_f32_16x16x32_bf16 v[56:59], v[162:165], v[170:173], v[56:59]
	v_mfma_f32_16x16x32_bf16 v[44:47], v[154:157], v[178:181], v[44:47]
	v_mfma_f32_16x16x32_bf16 v[40:43], v[162:165], v[178:181], v[40:43]
	v_mfma_f32_16x16x32_bf16 v[28:31], v[154:157], v[186:189], v[28:31]
	v_mfma_f32_16x16x32_bf16 v[24:27], v[162:165], v[186:189], v[24:27]
	v_mfma_f32_16x16x32_bf16 v[12:15], v[154:157], v[194:197], v[12:15]
	v_mfma_f32_16x16x32_bf16 v[8:11], v[162:165], v[194:197], v[8:11]
	v_mfma_f32_16x16x32_bf16 v[60:63], v[158:161], v[174:177], v[60:63]
	v_mfma_f32_16x16x32_bf16 v[56:59], v[166:169], v[174:177], v[56:59]
	v_mfma_f32_16x16x32_bf16 v[44:47], v[158:161], v[182:185], v[44:47]
	v_mfma_f32_16x16x32_bf16 v[40:43], v[166:169], v[182:185], v[40:43]
	v_mfma_f32_16x16x32_bf16 v[28:31], v[158:161], v[190:193], v[28:31]
	v_mfma_f32_16x16x32_bf16 v[24:27], v[166:169], v[190:193], v[24:27]
	v_mfma_f32_16x16x32_bf16 v[12:15], v[158:161], v[198:201], v[12:15]
	v_mfma_f32_16x16x32_bf16 v[8:11], v[166:169], v[198:201], v[8:11]
	s_barrier
	s_add_u32 s80, s36, 0x40000
	s_addc_u32 s81, s37, 0
	s_add_i32 s82, s63, s52
	v_lshl_add_u64 v[154:155], s[80:81], 0, v[132:133]
	s_mov_b32 m0, s82
	s_nop 0
	global_load_lds_dwordx4 v[154:155], off
	v_lshl_add_u64 v[154:155], s[80:81], 0, v[136:137]
	s_add_i32 m0, s82, 0x2000
	s_nop 0
	global_load_lds_dwordx4 v[154:155], off
	s_waitcnt vmcnt(6)
	s_barrier
	v_mfma_f32_16x16x32_bf16 v[52:55], v[202:205], v[170:173], v[52:55]
	v_mfma_f32_16x16x32_bf16 v[48:51], v[210:213], v[170:173], v[48:51]
	v_mfma_f32_16x16x32_bf16 v[36:39], v[202:205], v[178:181], v[36:39]
	v_mfma_f32_16x16x32_bf16 v[32:35], v[210:213], v[178:181], v[32:35]
	v_mfma_f32_16x16x32_bf16 v[20:23], v[202:205], v[186:189], v[20:23]
	v_mfma_f32_16x16x32_bf16 v[16:19], v[210:213], v[186:189], v[16:19]
	v_mfma_f32_16x16x32_bf16 v[4:7], v[202:205], v[194:197], v[4:7]
	v_mfma_f32_16x16x32_bf16 v[0:3], v[210:213], v[194:197], v[0:3]
	v_mfma_f32_16x16x32_bf16 v[52:55], v[206:209], v[174:177], v[52:55]
	v_mfma_f32_16x16x32_bf16 v[48:51], v[214:217], v[174:177], v[48:51]
	v_mfma_f32_16x16x32_bf16 v[36:39], v[206:209], v[182:185], v[36:39]
	v_mfma_f32_16x16x32_bf16 v[32:35], v[214:217], v[182:185], v[32:35]
	v_mfma_f32_16x16x32_bf16 v[20:23], v[206:209], v[190:193], v[20:23]
	v_mfma_f32_16x16x32_bf16 v[16:19], v[214:217], v[190:193], v[16:19]
	v_mfma_f32_16x16x32_bf16 v[4:7], v[206:209], v[198:201], v[4:7]
	v_mfma_f32_16x16x32_bf16 v[0:3], v[214:217], v[198:201], v[0:3]
	s_add_i32 s80, 0, 0x18000
	v_add_u32_e32 v166, s80, v149
	s_barrier
	ds_read_b128 v[154:157], v166
	ds_read_b128 v[158:161], v166 offset:1024
	ds_read_b128 v[162:165], v166 offset:2048
	ds_read_b128 v[166:169], v166 offset:3072
	s_add_u32 s38, s38, 0x40000
	s_addc_u32 s39, s39, 0
	s_mov_b32 m0, s54
	v_lshl_add_u64 v[202:203], s[38:39], 0, v[130:131]
	ds_read_b128 v[170:173], v152 offset:32768
	ds_read_b128 v[174:177], v152 offset:33792
	ds_read_b128 v[178:181], v152 offset:34816
	ds_read_b128 v[182:185], v152 offset:35840
	ds_read_b128 v[186:189], v152 offset:36864
	ds_read_b128 v[190:193], v152 offset:37888
	ds_read_b128 v[194:197], v152 offset:38912
	ds_read_b128 v[198:201], v152 offset:39936
	global_load_lds_dwordx4 v[202:203], off
	v_lshl_add_u64 v[202:203], s[38:39], 0, v[134:135]
	s_mov_b32 m0, s55
	s_nop 0
	global_load_lds_dwordx4 v[202:203], off
	s_barrier
	s_waitcnt lgkmcnt(0)
	s_waitcnt lgkmcnt(0)
	v_mfma_f32_16x16x32_bf16 v[124:127], v[154:157], v[170:173], v[124:127]
	v_mfma_f32_16x16x32_bf16 v[120:123], v[162:165], v[170:173], v[120:123]
	v_mfma_f32_16x16x32_bf16 v[108:111], v[154:157], v[178:181], v[108:111]
	v_mfma_f32_16x16x32_bf16 v[104:107], v[162:165], v[178:181], v[104:107]
	v_mfma_f32_16x16x32_bf16 v[92:95], v[154:157], v[186:189], v[92:95]
	v_mfma_f32_16x16x32_bf16 v[88:91], v[162:165], v[186:189], v[88:91]
	v_mfma_f32_16x16x32_bf16 v[76:79], v[154:157], v[194:197], v[76:79]
	v_mfma_f32_16x16x32_bf16 v[72:75], v[162:165], v[194:197], v[72:75]
	v_mfma_f32_16x16x32_bf16 v[124:127], v[158:161], v[174:177], v[124:127]
	v_mfma_f32_16x16x32_bf16 v[120:123], v[166:169], v[174:177], v[120:123]
	v_mfma_f32_16x16x32_bf16 v[108:111], v[158:161], v[182:185], v[108:111]
	v_mfma_f32_16x16x32_bf16 v[104:107], v[166:169], v[182:185], v[104:107]
	v_mfma_f32_16x16x32_bf16 v[92:95], v[158:161], v[190:193], v[92:95]
	v_mfma_f32_16x16x32_bf16 v[88:91], v[166:169], v[190:193], v[88:91]
	v_mfma_f32_16x16x32_bf16 v[76:79], v[158:161], v[198:201], v[76:79]
	v_mfma_f32_16x16x32_bf16 v[72:75], v[166:169], v[198:201], v[72:75]
	s_barrier
	s_add_i32 s38, 0, 0x1c000
	s_add_i32 s39, s80, s52
	v_add_u32_e32 v214, s38, v149
	v_lshl_add_u64 v[218:219], v[218:219], 0, s[8:9]
	s_mov_b32 m0, s39
	ds_read_b128 v[202:205], v214
	ds_read_b128 v[206:209], v214 offset:1024
	ds_read_b128 v[210:213], v214 offset:2048
	ds_read_b128 v[214:217], v214 offset:3072
	global_load_lds_dwordx4 v[218:219], off
	v_lshl_add_u64 v[218:219], v[220:221], 0, s[8:9]
	s_add_i32 m0, s39, 0x2000
	s_nop 0
	global_load_lds_dwordx4 v[218:219], off
	s_barrier
	s_waitcnt lgkmcnt(0)
	s_waitcnt lgkmcnt(0)
	v_mfma_f32_16x16x32_bf16 v[116:119], v[202:205], v[170:173], v[116:119]
	v_mfma_f32_16x16x32_bf16 v[112:115], v[210:213], v[170:173], v[112:115]
	v_mfma_f32_16x16x32_bf16 v[100:103], v[202:205], v[178:181], v[100:103]
	v_mfma_f32_16x16x32_bf16 v[96:99], v[210:213], v[178:181], v[96:99]
	v_mfma_f32_16x16x32_bf16 v[84:87], v[202:205], v[186:189], v[84:87]
	v_mfma_f32_16x16x32_bf16 v[80:83], v[210:213], v[186:189], v[80:83]
	v_mfma_f32_16x16x32_bf16 v[68:71], v[202:205], v[194:197], v[68:71]
	v_mfma_f32_16x16x32_bf16 v[64:67], v[210:213], v[194:197], v[64:67]
	v_mfma_f32_16x16x32_bf16 v[116:119], v[206:209], v[174:177], v[116:119]
	v_mfma_f32_16x16x32_bf16 v[112:115], v[214:217], v[174:177], v[112:115]
	v_mfma_f32_16x16x32_bf16 v[100:103], v[206:209], v[182:185], v[100:103]
	v_mfma_f32_16x16x32_bf16 v[96:99], v[214:217], v[182:185], v[96:99]
	v_mfma_f32_16x16x32_bf16 v[84:87], v[206:209], v[190:193], v[84:87]
	v_mfma_f32_16x16x32_bf16 v[80:83], v[214:217], v[190:193], v[80:83]
	v_mfma_f32_16x16x32_bf16 v[68:71], v[206:209], v[198:201], v[68:71]
	v_mfma_f32_16x16x32_bf16 v[64:67], v[214:217], v[198:201], v[64:67]
	s_mov_b32 m0, s57
	v_lshl_add_u64 v[218:219], v[222:223], 0, s[8:9]
	s_barrier
	ds_read_b128 v[170:173], v152 offset:49152
	ds_read_b128 v[174:177], v152 offset:50176
	ds_read_b128 v[178:181], v152 offset:51200
	ds_read_b128 v[182:185], v152 offset:52224
	ds_read_b128 v[186:189], v152 offset:53248
	ds_read_b128 v[190:193], v152 offset:54272
	ds_read_b128 v[194:197], v152 offset:55296
	ds_read_b128 v[198:201], v152 offset:56320
	global_load_lds_dwordx4 v[218:219], off
	v_lshl_add_u64 v[218:219], v[224:225], 0, s[8:9]
	s_mov_b32 m0, s60
	s_nop 0
	global_load_lds_dwordx4 v[218:219], off
	s_barrier
	s_waitcnt lgkmcnt(0)
	s_waitcnt lgkmcnt(0)
	v_mfma_f32_16x16x32_bf16 v[60:63], v[154:157], v[170:173], v[60:63]
	v_mfma_f32_16x16x32_bf16 v[56:59], v[162:165], v[170:173], v[56:59]
	v_mfma_f32_16x16x32_bf16 v[44:47], v[154:157], v[178:181], v[44:47]
	v_mfma_f32_16x16x32_bf16 v[40:43], v[162:165], v[178:181], v[40:43]
	v_mfma_f32_16x16x32_bf16 v[28:31], v[154:157], v[186:189], v[28:31]
	v_mfma_f32_16x16x32_bf16 v[24:27], v[162:165], v[186:189], v[24:27]
	v_mfma_f32_16x16x32_bf16 v[12:15], v[154:157], v[194:197], v[12:15]
	v_mfma_f32_16x16x32_bf16 v[8:11], v[162:165], v[194:197], v[8:11]
	v_mfma_f32_16x16x32_bf16 v[60:63], v[158:161], v[174:177], v[60:63]
	v_mfma_f32_16x16x32_bf16 v[56:59], v[166:169], v[174:177], v[56:59]
	v_mfma_f32_16x16x32_bf16 v[44:47], v[158:161], v[182:185], v[44:47]
	v_mfma_f32_16x16x32_bf16 v[40:43], v[166:169], v[182:185], v[40:43]
	v_mfma_f32_16x16x32_bf16 v[28:31], v[158:161], v[190:193], v[28:31]
	v_mfma_f32_16x16x32_bf16 v[24:27], v[166:169], v[190:193], v[24:27]
	v_mfma_f32_16x16x32_bf16 v[12:15], v[158:161], v[198:201], v[12:15]
	v_mfma_f32_16x16x32_bf16 v[8:11], v[166:169], v[198:201], v[8:11]
	s_barrier
	s_add_u32 s36, s36, 0x40080
	s_addc_u32 s37, s37, 0
	s_add_i32 s38, s38, s52
	v_lshl_add_u64 v[154:155], s[36:37], 0, v[132:133]
	s_mov_b32 m0, s38
	s_nop 0
	global_load_lds_dwordx4 v[154:155], off
	v_lshl_add_u64 v[154:155], s[36:37], 0, v[136:137]
	s_add_i32 m0, s38, 0x2000
	s_nop 0
	global_load_lds_dwordx4 v[154:155], off
	s_waitcnt vmcnt(6)
	s_barrier
	v_mfma_f32_16x16x32_bf16 v[52:55], v[202:205], v[170:173], v[52:55]
	v_mfma_f32_16x16x32_bf16 v[48:51], v[210:213], v[170:173], v[48:51]
	v_mfma_f32_16x16x32_bf16 v[36:39], v[202:205], v[178:181], v[36:39]
	v_mfma_f32_16x16x32_bf16 v[32:35], v[210:213], v[178:181], v[32:35]
	v_mfma_f32_16x16x32_bf16 v[20:23], v[202:205], v[186:189], v[20:23]
	v_mfma_f32_16x16x32_bf16 v[16:19], v[210:213], v[186:189], v[16:19]
	v_mfma_f32_16x16x32_bf16 v[4:7], v[202:205], v[194:197], v[4:7]
	v_mfma_f32_16x16x32_bf16 v[0:3], v[210:213], v[194:197], v[0:3]
	v_mfma_f32_16x16x32_bf16 v[52:55], v[206:209], v[174:177], v[52:55]
	v_mfma_f32_16x16x32_bf16 v[48:51], v[214:217], v[174:177], v[48:51]
	v_mfma_f32_16x16x32_bf16 v[36:39], v[206:209], v[182:185], v[36:39]
	v_mfma_f32_16x16x32_bf16 v[32:35], v[214:217], v[182:185], v[32:35]
	v_mfma_f32_16x16x32_bf16 v[20:23], v[206:209], v[190:193], v[20:23]
	v_mfma_f32_16x16x32_bf16 v[16:19], v[214:217], v[190:193], v[16:19]
	v_mfma_f32_16x16x32_bf16 v[4:7], v[206:209], v[198:201], v[4:7]
	v_mfma_f32_16x16x32_bf16 v[0:3], v[214:217], v[198:201], v[0:3]
	s_add_i32 s79, s79, 2
	s_add_u32 s34, s34, 0x100
	s_addc_u32 s35, s35, 0
	s_add_u32 s77, s77, 0x100
	s_addc_u32 s78, s78, 0
	s_cmp_gt_u32 s79, 13
	s_barrier
	s_cbranch_scc0 .LBB0_1291
	v_lshl_add_u32 v154, s30, 8, v148
	v_max_f32_e32 v126, v126, v126
	v_max_f32_e32 v127, v127, v127
	v_lshl_or_b32 v156, s74, 8, v150
	v_ashrrev_i32_e32 v155, 31, v154
	v_max_f32_e32 v124, v124, v124
	v_max_f32_e32 v120, v120, v120
	v_max_f32_e32 v125, v125, v125
	v_max_f32_e32 v121, v121, v121
	v_max_f32_e32 v126, 0, v126
	v_max_f32_e32 v122, v122, v122
	v_max_f32_e32 v127, 0, v127
	v_max_f32_e32 v123, v123, v123
	v_lshlrev_b64 v[158:159], 13, v[154:155]
	v_max_f32_e32 v124, 0, v124
	v_max_f32_e32 v120, 0, v120
	v_max_f32_e32 v125, 0, v125
	v_max_f32_e32 v121, 0, v121
	v_max_f32_e32 v122, 0, v122
	v_max_f32_e32 v123, 0, v123
	v_pk_mul_f32 v[126:127], v[126:127], v[126:127]
	v_ashrrev_i32_e32 v157, 31, v156
	v_lshl_add_u64 v[158:159], s[46:47], 0, v[158:159]
	v_pk_mul_f32 v[124:125], v[124:125], v[124:125]
	v_pk_mul_f32 v[120:121], v[120:121], v[120:121]
	v_pk_mul_f32 v[160:161], v[122:123], v[122:123]
	v_cvt_pk_bf16_f32 v123, v126, v127
	v_lshlrev_b64 v[126:127], 1, v[156:157]
	v_max_f32_e32 v112, v112, v112
	v_max_f32_e32 v113, v113, v113
	v_cvt_pk_bf16_f32 v122, v124, v125
	v_cvt_pk_bf16_f32 v124, v120, v121
	v_cvt_pk_bf16_f32 v125, v160, v161
	v_lshl_add_u64 v[120:121], v[158:159], 0, v[126:127]
	v_max_f32_e32 v112, 0, v112
	v_max_f32_e32 v113, 0, v113
	global_store_dwordx4 v[120:121], v[122:125], off
	v_max_f32_e32 v116, v116, v116
	v_max_f32_e32 v117, v117, v117
	v_pk_mul_f32 v[122:123], v[112:113], v[112:113]
	v_max_f32_e32 v113, v114, v114
	v_max_f32_e32 v112, v118, v118
	v_max_f32_e32 v114, 0, v113
	v_max_f32_e32 v113, v119, v119
	v_max_f32_e32 v115, v115, v115
	v_max_f32_e32 v116, 0, v116
	v_max_f32_e32 v117, 0, v117
	v_max_f32_e32 v112, 0, v112
	v_max_f32_e32 v113, 0, v113
	v_max_f32_e32 v115, 0, v115
	v_pk_mul_f32 v[116:117], v[116:117], v[116:117]
	v_pk_mul_f32 v[118:119], v[112:113], v[112:113]
	v_pk_mul_f32 v[124:125], v[114:115], v[114:115]
	v_max_f32_e32 v104, v104, v104
	v_max_f32_e32 v105, v105, v105
	v_cvt_pk_bf16_f32 v112, v116, v117
	v_cvt_pk_bf16_f32 v113, v118, v119
	v_cvt_pk_bf16_f32 v114, v122, v123
	v_cvt_pk_bf16_f32 v115, v124, v125
	v_max_f32_e32 v104, 0, v104
	v_max_f32_e32 v105, 0, v105
	global_store_dwordx4 v[120:121], v[112:115], off offset:256
	v_max_f32_e32 v108, v108, v108
	v_max_f32_e32 v109, v109, v109
	v_or_b32_e32 v112, 16, v154
	v_pk_mul_f32 v[114:115], v[104:105], v[104:105]
	v_max_f32_e32 v105, v106, v106
	v_ashrrev_i32_e32 v113, 31, v112
	v_max_f32_e32 v104, v110, v110
	v_max_f32_e32 v106, 0, v105
	v_max_f32_e32 v105, v111, v111
	v_max_f32_e32 v107, v107, v107
	v_lshlrev_b64 v[112:113], 13, v[112:113]
	v_max_f32_e32 v108, 0, v108
	v_max_f32_e32 v109, 0, v109
	v_max_f32_e32 v104, 0, v104
	v_max_f32_e32 v105, 0, v105
	v_max_f32_e32 v107, 0, v107
	v_lshl_add_u64 v[112:113], s[46:47], 0, v[112:113]
	v_pk_mul_f32 v[108:109], v[108:109], v[108:109]
	v_pk_mul_f32 v[110:111], v[104:105], v[104:105]
	v_pk_mul_f32 v[116:117], v[106:107], v[106:107]
	v_max_f32_e32 v96, v96, v96
	v_max_f32_e32 v97, v97, v97
	v_cvt_pk_bf16_f32 v104, v108, v109
	v_cvt_pk_bf16_f32 v105, v110, v111
	v_cvt_pk_bf16_f32 v106, v114, v115
	v_cvt_pk_bf16_f32 v107, v116, v117
	v_lshl_add_u64 v[108:109], v[112:113], 0, v[126:127]
	v_max_f32_e32 v96, 0, v96
	v_max_f32_e32 v97, 0, v97
	global_store_dwordx4 v[108:109], v[104:107], off
	v_max_f32_e32 v100, v100, v100
	v_max_f32_e32 v101, v101, v101
	v_pk_mul_f32 v[104:105], v[96:97], v[96:97]
	v_max_f32_e32 v97, v98, v98
	v_max_f32_e32 v96, v102, v102
	v_max_f32_e32 v98, 0, v97
	v_max_f32_e32 v97, v103, v103
	v_max_f32_e32 v99, v99, v99
	v_max_f32_e32 v100, 0, v100
	v_max_f32_e32 v101, 0, v101
	v_max_f32_e32 v96, 0, v96
	v_max_f32_e32 v97, 0, v97
	v_max_f32_e32 v99, 0, v99
	v_pk_mul_f32 v[100:101], v[100:101], v[100:101]
	v_pk_mul_f32 v[102:103], v[96:97], v[96:97]
	v_pk_mul_f32 v[106:107], v[98:99], v[98:99]
	v_max_f32_e32 v88, v88, v88
	v_max_f32_e32 v89, v89, v89
	v_cvt_pk_bf16_f32 v96, v100, v101
	v_cvt_pk_bf16_f32 v97, v102, v103
	v_cvt_pk_bf16_f32 v98, v104, v105
	v_cvt_pk_bf16_f32 v99, v106, v107
	v_max_f32_e32 v88, 0, v88
	v_max_f32_e32 v89, 0, v89
	global_store_dwordx4 v[108:109], v[96:99], off offset:256
	v_max_f32_e32 v92, v92, v92
	v_max_f32_e32 v93, v93, v93
	v_or_b32_e32 v96, 32, v154
	v_pk_mul_f32 v[98:99], v[88:89], v[88:89]
	v_max_f32_e32 v89, v90, v90
	v_ashrrev_i32_e32 v97, 31, v96
	v_max_f32_e32 v88, v94, v94
	v_max_f32_e32 v90, 0, v89
	v_max_f32_e32 v89, v95, v95
	v_max_f32_e32 v91, v91, v91
	v_lshlrev_b64 v[96:97], 13, v[96:97]
	v_max_f32_e32 v92, 0, v92
	v_max_f32_e32 v93, 0, v93
	v_max_f32_e32 v88, 0, v88
	v_max_f32_e32 v89, 0, v89
	v_max_f32_e32 v91, 0, v91
	v_lshl_add_u64 v[96:97], s[46:47], 0, v[96:97]
	v_pk_mul_f32 v[92:93], v[92:93], v[92:93]
	v_pk_mul_f32 v[94:95], v[88:89], v[88:89]
	v_pk_mul_f32 v[100:101], v[90:91], v[90:91]
	v_max_f32_e32 v80, v80, v80
	v_max_f32_e32 v81, v81, v81
	v_cvt_pk_bf16_f32 v88, v92, v93
	v_cvt_pk_bf16_f32 v89, v94, v95
	v_cvt_pk_bf16_f32 v90, v98, v99
	v_cvt_pk_bf16_f32 v91, v100, v101
	v_lshl_add_u64 v[92:93], v[96:97], 0, v[126:127]
	v_max_f32_e32 v80, 0, v80
	v_max_f32_e32 v81, 0, v81
	global_store_dwordx4 v[92:93], v[88:91], off
	v_max_f32_e32 v84, v84, v84
	v_max_f32_e32 v85, v85, v85
	v_pk_mul_f32 v[88:89], v[80:81], v[80:81]
	v_max_f32_e32 v81, v82, v82
	v_max_f32_e32 v80, v86, v86
	v_max_f32_e32 v82, 0, v81
	v_max_f32_e32 v81, v87, v87
	v_max_f32_e32 v83, v83, v83
	v_max_f32_e32 v84, 0, v84
	v_max_f32_e32 v85, 0, v85
	v_max_f32_e32 v80, 0, v80
	v_max_f32_e32 v81, 0, v81
	v_max_f32_e32 v83, 0, v83
	v_pk_mul_f32 v[84:85], v[84:85], v[84:85]
	v_pk_mul_f32 v[86:87], v[80:81], v[80:81]
	v_pk_mul_f32 v[90:91], v[82:83], v[82:83]
	v_max_f32_e32 v72, v72, v72
	v_max_f32_e32 v73, v73, v73
	v_cvt_pk_bf16_f32 v80, v84, v85
	v_cvt_pk_bf16_f32 v81, v86, v87
	v_cvt_pk_bf16_f32 v82, v88, v89
	v_cvt_pk_bf16_f32 v83, v90, v91
	v_max_f32_e32 v72, 0, v72
	v_max_f32_e32 v73, 0, v73
	global_store_dwordx4 v[92:93], v[80:83], off offset:256
	v_max_f32_e32 v76, v76, v76
	v_max_f32_e32 v77, v77, v77
	v_or_b32_e32 v80, 48, v154
	v_pk_mul_f32 v[82:83], v[72:73], v[72:73]
	v_max_f32_e32 v73, v74, v74
	v_ashrrev_i32_e32 v81, 31, v80
	v_max_f32_e32 v72, v78, v78
	v_max_f32_e32 v74, 0, v73
	v_max_f32_e32 v73, v79, v79
	v_max_f32_e32 v75, v75, v75
	v_lshlrev_b64 v[80:81], 13, v[80:81]
	v_max_f32_e32 v76, 0, v76
	v_max_f32_e32 v77, 0, v77
	v_max_f32_e32 v72, 0, v72
	v_max_f32_e32 v73, 0, v73
	v_max_f32_e32 v75, 0, v75
	v_lshl_add_u64 v[80:81], s[46:47], 0, v[80:81]
	v_pk_mul_f32 v[76:77], v[76:77], v[76:77]
	v_pk_mul_f32 v[78:79], v[72:73], v[72:73]
	v_pk_mul_f32 v[84:85], v[74:75], v[74:75]
	v_max_f32_e32 v64, v64, v64
	v_max_f32_e32 v65, v65, v65
	v_cvt_pk_bf16_f32 v72, v76, v77
	v_cvt_pk_bf16_f32 v73, v78, v79
	v_cvt_pk_bf16_f32 v74, v82, v83
	v_cvt_pk_bf16_f32 v75, v84, v85
	v_lshl_add_u64 v[76:77], v[80:81], 0, v[126:127]
	v_max_f32_e32 v64, 0, v64
	v_max_f32_e32 v65, 0, v65
	global_store_dwordx4 v[76:77], v[72:75], off
	v_max_f32_e32 v68, v68, v68
	v_max_f32_e32 v69, v69, v69
	v_pk_mul_f32 v[72:73], v[64:65], v[64:65]
	v_max_f32_e32 v65, v66, v66
	v_max_f32_e32 v64, v70, v70
	v_max_f32_e32 v66, 0, v65
	v_max_f32_e32 v65, v71, v71
	v_max_f32_e32 v67, v67, v67
	v_max_f32_e32 v68, 0, v68
	v_max_f32_e32 v69, 0, v69
	v_max_f32_e32 v64, 0, v64
	v_max_f32_e32 v65, 0, v65
	v_max_f32_e32 v67, 0, v67
	v_pk_mul_f32 v[68:69], v[68:69], v[68:69]
	v_pk_mul_f32 v[70:71], v[64:65], v[64:65]
	v_pk_mul_f32 v[74:75], v[66:67], v[66:67]
	v_max_f32_e32 v56, v56, v56
	v_max_f32_e32 v57, v57, v57
	v_cvt_pk_bf16_f32 v64, v68, v69
	v_cvt_pk_bf16_f32 v65, v70, v71
	v_cvt_pk_bf16_f32 v66, v72, v73
	v_cvt_pk_bf16_f32 v67, v74, v75
	v_max_f32_e32 v56, 0, v56
	v_max_f32_e32 v57, 0, v57
	global_store_dwordx4 v[76:77], v[64:67], off offset:256
	v_max_f32_e32 v60, v60, v60
	v_max_f32_e32 v61, v61, v61
	v_pk_mul_f32 v[64:65], v[56:57], v[56:57]
	v_max_f32_e32 v57, v58, v58
	v_max_f32_e32 v56, v62, v62
	v_max_f32_e32 v58, 0, v57
	v_max_f32_e32 v57, v63, v63
	v_max_f32_e32 v56, 0, v56
	v_max_f32_e32 v57, 0, v57
	v_max_f32_e32 v59, v59, v59
	v_max_f32_e32 v60, 0, v60
	v_max_f32_e32 v61, 0, v61
	v_max_f32_e32 v59, 0, v59
	v_pk_mul_f32 v[62:63], v[56:57], v[56:57]
	v_pk_mul_f32 v[60:61], v[60:61], v[60:61]
	v_pk_mul_f32 v[66:67], v[58:59], v[58:59]
	v_cvt_pk_bf16_f32 v57, v62, v63
	v_add_co_u32_e32 v62, vcc, s70, v120
	v_max_f32_e32 v48, v48, v48
	v_max_f32_e32 v49, v49, v49
	v_cvt_pk_bf16_f32 v56, v60, v61
	v_cvt_pk_bf16_f32 v58, v64, v65
	v_cvt_pk_bf16_f32 v59, v66, v67
	v_addc_co_u32_e32 v63, vcc, 0, v121, vcc
	v_max_f32_e32 v48, 0, v48
	v_max_f32_e32 v49, 0, v49
	global_store_dwordx4 v[62:63], v[56:59], off
	v_max_f32_e32 v52, v52, v52
	v_max_f32_e32 v53, v53, v53
	v_pk_mul_f32 v[56:57], v[48:49], v[48:49]
	v_max_f32_e32 v49, v50, v50
	v_max_f32_e32 v48, v54, v54
	v_max_f32_e32 v50, 0, v49
	v_max_f32_e32 v49, v55, v55
	v_max_f32_e32 v51, v51, v51
	v_max_f32_e32 v52, 0, v52
	v_max_f32_e32 v53, 0, v53
	v_max_f32_e32 v48, 0, v48
	v_max_f32_e32 v49, 0, v49
	v_max_f32_e32 v51, 0, v51
	v_pk_mul_f32 v[52:53], v[52:53], v[52:53]
	v_pk_mul_f32 v[54:55], v[48:49], v[48:49]
	v_pk_mul_f32 v[58:59], v[50:51], v[50:51]
	v_max_f32_e32 v40, v40, v40
	v_max_f32_e32 v41, v41, v41
	v_lshl_add_u64 v[60:61], v[120:121], 0, s[10:11]
	v_cvt_pk_bf16_f32 v48, v52, v53
	v_cvt_pk_bf16_f32 v49, v54, v55
	v_cvt_pk_bf16_f32 v50, v56, v57
	v_cvt_pk_bf16_f32 v51, v58, v59
	v_max_f32_e32 v40, 0, v40
	v_max_f32_e32 v41, 0, v41
	global_store_dwordx4 v[60:61], v[48:51], off offset:256
	v_max_f32_e32 v44, v44, v44
	v_max_f32_e32 v45, v45, v45
	v_pk_mul_f32 v[48:49], v[40:41], v[40:41]
	v_max_f32_e32 v41, v42, v42
	v_max_f32_e32 v40, v46, v46
	v_max_f32_e32 v42, 0, v41
	v_max_f32_e32 v41, v47, v47
	v_max_f32_e32 v40, 0, v40
	v_max_f32_e32 v41, 0, v41
	v_max_f32_e32 v43, v43, v43
	v_max_f32_e32 v44, 0, v44
	v_max_f32_e32 v45, 0, v45
	v_max_f32_e32 v43, 0, v43
	v_pk_mul_f32 v[46:47], v[40:41], v[40:41]
	v_pk_mul_f32 v[44:45], v[44:45], v[44:45]
	v_pk_mul_f32 v[50:51], v[42:43], v[42:43]
	v_cvt_pk_bf16_f32 v41, v46, v47
	v_add_co_u32_e32 v46, vcc, s71, v120
	v_max_f32_e32 v32, v32, v32
	v_max_f32_e32 v33, v33, v33
	v_cvt_pk_bf16_f32 v40, v44, v45
	v_cvt_pk_bf16_f32 v42, v48, v49
	v_cvt_pk_bf16_f32 v43, v50, v51
	v_addc_co_u32_e32 v47, vcc, 0, v121, vcc
	v_max_f32_e32 v32, 0, v32
	v_max_f32_e32 v33, 0, v33
	global_store_dwordx4 v[46:47], v[40:43], off
	v_max_f32_e32 v36, v36, v36
	v_max_f32_e32 v37, v37, v37
	v_pk_mul_f32 v[40:41], v[32:33], v[32:33]
	v_max_f32_e32 v33, v34, v34
	v_max_f32_e32 v32, v38, v38
	v_max_f32_e32 v34, 0, v33
	v_max_f32_e32 v33, v39, v39
	v_max_f32_e32 v35, v35, v35
	v_max_f32_e32 v36, 0, v36
	v_max_f32_e32 v37, 0, v37
	v_max_f32_e32 v32, 0, v32
	v_max_f32_e32 v33, 0, v33
	v_max_f32_e32 v35, 0, v35
	v_pk_mul_f32 v[36:37], v[36:37], v[36:37]
	v_pk_mul_f32 v[38:39], v[32:33], v[32:33]
	v_pk_mul_f32 v[42:43], v[34:35], v[34:35]
	v_max_f32_e32 v24, v24, v24
	v_max_f32_e32 v25, v25, v25
	v_lshl_add_u64 v[44:45], v[120:121], 0, s[12:13]
	v_cvt_pk_bf16_f32 v32, v36, v37
	v_cvt_pk_bf16_f32 v33, v38, v39
	v_cvt_pk_bf16_f32 v34, v40, v41
	v_cvt_pk_bf16_f32 v35, v42, v43
	v_max_f32_e32 v24, 0, v24
	v_max_f32_e32 v25, 0, v25
	global_store_dwordx4 v[44:45], v[32:35], off offset:256
	v_max_f32_e32 v28, v28, v28
	v_max_f32_e32 v29, v29, v29
	v_pk_mul_f32 v[32:33], v[24:25], v[24:25]
	v_max_f32_e32 v25, v26, v26
	v_max_f32_e32 v24, v30, v30
	v_max_f32_e32 v26, 0, v25
	v_max_f32_e32 v25, v31, v31
	v_max_f32_e32 v24, 0, v24
	v_max_f32_e32 v25, 0, v25
	v_max_f32_e32 v27, v27, v27
	v_max_f32_e32 v28, 0, v28
	v_max_f32_e32 v29, 0, v29
	v_max_f32_e32 v27, 0, v27
	v_pk_mul_f32 v[30:31], v[24:25], v[24:25]
	v_pk_mul_f32 v[28:29], v[28:29], v[28:29]
	v_pk_mul_f32 v[34:35], v[26:27], v[26:27]
	v_cvt_pk_bf16_f32 v25, v30, v31
	v_add_co_u32_e32 v30, vcc, s72, v120
	v_max_f32_e32 v16, v16, v16
	v_max_f32_e32 v17, v17, v17
	v_cvt_pk_bf16_f32 v24, v28, v29
	v_cvt_pk_bf16_f32 v26, v32, v33
	v_cvt_pk_bf16_f32 v27, v34, v35
	v_addc_co_u32_e32 v31, vcc, 0, v121, vcc
	v_max_f32_e32 v16, 0, v16
	v_max_f32_e32 v17, 0, v17
	global_store_dwordx4 v[30:31], v[24:27], off
	v_max_f32_e32 v20, v20, v20
	v_max_f32_e32 v21, v21, v21
	v_pk_mul_f32 v[24:25], v[16:17], v[16:17]
	v_max_f32_e32 v17, v18, v18
	v_max_f32_e32 v16, v22, v22
	v_max_f32_e32 v18, 0, v17
	v_max_f32_e32 v17, v23, v23
	v_max_f32_e32 v19, v19, v19
	v_max_f32_e32 v20, 0, v20
	v_max_f32_e32 v21, 0, v21
	v_max_f32_e32 v16, 0, v16
	v_max_f32_e32 v17, 0, v17
	v_max_f32_e32 v19, 0, v19
	v_pk_mul_f32 v[20:21], v[20:21], v[20:21]
	v_pk_mul_f32 v[22:23], v[16:17], v[16:17]
	v_pk_mul_f32 v[26:27], v[18:19], v[18:19]
	v_max_f32_e32 v8, v8, v8
	v_max_f32_e32 v9, v9, v9
	v_lshl_add_u64 v[28:29], v[120:121], 0, s[14:15]
	v_cvt_pk_bf16_f32 v16, v20, v21
	v_cvt_pk_bf16_f32 v17, v22, v23
	v_cvt_pk_bf16_f32 v18, v24, v25
	v_cvt_pk_bf16_f32 v19, v26, v27
	v_max_f32_e32 v8, 0, v8
	v_max_f32_e32 v9, 0, v9
	global_store_dwordx4 v[28:29], v[16:19], off offset:256
	v_max_f32_e32 v12, v12, v12
	v_max_f32_e32 v13, v13, v13
	v_pk_mul_f32 v[16:17], v[8:9], v[8:9]
	v_max_f32_e32 v9, v10, v10
	v_max_f32_e32 v8, v14, v14
	v_max_f32_e32 v10, 0, v9
	v_max_f32_e32 v9, v15, v15
	v_max_f32_e32 v8, 0, v8
	v_max_f32_e32 v9, 0, v9
	v_max_f32_e32 v11, v11, v11
	v_max_f32_e32 v12, 0, v12
	v_max_f32_e32 v13, 0, v13
	v_max_f32_e32 v11, 0, v11
	v_pk_mul_f32 v[14:15], v[8:9], v[8:9]
	v_pk_mul_f32 v[12:13], v[12:13], v[12:13]
	v_pk_mul_f32 v[18:19], v[10:11], v[10:11]
	v_cvt_pk_bf16_f32 v9, v14, v15
	v_add_co_u32_e32 v14, vcc, s73, v120
	v_max_f32_e32 v0, v0, v0
	v_max_f32_e32 v1, v1, v1
	v_cvt_pk_bf16_f32 v8, v12, v13
	v_cvt_pk_bf16_f32 v10, v16, v17
	v_cvt_pk_bf16_f32 v11, v18, v19
	v_addc_co_u32_e32 v15, vcc, 0, v121, vcc
	v_max_f32_e32 v0, 0, v0
	v_max_f32_e32 v1, 0, v1
	global_store_dwordx4 v[14:15], v[8:11], off
	v_max_f32_e32 v4, v4, v4
	v_max_f32_e32 v5, v5, v5
	v_pk_mul_f32 v[8:9], v[0:1], v[0:1]
	v_max_f32_e32 v1, v2, v2
	v_max_f32_e32 v0, v6, v6
	v_max_f32_e32 v2, 0, v1
	v_max_f32_e32 v1, v7, v7
	v_max_f32_e32 v3, v3, v3
	v_max_f32_e32 v4, 0, v4
	v_max_f32_e32 v5, 0, v5
	v_max_f32_e32 v0, 0, v0
	v_max_f32_e32 v1, 0, v1
	v_max_f32_e32 v3, 0, v3
	v_pk_mul_f32 v[4:5], v[4:5], v[4:5]
	v_pk_mul_f32 v[6:7], v[0:1], v[0:1]
	v_pk_mul_f32 v[10:11], v[2:3], v[2:3]
	v_lshl_add_u64 v[12:13], v[120:121], 0, s[16:17]
	v_cvt_pk_bf16_f32 v0, v4, v5
	v_cvt_pk_bf16_f32 v1, v6, v7
	v_cvt_pk_bf16_f32 v2, v8, v9
	v_cvt_pk_bf16_f32 v3, v10, v11
	s_and_b64 vcc, exec, s[4:5]
	s_mov_b32 s74, s18
	s_mov_b32 s30, s20
	s_mov_b64 s[36:37], s[28:29]
	s_mov_b64 s[34:35], s[26:27]
	global_store_dwordx4 v[12:13], v[0:3], off offset:256
	s_cbranch_vccz .LBB0_1284
	s_waitcnt vmcnt(0)
	s_cmpk_gt_u32 s40, 0xff
	s_cbranch_scc1 .LBB0_1295
	s_barrier

.LBB0_1310:
	ds_read_b128 v[154:157], v151
	ds_read_b128 v[158:161], v151 offset:1024
	ds_read_b128 v[162:165], v151 offset:2048
	ds_read_b128 v[166:169], v151 offset:3072
	s_add_u32 s38, s36, 0xfffc0080
	s_addc_u32 s39, s37, -1
	s_cmp_eq_u32 s77, 12
	s_cselect_b32 s41, s27, s39
	s_cselect_b32 s40, s73, s38
	s_cselect_b32 s39, s21, s76
	s_cselect_b32 s38, s74, s75
	v_lshl_add_u64 v[202:203], s[36:37], 0, v[138:139]
	s_add_i32 m0, s35, 0xc000
	ds_read_b128 v[170:173], v152
	ds_read_b128 v[174:177], v152 offset:1024
	ds_read_b128 v[178:181], v152 offset:2048
	ds_read_b128 v[182:185], v152 offset:3072
	ds_read_b128 v[186:189], v152 offset:4096
	ds_read_b128 v[190:193], v152 offset:5120
	ds_read_b128 v[194:197], v152 offset:6144
	ds_read_b128 v[198:201], v152 offset:7168
	global_load_lds_dwordx4 v[202:203], off
	v_lshl_add_u64 v[202:203], s[36:37], 0, v[140:141]
	s_add_i32 m0, s35, 0xe000
	s_nop 0
	global_load_lds_dwordx4 v[202:203], off
	s_barrier
	s_waitcnt lgkmcnt(0)
	s_waitcnt lgkmcnt(0)
	v_mfma_f32_16x16x32_bf16 v[124:127], v[154:157], v[170:173], v[124:127]
	v_mfma_f32_16x16x32_bf16 v[120:123], v[162:165], v[170:173], v[120:123]
	v_mfma_f32_16x16x32_bf16 v[108:111], v[154:157], v[178:181], v[108:111]
	v_mfma_f32_16x16x32_bf16 v[104:107], v[162:165], v[178:181], v[104:107]
	v_mfma_f32_16x16x32_bf16 v[92:95], v[154:157], v[186:189], v[92:95]
	v_mfma_f32_16x16x32_bf16 v[88:91], v[162:165], v[186:189], v[88:91]
	v_mfma_f32_16x16x32_bf16 v[76:79], v[154:157], v[194:197], v[76:79]
	v_mfma_f32_16x16x32_bf16 v[72:75], v[162:165], v[194:197], v[72:75]
	v_mfma_f32_16x16x32_bf16 v[124:127], v[158:161], v[174:177], v[124:127]
	v_mfma_f32_16x16x32_bf16 v[120:123], v[166:169], v[174:177], v[120:123]
	v_mfma_f32_16x16x32_bf16 v[108:111], v[158:161], v[182:185], v[108:111]
	v_mfma_f32_16x16x32_bf16 v[104:107], v[166:169], v[182:185], v[104:107]
	v_mfma_f32_16x16x32_bf16 v[92:95], v[158:161], v[190:193], v[92:95]
	v_mfma_f32_16x16x32_bf16 v[88:91], v[166:169], v[190:193], v[88:91]
	v_mfma_f32_16x16x32_bf16 v[76:79], v[158:161], v[198:201], v[76:79]
	v_mfma_f32_16x16x32_bf16 v[72:75], v[166:169], v[198:201], v[72:75]
	s_barrier
	s_add_i32 s78, s62, s52
	v_lshl_add_u64 v[218:219], s[38:39], 0, v[132:133]
	s_mov_b32 m0, s78
	ds_read_b128 v[202:205], v153
	ds_read_b128 v[206:209], v153 offset:1024
	ds_read_b128 v[210:213], v153 offset:2048
	ds_read_b128 v[214:217], v153 offset:3072
	global_load_lds_dwordx4 v[218:219], off
	v_lshl_add_u64 v[220:221], s[38:39], 0, v[136:137]
	s_add_i32 m0, s78, 0x2000
	s_nop 0
	global_load_lds_dwordx4 v[220:221], off
	s_barrier
	s_waitcnt lgkmcnt(0)
	s_waitcnt lgkmcnt(0)
	v_mfma_f32_16x16x32_bf16 v[116:119], v[202:205], v[170:173], v[116:119]
	v_mfma_f32_16x16x32_bf16 v[112:115], v[210:213], v[170:173], v[112:115]
	v_mfma_f32_16x16x32_bf16 v[100:103], v[202:205], v[178:181], v[100:103]
	v_mfma_f32_16x16x32_bf16 v[96:99], v[210:213], v[178:181], v[96:99]
	v_mfma_f32_16x16x32_bf16 v[84:87], v[202:205], v[186:189], v[84:87]
	v_mfma_f32_16x16x32_bf16 v[80:83], v[210:213], v[186:189], v[80:83]
	v_mfma_f32_16x16x32_bf16 v[68:71], v[202:205], v[194:197], v[68:71]
	v_mfma_f32_16x16x32_bf16 v[64:67], v[210:213], v[194:197], v[64:67]
	v_mfma_f32_16x16x32_bf16 v[116:119], v[206:209], v[174:177], v[116:119]
	v_mfma_f32_16x16x32_bf16 v[112:115], v[214:217], v[174:177], v[112:115]
	v_mfma_f32_16x16x32_bf16 v[100:103], v[206:209], v[182:185], v[100:103]
	v_mfma_f32_16x16x32_bf16 v[96:99], v[214:217], v[182:185], v[96:99]
	v_mfma_f32_16x16x32_bf16 v[84:87], v[206:209], v[190:193], v[84:87]
	v_mfma_f32_16x16x32_bf16 v[80:83], v[214:217], v[190:193], v[80:83]
	v_mfma_f32_16x16x32_bf16 v[68:71], v[206:209], v[198:201], v[68:71]
	v_mfma_f32_16x16x32_bf16 v[64:67], v[214:217], v[198:201], v[64:67]
	s_mov_b32 m0, s35
	v_lshl_add_u64 v[222:223], s[40:41], 0, v[130:131]
	s_barrier
	ds_read_b128 v[170:173], v152 offset:16384
	ds_read_b128 v[174:177], v152 offset:17408
	ds_read_b128 v[178:181], v152 offset:18432
	ds_read_b128 v[182:185], v152 offset:19456
	ds_read_b128 v[186:189], v152 offset:20480
	ds_read_b128 v[190:193], v152 offset:21504
	ds_read_b128 v[194:197], v152 offset:22528
	ds_read_b128 v[198:201], v152 offset:23552
	global_load_lds_dwordx4 v[222:223], off
	v_lshl_add_u64 v[224:225], s[40:41], 0, v[134:135]
	s_mov_b32 m0, s53
	s_nop 0
	global_load_lds_dwordx4 v[224:225], off
	s_barrier
	s_waitcnt lgkmcnt(0)
	s_waitcnt lgkmcnt(0)
	v_mfma_f32_16x16x32_bf16 v[60:63], v[154:157], v[170:173], v[60:63]
	v_mfma_f32_16x16x32_bf16 v[56:59], v[162:165], v[170:173], v[56:59]
	v_mfma_f32_16x16x32_bf16 v[44:47], v[154:157], v[178:181], v[44:47]
	v_mfma_f32_16x16x32_bf16 v[40:43], v[162:165], v[178:181], v[40:43]
	v_mfma_f32_16x16x32_bf16 v[28:31], v[154:157], v[186:189], v[28:31]
	v_mfma_f32_16x16x32_bf16 v[24:27], v[162:165], v[186:189], v[24:27]
	v_mfma_f32_16x16x32_bf16 v[12:15], v[154:157], v[194:197], v[12:15]
	v_mfma_f32_16x16x32_bf16 v[8:11], v[162:165], v[194:197], v[8:11]
	v_mfma_f32_16x16x32_bf16 v[60:63], v[158:161], v[174:177], v[60:63]
	v_mfma_f32_16x16x32_bf16 v[56:59], v[166:169], v[174:177], v[56:59]
	v_mfma_f32_16x16x32_bf16 v[44:47], v[158:161], v[182:185], v[44:47]
	v_mfma_f32_16x16x32_bf16 v[40:43], v[166:169], v[182:185], v[40:43]
	v_mfma_f32_16x16x32_bf16 v[28:31], v[158:161], v[190:193], v[28:31]
	v_mfma_f32_16x16x32_bf16 v[24:27], v[166:169], v[190:193], v[24:27]
	v_mfma_f32_16x16x32_bf16 v[12:15], v[158:161], v[198:201], v[12:15]
	v_mfma_f32_16x16x32_bf16 v[8:11], v[166:169], v[198:201], v[8:11]
	s_barrier
	s_add_u32 s78, s38, 0x40000
	s_addc_u32 s79, s39, 0
	s_add_i32 s80, s63, s52
	v_lshl_add_u64 v[154:155], s[78:79], 0, v[132:133]
	s_mov_b32 m0, s80
	s_nop 0
	global_load_lds_dwordx4 v[154:155], off
	v_lshl_add_u64 v[154:155], s[78:79], 0, v[136:137]
	s_add_i32 m0, s80, 0x2000
	s_nop 0
	global_load_lds_dwordx4 v[154:155], off
	s_waitcnt vmcnt(6)
	s_barrier
	v_mfma_f32_16x16x32_bf16 v[52:55], v[202:205], v[170:173], v[52:55]
	v_mfma_f32_16x16x32_bf16 v[48:51], v[210:213], v[170:173], v[48:51]
	v_mfma_f32_16x16x32_bf16 v[36:39], v[202:205], v[178:181], v[36:39]
	v_mfma_f32_16x16x32_bf16 v[32:35], v[210:213], v[178:181], v[32:35]
	v_mfma_f32_16x16x32_bf16 v[20:23], v[202:205], v[186:189], v[20:23]
	v_mfma_f32_16x16x32_bf16 v[16:19], v[210:213], v[186:189], v[16:19]
	v_mfma_f32_16x16x32_bf16 v[4:7], v[202:205], v[194:197], v[4:7]
	v_mfma_f32_16x16x32_bf16 v[0:3], v[210:213], v[194:197], v[0:3]
	v_mfma_f32_16x16x32_bf16 v[52:55], v[206:209], v[174:177], v[52:55]
	v_mfma_f32_16x16x32_bf16 v[48:51], v[214:217], v[174:177], v[48:51]
	v_mfma_f32_16x16x32_bf16 v[36:39], v[206:209], v[182:185], v[36:39]
	v_mfma_f32_16x16x32_bf16 v[32:35], v[214:217], v[182:185], v[32:35]
	v_mfma_f32_16x16x32_bf16 v[20:23], v[206:209], v[190:193], v[20:23]
	v_mfma_f32_16x16x32_bf16 v[16:19], v[214:217], v[190:193], v[16:19]
	v_mfma_f32_16x16x32_bf16 v[4:7], v[206:209], v[198:201], v[4:7]
	v_mfma_f32_16x16x32_bf16 v[0:3], v[214:217], v[198:201], v[0:3]
	s_add_i32 s78, 0, 0x18000
	v_add_u32_e32 v166, s78, v149
	s_barrier
	ds_read_b128 v[154:157], v166
	ds_read_b128 v[158:161], v166 offset:1024
	ds_read_b128 v[162:165], v166 offset:2048
	ds_read_b128 v[166:169], v166 offset:3072
	s_add_u32 s40, s40, 0x40000
	s_addc_u32 s41, s41, 0
	s_mov_b32 m0, s54
	v_lshl_add_u64 v[202:203], s[40:41], 0, v[130:131]
	ds_read_b128 v[170:173], v152 offset:32768
	ds_read_b128 v[174:177], v152 offset:33792
	ds_read_b128 v[178:181], v152 offset:34816
	ds_read_b128 v[182:185], v152 offset:35840
	ds_read_b128 v[186:189], v152 offset:36864
	ds_read_b128 v[190:193], v152 offset:37888
	ds_read_b128 v[194:197], v152 offset:38912
	ds_read_b128 v[198:201], v152 offset:39936
	global_load_lds_dwordx4 v[202:203], off
	v_lshl_add_u64 v[202:203], s[40:41], 0, v[134:135]
	s_mov_b32 m0, s55
	s_nop 0
	global_load_lds_dwordx4 v[202:203], off
	s_barrier
	s_waitcnt lgkmcnt(0)
	s_waitcnt lgkmcnt(0)
	v_mfma_f32_16x16x32_bf16 v[124:127], v[154:157], v[170:173], v[124:127]
	v_mfma_f32_16x16x32_bf16 v[120:123], v[162:165], v[170:173], v[120:123]
	v_mfma_f32_16x16x32_bf16 v[108:111], v[154:157], v[178:181], v[108:111]
	v_mfma_f32_16x16x32_bf16 v[104:107], v[162:165], v[178:181], v[104:107]
	v_mfma_f32_16x16x32_bf16 v[92:95], v[154:157], v[186:189], v[92:95]
	v_mfma_f32_16x16x32_bf16 v[88:91], v[162:165], v[186:189], v[88:91]
	v_mfma_f32_16x16x32_bf16 v[76:79], v[154:157], v[194:197], v[76:79]
	v_mfma_f32_16x16x32_bf16 v[72:75], v[162:165], v[194:197], v[72:75]
	v_mfma_f32_16x16x32_bf16 v[124:127], v[158:161], v[174:177], v[124:127]
	v_mfma_f32_16x16x32_bf16 v[120:123], v[166:169], v[174:177], v[120:123]
	v_mfma_f32_16x16x32_bf16 v[108:111], v[158:161], v[182:185], v[108:111]
	v_mfma_f32_16x16x32_bf16 v[104:107], v[166:169], v[182:185], v[104:107]
	v_mfma_f32_16x16x32_bf16 v[92:95], v[158:161], v[190:193], v[92:95]
	v_mfma_f32_16x16x32_bf16 v[88:91], v[166:169], v[190:193], v[88:91]
	v_mfma_f32_16x16x32_bf16 v[76:79], v[158:161], v[198:201], v[76:79]
	v_mfma_f32_16x16x32_bf16 v[72:75], v[166:169], v[198:201], v[72:75]
	s_barrier
	s_add_i32 s40, 0, 0x1c000
	s_add_i32 s41, s78, s52
	v_add_u32_e32 v214, s40, v149
	v_lshl_add_u64 v[218:219], v[218:219], 0, s[10:11]
	s_mov_b32 m0, s41
	ds_read_b128 v[202:205], v214
	ds_read_b128 v[206:209], v214 offset:1024
	ds_read_b128 v[210:213], v214 offset:2048
	ds_read_b128 v[214:217], v214 offset:3072
	global_load_lds_dwordx4 v[218:219], off
	v_lshl_add_u64 v[218:219], v[220:221], 0, s[10:11]
	s_add_i32 m0, s41, 0x2000
	s_nop 0
	global_load_lds_dwordx4 v[218:219], off
	s_barrier
	s_waitcnt lgkmcnt(0)
	s_waitcnt lgkmcnt(0)
	v_mfma_f32_16x16x32_bf16 v[116:119], v[202:205], v[170:173], v[116:119]
	v_mfma_f32_16x16x32_bf16 v[112:115], v[210:213], v[170:173], v[112:115]
	v_mfma_f32_16x16x32_bf16 v[100:103], v[202:205], v[178:181], v[100:103]
	v_mfma_f32_16x16x32_bf16 v[96:99], v[210:213], v[178:181], v[96:99]
	v_mfma_f32_16x16x32_bf16 v[84:87], v[202:205], v[186:189], v[84:87]
	v_mfma_f32_16x16x32_bf16 v[80:83], v[210:213], v[186:189], v[80:83]
	v_mfma_f32_16x16x32_bf16 v[68:71], v[202:205], v[194:197], v[68:71]
	v_mfma_f32_16x16x32_bf16 v[64:67], v[210:213], v[194:197], v[64:67]
	v_mfma_f32_16x16x32_bf16 v[116:119], v[206:209], v[174:177], v[116:119]
	v_mfma_f32_16x16x32_bf16 v[112:115], v[214:217], v[174:177], v[112:115]
	v_mfma_f32_16x16x32_bf16 v[100:103], v[206:209], v[182:185], v[100:103]
	v_mfma_f32_16x16x32_bf16 v[96:99], v[214:217], v[182:185], v[96:99]
	v_mfma_f32_16x16x32_bf16 v[84:87], v[206:209], v[190:193], v[84:87]
	v_mfma_f32_16x16x32_bf16 v[80:83], v[214:217], v[190:193], v[80:83]
	v_mfma_f32_16x16x32_bf16 v[68:71], v[206:209], v[198:201], v[68:71]
	v_mfma_f32_16x16x32_bf16 v[64:67], v[214:217], v[198:201], v[64:67]
	s_mov_b32 m0, s57
	v_lshl_add_u64 v[218:219], v[222:223], 0, s[10:11]
	s_barrier
	ds_read_b128 v[170:173], v152 offset:49152
	ds_read_b128 v[174:177], v152 offset:50176
	ds_read_b128 v[178:181], v152 offset:51200
	ds_read_b128 v[182:185], v152 offset:52224
	ds_read_b128 v[186:189], v152 offset:53248
	ds_read_b128 v[190:193], v152 offset:54272
	ds_read_b128 v[194:197], v152 offset:55296
	ds_read_b128 v[198:201], v152 offset:56320
	global_load_lds_dwordx4 v[218:219], off
	v_lshl_add_u64 v[218:219], v[224:225], 0, s[10:11]
	s_mov_b32 m0, s60
	s_nop 0
	global_load_lds_dwordx4 v[218:219], off
	s_barrier
	s_waitcnt lgkmcnt(0)
	s_waitcnt lgkmcnt(0)
	v_mfma_f32_16x16x32_bf16 v[60:63], v[154:157], v[170:173], v[60:63]
	v_mfma_f32_16x16x32_bf16 v[56:59], v[162:165], v[170:173], v[56:59]
	v_mfma_f32_16x16x32_bf16 v[44:47], v[154:157], v[178:181], v[44:47]
	v_mfma_f32_16x16x32_bf16 v[40:43], v[162:165], v[178:181], v[40:43]
	v_mfma_f32_16x16x32_bf16 v[28:31], v[154:157], v[186:189], v[28:31]
	v_mfma_f32_16x16x32_bf16 v[24:27], v[162:165], v[186:189], v[24:27]
	v_mfma_f32_16x16x32_bf16 v[12:15], v[154:157], v[194:197], v[12:15]
	v_mfma_f32_16x16x32_bf16 v[8:11], v[162:165], v[194:197], v[8:11]
	v_mfma_f32_16x16x32_bf16 v[60:63], v[158:161], v[174:177], v[60:63]
	v_mfma_f32_16x16x32_bf16 v[56:59], v[166:169], v[174:177], v[56:59]
	v_mfma_f32_16x16x32_bf16 v[44:47], v[158:161], v[182:185], v[44:47]
	v_mfma_f32_16x16x32_bf16 v[40:43], v[166:169], v[182:185], v[40:43]
	v_mfma_f32_16x16x32_bf16 v[28:31], v[158:161], v[190:193], v[28:31]
	v_mfma_f32_16x16x32_bf16 v[24:27], v[166:169], v[190:193], v[24:27]
	v_mfma_f32_16x16x32_bf16 v[12:15], v[158:161], v[198:201], v[12:15]
	v_mfma_f32_16x16x32_bf16 v[8:11], v[166:169], v[198:201], v[8:11]
	s_barrier
	s_add_u32 s38, s38, 0x40080
	s_addc_u32 s39, s39, 0
	s_add_i32 s40, s40, s52
	v_lshl_add_u64 v[154:155], s[38:39], 0, v[132:133]
	s_mov_b32 m0, s40
	s_nop 0
	global_load_lds_dwordx4 v[154:155], off
	v_lshl_add_u64 v[154:155], s[38:39], 0, v[136:137]
	s_add_i32 m0, s40, 0x2000
	s_nop 0
	global_load_lds_dwordx4 v[154:155], off
	s_waitcnt vmcnt(6)
	s_barrier
	v_mfma_f32_16x16x32_bf16 v[52:55], v[202:205], v[170:173], v[52:55]
	v_mfma_f32_16x16x32_bf16 v[48:51], v[210:213], v[170:173], v[48:51]
	v_mfma_f32_16x16x32_bf16 v[36:39], v[202:205], v[178:181], v[36:39]
	v_mfma_f32_16x16x32_bf16 v[32:35], v[210:213], v[178:181], v[32:35]
	v_mfma_f32_16x16x32_bf16 v[20:23], v[202:205], v[186:189], v[20:23]
	v_mfma_f32_16x16x32_bf16 v[16:19], v[210:213], v[186:189], v[16:19]
	v_mfma_f32_16x16x32_bf16 v[4:7], v[202:205], v[194:197], v[4:7]
	v_mfma_f32_16x16x32_bf16 v[0:3], v[210:213], v[194:197], v[0:3]
	v_mfma_f32_16x16x32_bf16 v[52:55], v[206:209], v[174:177], v[52:55]
	v_mfma_f32_16x16x32_bf16 v[48:51], v[214:217], v[174:177], v[48:51]
	v_mfma_f32_16x16x32_bf16 v[36:39], v[206:209], v[182:185], v[36:39]
	v_mfma_f32_16x16x32_bf16 v[32:35], v[214:217], v[182:185], v[32:35]
	v_mfma_f32_16x16x32_bf16 v[20:23], v[206:209], v[190:193], v[20:23]
	v_mfma_f32_16x16x32_bf16 v[16:19], v[214:217], v[190:193], v[16:19]
	v_mfma_f32_16x16x32_bf16 v[4:7], v[206:209], v[198:201], v[4:7]
	v_mfma_f32_16x16x32_bf16 v[0:3], v[214:217], v[198:201], v[0:3]
	s_add_i32 s77, s77, 2
	s_add_u32 s36, s36, 0x100
	s_addc_u32 s37, s37, 0
	s_add_u32 s75, s75, 0x100
	s_addc_u32 s76, s76, 0
	s_cmp_gt_u32 s77, 13
	s_barrier
	s_cbranch_scc0 .LBB0_1310
	v_lshl_add_u32 v154, s34, 8, v148
	v_max_f32_e32 v126, v126, v126
	v_max_f32_e32 v127, v127, v127
	v_lshl_or_b32 v156, s72, 8, v150
	v_ashrrev_i32_e32 v155, 31, v154
	v_max_f32_e32 v124, v124, v124
	v_max_f32_e32 v120, v120, v120
	v_max_f32_e32 v125, v125, v125
	v_max_f32_e32 v121, v121, v121
	v_max_f32_e32 v126, 0, v126
	v_max_f32_e32 v122, v122, v122
	v_max_f32_e32 v127, 0, v127
	v_max_f32_e32 v123, v123, v123
	v_lshlrev_b64 v[158:159], 13, v[154:155]
	v_max_f32_e32 v124, 0, v124
	v_max_f32_e32 v120, 0, v120
	v_max_f32_e32 v125, 0, v125
	v_max_f32_e32 v121, 0, v121
	v_max_f32_e32 v122, 0, v122
	v_max_f32_e32 v123, 0, v123
	v_pk_mul_f32 v[126:127], v[126:127], v[126:127]
	v_ashrrev_i32_e32 v157, 31, v156
	v_lshl_add_u64 v[158:159], s[46:47], 0, v[158:159]
	v_pk_mul_f32 v[124:125], v[124:125], v[124:125]
	v_pk_mul_f32 v[120:121], v[120:121], v[120:121]
	v_pk_mul_f32 v[160:161], v[122:123], v[122:123]
	v_cvt_pk_bf16_f32 v123, v126, v127
	v_lshlrev_b64 v[126:127], 1, v[156:157]
	v_max_f32_e32 v112, v112, v112
	v_max_f32_e32 v113, v113, v113
	v_cvt_pk_bf16_f32 v122, v124, v125
	v_cvt_pk_bf16_f32 v124, v120, v121
	v_cvt_pk_bf16_f32 v125, v160, v161
	v_lshl_add_u64 v[120:121], v[158:159], 0, v[126:127]
	v_max_f32_e32 v112, 0, v112
	v_max_f32_e32 v113, 0, v113
	global_store_dwordx4 v[120:121], v[122:125], off
	v_max_f32_e32 v116, v116, v116
	v_max_f32_e32 v117, v117, v117
	v_pk_mul_f32 v[122:123], v[112:113], v[112:113]
	v_max_f32_e32 v113, v114, v114
	v_max_f32_e32 v112, v118, v118
	v_max_f32_e32 v114, 0, v113
	v_max_f32_e32 v113, v119, v119
	v_max_f32_e32 v115, v115, v115
	v_max_f32_e32 v116, 0, v116
	v_max_f32_e32 v117, 0, v117
	v_max_f32_e32 v112, 0, v112
	v_max_f32_e32 v113, 0, v113
	v_max_f32_e32 v115, 0, v115
	v_pk_mul_f32 v[116:117], v[116:117], v[116:117]
	v_pk_mul_f32 v[118:119], v[112:113], v[112:113]
	v_pk_mul_f32 v[124:125], v[114:115], v[114:115]
	v_max_f32_e32 v104, v104, v104
	v_max_f32_e32 v105, v105, v105
	v_cvt_pk_bf16_f32 v112, v116, v117
	v_cvt_pk_bf16_f32 v113, v118, v119
	v_cvt_pk_bf16_f32 v114, v122, v123
	v_cvt_pk_bf16_f32 v115, v124, v125
	v_max_f32_e32 v104, 0, v104
	v_max_f32_e32 v105, 0, v105
	global_store_dwordx4 v[120:121], v[112:115], off offset:256
	v_max_f32_e32 v108, v108, v108
	v_max_f32_e32 v109, v109, v109
	v_or_b32_e32 v112, 16, v154
	v_pk_mul_f32 v[114:115], v[104:105], v[104:105]
	v_max_f32_e32 v105, v106, v106
	v_ashrrev_i32_e32 v113, 31, v112
	v_max_f32_e32 v104, v110, v110
	v_max_f32_e32 v106, 0, v105
	v_max_f32_e32 v105, v111, v111
	v_max_f32_e32 v107, v107, v107
	v_lshlrev_b64 v[112:113], 13, v[112:113]
	v_max_f32_e32 v108, 0, v108
	v_max_f32_e32 v109, 0, v109
	v_max_f32_e32 v104, 0, v104
	v_max_f32_e32 v105, 0, v105
	v_max_f32_e32 v107, 0, v107
	v_lshl_add_u64 v[112:113], s[46:47], 0, v[112:113]
	v_pk_mul_f32 v[108:109], v[108:109], v[108:109]
	v_pk_mul_f32 v[110:111], v[104:105], v[104:105]
	v_pk_mul_f32 v[116:117], v[106:107], v[106:107]
	v_max_f32_e32 v96, v96, v96
	v_max_f32_e32 v97, v97, v97
	v_cvt_pk_bf16_f32 v104, v108, v109
	v_cvt_pk_bf16_f32 v105, v110, v111
	v_cvt_pk_bf16_f32 v106, v114, v115
	v_cvt_pk_bf16_f32 v107, v116, v117
	v_lshl_add_u64 v[108:109], v[112:113], 0, v[126:127]
	v_max_f32_e32 v96, 0, v96
	v_max_f32_e32 v97, 0, v97
	global_store_dwordx4 v[108:109], v[104:107], off
	v_max_f32_e32 v100, v100, v100
	v_max_f32_e32 v101, v101, v101
	v_pk_mul_f32 v[104:105], v[96:97], v[96:97]
	v_max_f32_e32 v97, v98, v98
	v_max_f32_e32 v96, v102, v102
	v_max_f32_e32 v98, 0, v97
	v_max_f32_e32 v97, v103, v103
	v_max_f32_e32 v99, v99, v99
	v_max_f32_e32 v100, 0, v100
	v_max_f32_e32 v101, 0, v101
	v_max_f32_e32 v96, 0, v96
	v_max_f32_e32 v97, 0, v97
	v_max_f32_e32 v99, 0, v99
	v_pk_mul_f32 v[100:101], v[100:101], v[100:101]
	v_pk_mul_f32 v[102:103], v[96:97], v[96:97]
	v_pk_mul_f32 v[106:107], v[98:99], v[98:99]
	v_max_f32_e32 v88, v88, v88
	v_max_f32_e32 v89, v89, v89
	v_cvt_pk_bf16_f32 v96, v100, v101
	v_cvt_pk_bf16_f32 v97, v102, v103
	v_cvt_pk_bf16_f32 v98, v104, v105
	v_cvt_pk_bf16_f32 v99, v106, v107
	v_max_f32_e32 v88, 0, v88
	v_max_f32_e32 v89, 0, v89
	global_store_dwordx4 v[108:109], v[96:99], off offset:256
	v_max_f32_e32 v92, v92, v92
	v_max_f32_e32 v93, v93, v93
	v_or_b32_e32 v96, 32, v154
	v_pk_mul_f32 v[98:99], v[88:89], v[88:89]
	v_max_f32_e32 v89, v90, v90
	v_ashrrev_i32_e32 v97, 31, v96
	v_max_f32_e32 v88, v94, v94
	v_max_f32_e32 v90, 0, v89
	v_max_f32_e32 v89, v95, v95
	v_max_f32_e32 v91, v91, v91
	v_lshlrev_b64 v[96:97], 13, v[96:97]
	v_max_f32_e32 v92, 0, v92
	v_max_f32_e32 v93, 0, v93
	v_max_f32_e32 v88, 0, v88
	v_max_f32_e32 v89, 0, v89
	v_max_f32_e32 v91, 0, v91
	v_lshl_add_u64 v[96:97], s[46:47], 0, v[96:97]
	v_pk_mul_f32 v[92:93], v[92:93], v[92:93]
	v_pk_mul_f32 v[94:95], v[88:89], v[88:89]
	v_pk_mul_f32 v[100:101], v[90:91], v[90:91]
	v_max_f32_e32 v80, v80, v80
	v_max_f32_e32 v81, v81, v81
	v_cvt_pk_bf16_f32 v88, v92, v93
	v_cvt_pk_bf16_f32 v89, v94, v95
	v_cvt_pk_bf16_f32 v90, v98, v99
	v_cvt_pk_bf16_f32 v91, v100, v101
	v_lshl_add_u64 v[92:93], v[96:97], 0, v[126:127]
	v_max_f32_e32 v80, 0, v80
	v_max_f32_e32 v81, 0, v81
	global_store_dwordx4 v[92:93], v[88:91], off
	v_max_f32_e32 v84, v84, v84
	v_max_f32_e32 v85, v85, v85
	v_pk_mul_f32 v[88:89], v[80:81], v[80:81]
	v_max_f32_e32 v81, v82, v82
	v_max_f32_e32 v80, v86, v86
	v_max_f32_e32 v82, 0, v81
	v_max_f32_e32 v81, v87, v87
	v_max_f32_e32 v83, v83, v83
	v_max_f32_e32 v84, 0, v84
	v_max_f32_e32 v85, 0, v85
	v_max_f32_e32 v80, 0, v80
	v_max_f32_e32 v81, 0, v81
	v_max_f32_e32 v83, 0, v83
	v_pk_mul_f32 v[84:85], v[84:85], v[84:85]
	v_pk_mul_f32 v[86:87], v[80:81], v[80:81]
	v_pk_mul_f32 v[90:91], v[82:83], v[82:83]
	v_max_f32_e32 v72, v72, v72
	v_max_f32_e32 v73, v73, v73
	v_cvt_pk_bf16_f32 v80, v84, v85
	v_cvt_pk_bf16_f32 v81, v86, v87
	v_cvt_pk_bf16_f32 v82, v88, v89
	v_cvt_pk_bf16_f32 v83, v90, v91
	v_max_f32_e32 v72, 0, v72
	v_max_f32_e32 v73, 0, v73
	global_store_dwordx4 v[92:93], v[80:83], off offset:256
	v_max_f32_e32 v76, v76, v76
	v_max_f32_e32 v77, v77, v77
	v_or_b32_e32 v80, 48, v154
	v_pk_mul_f32 v[82:83], v[72:73], v[72:73]
	v_max_f32_e32 v73, v74, v74
	v_ashrrev_i32_e32 v81, 31, v80
	v_max_f32_e32 v72, v78, v78
	v_max_f32_e32 v74, 0, v73
	v_max_f32_e32 v73, v79, v79
	v_max_f32_e32 v75, v75, v75
	v_lshlrev_b64 v[80:81], 13, v[80:81]
	v_max_f32_e32 v76, 0, v76
	v_max_f32_e32 v77, 0, v77
	v_max_f32_e32 v72, 0, v72
	v_max_f32_e32 v73, 0, v73
	v_max_f32_e32 v75, 0, v75
	v_lshl_add_u64 v[80:81], s[46:47], 0, v[80:81]
	v_pk_mul_f32 v[76:77], v[76:77], v[76:77]
	v_pk_mul_f32 v[78:79], v[72:73], v[72:73]
	v_pk_mul_f32 v[84:85], v[74:75], v[74:75]
	v_max_f32_e32 v64, v64, v64
	v_max_f32_e32 v65, v65, v65
	v_cvt_pk_bf16_f32 v72, v76, v77
	v_cvt_pk_bf16_f32 v73, v78, v79
	v_cvt_pk_bf16_f32 v74, v82, v83
	v_cvt_pk_bf16_f32 v75, v84, v85
	v_lshl_add_u64 v[76:77], v[80:81], 0, v[126:127]
	v_max_f32_e32 v64, 0, v64
	v_max_f32_e32 v65, 0, v65
	global_store_dwordx4 v[76:77], v[72:75], off
	v_max_f32_e32 v68, v68, v68
	v_max_f32_e32 v69, v69, v69
	v_pk_mul_f32 v[72:73], v[64:65], v[64:65]
	v_max_f32_e32 v65, v66, v66
	v_max_f32_e32 v64, v70, v70
	v_max_f32_e32 v66, 0, v65
	v_max_f32_e32 v65, v71, v71
	v_max_f32_e32 v67, v67, v67
	v_max_f32_e32 v68, 0, v68
	v_max_f32_e32 v69, 0, v69
	v_max_f32_e32 v64, 0, v64
	v_max_f32_e32 v65, 0, v65
	v_max_f32_e32 v67, 0, v67
	v_pk_mul_f32 v[68:69], v[68:69], v[68:69]
	v_pk_mul_f32 v[70:71], v[64:65], v[64:65]
	v_pk_mul_f32 v[74:75], v[66:67], v[66:67]
	v_max_f32_e32 v56, v56, v56
	v_max_f32_e32 v57, v57, v57
	v_cvt_pk_bf16_f32 v64, v68, v69
	v_cvt_pk_bf16_f32 v65, v70, v71
	v_cvt_pk_bf16_f32 v66, v72, v73
	v_cvt_pk_bf16_f32 v67, v74, v75
	v_max_f32_e32 v56, 0, v56
	v_max_f32_e32 v57, 0, v57
	global_store_dwordx4 v[76:77], v[64:67], off offset:256
	v_max_f32_e32 v60, v60, v60
	v_max_f32_e32 v61, v61, v61
	v_pk_mul_f32 v[64:65], v[56:57], v[56:57]
	v_max_f32_e32 v57, v58, v58
	v_max_f32_e32 v56, v62, v62
	v_max_f32_e32 v58, 0, v57
	v_max_f32_e32 v57, v63, v63
	v_max_f32_e32 v56, 0, v56
	v_max_f32_e32 v57, 0, v57
	v_max_f32_e32 v59, v59, v59
	v_max_f32_e32 v60, 0, v60
	v_max_f32_e32 v61, 0, v61
	v_max_f32_e32 v59, 0, v59
	v_pk_mul_f32 v[62:63], v[56:57], v[56:57]
	v_pk_mul_f32 v[60:61], v[60:61], v[60:61]
	v_pk_mul_f32 v[66:67], v[58:59], v[58:59]
	v_cvt_pk_bf16_f32 v57, v62, v63
	v_add_co_u32_e32 v62, vcc, s64, v120
	v_max_f32_e32 v48, v48, v48
	v_max_f32_e32 v49, v49, v49
	v_cvt_pk_bf16_f32 v56, v60, v61
	v_cvt_pk_bf16_f32 v58, v64, v65
	v_cvt_pk_bf16_f32 v59, v66, v67
	v_addc_co_u32_e32 v63, vcc, 0, v121, vcc
	v_max_f32_e32 v48, 0, v48
	v_max_f32_e32 v49, 0, v49
	global_store_dwordx4 v[62:63], v[56:59], off
	v_max_f32_e32 v52, v52, v52
	v_max_f32_e32 v53, v53, v53
	v_pk_mul_f32 v[56:57], v[48:49], v[48:49]
	v_max_f32_e32 v49, v50, v50
	v_max_f32_e32 v48, v54, v54
	v_max_f32_e32 v50, 0, v49
	v_max_f32_e32 v49, v55, v55
	v_max_f32_e32 v51, v51, v51
	v_max_f32_e32 v52, 0, v52
	v_max_f32_e32 v53, 0, v53
	v_max_f32_e32 v48, 0, v48
	v_max_f32_e32 v49, 0, v49
	v_max_f32_e32 v51, 0, v51
	v_pk_mul_f32 v[52:53], v[52:53], v[52:53]
	v_pk_mul_f32 v[54:55], v[48:49], v[48:49]
	v_pk_mul_f32 v[58:59], v[50:51], v[50:51]
	v_max_f32_e32 v40, v40, v40
	v_max_f32_e32 v41, v41, v41
	v_lshl_add_u64 v[60:61], v[120:121], 0, s[12:13]
	v_cvt_pk_bf16_f32 v48, v52, v53
	v_cvt_pk_bf16_f32 v49, v54, v55
	v_cvt_pk_bf16_f32 v50, v56, v57
	v_cvt_pk_bf16_f32 v51, v58, v59
	v_max_f32_e32 v40, 0, v40
	v_max_f32_e32 v41, 0, v41
	global_store_dwordx4 v[60:61], v[48:51], off offset:256
	v_max_f32_e32 v44, v44, v44
	v_max_f32_e32 v45, v45, v45
	v_pk_mul_f32 v[48:49], v[40:41], v[40:41]
	v_max_f32_e32 v41, v42, v42
	v_max_f32_e32 v40, v46, v46
	v_max_f32_e32 v42, 0, v41
	v_max_f32_e32 v41, v47, v47
	v_max_f32_e32 v40, 0, v40
	v_max_f32_e32 v41, 0, v41
	v_max_f32_e32 v43, v43, v43
	v_max_f32_e32 v44, 0, v44
	v_max_f32_e32 v45, 0, v45
	v_max_f32_e32 v43, 0, v43
	v_pk_mul_f32 v[46:47], v[40:41], v[40:41]
	v_pk_mul_f32 v[44:45], v[44:45], v[44:45]
	v_pk_mul_f32 v[50:51], v[42:43], v[42:43]
	v_cvt_pk_bf16_f32 v41, v46, v47
	v_add_co_u32_e32 v46, vcc, s65, v120
	v_max_f32_e32 v32, v32, v32
	v_max_f32_e32 v33, v33, v33
	v_cvt_pk_bf16_f32 v40, v44, v45
	v_cvt_pk_bf16_f32 v42, v48, v49
	v_cvt_pk_bf16_f32 v43, v50, v51
	v_addc_co_u32_e32 v47, vcc, 0, v121, vcc
	v_max_f32_e32 v32, 0, v32
	v_max_f32_e32 v33, 0, v33
	global_store_dwordx4 v[46:47], v[40:43], off
	v_max_f32_e32 v36, v36, v36
	v_max_f32_e32 v37, v37, v37
	v_pk_mul_f32 v[40:41], v[32:33], v[32:33]
	v_max_f32_e32 v33, v34, v34
	v_max_f32_e32 v32, v38, v38
	v_max_f32_e32 v34, 0, v33
	v_max_f32_e32 v33, v39, v39
	v_max_f32_e32 v35, v35, v35
	v_max_f32_e32 v36, 0, v36
	v_max_f32_e32 v37, 0, v37
	v_max_f32_e32 v32, 0, v32
	v_max_f32_e32 v33, 0, v33
	v_max_f32_e32 v35, 0, v35
	v_pk_mul_f32 v[36:37], v[36:37], v[36:37]
	v_pk_mul_f32 v[38:39], v[32:33], v[32:33]
	v_pk_mul_f32 v[42:43], v[34:35], v[34:35]
	v_max_f32_e32 v24, v24, v24
	v_max_f32_e32 v25, v25, v25
	v_lshl_add_u64 v[44:45], v[120:121], 0, s[14:15]
	v_cvt_pk_bf16_f32 v32, v36, v37
	v_cvt_pk_bf16_f32 v33, v38, v39
	v_cvt_pk_bf16_f32 v34, v40, v41
	v_cvt_pk_bf16_f32 v35, v42, v43
	v_max_f32_e32 v24, 0, v24
	v_max_f32_e32 v25, 0, v25
	global_store_dwordx4 v[44:45], v[32:35], off offset:256
	v_max_f32_e32 v28, v28, v28
	v_max_f32_e32 v29, v29, v29
	v_pk_mul_f32 v[32:33], v[24:25], v[24:25]
	v_max_f32_e32 v25, v26, v26
	v_max_f32_e32 v24, v30, v30
	v_max_f32_e32 v26, 0, v25
	v_max_f32_e32 v25, v31, v31
	v_max_f32_e32 v24, 0, v24
	v_max_f32_e32 v25, 0, v25
	v_max_f32_e32 v27, v27, v27
	v_max_f32_e32 v28, 0, v28
	v_max_f32_e32 v29, 0, v29
	v_max_f32_e32 v27, 0, v27
	v_pk_mul_f32 v[30:31], v[24:25], v[24:25]
	v_pk_mul_f32 v[28:29], v[28:29], v[28:29]
	v_pk_mul_f32 v[34:35], v[26:27], v[26:27]
	v_cvt_pk_bf16_f32 v25, v30, v31
	v_add_co_u32_e32 v30, vcc, s70, v120
	v_max_f32_e32 v16, v16, v16
	v_max_f32_e32 v17, v17, v17
	v_cvt_pk_bf16_f32 v24, v28, v29
	v_cvt_pk_bf16_f32 v26, v32, v33
	v_cvt_pk_bf16_f32 v27, v34, v35
	v_addc_co_u32_e32 v31, vcc, 0, v121, vcc
	v_max_f32_e32 v16, 0, v16
	v_max_f32_e32 v17, 0, v17
	global_store_dwordx4 v[30:31], v[24:27], off
	v_max_f32_e32 v20, v20, v20
	v_max_f32_e32 v21, v21, v21
	v_pk_mul_f32 v[24:25], v[16:17], v[16:17]
	v_max_f32_e32 v17, v18, v18
	v_max_f32_e32 v16, v22, v22
	v_max_f32_e32 v18, 0, v17
	v_max_f32_e32 v17, v23, v23
	v_max_f32_e32 v19, v19, v19
	v_max_f32_e32 v20, 0, v20
	v_max_f32_e32 v21, 0, v21
	v_max_f32_e32 v16, 0, v16
	v_max_f32_e32 v17, 0, v17
	v_max_f32_e32 v19, 0, v19
	v_pk_mul_f32 v[20:21], v[20:21], v[20:21]
	v_pk_mul_f32 v[22:23], v[16:17], v[16:17]
	v_pk_mul_f32 v[26:27], v[18:19], v[18:19]
	v_max_f32_e32 v8, v8, v8
	v_max_f32_e32 v9, v9, v9
	v_lshl_add_u64 v[28:29], v[120:121], 0, s[16:17]
	v_cvt_pk_bf16_f32 v16, v20, v21
	v_cvt_pk_bf16_f32 v17, v22, v23
	v_cvt_pk_bf16_f32 v18, v24, v25
	v_cvt_pk_bf16_f32 v19, v26, v27
	v_max_f32_e32 v8, 0, v8
	v_max_f32_e32 v9, 0, v9
	global_store_dwordx4 v[28:29], v[16:19], off offset:256
	v_max_f32_e32 v12, v12, v12
	v_max_f32_e32 v13, v13, v13
	v_pk_mul_f32 v[16:17], v[8:9], v[8:9]
	v_max_f32_e32 v9, v10, v10
	v_max_f32_e32 v8, v14, v14
	v_max_f32_e32 v10, 0, v9
	v_max_f32_e32 v9, v15, v15
	v_max_f32_e32 v8, 0, v8
	v_max_f32_e32 v9, 0, v9
	v_max_f32_e32 v11, v11, v11
	v_max_f32_e32 v12, 0, v12
	v_max_f32_e32 v13, 0, v13
	v_max_f32_e32 v11, 0, v11
	v_pk_mul_f32 v[14:15], v[8:9], v[8:9]
	v_pk_mul_f32 v[12:13], v[12:13], v[12:13]
	v_pk_mul_f32 v[18:19], v[10:11], v[10:11]
	v_cvt_pk_bf16_f32 v9, v14, v15
	v_add_co_u32_e32 v14, vcc, s71, v120
	v_max_f32_e32 v0, v0, v0
	v_max_f32_e32 v1, v1, v1
	v_cvt_pk_bf16_f32 v8, v12, v13
	v_cvt_pk_bf16_f32 v10, v16, v17
	v_cvt_pk_bf16_f32 v11, v18, v19
	v_addc_co_u32_e32 v15, vcc, 0, v121, vcc
	v_max_f32_e32 v0, 0, v0
	v_max_f32_e32 v1, 0, v1
	global_store_dwordx4 v[14:15], v[8:11], off
	v_max_f32_e32 v4, v4, v4
	v_max_f32_e32 v5, v5, v5
	v_pk_mul_f32 v[8:9], v[0:1], v[0:1]
	v_max_f32_e32 v1, v2, v2
	v_max_f32_e32 v0, v6, v6
	v_max_f32_e32 v2, 0, v1
	v_max_f32_e32 v1, v7, v7
	v_max_f32_e32 v3, v3, v3
	v_max_f32_e32 v4, 0, v4
	v_max_f32_e32 v5, 0, v5
	v_max_f32_e32 v0, 0, v0
	v_max_f32_e32 v1, 0, v1
	v_max_f32_e32 v3, 0, v3
	v_pk_mul_f32 v[4:5], v[4:5], v[4:5]
	v_pk_mul_f32 v[6:7], v[0:1], v[0:1]
	v_pk_mul_f32 v[10:11], v[2:3], v[2:3]
	v_lshl_add_u64 v[12:13], v[120:121], 0, s[18:19]
	v_cvt_pk_bf16_f32 v0, v4, v5
	v_cvt_pk_bf16_f32 v1, v6, v7
	v_cvt_pk_bf16_f32 v2, v8, v9
	v_cvt_pk_bf16_f32 v3, v10, v11
	s_and_b64 vcc, exec, s[4:5]
	s_mov_b32 s72, s20
	s_mov_b32 s34, s26
	s_mov_b64 s[38:39], s[30:31]
	s_mov_b64 s[36:37], s[28:29]
	global_store_dwordx4 v[12:13], v[0:3], off offset:256
	s_cbranch_vccz .LBB0_1303
	s_waitcnt vmcnt(0)
	s_cmpk_gt_u32 s42, 0xff
	s_cbranch_scc1 .LBB0_1314
	s_barrier

.LBB0_1384:
	ds_read_b128 v[156:159], v153
	ds_read_b128 v[160:163], v153 offset:1024
	ds_read_b128 v[164:167], v153 offset:2048
	ds_read_b128 v[168:171], v153 offset:3072
	s_add_u32 s36, s34, 0xfff00080
	s_addc_u32 s37, s35, -1
	s_cmp_eq_u32 s77, 60
	s_cselect_b32 s39, s27, s37
	s_cselect_b32 s38, s73, s36
	s_cselect_b32 s37, s21, s76
	s_cselect_b32 s36, s74, s75
	v_lshl_add_u64 v[204:205], s[34:35], 0, v[138:139]
	s_add_i32 m0, s19, 0xc000
	ds_read_b128 v[172:175], v154
	ds_read_b128 v[176:179], v154 offset:1024
	ds_read_b128 v[180:183], v154 offset:2048
	ds_read_b128 v[184:187], v154 offset:3072
	ds_read_b128 v[188:191], v154 offset:4096
	ds_read_b128 v[192:195], v154 offset:5120
	ds_read_b128 v[196:199], v154 offset:6144
	ds_read_b128 v[200:203], v154 offset:7168
	global_load_lds_dwordx4 v[204:205], off
	v_lshl_add_u64 v[204:205], s[34:35], 0, v[140:141]
	s_add_i32 m0, s19, 0xe000
	s_nop 0
	global_load_lds_dwordx4 v[204:205], off
	s_barrier
	s_waitcnt lgkmcnt(0)
	s_waitcnt lgkmcnt(0)
	v_mfma_f32_16x16x32_bf16 v[124:127], v[156:159], v[172:175], v[124:127]
	v_mfma_f32_16x16x32_bf16 v[120:123], v[164:167], v[172:175], v[120:123]
	v_mfma_f32_16x16x32_bf16 v[116:119], v[156:159], v[180:183], v[116:119]
	v_mfma_f32_16x16x32_bf16 v[112:115], v[164:167], v[180:183], v[112:115]
	v_mfma_f32_16x16x32_bf16 v[100:103], v[156:159], v[188:191], v[100:103]
	v_mfma_f32_16x16x32_bf16 v[96:99], v[164:167], v[188:191], v[96:99]
	v_mfma_f32_16x16x32_bf16 v[84:87], v[156:159], v[196:199], v[84:87]
	v_mfma_f32_16x16x32_bf16 v[80:83], v[164:167], v[196:199], v[80:83]
	v_mfma_f32_16x16x32_bf16 v[124:127], v[160:163], v[176:179], v[124:127]
	v_mfma_f32_16x16x32_bf16 v[120:123], v[168:171], v[176:179], v[120:123]
	v_mfma_f32_16x16x32_bf16 v[116:119], v[160:163], v[184:187], v[116:119]
	v_mfma_f32_16x16x32_bf16 v[112:115], v[168:171], v[184:187], v[112:115]
	v_mfma_f32_16x16x32_bf16 v[100:103], v[160:163], v[192:195], v[100:103]
	v_mfma_f32_16x16x32_bf16 v[96:99], v[168:171], v[192:195], v[96:99]
	v_mfma_f32_16x16x32_bf16 v[84:87], v[160:163], v[200:203], v[84:87]
	v_mfma_f32_16x16x32_bf16 v[80:83], v[168:171], v[200:203], v[80:83]
	s_barrier
	s_add_i32 s78, s62, s43
	v_lshl_add_u64 v[220:221], s[36:37], 0, v[134:135]
	s_mov_b32 m0, s78
	ds_read_b128 v[204:207], v155
	ds_read_b128 v[208:211], v155 offset:1024
	ds_read_b128 v[212:215], v155 offset:2048
	ds_read_b128 v[216:219], v155 offset:3072
	global_load_lds_dwordx4 v[220:221], off
	v_lshl_add_u64 v[222:223], s[36:37], 0, v[130:131]
	s_add_i32 m0, s78, 0x2000
	s_nop 0
	global_load_lds_dwordx4 v[222:223], off
	s_barrier
	s_waitcnt lgkmcnt(0)
	s_waitcnt lgkmcnt(0)
	v_mfma_f32_16x16x32_bf16 v[108:111], v[204:207], v[172:175], v[108:111]
	v_mfma_f32_16x16x32_bf16 v[104:107], v[212:215], v[172:175], v[104:107]
	v_mfma_f32_16x16x32_bf16 v[92:95], v[204:207], v[180:183], v[92:95]
	v_mfma_f32_16x16x32_bf16 v[88:91], v[212:215], v[180:183], v[88:91]
	v_mfma_f32_16x16x32_bf16 v[76:79], v[204:207], v[188:191], v[76:79]
	v_mfma_f32_16x16x32_bf16 v[72:75], v[212:215], v[188:191], v[72:75]
	v_mfma_f32_16x16x32_bf16 v[68:71], v[204:207], v[196:199], v[68:71]
	v_mfma_f32_16x16x32_bf16 v[64:67], v[212:215], v[196:199], v[64:67]
	v_mfma_f32_16x16x32_bf16 v[108:111], v[208:211], v[176:179], v[108:111]
	v_mfma_f32_16x16x32_bf16 v[104:107], v[216:219], v[176:179], v[104:107]
	v_mfma_f32_16x16x32_bf16 v[92:95], v[208:211], v[184:187], v[92:95]
	v_mfma_f32_16x16x32_bf16 v[88:91], v[216:219], v[184:187], v[88:91]
	v_mfma_f32_16x16x32_bf16 v[76:79], v[208:211], v[192:195], v[76:79]
	v_mfma_f32_16x16x32_bf16 v[72:75], v[216:219], v[192:195], v[72:75]
	v_mfma_f32_16x16x32_bf16 v[68:71], v[208:211], v[200:203], v[68:71]
	v_mfma_f32_16x16x32_bf16 v[64:67], v[216:219], v[200:203], v[64:67]
	s_mov_b32 m0, s19
	v_lshl_add_u64 v[224:225], s[38:39], 0, v[136:137]
	s_barrier
	ds_read_b128 v[172:175], v154 offset:16384
	ds_read_b128 v[176:179], v154 offset:17408
	ds_read_b128 v[180:183], v154 offset:18432
	ds_read_b128 v[184:187], v154 offset:19456
	ds_read_b128 v[188:191], v154 offset:20480
	ds_read_b128 v[192:195], v154 offset:21504
	ds_read_b128 v[196:199], v154 offset:22528
	ds_read_b128 v[200:203], v154 offset:23552
	global_load_lds_dwordx4 v[224:225], off
	v_lshl_add_u64 v[226:227], s[38:39], 0, v[132:133]
	s_mov_b32 m0, s53
	s_nop 0
	global_load_lds_dwordx4 v[226:227], off
	s_barrier
	s_waitcnt lgkmcnt(0)
	s_waitcnt lgkmcnt(0)
	v_mfma_f32_16x16x32_bf16 v[60:63], v[156:159], v[172:175], v[60:63]
	v_mfma_f32_16x16x32_bf16 v[56:59], v[164:167], v[172:175], v[56:59]
	v_mfma_f32_16x16x32_bf16 v[52:55], v[156:159], v[180:183], v[52:55]
	v_mfma_f32_16x16x32_bf16 v[48:51], v[164:167], v[180:183], v[48:51]
	v_mfma_f32_16x16x32_bf16 v[36:39], v[156:159], v[188:191], v[36:39]
	v_mfma_f32_16x16x32_bf16 v[32:35], v[164:167], v[188:191], v[32:35]
	v_mfma_f32_16x16x32_bf16 v[20:23], v[156:159], v[196:199], v[20:23]
	v_mfma_f32_16x16x32_bf16 v[16:19], v[164:167], v[196:199], v[16:19]
	v_mfma_f32_16x16x32_bf16 v[60:63], v[160:163], v[176:179], v[60:63]
	v_mfma_f32_16x16x32_bf16 v[56:59], v[168:171], v[176:179], v[56:59]
	v_mfma_f32_16x16x32_bf16 v[52:55], v[160:163], v[184:187], v[52:55]
	v_mfma_f32_16x16x32_bf16 v[48:51], v[168:171], v[184:187], v[48:51]
	v_mfma_f32_16x16x32_bf16 v[36:39], v[160:163], v[192:195], v[36:39]
	v_mfma_f32_16x16x32_bf16 v[32:35], v[168:171], v[192:195], v[32:35]
	v_mfma_f32_16x16x32_bf16 v[20:23], v[160:163], v[200:203], v[20:23]
	v_mfma_f32_16x16x32_bf16 v[16:19], v[168:171], v[200:203], v[16:19]
	s_barrier
	s_add_u32 s78, s36, 0x100000
	s_addc_u32 s79, s37, 0
	s_add_i32 s80, s63, s43
	v_lshl_add_u64 v[156:157], s[78:79], 0, v[134:135]
	s_mov_b32 m0, s80
	s_nop 0
	global_load_lds_dwordx4 v[156:157], off
	v_lshl_add_u64 v[156:157], s[78:79], 0, v[130:131]
	s_add_i32 m0, s80, 0x2000
	s_nop 0
	global_load_lds_dwordx4 v[156:157], off
	s_waitcnt vmcnt(6)
	s_barrier
	v_mfma_f32_16x16x32_bf16 v[44:47], v[204:207], v[172:175], v[44:47]
	v_mfma_f32_16x16x32_bf16 v[40:43], v[212:215], v[172:175], v[40:43]
	v_mfma_f32_16x16x32_bf16 v[28:31], v[204:207], v[180:183], v[28:31]
	v_mfma_f32_16x16x32_bf16 v[24:27], v[212:215], v[180:183], v[24:27]
	v_mfma_f32_16x16x32_bf16 v[12:15], v[204:207], v[188:191], v[12:15]
	v_mfma_f32_16x16x32_bf16 v[8:11], v[212:215], v[188:191], v[8:11]
	v_mfma_f32_16x16x32_bf16 v[4:7], v[204:207], v[196:199], v[4:7]
	v_mfma_f32_16x16x32_bf16 v[0:3], v[212:215], v[196:199], v[0:3]
	v_mfma_f32_16x16x32_bf16 v[44:47], v[208:211], v[176:179], v[44:47]
	v_mfma_f32_16x16x32_bf16 v[40:43], v[216:219], v[176:179], v[40:43]
	v_mfma_f32_16x16x32_bf16 v[28:31], v[208:211], v[184:187], v[28:31]
	v_mfma_f32_16x16x32_bf16 v[24:27], v[216:219], v[184:187], v[24:27]
	v_mfma_f32_16x16x32_bf16 v[12:15], v[208:211], v[192:195], v[12:15]
	v_mfma_f32_16x16x32_bf16 v[8:11], v[216:219], v[192:195], v[8:11]
	v_mfma_f32_16x16x32_bf16 v[4:7], v[208:211], v[200:203], v[4:7]
	v_mfma_f32_16x16x32_bf16 v[0:3], v[216:219], v[200:203], v[0:3]
	s_add_i32 s78, 0, 0x18000
	v_add_u32_e32 v168, s78, v151
	s_barrier
	ds_read_b128 v[156:159], v168
	ds_read_b128 v[160:163], v168 offset:1024
	ds_read_b128 v[164:167], v168 offset:2048
	ds_read_b128 v[168:171], v168 offset:3072
	s_add_u32 s38, s38, 0x100000
	s_addc_u32 s39, s39, 0
	s_mov_b32 m0, s54
	v_lshl_add_u64 v[204:205], s[38:39], 0, v[136:137]
	ds_read_b128 v[172:175], v154 offset:32768
	ds_read_b128 v[176:179], v154 offset:33792
	ds_read_b128 v[180:183], v154 offset:34816
	ds_read_b128 v[184:187], v154 offset:35840
	ds_read_b128 v[188:191], v154 offset:36864
	ds_read_b128 v[192:195], v154 offset:37888
	ds_read_b128 v[196:199], v154 offset:38912
	ds_read_b128 v[200:203], v154 offset:39936
	global_load_lds_dwordx4 v[204:205], off
	v_lshl_add_u64 v[204:205], s[38:39], 0, v[132:133]
	s_mov_b32 m0, s55
	s_nop 0
	global_load_lds_dwordx4 v[204:205], off
	s_barrier
	s_waitcnt lgkmcnt(0)
	s_waitcnt lgkmcnt(0)
	v_mfma_f32_16x16x32_bf16 v[124:127], v[156:159], v[172:175], v[124:127]
	v_mfma_f32_16x16x32_bf16 v[120:123], v[164:167], v[172:175], v[120:123]
	v_mfma_f32_16x16x32_bf16 v[116:119], v[156:159], v[180:183], v[116:119]
	v_mfma_f32_16x16x32_bf16 v[112:115], v[164:167], v[180:183], v[112:115]
	v_mfma_f32_16x16x32_bf16 v[100:103], v[156:159], v[188:191], v[100:103]
	v_mfma_f32_16x16x32_bf16 v[96:99], v[164:167], v[188:191], v[96:99]
	v_mfma_f32_16x16x32_bf16 v[84:87], v[156:159], v[196:199], v[84:87]
	v_mfma_f32_16x16x32_bf16 v[80:83], v[164:167], v[196:199], v[80:83]
	v_mfma_f32_16x16x32_bf16 v[124:127], v[160:163], v[176:179], v[124:127]
	v_mfma_f32_16x16x32_bf16 v[120:123], v[168:171], v[176:179], v[120:123]
	v_mfma_f32_16x16x32_bf16 v[116:119], v[160:163], v[184:187], v[116:119]
	v_mfma_f32_16x16x32_bf16 v[112:115], v[168:171], v[184:187], v[112:115]
	v_mfma_f32_16x16x32_bf16 v[100:103], v[160:163], v[192:195], v[100:103]
	v_mfma_f32_16x16x32_bf16 v[96:99], v[168:171], v[192:195], v[96:99]
	v_mfma_f32_16x16x32_bf16 v[84:87], v[160:163], v[200:203], v[84:87]
	v_mfma_f32_16x16x32_bf16 v[80:83], v[168:171], v[200:203], v[80:83]
	s_barrier
	s_add_i32 s38, 0, 0x1c000
	s_add_i32 s39, s78, s43
	v_add_u32_e32 v216, s38, v151
	v_lshl_add_u64 v[220:221], v[220:221], 0, s[8:9]
	s_mov_b32 m0, s39
	ds_read_b128 v[204:207], v216
	ds_read_b128 v[208:211], v216 offset:1024
	ds_read_b128 v[212:215], v216 offset:2048
	ds_read_b128 v[216:219], v216 offset:3072
	global_load_lds_dwordx4 v[220:221], off
	v_lshl_add_u64 v[220:221], v[222:223], 0, s[8:9]
	s_add_i32 m0, s39, 0x2000
	s_nop 0
	global_load_lds_dwordx4 v[220:221], off
	s_barrier
	s_waitcnt lgkmcnt(0)
	s_waitcnt lgkmcnt(0)
	v_mfma_f32_16x16x32_bf16 v[108:111], v[204:207], v[172:175], v[108:111]
	v_mfma_f32_16x16x32_bf16 v[104:107], v[212:215], v[172:175], v[104:107]
	v_mfma_f32_16x16x32_bf16 v[92:95], v[204:207], v[180:183], v[92:95]
	v_mfma_f32_16x16x32_bf16 v[88:91], v[212:215], v[180:183], v[88:91]
	v_mfma_f32_16x16x32_bf16 v[76:79], v[204:207], v[188:191], v[76:79]
	v_mfma_f32_16x16x32_bf16 v[72:75], v[212:215], v[188:191], v[72:75]
	v_mfma_f32_16x16x32_bf16 v[68:71], v[204:207], v[196:199], v[68:71]
	v_mfma_f32_16x16x32_bf16 v[64:67], v[212:215], v[196:199], v[64:67]
	v_mfma_f32_16x16x32_bf16 v[108:111], v[208:211], v[176:179], v[108:111]
	v_mfma_f32_16x16x32_bf16 v[104:107], v[216:219], v[176:179], v[104:107]
	v_mfma_f32_16x16x32_bf16 v[92:95], v[208:211], v[184:187], v[92:95]
	v_mfma_f32_16x16x32_bf16 v[88:91], v[216:219], v[184:187], v[88:91]
	v_mfma_f32_16x16x32_bf16 v[76:79], v[208:211], v[192:195], v[76:79]
	v_mfma_f32_16x16x32_bf16 v[72:75], v[216:219], v[192:195], v[72:75]
	v_mfma_f32_16x16x32_bf16 v[68:71], v[208:211], v[200:203], v[68:71]
	v_mfma_f32_16x16x32_bf16 v[64:67], v[216:219], v[200:203], v[64:67]
	s_mov_b32 m0, s57
	v_lshl_add_u64 v[220:221], v[224:225], 0, s[8:9]
	s_barrier
	ds_read_b128 v[172:175], v154 offset:49152
	ds_read_b128 v[176:179], v154 offset:50176
	ds_read_b128 v[180:183], v154 offset:51200
	ds_read_b128 v[184:187], v154 offset:52224
	ds_read_b128 v[188:191], v154 offset:53248
	ds_read_b128 v[192:195], v154 offset:54272
	ds_read_b128 v[196:199], v154 offset:55296
	ds_read_b128 v[200:203], v154 offset:56320
	global_load_lds_dwordx4 v[220:221], off
	v_lshl_add_u64 v[220:221], v[226:227], 0, s[8:9]
	s_mov_b32 m0, s60
	s_nop 0
	global_load_lds_dwordx4 v[220:221], off
	s_barrier
	s_waitcnt lgkmcnt(0)
	s_waitcnt lgkmcnt(0)
	v_mfma_f32_16x16x32_bf16 v[60:63], v[156:159], v[172:175], v[60:63]
	v_mfma_f32_16x16x32_bf16 v[56:59], v[164:167], v[172:175], v[56:59]
	v_mfma_f32_16x16x32_bf16 v[52:55], v[156:159], v[180:183], v[52:55]
	v_mfma_f32_16x16x32_bf16 v[48:51], v[164:167], v[180:183], v[48:51]
	v_mfma_f32_16x16x32_bf16 v[36:39], v[156:159], v[188:191], v[36:39]
	v_mfma_f32_16x16x32_bf16 v[32:35], v[164:167], v[188:191], v[32:35]
	v_mfma_f32_16x16x32_bf16 v[20:23], v[156:159], v[196:199], v[20:23]
	v_mfma_f32_16x16x32_bf16 v[16:19], v[164:167], v[196:199], v[16:19]
	v_mfma_f32_16x16x32_bf16 v[60:63], v[160:163], v[176:179], v[60:63]
	v_mfma_f32_16x16x32_bf16 v[56:59], v[168:171], v[176:179], v[56:59]
	v_mfma_f32_16x16x32_bf16 v[52:55], v[160:163], v[184:187], v[52:55]
	v_mfma_f32_16x16x32_bf16 v[48:51], v[168:171], v[184:187], v[48:51]
	v_mfma_f32_16x16x32_bf16 v[36:39], v[160:163], v[192:195], v[36:39]
	v_mfma_f32_16x16x32_bf16 v[32:35], v[168:171], v[192:195], v[32:35]
	v_mfma_f32_16x16x32_bf16 v[20:23], v[160:163], v[200:203], v[20:23]
	v_mfma_f32_16x16x32_bf16 v[16:19], v[168:171], v[200:203], v[16:19]
	s_barrier
	s_add_u32 s36, s36, 0x100080
	s_addc_u32 s37, s37, 0
	s_add_i32 s38, s38, s43
	v_lshl_add_u64 v[156:157], s[36:37], 0, v[134:135]
	s_mov_b32 m0, s38
	s_nop 0
	global_load_lds_dwordx4 v[156:157], off
	v_lshl_add_u64 v[156:157], s[36:37], 0, v[130:131]
	s_add_i32 m0, s38, 0x2000
	s_nop 0
	global_load_lds_dwordx4 v[156:157], off
	s_waitcnt vmcnt(6)
	s_barrier
	v_mfma_f32_16x16x32_bf16 v[44:47], v[204:207], v[172:175], v[44:47]
	v_mfma_f32_16x16x32_bf16 v[40:43], v[212:215], v[172:175], v[40:43]
	v_mfma_f32_16x16x32_bf16 v[28:31], v[204:207], v[180:183], v[28:31]
	v_mfma_f32_16x16x32_bf16 v[24:27], v[212:215], v[180:183], v[24:27]
	v_mfma_f32_16x16x32_bf16 v[12:15], v[204:207], v[188:191], v[12:15]
	v_mfma_f32_16x16x32_bf16 v[8:11], v[212:215], v[188:191], v[8:11]
	v_mfma_f32_16x16x32_bf16 v[4:7], v[204:207], v[196:199], v[4:7]
	v_mfma_f32_16x16x32_bf16 v[0:3], v[212:215], v[196:199], v[0:3]
	v_mfma_f32_16x16x32_bf16 v[44:47], v[208:211], v[176:179], v[44:47]
	v_mfma_f32_16x16x32_bf16 v[40:43], v[216:219], v[176:179], v[40:43]
	v_mfma_f32_16x16x32_bf16 v[28:31], v[208:211], v[184:187], v[28:31]
	v_mfma_f32_16x16x32_bf16 v[24:27], v[216:219], v[184:187], v[24:27]
	v_mfma_f32_16x16x32_bf16 v[12:15], v[208:211], v[192:195], v[12:15]
	v_mfma_f32_16x16x32_bf16 v[8:11], v[216:219], v[192:195], v[8:11]
	v_mfma_f32_16x16x32_bf16 v[4:7], v[208:211], v[200:203], v[4:7]
	v_mfma_f32_16x16x32_bf16 v[0:3], v[216:219], v[200:203], v[0:3]
	s_add_i32 s77, s77, 2
	s_add_u32 s34, s34, 0x100
	s_addc_u32 s35, s35, 0
	s_add_u32 s75, s75, 0x100
	s_addc_u32 s76, s76, 0
	s_cmp_gt_u32 s77, 61
	s_barrier
	s_cbranch_scc0 .LBB0_1384
	v_lshl_add_u32 v156, s18, 8, v150
	v_lshl_or_b32 v158, s72, 8, v152
	v_ashrrev_i32_e32 v157, 31, v156
	v_lshlrev_b64 v[160:161], 11, v[156:157]
	v_ashrrev_i32_e32 v159, 31, v158
	v_lshl_add_u64 v[160:161], s[44:45], 0, v[160:161]
	v_cvt_pk_bf16_f32 v124, v124, v125
	v_cvt_pk_bf16_f32 v125, v126, v127
	v_cvt_pk_bf16_f32 v126, v120, v121
	v_lshlrev_b64 v[120:121], 1, v[158:159]
	v_cvt_pk_bf16_f32 v127, v122, v123
	v_lshl_add_u64 v[122:123], v[160:161], 0, v[120:121]
	v_cvt_pk_bf16_f32 v108, v108, v109
	v_cvt_pk_bf16_f32 v109, v110, v111
	v_cvt_pk_bf16_f32 v110, v104, v105
	v_or_b32_e32 v104, 16, v156
	v_cvt_pk_bf16_f32 v60, v60, v61
	v_cvt_pk_bf16_f32 v61, v62, v63
	v_cvt_pk_bf16_f32 v63, v58, v59
	v_add_co_u32_e32 v58, vcc, s64, v122
	v_ashrrev_i32_e32 v105, 31, v104
	v_cvt_pk_bf16_f32 v62, v56, v57
	v_lshl_add_u64 v[56:57], v[122:123], 0, s[10:11]
	v_addc_co_u32_e32 v59, vcc, 0, v123, vcc
	v_cvt_pk_bf16_f32 v44, v44, v45
	v_cvt_pk_bf16_f32 v45, v46, v47
	v_cvt_pk_bf16_f32 v46, v40, v41
	v_cvt_pk_bf16_f32 v47, v42, v43
	v_cvt_pk_bf16_f32 v111, v106, v107
	v_lshlrev_b64 v[104:105], 11, v[104:105]
	v_cvt_pk_bf16_f32 v92, v92, v93
	v_cvt_pk_bf16_f32 v93, v94, v95
	v_cvt_pk_bf16_f32 v94, v88, v89
	v_or_b32_e32 v88, 32, v156
	global_store_dwordx4 v[56:57], v[44:47], off offset:256
	global_store_dwordx4 v[122:123], v[108:111], off offset:256
	v_ashrrev_i32_e32 v89, 31, v88
	v_add_co_u32_e32 v46, vcc, s65, v122
	v_lshl_add_u64 v[108:109], s[44:45], 0, v[104:105]
	v_lshl_add_u64 v[44:45], v[122:123], 0, s[12:13]
	v_addc_co_u32_e32 v47, vcc, 0, v123, vcc
	v_cvt_pk_bf16_f32 v28, v28, v29
	v_cvt_pk_bf16_f32 v29, v30, v31
	v_cvt_pk_bf16_f32 v30, v24, v25
	v_cvt_pk_bf16_f32 v31, v26, v27
	v_lshl_add_u64 v[108:109], v[108:109], 0, v[120:121]
	v_cvt_pk_bf16_f32 v95, v90, v91
	v_lshlrev_b64 v[88:89], 11, v[88:89]
	v_cvt_pk_bf16_f32 v76, v76, v77
	v_cvt_pk_bf16_f32 v77, v78, v79
	v_cvt_pk_bf16_f32 v78, v72, v73
	v_or_b32_e32 v72, 48, v156
	global_store_dwordx4 v[44:45], v[28:31], off offset:256
	global_store_dwordx4 v[108:109], v[92:95], off offset:256
	v_ashrrev_i32_e32 v73, 31, v72
	v_add_co_u32_e32 v30, vcc, s70, v122
	v_lshl_add_u64 v[92:93], s[44:45], 0, v[88:89]
	v_lshl_add_u64 v[28:29], v[122:123], 0, s[14:15]
	v_addc_co_u32_e32 v31, vcc, 0, v123, vcc
	v_cvt_pk_bf16_f32 v12, v12, v13
	v_cvt_pk_bf16_f32 v13, v14, v15
	v_cvt_pk_bf16_f32 v14, v8, v9
	v_cvt_pk_bf16_f32 v15, v10, v11
	v_lshl_add_u64 v[92:93], v[92:93], 0, v[120:121]
	v_cvt_pk_bf16_f32 v79, v74, v75
	v_lshlrev_b64 v[72:73], 11, v[72:73]
	global_store_dwordx4 v[28:29], v[12:15], off offset:256
	global_store_dwordx4 v[92:93], v[76:79], off offset:256
	v_cvt_pk_bf16_f32 v104, v116, v117
	v_add_co_u32_e32 v14, vcc, s71, v122
	v_lshl_add_u64 v[76:77], s[44:45], 0, v[72:73]
	s_nop 0
	v_addc_co_u32_e32 v15, vcc, 0, v123, vcc
	v_cvt_pk_bf16_f32 v105, v118, v119
	v_cvt_pk_bf16_f32 v106, v112, v113
	v_cvt_pk_bf16_f32 v107, v114, v115
	v_cvt_pk_bf16_f32 v88, v100, v101
	v_cvt_pk_bf16_f32 v89, v102, v103
	v_cvt_pk_bf16_f32 v90, v96, v97
	v_cvt_pk_bf16_f32 v91, v98, v99
	v_cvt_pk_bf16_f32 v72, v84, v85
	v_cvt_pk_bf16_f32 v73, v86, v87
	v_cvt_pk_bf16_f32 v74, v80, v81
	v_cvt_pk_bf16_f32 v75, v82, v83
	v_lshl_add_u64 v[76:77], v[76:77], 0, v[120:121]
	v_cvt_pk_bf16_f32 v68, v68, v69
	v_cvt_pk_bf16_f32 v69, v70, v71
	v_cvt_pk_bf16_f32 v70, v64, v65
	v_cvt_pk_bf16_f32 v71, v66, v67
	v_cvt_pk_bf16_f32 v40, v52, v53
	v_cvt_pk_bf16_f32 v41, v54, v55
	v_cvt_pk_bf16_f32 v42, v48, v49
	v_cvt_pk_bf16_f32 v43, v50, v51
	v_cvt_pk_bf16_f32 v24, v36, v37
	v_cvt_pk_bf16_f32 v25, v38, v39
	v_cvt_pk_bf16_f32 v26, v32, v33
	v_cvt_pk_bf16_f32 v27, v34, v35
	v_cvt_pk_bf16_f32 v8, v20, v21
	v_cvt_pk_bf16_f32 v9, v22, v23
	v_cvt_pk_bf16_f32 v10, v16, v17
	v_cvt_pk_bf16_f32 v11, v18, v19
	v_lshl_add_u64 v[12:13], v[122:123], 0, s[16:17]
	v_cvt_pk_bf16_f32 v4, v4, v5
	v_cvt_pk_bf16_f32 v5, v6, v7
	v_cvt_pk_bf16_f32 v6, v0, v1
	v_cvt_pk_bf16_f32 v7, v2, v3
	s_and_b64 vcc, exec, s[4:5]
	s_mov_b32 s72, s20
	s_mov_b32 s18, s26
	s_mov_b64 s[36:37], s[30:31]
	s_mov_b64 s[34:35], s[28:29]
	global_store_dwordx4 v[122:123], v[124:127], off
	global_store_dwordx4 v[108:109], v[104:107], off
	global_store_dwordx4 v[92:93], v[88:91], off
	global_store_dwordx4 v[76:77], v[72:75], off
	global_store_dwordx4 v[76:77], v[68:71], off offset:256
	global_store_dwordx4 v[58:59], v[60:63], off
	global_store_dwordx4 v[46:47], v[40:43], off
	global_store_dwordx4 v[30:31], v[24:27], off
	global_store_dwordx4 v[14:15], v[8:11], off
	global_store_dwordx4 v[12:13], v[4:7], off offset:256
	s_cbranch_vccz .LBB0_1381
	s_waitcnt vmcnt(0)
	s_cmpk_gt_u32 s40, 0xff
	s_cbranch_scc1 .LBB0_1388
	s_barrier
